# GEMM K-loops: priority raise moved in front of each segment barrier, repeated lgkmcnt(0) after the barrier and mid-burst priority flip pairs removed
# speedup vs baseline: 1.0125x; 1.0125x over previous
; #define PG8_STAGE(bufoff, gbase, voff) do { _Pragma("unroll") for (int _i = 0; _i < 2; ++_i) \
;         __builtin_amdgcn_global_load_lds((const unsigned*)((const char*)(gbase) + (voff)[_i]), (PG8_LAS unsigned*)(lds + (bufoff) + ldsw + _i * 8192), 16, 0, 0); } while (0)
; #define PG8_WAIT_V(n) asm volatile("s_waitcnt vmcnt(" #n ")" ::: "memory")
; #define PG8_WAIT_L(n) asm volatile("s_waitcnt lgkmcnt(" #n ")" ::: "memory")
; #define PG8_BAR __builtin_amdgcn_s_barrier()
; template <class Epi, class Sched, bool ALIGN_EPI = false, bool SP2 = false>
; __device__ __forceinline__ void gemm_phase(PG8_LAS unsigned char* lds, const Gemm g, const Sched& S, const Epi& E, const int wid) {
;     ...
;     for (;;) {
;         const bool has_next = S.next(ui + 1, nxt);
;         const char* nA = has_next ? (const char*)g.A + (size_t)nxt.pm * tstep : cA; const char* nB = has_next ? (const char*)g.Bt + (size_t)nxt.pn * tstep : cB;
;         for (int t = 0; t < nt; t += 2) {
;             const bool last = (t == nt - 2);
;             const char* a1 = cA + (size_t)(t + 1) * kstep;
;             const char* a2 = last ? nA : cA + (size_t)(t + 2) * kstep; const char* b2 = last ? nB : cB + (size_t)(t + 2) * kstep;
;             const char* a3 = a2 + kstep; const char* b3 = b2 + kstep;
;             if (last && has_next) S.a_ready(nxt);
;             if constexpr (SP2) {
;             PG8_LDB(B0, 0, 0); PG8_LDB(B1, 0, 1); PG8_SCHED; PG8_LDA(At, 0, 0); PG8_STAGE(PG8_SA(1, 1), a1 + hstep, voffA);
;             PG8_WAIT_V(8); PG8_WAIT_L(0); PG8_BAR; PG8_MMA(0, 0, At, B0); PG8_MMA(0, 1, At, B1); PG8_BAR; PG8_SCHED;
;             PG8_LDA(At, 0, 1); PG8_STAGE(PG8_SB(0, 0), b2, voffB); PG8_STAGE(PG8_SB(0, 1), b2 + hstep, voffB); PG8_STAGE(PG8_SA(0, 0), a2, voffA);
;             PG8_WAIT_V(8); PG8_WAIT_L(0); PG8_BAR; PG8_MMA(1, 0, At, B0); PG8_MMA(1, 1, At, B1); PG8_BAR; PG8_SCHED;
;             PG8_LDB(B0, 1, 0); PG8_LDB(B1, 1, 1); PG8_SCHED; PG8_LDA(At, 1, 0); PG8_STAGE(PG8_SA(0, 1), a2 + hstep, voffA);
;             PG8_WAIT_V(8); PG8_WAIT_L(0); PG8_BAR; PG8_MMA(0, 0, At, B0); PG8_MMA(0, 1, At, B1); PG8_BAR; PG8_SCHED;
;             PG8_LDA(At, 1, 1); PG8_STAGE(PG8_SB(1, 0), b3, voffB); PG8_STAGE(PG8_SB(1, 1), b3 + hstep, voffB); PG8_STAGE(PG8_SA(1, 0), a3, voffA);
;             PG8_WAIT_V(8); PG8_WAIT_L(0); PG8_BAR; PG8_MMA(1, 0, At, B0); PG8_MMA(1, 1, At, B1); PG8_BAR; PG8_SCHED;
.LBB0_18:
	s_andn2_b64 vcc, exec, s[24:25]
	s_cbranch_vccnz .Lz_G1A
	s_add_u32 s4, s38, 0x80
	s_addc_u32 s5, s39, 0
	s_add_u32 s0, s36, 0x100
	s_addc_u32 s1, s37, 0
	s_mov_b32 s36, 0
	ds_read_b128 v[128:131], v165
	ds_read_b128 v[146:149], v165 offset:1024
	ds_read_b128 v[150:153], v165 offset:2048
	ds_read_b128 v[154:157], v165 offset:3072
	ds_read_b128 v[158:161], v166
	ds_read_b128 v[172:175], v166 offset:1024
	ds_read_b128 v[176:179], v166 offset:2048
	ds_read_b128 v[180:183], v166 offset:3072
	s_add_i32 s38, s36, 2
	s_add_u32 s33, s4, 0x80
	s_addc_u32 s37, s5, 0
	s_cmp_eq_u32 s57, s36
	s_cselect_b32 s36, s30, s33
	s_cselect_b32 s37, s31, s37
	s_cselect_b32 s71, s35, s1
	s_cselect_b32 s70, s34, s0
	v_lshl_add_u64 v[216:217], s[4:5], 0, v[140:141]
	s_add_i32 m0, s47, 0xc000
	ds_read_b128 v[184:187], v167
	ds_read_b128 v[188:191], v167 offset:1024
	ds_read_b128 v[192:195], v167 offset:2048
	ds_read_b128 v[196:199], v167 offset:3072
	ds_read_b128 v[200:203], v167 offset:4096
	ds_read_b128 v[204:207], v167 offset:5120
	ds_read_b128 v[208:211], v167 offset:6144
	ds_read_b128 v[212:215], v167 offset:7168
	global_load_lds_dwordx4 v[216:217], off
	v_lshl_add_u64 v[216:217], s[4:5], 0, v[142:143]
	s_add_i32 m0, s47, 0xe000
	s_nop 0
	global_load_lds_dwordx4 v[216:217], off
	s_waitcnt vmcnt(8)
	s_waitcnt lgkmcnt(0)
	s_setprio 1
	s_barrier
	v_mfma_f32_16x16x32_bf16 v[124:127], v[128:131], v[184:187], 0
	v_mfma_f32_16x16x32_bf16 v[120:123], v[150:153], v[184:187], 0
	v_mfma_f32_16x16x32_bf16 v[108:111], v[128:131], v[192:195], 0
	v_mfma_f32_16x16x32_bf16 v[104:107], v[150:153], v[192:195], 0
	v_mfma_f32_16x16x32_bf16 v[92:95], v[128:131], v[200:203], 0
	v_mfma_f32_16x16x32_bf16 v[88:91], v[150:153], v[200:203], 0
	v_mfma_f32_16x16x32_bf16 v[76:79], v[128:131], v[208:211], 0
	v_mfma_f32_16x16x32_bf16 v[72:75], v[150:153], v[208:211], 0
	v_mfma_f32_16x16x32_bf16 v[124:127], v[146:149], v[188:191], v[124:127]
	v_mfma_f32_16x16x32_bf16 v[120:123], v[154:157], v[188:191], v[120:123]
	v_mfma_f32_16x16x32_bf16 v[108:111], v[146:149], v[196:199], v[108:111]
	v_mfma_f32_16x16x32_bf16 v[104:107], v[154:157], v[196:199], v[104:107]
	v_mfma_f32_16x16x32_bf16 v[92:95], v[146:149], v[204:207], v[92:95]
	v_mfma_f32_16x16x32_bf16 v[88:91], v[154:157], v[204:207], v[88:91]
	v_mfma_f32_16x16x32_bf16 v[76:79], v[146:149], v[212:215], v[76:79]
	v_mfma_f32_16x16x32_bf16 v[72:75], v[154:157], v[212:215], v[72:75]
	v_mfma_f32_16x16x32_bf16 v[116:119], v[158:161], v[184:187], 0
	v_mfma_f32_16x16x32_bf16 v[112:115], v[176:179], v[184:187], 0
	v_mfma_f32_16x16x32_bf16 v[100:103], v[158:161], v[192:195], 0
	v_mfma_f32_16x16x32_bf16 v[96:99], v[176:179], v[192:195], 0
	v_mfma_f32_16x16x32_bf16 v[84:87], v[158:161], v[200:203], 0
	v_mfma_f32_16x16x32_bf16 v[80:83], v[176:179], v[200:203], 0
	v_mfma_f32_16x16x32_bf16 v[68:71], v[158:161], v[208:211], 0
	v_mfma_f32_16x16x32_bf16 v[64:67], v[176:179], v[208:211], 0
	v_mfma_f32_16x16x32_bf16 v[116:119], v[172:175], v[188:191], v[116:119]
	v_mfma_f32_16x16x32_bf16 v[112:115], v[180:183], v[188:191], v[112:115]
	v_mfma_f32_16x16x32_bf16 v[100:103], v[172:175], v[196:199], v[100:103]
	v_mfma_f32_16x16x32_bf16 v[96:99], v[180:183], v[196:199], v[96:99]
	v_mfma_f32_16x16x32_bf16 v[84:87], v[172:175], v[204:207], v[84:87]
	v_mfma_f32_16x16x32_bf16 v[80:83], v[180:183], v[204:207], v[80:83]
	v_mfma_f32_16x16x32_bf16 v[68:71], v[172:175], v[212:215], v[68:71]
	v_mfma_f32_16x16x32_bf16 v[64:67], v[180:183], v[212:215], v[64:67]
	s_setprio 0
	s_barrier
	s_add_i32 s33, s60, s40
	v_lshl_add_u64 v[216:217], s[70:71], 0, v[136:137]
	s_mov_b32 m0, s33
	ds_read_b128 v[184:187], v167 offset:16384
	ds_read_b128 v[188:191], v167 offset:17408
	ds_read_b128 v[192:195], v167 offset:18432
	ds_read_b128 v[196:199], v167 offset:19456
	ds_read_b128 v[200:203], v167 offset:20480
	ds_read_b128 v[204:207], v167 offset:21504
	ds_read_b128 v[208:211], v167 offset:22528
	ds_read_b128 v[212:215], v167 offset:23552
	global_load_lds_dwordx4 v[216:217], off
	s_add_i32 m0, s33, 0x2000
	v_lshl_add_u64 v[218:219], s[70:71], 0, v[132:133]
	s_add_u32 s70, s70, s6
	s_addc_u32 s71, s71, s7
	s_add_i32 s33, s61, s40
	global_load_lds_dwordx4 v[218:219], off
	v_lshl_add_u64 v[220:221], s[70:71], 0, v[136:137]
	s_mov_b32 m0, s33
	v_lshl_add_u64 v[222:223], s[70:71], 0, v[132:133]
	global_load_lds_dwordx4 v[220:221], off
	s_add_i32 m0, s33, 0x2000
	v_lshl_add_u64 v[224:225], s[36:37], 0, v[138:139]
	global_load_lds_dwordx4 v[222:223], off
	s_mov_b32 m0, s47
	v_lshl_add_u64 v[226:227], s[36:37], 0, v[134:135]
	global_load_lds_dwordx4 v[224:225], off
	s_mov_b32 m0, s49
	s_nop 0
	global_load_lds_dwordx4 v[226:227], off
	s_waitcnt vmcnt(8)
	s_waitcnt lgkmcnt(0)
	s_setprio 1
	s_barrier
; #define PG8_STAGE(bufoff, gbase, voff) do { _Pragma("unroll") for (int _i = 0; _i < 2; ++_i) \
;         __builtin_amdgcn_global_load_lds((const unsigned*)((const char*)(gbase) + (voff)[_i]), (PG8_LAS unsigned*)(lds + (bufoff) + ldsw + _i * 8192), 16, 0, 0); } while (0)
; #define PG8_LDA(dst, b, h) do { _Pragma("unroll") for (int m = 0; m < 4; ++m) _Pragma("unroll") for (int k = 0; k < 2; ++k) dst[m][k] = *(const PG8_LAS bf16x8*)(lds + PG8_SA(b, h) + aoff + m * 2048 + k * 1024); } while (0)
; #define PG8_LDB(dst, b, h) do { _Pragma("unroll") for (int n = 0; n < 2; ++n) _Pragma("unroll") for (int k = 0; k < 2; ++k) dst[n][k] = *(const PG8_LAS bf16x8*)(lds + PG8_SB(b, h) + boff + n * 2048 + k * 1024); } while (0)
; #define PG8_MMA(ai, bj, At, Bt) do { __builtin_amdgcn_s_setprio(1); _Pragma("unroll") for (int m = 0; m < 4; ++m) _Pragma("unroll") for (int n = 0; n < 2; ++n) _Pragma("unroll") for (int k = 0; k < 2; ++k) \
;         acc[ai][bj][m][n] = __builtin_amdgcn_mfma_f32_16x16x32_bf16(Bt[n][k], At[m][k], acc[ai][bj][m][n], 0, 0, 0); __builtin_amdgcn_s_setprio(0); } while (0)
; template <class Epi, class Sched, bool ALIGN_EPI = false, bool SP2 = false>
; __device__ __forceinline__ void gemm_phase(PG8_LAS unsigned char* lds, const Gemm g, const Sched& S, const Epi& E, const int wid) {
;     ...
;             if constexpr (SP2) {
;             PG8_LDB(B0, 0, 0); PG8_LDB(B1, 0, 1); PG8_SCHED; PG8_LDA(At, 0, 0); PG8_STAGE(PG8_SA(1, 1), a1 + hstep, voffA);
;             PG8_WAIT_V(8); PG8_WAIT_L(0); PG8_BAR; PG8_MMA(0, 0, At, B0); PG8_MMA(0, 1, At, B1); PG8_BAR; PG8_SCHED;
;             PG8_LDA(At, 0, 1); PG8_STAGE(PG8_SB(0, 0), b2, voffB); PG8_STAGE(PG8_SB(0, 1), b2 + hstep, voffB); PG8_STAGE(PG8_SA(0, 0), a2, voffA);
;             PG8_WAIT_V(8); PG8_WAIT_L(0); PG8_BAR; PG8_MMA(1, 0, At, B0); PG8_MMA(1, 1, At, B1); PG8_BAR; PG8_SCHED;
;             PG8_LDB(B0, 1, 0); PG8_LDB(B1, 1, 1); PG8_SCHED; PG8_LDA(At, 1, 0); PG8_STAGE(PG8_SA(0, 1), a2 + hstep, voffA);
;             PG8_WAIT_V(8); PG8_WAIT_L(0); PG8_BAR; PG8_MMA(0, 0, At, B0); PG8_MMA(0, 1, At, B1); PG8_BAR; PG8_SCHED;
;             PG8_LDA(At, 1, 1); PG8_STAGE(PG8_SB(1, 0), b3, voffB); PG8_STAGE(PG8_SB(1, 1), b3 + hstep, voffB); PG8_STAGE(PG8_SA(1, 0), a3, voffA);
;             PG8_WAIT_V(8); PG8_WAIT_L(0); PG8_BAR; PG8_MMA(1, 0, At, B0); PG8_MMA(1, 1, At, B1); PG8_BAR; PG8_SCHED;
	v_mfma_f32_16x16x32_bf16 v[60:63], v[128:131], v[184:187], 0
	v_mfma_f32_16x16x32_bf16 v[56:59], v[150:153], v[184:187], 0
	v_mfma_f32_16x16x32_bf16 v[44:47], v[128:131], v[192:195], 0
	v_mfma_f32_16x16x32_bf16 v[40:43], v[150:153], v[192:195], 0
	v_mfma_f32_16x16x32_bf16 v[28:31], v[128:131], v[200:203], 0
	v_mfma_f32_16x16x32_bf16 v[24:27], v[150:153], v[200:203], 0
	v_mfma_f32_16x16x32_bf16 v[12:15], v[128:131], v[208:211], 0
	v_mfma_f32_16x16x32_bf16 v[8:11], v[150:153], v[208:211], 0
	v_mfma_f32_16x16x32_bf16 v[60:63], v[146:149], v[188:191], v[60:63]
	v_mfma_f32_16x16x32_bf16 v[56:59], v[154:157], v[188:191], v[56:59]
	v_mfma_f32_16x16x32_bf16 v[44:47], v[146:149], v[196:199], v[44:47]
	v_mfma_f32_16x16x32_bf16 v[40:43], v[154:157], v[196:199], v[40:43]
	v_mfma_f32_16x16x32_bf16 v[28:31], v[146:149], v[204:207], v[28:31]
	v_mfma_f32_16x16x32_bf16 v[24:27], v[154:157], v[204:207], v[24:27]
	v_mfma_f32_16x16x32_bf16 v[12:15], v[146:149], v[212:215], v[12:15]
	v_mfma_f32_16x16x32_bf16 v[8:11], v[154:157], v[212:215], v[8:11]
	v_mfma_f32_16x16x32_bf16 v[52:55], v[158:161], v[184:187], 0
	v_mfma_f32_16x16x32_bf16 v[48:51], v[176:179], v[184:187], 0
	v_mfma_f32_16x16x32_bf16 v[36:39], v[158:161], v[192:195], 0
	v_mfma_f32_16x16x32_bf16 v[32:35], v[176:179], v[192:195], 0
	v_mfma_f32_16x16x32_bf16 v[20:23], v[158:161], v[200:203], 0
	v_mfma_f32_16x16x32_bf16 v[16:19], v[176:179], v[200:203], 0
	v_mfma_f32_16x16x32_bf16 v[4:7], v[158:161], v[208:211], 0
	v_mfma_f32_16x16x32_bf16 v[0:3], v[176:179], v[208:211], 0
	v_mfma_f32_16x16x32_bf16 v[52:55], v[172:175], v[188:191], v[52:55]
	v_mfma_f32_16x16x32_bf16 v[48:51], v[180:183], v[188:191], v[48:51]
	v_mfma_f32_16x16x32_bf16 v[36:39], v[172:175], v[196:199], v[36:39]
	v_mfma_f32_16x16x32_bf16 v[32:35], v[180:183], v[196:199], v[32:35]
	v_mfma_f32_16x16x32_bf16 v[20:23], v[172:175], v[204:207], v[20:23]
	v_mfma_f32_16x16x32_bf16 v[16:19], v[180:183], v[204:207], v[16:19]
	v_mfma_f32_16x16x32_bf16 v[4:7], v[172:175], v[212:215], v[4:7]
	v_mfma_f32_16x16x32_bf16 v[0:3], v[180:183], v[212:215], v[0:3]
	s_setprio 0
	s_barrier
	s_add_i32 s33, 0, 0x18000
	s_add_i32 s39, 0, 0x1c000
	v_add_u32_e32 v154, s33, v164
	v_add_u32_e32 v180, s39, v164
	ds_read_b128 v[128:131], v154
	ds_read_b128 v[146:149], v154 offset:1024
	ds_read_b128 v[150:153], v154 offset:2048
	ds_read_b128 v[154:157], v154 offset:3072
	ds_read_b128 v[158:161], v180
	ds_read_b128 v[172:175], v180 offset:1024
	ds_read_b128 v[176:179], v180 offset:2048
	ds_read_b128 v[180:183], v180 offset:3072
	s_add_u32 s36, s36, s6
	s_addc_u32 s37, s37, s7
	s_mov_b32 m0, s50
	v_lshl_add_u64 v[228:229], s[36:37], 0, v[138:139]
	ds_read_b128 v[184:187], v167 offset:32768
	ds_read_b128 v[188:191], v167 offset:33792
	ds_read_b128 v[192:195], v167 offset:34816
	ds_read_b128 v[196:199], v167 offset:35840
	ds_read_b128 v[200:203], v167 offset:36864
	ds_read_b128 v[204:207], v167 offset:37888
	ds_read_b128 v[208:211], v167 offset:38912
	ds_read_b128 v[212:215], v167 offset:39936
	global_load_lds_dwordx4 v[228:229], off
	v_lshl_add_u64 v[228:229], s[36:37], 0, v[134:135]
	s_mov_b32 m0, s51
	s_nop 0
	global_load_lds_dwordx4 v[228:229], off
	s_waitcnt vmcnt(8)
	s_waitcnt lgkmcnt(0)
	s_setprio 1
	s_barrier
	v_mfma_f32_16x16x32_bf16 v[124:127], v[128:131], v[184:187], v[124:127]
	v_mfma_f32_16x16x32_bf16 v[120:123], v[150:153], v[184:187], v[120:123]
	v_mfma_f32_16x16x32_bf16 v[108:111], v[128:131], v[192:195], v[108:111]
	v_mfma_f32_16x16x32_bf16 v[104:107], v[150:153], v[192:195], v[104:107]
	v_mfma_f32_16x16x32_bf16 v[92:95], v[128:131], v[200:203], v[92:95]
	v_mfma_f32_16x16x32_bf16 v[88:91], v[150:153], v[200:203], v[88:91]
	v_mfma_f32_16x16x32_bf16 v[76:79], v[128:131], v[208:211], v[76:79]
	v_mfma_f32_16x16x32_bf16 v[72:75], v[150:153], v[208:211], v[72:75]
	v_mfma_f32_16x16x32_bf16 v[124:127], v[146:149], v[188:191], v[124:127]
	v_mfma_f32_16x16x32_bf16 v[120:123], v[154:157], v[188:191], v[120:123]
	v_mfma_f32_16x16x32_bf16 v[108:111], v[146:149], v[196:199], v[108:111]
	v_mfma_f32_16x16x32_bf16 v[104:107], v[154:157], v[196:199], v[104:107]
	v_mfma_f32_16x16x32_bf16 v[92:95], v[146:149], v[204:207], v[92:95]
	v_mfma_f32_16x16x32_bf16 v[88:91], v[154:157], v[204:207], v[88:91]
	v_mfma_f32_16x16x32_bf16 v[76:79], v[146:149], v[212:215], v[76:79]
	v_mfma_f32_16x16x32_bf16 v[72:75], v[154:157], v[212:215], v[72:75]
	v_mfma_f32_16x16x32_bf16 v[116:119], v[158:161], v[184:187], v[116:119]
	v_mfma_f32_16x16x32_bf16 v[112:115], v[176:179], v[184:187], v[112:115]
	v_mfma_f32_16x16x32_bf16 v[100:103], v[158:161], v[192:195], v[100:103]
	v_mfma_f32_16x16x32_bf16 v[96:99], v[176:179], v[192:195], v[96:99]
	v_mfma_f32_16x16x32_bf16 v[84:87], v[158:161], v[200:203], v[84:87]
	v_mfma_f32_16x16x32_bf16 v[80:83], v[176:179], v[200:203], v[80:83]
	v_mfma_f32_16x16x32_bf16 v[68:71], v[158:161], v[208:211], v[68:71]
	v_mfma_f32_16x16x32_bf16 v[64:67], v[176:179], v[208:211], v[64:67]
	v_mfma_f32_16x16x32_bf16 v[116:119], v[172:175], v[188:191], v[116:119]
	v_mfma_f32_16x16x32_bf16 v[112:115], v[180:183], v[188:191], v[112:115]
	v_mfma_f32_16x16x32_bf16 v[100:103], v[172:175], v[196:199], v[100:103]
	v_mfma_f32_16x16x32_bf16 v[96:99], v[180:183], v[196:199], v[96:99]
	v_mfma_f32_16x16x32_bf16 v[84:87], v[172:175], v[204:207], v[84:87]
	v_mfma_f32_16x16x32_bf16 v[80:83], v[180:183], v[204:207], v[80:83]
	v_mfma_f32_16x16x32_bf16 v[68:71], v[172:175], v[212:215], v[68:71]
	v_mfma_f32_16x16x32_bf16 v[64:67], v[180:183], v[212:215], v[64:67]
	s_setprio 0
	s_barrier
; #define PG8_STAGE(bufoff, gbase, voff) do { _Pragma("unroll") for (int _i = 0; _i < 2; ++_i) \
;         __builtin_amdgcn_global_load_lds((const unsigned*)((const char*)(gbase) + (voff)[_i]), (PG8_LAS unsigned*)(lds + (bufoff) + ldsw + _i * 8192), 16, 0, 0); } while (0)
; #define PG8_LDA(dst, b, h) do { _Pragma("unroll") for (int m = 0; m < 4; ++m) _Pragma("unroll") for (int k = 0; k < 2; ++k) dst[m][k] = *(const PG8_LAS bf16x8*)(lds + PG8_SA(b, h) + aoff + m * 2048 + k * 1024); } while (0)
; #define PG8_WAIT_V(n) asm volatile("s_waitcnt vmcnt(" #n ")" ::: "memory")
; #define PG8_WAIT_L(n) asm volatile("s_waitcnt lgkmcnt(" #n ")" ::: "memory")
; #define PG8_BAR __builtin_amdgcn_s_barrier()
; template <class Epi, class Sched, bool ALIGN_EPI = false, bool SP2 = false>
; __device__ __forceinline__ void gemm_phase(PG8_LAS unsigned char* lds, const Gemm g, const Sched& S, const Epi& E, const int wid) {
;     ...
;         for (int t = 0; t < nt; t += 2) {
;             const bool last = (t == nt - 2);
;             const char* a1 = cA + (size_t)(t + 1) * kstep;
;             const char* a2 = last ? nA : cA + (size_t)(t + 2) * kstep; const char* b2 = last ? nB : cB + (size_t)(t + 2) * kstep;
;             const char* a3 = a2 + kstep; const char* b3 = b2 + kstep;
;             if (last && has_next) S.a_ready(nxt);
;             if constexpr (SP2) {
;             PG8_LDB(B0, 0, 0); PG8_LDB(B1, 0, 1); PG8_SCHED; PG8_LDA(At, 0, 0); PG8_STAGE(PG8_SA(1, 1), a1 + hstep, voffA);
;             PG8_WAIT_V(8); PG8_WAIT_L(0); PG8_BAR; PG8_MMA(0, 0, At, B0); PG8_MMA(0, 1, At, B1); PG8_BAR; PG8_SCHED;
;             PG8_LDA(At, 0, 1); PG8_STAGE(PG8_SB(0, 0), b2, voffB); PG8_STAGE(PG8_SB(0, 1), b2 + hstep, voffB); PG8_STAGE(PG8_SA(0, 0), a2, voffA);
;             PG8_WAIT_V(8); PG8_WAIT_L(0); PG8_BAR; PG8_MMA(1, 0, At, B0); PG8_MMA(1, 1, At, B1); PG8_BAR; PG8_SCHED;
;             PG8_LDB(B0, 1, 0); PG8_LDB(B1, 1, 1); PG8_SCHED; PG8_LDA(At, 1, 0); PG8_STAGE(PG8_SA(0, 1), a2 + hstep, voffA);
;             PG8_WAIT_V(8); PG8_WAIT_L(0); PG8_BAR; PG8_MMA(0, 0, At, B0); PG8_MMA(0, 1, At, B1); PG8_BAR; PG8_SCHED;
;             PG8_LDA(At, 1, 1); PG8_STAGE(PG8_SB(1, 0), b3, voffB); PG8_STAGE(PG8_SB(1, 1), b3 + hstep, voffB); PG8_STAGE(PG8_SA(1, 0), a3, voffA);
;             PG8_WAIT_V(8); PG8_WAIT_L(0); PG8_BAR; PG8_MMA(1, 0, At, B0); PG8_MMA(1, 1, At, B1); PG8_BAR; PG8_SCHED;
	s_add_i32 s33, s33, s40
	v_lshl_add_u64 v[216:217], v[216:217], 0, s[22:23]
	s_mov_b32 m0, s33
	ds_read_b128 v[184:187], v167 offset:49152
	ds_read_b128 v[188:191], v167 offset:50176
	ds_read_b128 v[192:195], v167 offset:51200
	ds_read_b128 v[196:199], v167 offset:52224
	ds_read_b128 v[200:203], v167 offset:53248
	ds_read_b128 v[204:207], v167 offset:54272
	ds_read_b128 v[208:211], v167 offset:55296
	ds_read_b128 v[212:215], v167 offset:56320
	global_load_lds_dwordx4 v[216:217], off
	v_lshl_add_u64 v[216:217], v[218:219], 0, s[22:23]
	s_add_i32 m0, s33, 0x2000
	s_add_i32 s33, s39, s40
	global_load_lds_dwordx4 v[216:217], off
	v_lshl_add_u64 v[216:217], v[220:221], 0, s[22:23]
	s_mov_b32 m0, s33
	s_nop 0
	global_load_lds_dwordx4 v[216:217], off
	v_lshl_add_u64 v[216:217], v[222:223], 0, s[22:23]
	s_add_i32 m0, s33, 0x2000
	s_nop 0
	global_load_lds_dwordx4 v[216:217], off
	v_lshl_add_u64 v[216:217], v[224:225], 0, s[22:23]
	s_mov_b32 m0, s53
	s_nop 0
	global_load_lds_dwordx4 v[216:217], off
	v_lshl_add_u64 v[216:217], v[226:227], 0, s[22:23]
	s_mov_b32 m0, s54
	s_nop 0
	global_load_lds_dwordx4 v[216:217], off
	s_waitcnt vmcnt(8)
	s_waitcnt lgkmcnt(0)
	s_setprio 1
	s_barrier
	v_mfma_f32_16x16x32_bf16 v[60:63], v[128:131], v[184:187], v[60:63]
	v_mfma_f32_16x16x32_bf16 v[56:59], v[150:153], v[184:187], v[56:59]
	v_mfma_f32_16x16x32_bf16 v[44:47], v[128:131], v[192:195], v[44:47]
	v_mfma_f32_16x16x32_bf16 v[40:43], v[150:153], v[192:195], v[40:43]
	v_mfma_f32_16x16x32_bf16 v[28:31], v[128:131], v[200:203], v[28:31]
	v_mfma_f32_16x16x32_bf16 v[24:27], v[150:153], v[200:203], v[24:27]
	v_mfma_f32_16x16x32_bf16 v[12:15], v[128:131], v[208:211], v[12:15]
	v_mfma_f32_16x16x32_bf16 v[8:11], v[150:153], v[208:211], v[8:11]
	v_mfma_f32_16x16x32_bf16 v[60:63], v[146:149], v[188:191], v[60:63]
	v_mfma_f32_16x16x32_bf16 v[56:59], v[154:157], v[188:191], v[56:59]
	v_mfma_f32_16x16x32_bf16 v[44:47], v[146:149], v[196:199], v[44:47]
	v_mfma_f32_16x16x32_bf16 v[40:43], v[154:157], v[196:199], v[40:43]
	v_mfma_f32_16x16x32_bf16 v[28:31], v[146:149], v[204:207], v[28:31]
	v_mfma_f32_16x16x32_bf16 v[24:27], v[154:157], v[204:207], v[24:27]
	v_mfma_f32_16x16x32_bf16 v[12:15], v[146:149], v[212:215], v[12:15]
	v_mfma_f32_16x16x32_bf16 v[8:11], v[154:157], v[212:215], v[8:11]
	v_mfma_f32_16x16x32_bf16 v[52:55], v[158:161], v[184:187], v[52:55]
	v_mfma_f32_16x16x32_bf16 v[48:51], v[176:179], v[184:187], v[48:51]
	v_mfma_f32_16x16x32_bf16 v[36:39], v[158:161], v[192:195], v[36:39]
	v_mfma_f32_16x16x32_bf16 v[32:35], v[176:179], v[192:195], v[32:35]
	v_mfma_f32_16x16x32_bf16 v[20:23], v[158:161], v[200:203], v[20:23]
	v_mfma_f32_16x16x32_bf16 v[16:19], v[176:179], v[200:203], v[16:19]
	v_mfma_f32_16x16x32_bf16 v[4:7], v[158:161], v[208:211], v[4:7]
	v_mfma_f32_16x16x32_bf16 v[0:3], v[176:179], v[208:211], v[0:3]
	v_mfma_f32_16x16x32_bf16 v[52:55], v[172:175], v[188:191], v[52:55]
	v_mfma_f32_16x16x32_bf16 v[48:51], v[180:183], v[188:191], v[48:51]
	v_mfma_f32_16x16x32_bf16 v[36:39], v[172:175], v[196:199], v[36:39]
	v_mfma_f32_16x16x32_bf16 v[32:35], v[180:183], v[196:199], v[32:35]
	v_mfma_f32_16x16x32_bf16 v[20:23], v[172:175], v[204:207], v[20:23]
	v_mfma_f32_16x16x32_bf16 v[16:19], v[180:183], v[204:207], v[16:19]
	v_mfma_f32_16x16x32_bf16 v[4:7], v[172:175], v[212:215], v[4:7]
	v_mfma_f32_16x16x32_bf16 v[0:3], v[180:183], v[212:215], v[0:3]
	s_setprio 0
	s_barrier
	s_add_u32 s4, s4, 0x100
	s_addc_u32 s5, s5, 0
	s_add_u32 s0, s0, 0x100
	s_addc_u32 s1, s1, 0
	s_cmp_ge_i32 s38, s55
	s_mov_b32 s36, s38
	s_cbranch_scc1 .LBB0_21
.LBB0_20:
	ds_read_b128 v[128:131], v165
	ds_read_b128 v[146:149], v165 offset:1024
	ds_read_b128 v[150:153], v165 offset:2048
	ds_read_b128 v[154:157], v165 offset:3072
	ds_read_b128 v[158:161], v166
	ds_read_b128 v[172:175], v166 offset:1024
	ds_read_b128 v[176:179], v166 offset:2048
	ds_read_b128 v[180:183], v166 offset:3072
	s_add_i32 s38, s36, 2
	s_add_u32 s33, s4, 0x80
	s_addc_u32 s37, s5, 0
	s_cmp_eq_u32 s57, s36
	s_cselect_b32 s36, s30, s33
	s_cselect_b32 s37, s31, s37
	s_cselect_b32 s71, s35, s1
	s_cselect_b32 s70, s34, s0
	v_lshl_add_u64 v[216:217], s[4:5], 0, v[140:141]
	s_add_i32 m0, s47, 0xc000
	ds_read_b128 v[184:187], v167
	ds_read_b128 v[188:191], v167 offset:1024
	ds_read_b128 v[192:195], v167 offset:2048
	ds_read_b128 v[196:199], v167 offset:3072
	ds_read_b128 v[200:203], v167 offset:4096
	ds_read_b128 v[204:207], v167 offset:5120
	ds_read_b128 v[208:211], v167 offset:6144
	ds_read_b128 v[212:215], v167 offset:7168
	global_load_lds_dwordx4 v[216:217], off
	v_lshl_add_u64 v[216:217], s[4:5], 0, v[142:143]
	s_add_i32 m0, s47, 0xe000
	s_nop 0
	global_load_lds_dwordx4 v[216:217], off
	s_waitcnt vmcnt(8)
	s_waitcnt lgkmcnt(0)
	s_setprio 1
	s_barrier
; #define PG8_STAGE(bufoff, gbase, voff) do { _Pragma("unroll") for (int _i = 0; _i < 2; ++_i) \
;         __builtin_amdgcn_global_load_lds((const unsigned*)((const char*)(gbase) + (voff)[_i]), (PG8_LAS unsigned*)(lds + (bufoff) + ldsw + _i * 8192), 16, 0, 0); } while (0)
; #define PG8_LDA(dst, b, h) do { _Pragma("unroll") for (int m = 0; m < 4; ++m) _Pragma("unroll") for (int k = 0; k < 2; ++k) dst[m][k] = *(const PG8_LAS bf16x8*)(lds + PG8_SA(b, h) + aoff + m * 2048 + k * 1024); } while (0)
; #define PG8_LDB(dst, b, h) do { _Pragma("unroll") for (int n = 0; n < 2; ++n) _Pragma("unroll") for (int k = 0; k < 2; ++k) dst[n][k] = *(const PG8_LAS bf16x8*)(lds + PG8_SB(b, h) + boff + n * 2048 + k * 1024); } while (0)
; #define PG8_MMA(ai, bj, At, Bt) do { __builtin_amdgcn_s_setprio(1); _Pragma("unroll") for (int m = 0; m < 4; ++m) _Pragma("unroll") for (int n = 0; n < 2; ++n) _Pragma("unroll") for (int k = 0; k < 2; ++k) \
;         acc[ai][bj][m][n] = __builtin_amdgcn_mfma_f32_16x16x32_bf16(Bt[n][k], At[m][k], acc[ai][bj][m][n], 0, 0, 0); __builtin_amdgcn_s_setprio(0); } while (0)
; template <class Epi, class Sched, bool ALIGN_EPI = false, bool SP2 = false>
; __device__ __forceinline__ void gemm_phase(PG8_LAS unsigned char* lds, const Gemm g, const Sched& S, const Epi& E, const int wid) {
;     ...
;             if constexpr (SP2) {
;             PG8_LDB(B0, 0, 0); PG8_LDB(B1, 0, 1); PG8_SCHED; PG8_LDA(At, 0, 0); PG8_STAGE(PG8_SA(1, 1), a1 + hstep, voffA);
;             PG8_WAIT_V(8); PG8_WAIT_L(0); PG8_BAR; PG8_MMA(0, 0, At, B0); PG8_MMA(0, 1, At, B1); PG8_BAR; PG8_SCHED;
;             PG8_LDA(At, 0, 1); PG8_STAGE(PG8_SB(0, 0), b2, voffB); PG8_STAGE(PG8_SB(0, 1), b2 + hstep, voffB); PG8_STAGE(PG8_SA(0, 0), a2, voffA);
;             PG8_WAIT_V(8); PG8_WAIT_L(0); PG8_BAR; PG8_MMA(1, 0, At, B0); PG8_MMA(1, 1, At, B1); PG8_BAR; PG8_SCHED;
;             PG8_LDB(B0, 1, 0); PG8_LDB(B1, 1, 1); PG8_SCHED; PG8_LDA(At, 1, 0); PG8_STAGE(PG8_SA(0, 1), a2 + hstep, voffA);
;             PG8_WAIT_V(8); PG8_WAIT_L(0); PG8_BAR; PG8_MMA(0, 0, At, B0); PG8_MMA(0, 1, At, B1); PG8_BAR; PG8_SCHED;
;             PG8_LDA(At, 1, 1); PG8_STAGE(PG8_SB(1, 0), b3, voffB); PG8_STAGE(PG8_SB(1, 1), b3 + hstep, voffB); PG8_STAGE(PG8_SA(1, 0), a3, voffA);
;             PG8_WAIT_V(8); PG8_WAIT_L(0); PG8_BAR; PG8_MMA(1, 0, At, B0); PG8_MMA(1, 1, At, B1); PG8_BAR; PG8_SCHED;
	v_mfma_f32_16x16x32_bf16 v[124:127], v[128:131], v[184:187], v[124:127]
	v_mfma_f32_16x16x32_bf16 v[120:123], v[150:153], v[184:187], v[120:123]
	v_mfma_f32_16x16x32_bf16 v[108:111], v[128:131], v[192:195], v[108:111]
	v_mfma_f32_16x16x32_bf16 v[104:107], v[150:153], v[192:195], v[104:107]
	v_mfma_f32_16x16x32_bf16 v[92:95], v[128:131], v[200:203], v[92:95]
	v_mfma_f32_16x16x32_bf16 v[88:91], v[150:153], v[200:203], v[88:91]
	v_mfma_f32_16x16x32_bf16 v[76:79], v[128:131], v[208:211], v[76:79]
	v_mfma_f32_16x16x32_bf16 v[72:75], v[150:153], v[208:211], v[72:75]
	v_mfma_f32_16x16x32_bf16 v[124:127], v[146:149], v[188:191], v[124:127]
	v_mfma_f32_16x16x32_bf16 v[120:123], v[154:157], v[188:191], v[120:123]
	v_mfma_f32_16x16x32_bf16 v[108:111], v[146:149], v[196:199], v[108:111]
	v_mfma_f32_16x16x32_bf16 v[104:107], v[154:157], v[196:199], v[104:107]
	v_mfma_f32_16x16x32_bf16 v[92:95], v[146:149], v[204:207], v[92:95]
	v_mfma_f32_16x16x32_bf16 v[88:91], v[154:157], v[204:207], v[88:91]
	v_mfma_f32_16x16x32_bf16 v[76:79], v[146:149], v[212:215], v[76:79]
	v_mfma_f32_16x16x32_bf16 v[72:75], v[154:157], v[212:215], v[72:75]
	v_mfma_f32_16x16x32_bf16 v[116:119], v[158:161], v[184:187], v[116:119]
	v_mfma_f32_16x16x32_bf16 v[112:115], v[176:179], v[184:187], v[112:115]
	v_mfma_f32_16x16x32_bf16 v[100:103], v[158:161], v[192:195], v[100:103]
	v_mfma_f32_16x16x32_bf16 v[96:99], v[176:179], v[192:195], v[96:99]
	v_mfma_f32_16x16x32_bf16 v[84:87], v[158:161], v[200:203], v[84:87]
	v_mfma_f32_16x16x32_bf16 v[80:83], v[176:179], v[200:203], v[80:83]
	v_mfma_f32_16x16x32_bf16 v[68:71], v[158:161], v[208:211], v[68:71]
	v_mfma_f32_16x16x32_bf16 v[64:67], v[176:179], v[208:211], v[64:67]
	v_mfma_f32_16x16x32_bf16 v[116:119], v[172:175], v[188:191], v[116:119]
	v_mfma_f32_16x16x32_bf16 v[112:115], v[180:183], v[188:191], v[112:115]
	v_mfma_f32_16x16x32_bf16 v[100:103], v[172:175], v[196:199], v[100:103]
	v_mfma_f32_16x16x32_bf16 v[96:99], v[180:183], v[196:199], v[96:99]
	v_mfma_f32_16x16x32_bf16 v[84:87], v[172:175], v[204:207], v[84:87]
	v_mfma_f32_16x16x32_bf16 v[80:83], v[180:183], v[204:207], v[80:83]
	v_mfma_f32_16x16x32_bf16 v[68:71], v[172:175], v[212:215], v[68:71]
	v_mfma_f32_16x16x32_bf16 v[64:67], v[180:183], v[212:215], v[64:67]
	s_setprio 0
	s_barrier
	s_add_i32 s33, s60, s40
	v_lshl_add_u64 v[216:217], s[70:71], 0, v[136:137]
	s_mov_b32 m0, s33
	ds_read_b128 v[184:187], v167 offset:16384
	ds_read_b128 v[188:191], v167 offset:17408
	ds_read_b128 v[192:195], v167 offset:18432
	ds_read_b128 v[196:199], v167 offset:19456
	ds_read_b128 v[200:203], v167 offset:20480
	ds_read_b128 v[204:207], v167 offset:21504
	ds_read_b128 v[208:211], v167 offset:22528
	ds_read_b128 v[212:215], v167 offset:23552
	global_load_lds_dwordx4 v[216:217], off
	s_add_i32 m0, s33, 0x2000
	v_lshl_add_u64 v[218:219], s[70:71], 0, v[132:133]
	s_add_u32 s70, s70, s6
	s_addc_u32 s71, s71, s7
	s_add_i32 s33, s61, s40
	global_load_lds_dwordx4 v[218:219], off
	v_lshl_add_u64 v[220:221], s[70:71], 0, v[136:137]
	s_mov_b32 m0, s33
	v_lshl_add_u64 v[222:223], s[70:71], 0, v[132:133]
	global_load_lds_dwordx4 v[220:221], off
	s_add_i32 m0, s33, 0x2000
	v_lshl_add_u64 v[224:225], s[36:37], 0, v[138:139]
	global_load_lds_dwordx4 v[222:223], off
	s_mov_b32 m0, s47
	v_lshl_add_u64 v[226:227], s[36:37], 0, v[134:135]
	global_load_lds_dwordx4 v[224:225], off
	s_mov_b32 m0, s49
	s_nop 0
	global_load_lds_dwordx4 v[226:227], off
	s_waitcnt vmcnt(8)
	s_waitcnt lgkmcnt(0)
	s_setprio 1
	s_barrier
	v_mfma_f32_16x16x32_bf16 v[60:63], v[128:131], v[184:187], v[60:63]
	v_mfma_f32_16x16x32_bf16 v[56:59], v[150:153], v[184:187], v[56:59]
	v_mfma_f32_16x16x32_bf16 v[44:47], v[128:131], v[192:195], v[44:47]
	v_mfma_f32_16x16x32_bf16 v[40:43], v[150:153], v[192:195], v[40:43]
	v_mfma_f32_16x16x32_bf16 v[28:31], v[128:131], v[200:203], v[28:31]
	v_mfma_f32_16x16x32_bf16 v[24:27], v[150:153], v[200:203], v[24:27]
	v_mfma_f32_16x16x32_bf16 v[12:15], v[128:131], v[208:211], v[12:15]
	v_mfma_f32_16x16x32_bf16 v[8:11], v[150:153], v[208:211], v[8:11]
	v_mfma_f32_16x16x32_bf16 v[60:63], v[146:149], v[188:191], v[60:63]
	v_mfma_f32_16x16x32_bf16 v[56:59], v[154:157], v[188:191], v[56:59]
	v_mfma_f32_16x16x32_bf16 v[44:47], v[146:149], v[196:199], v[44:47]
	v_mfma_f32_16x16x32_bf16 v[40:43], v[154:157], v[196:199], v[40:43]
	v_mfma_f32_16x16x32_bf16 v[28:31], v[146:149], v[204:207], v[28:31]
	v_mfma_f32_16x16x32_bf16 v[24:27], v[154:157], v[204:207], v[24:27]
	v_mfma_f32_16x16x32_bf16 v[12:15], v[146:149], v[212:215], v[12:15]
	v_mfma_f32_16x16x32_bf16 v[8:11], v[154:157], v[212:215], v[8:11]
	v_mfma_f32_16x16x32_bf16 v[52:55], v[158:161], v[184:187], v[52:55]
	v_mfma_f32_16x16x32_bf16 v[48:51], v[176:179], v[184:187], v[48:51]
	v_mfma_f32_16x16x32_bf16 v[36:39], v[158:161], v[192:195], v[36:39]
	v_mfma_f32_16x16x32_bf16 v[32:35], v[176:179], v[192:195], v[32:35]
	v_mfma_f32_16x16x32_bf16 v[20:23], v[158:161], v[200:203], v[20:23]
	v_mfma_f32_16x16x32_bf16 v[16:19], v[176:179], v[200:203], v[16:19]
	v_mfma_f32_16x16x32_bf16 v[4:7], v[158:161], v[208:211], v[4:7]
	v_mfma_f32_16x16x32_bf16 v[0:3], v[176:179], v[208:211], v[0:3]
	v_mfma_f32_16x16x32_bf16 v[52:55], v[172:175], v[188:191], v[52:55]
	v_mfma_f32_16x16x32_bf16 v[48:51], v[180:183], v[188:191], v[48:51]
	v_mfma_f32_16x16x32_bf16 v[36:39], v[172:175], v[196:199], v[36:39]
	v_mfma_f32_16x16x32_bf16 v[32:35], v[180:183], v[196:199], v[32:35]
	v_mfma_f32_16x16x32_bf16 v[20:23], v[172:175], v[204:207], v[20:23]
	v_mfma_f32_16x16x32_bf16 v[16:19], v[180:183], v[204:207], v[16:19]
	v_mfma_f32_16x16x32_bf16 v[4:7], v[172:175], v[212:215], v[4:7]
	v_mfma_f32_16x16x32_bf16 v[0:3], v[180:183], v[212:215], v[0:3]
	s_setprio 0
	s_barrier
; #define PG8_STAGE(bufoff, gbase, voff) do { _Pragma("unroll") for (int _i = 0; _i < 2; ++_i) \
;         __builtin_amdgcn_global_load_lds((const unsigned*)((const char*)(gbase) + (voff)[_i]), (PG8_LAS unsigned*)(lds + (bufoff) + ldsw + _i * 8192), 16, 0, 0); } while (0)
; #define PG8_LDA(dst, b, h) do { _Pragma("unroll") for (int m = 0; m < 4; ++m) _Pragma("unroll") for (int k = 0; k < 2; ++k) dst[m][k] = *(const PG8_LAS bf16x8*)(lds + PG8_SA(b, h) + aoff + m * 2048 + k * 1024); } while (0)
; #define PG8_LDB(dst, b, h) do { _Pragma("unroll") for (int n = 0; n < 2; ++n) _Pragma("unroll") for (int k = 0; k < 2; ++k) dst[n][k] = *(const PG8_LAS bf16x8*)(lds + PG8_SB(b, h) + boff + n * 2048 + k * 1024); } while (0)
; #define PG8_MMA(ai, bj, At, Bt) do { __builtin_amdgcn_s_setprio(1); _Pragma("unroll") for (int m = 0; m < 4; ++m) _Pragma("unroll") for (int n = 0; n < 2; ++n) _Pragma("unroll") for (int k = 0; k < 2; ++k) \
;         acc[ai][bj][m][n] = __builtin_amdgcn_mfma_f32_16x16x32_bf16(Bt[n][k], At[m][k], acc[ai][bj][m][n], 0, 0, 0); __builtin_amdgcn_s_setprio(0); } while (0)
; template <class Epi, class Sched, bool ALIGN_EPI = false, bool SP2 = false>
; __device__ __forceinline__ void gemm_phase(PG8_LAS unsigned char* lds, const Gemm g, const Sched& S, const Epi& E, const int wid) {
;     ...
;             if constexpr (SP2) {
;             PG8_LDB(B0, 0, 0); PG8_LDB(B1, 0, 1); PG8_SCHED; PG8_LDA(At, 0, 0); PG8_STAGE(PG8_SA(1, 1), a1 + hstep, voffA);
;             PG8_WAIT_V(8); PG8_WAIT_L(0); PG8_BAR; PG8_MMA(0, 0, At, B0); PG8_MMA(0, 1, At, B1); PG8_BAR; PG8_SCHED;
;             PG8_LDA(At, 0, 1); PG8_STAGE(PG8_SB(0, 0), b2, voffB); PG8_STAGE(PG8_SB(0, 1), b2 + hstep, voffB); PG8_STAGE(PG8_SA(0, 0), a2, voffA);
;             PG8_WAIT_V(8); PG8_WAIT_L(0); PG8_BAR; PG8_MMA(1, 0, At, B0); PG8_MMA(1, 1, At, B1); PG8_BAR; PG8_SCHED;
;             PG8_LDB(B0, 1, 0); PG8_LDB(B1, 1, 1); PG8_SCHED; PG8_LDA(At, 1, 0); PG8_STAGE(PG8_SA(0, 1), a2 + hstep, voffA);
;             PG8_WAIT_V(8); PG8_WAIT_L(0); PG8_BAR; PG8_MMA(0, 0, At, B0); PG8_MMA(0, 1, At, B1); PG8_BAR; PG8_SCHED;
;             PG8_LDA(At, 1, 1); PG8_STAGE(PG8_SB(1, 0), b3, voffB); PG8_STAGE(PG8_SB(1, 1), b3 + hstep, voffB); PG8_STAGE(PG8_SA(1, 0), a3, voffA);
;             PG8_WAIT_V(8); PG8_WAIT_L(0); PG8_BAR; PG8_MMA(1, 0, At, B0); PG8_MMA(1, 1, At, B1); PG8_BAR; PG8_SCHED;
	s_add_i32 s33, 0, 0x18000
	s_add_i32 s39, 0, 0x1c000
	v_add_u32_e32 v154, s33, v164
	v_add_u32_e32 v180, s39, v164
	ds_read_b128 v[128:131], v154
	ds_read_b128 v[146:149], v154 offset:1024
	ds_read_b128 v[150:153], v154 offset:2048
	ds_read_b128 v[154:157], v154 offset:3072
	ds_read_b128 v[158:161], v180
	ds_read_b128 v[172:175], v180 offset:1024
	ds_read_b128 v[176:179], v180 offset:2048
	ds_read_b128 v[180:183], v180 offset:3072
	s_add_u32 s36, s36, s6
	s_addc_u32 s37, s37, s7
	s_mov_b32 m0, s50
	v_lshl_add_u64 v[228:229], s[36:37], 0, v[138:139]
	ds_read_b128 v[184:187], v167 offset:32768
	ds_read_b128 v[188:191], v167 offset:33792
	ds_read_b128 v[192:195], v167 offset:34816
	ds_read_b128 v[196:199], v167 offset:35840
	ds_read_b128 v[200:203], v167 offset:36864
	ds_read_b128 v[204:207], v167 offset:37888
	ds_read_b128 v[208:211], v167 offset:38912
	ds_read_b128 v[212:215], v167 offset:39936
	global_load_lds_dwordx4 v[228:229], off
	v_lshl_add_u64 v[228:229], s[36:37], 0, v[134:135]
	s_mov_b32 m0, s51
	s_nop 0
	global_load_lds_dwordx4 v[228:229], off
	s_waitcnt vmcnt(8)
	s_waitcnt lgkmcnt(0)
	s_setprio 1
	s_barrier
	v_mfma_f32_16x16x32_bf16 v[124:127], v[128:131], v[184:187], v[124:127]
	v_mfma_f32_16x16x32_bf16 v[120:123], v[150:153], v[184:187], v[120:123]
	v_mfma_f32_16x16x32_bf16 v[108:111], v[128:131], v[192:195], v[108:111]
	v_mfma_f32_16x16x32_bf16 v[104:107], v[150:153], v[192:195], v[104:107]
	v_mfma_f32_16x16x32_bf16 v[92:95], v[128:131], v[200:203], v[92:95]
	v_mfma_f32_16x16x32_bf16 v[88:91], v[150:153], v[200:203], v[88:91]
	v_mfma_f32_16x16x32_bf16 v[76:79], v[128:131], v[208:211], v[76:79]
	v_mfma_f32_16x16x32_bf16 v[72:75], v[150:153], v[208:211], v[72:75]
	v_mfma_f32_16x16x32_bf16 v[124:127], v[146:149], v[188:191], v[124:127]
	v_mfma_f32_16x16x32_bf16 v[120:123], v[154:157], v[188:191], v[120:123]
	v_mfma_f32_16x16x32_bf16 v[108:111], v[146:149], v[196:199], v[108:111]
	v_mfma_f32_16x16x32_bf16 v[104:107], v[154:157], v[196:199], v[104:107]
	v_mfma_f32_16x16x32_bf16 v[92:95], v[146:149], v[204:207], v[92:95]
	v_mfma_f32_16x16x32_bf16 v[88:91], v[154:157], v[204:207], v[88:91]
	v_mfma_f32_16x16x32_bf16 v[76:79], v[146:149], v[212:215], v[76:79]
	v_mfma_f32_16x16x32_bf16 v[72:75], v[154:157], v[212:215], v[72:75]
	v_mfma_f32_16x16x32_bf16 v[116:119], v[158:161], v[184:187], v[116:119]
	v_mfma_f32_16x16x32_bf16 v[112:115], v[176:179], v[184:187], v[112:115]
	v_mfma_f32_16x16x32_bf16 v[100:103], v[158:161], v[192:195], v[100:103]
	v_mfma_f32_16x16x32_bf16 v[96:99], v[176:179], v[192:195], v[96:99]
	v_mfma_f32_16x16x32_bf16 v[84:87], v[158:161], v[200:203], v[84:87]
	v_mfma_f32_16x16x32_bf16 v[80:83], v[176:179], v[200:203], v[80:83]
	v_mfma_f32_16x16x32_bf16 v[68:71], v[158:161], v[208:211], v[68:71]
	v_mfma_f32_16x16x32_bf16 v[64:67], v[176:179], v[208:211], v[64:67]
	v_mfma_f32_16x16x32_bf16 v[116:119], v[172:175], v[188:191], v[116:119]
	v_mfma_f32_16x16x32_bf16 v[112:115], v[180:183], v[188:191], v[112:115]
	v_mfma_f32_16x16x32_bf16 v[100:103], v[172:175], v[196:199], v[100:103]
	v_mfma_f32_16x16x32_bf16 v[96:99], v[180:183], v[196:199], v[96:99]
	v_mfma_f32_16x16x32_bf16 v[84:87], v[172:175], v[204:207], v[84:87]
	v_mfma_f32_16x16x32_bf16 v[80:83], v[180:183], v[204:207], v[80:83]
	v_mfma_f32_16x16x32_bf16 v[68:71], v[172:175], v[212:215], v[68:71]
	v_mfma_f32_16x16x32_bf16 v[64:67], v[180:183], v[212:215], v[64:67]
	s_setprio 0
	s_barrier
	s_add_i32 s33, s33, s40
	v_lshl_add_u64 v[216:217], v[216:217], 0, s[22:23]
	s_mov_b32 m0, s33
	ds_read_b128 v[184:187], v167 offset:49152
	ds_read_b128 v[188:191], v167 offset:50176
	ds_read_b128 v[192:195], v167 offset:51200
	ds_read_b128 v[196:199], v167 offset:52224
	ds_read_b128 v[200:203], v167 offset:53248
	ds_read_b128 v[204:207], v167 offset:54272
	ds_read_b128 v[208:211], v167 offset:55296
	ds_read_b128 v[212:215], v167 offset:56320
	global_load_lds_dwordx4 v[216:217], off
	v_lshl_add_u64 v[216:217], v[218:219], 0, s[22:23]
	s_add_i32 m0, s33, 0x2000
	s_add_i32 s33, s39, s40
	global_load_lds_dwordx4 v[216:217], off
	v_lshl_add_u64 v[216:217], v[220:221], 0, s[22:23]
	s_mov_b32 m0, s33
	s_nop 0
	global_load_lds_dwordx4 v[216:217], off
	v_lshl_add_u64 v[216:217], v[222:223], 0, s[22:23]
	s_add_i32 m0, s33, 0x2000
	s_nop 0
	global_load_lds_dwordx4 v[216:217], off
	v_lshl_add_u64 v[216:217], v[224:225], 0, s[22:23]
	s_mov_b32 m0, s53
	s_nop 0
	global_load_lds_dwordx4 v[216:217], off
	v_lshl_add_u64 v[216:217], v[226:227], 0, s[22:23]
	s_mov_b32 m0, s54
	s_nop 0
	global_load_lds_dwordx4 v[216:217], off
	s_waitcnt vmcnt(8)
	s_waitcnt lgkmcnt(0)
	s_setprio 1
	s_barrier
	v_mfma_f32_16x16x32_bf16 v[60:63], v[128:131], v[184:187], v[60:63]
	v_mfma_f32_16x16x32_bf16 v[56:59], v[150:153], v[184:187], v[56:59]
	v_mfma_f32_16x16x32_bf16 v[44:47], v[128:131], v[192:195], v[44:47]
	v_mfma_f32_16x16x32_bf16 v[40:43], v[150:153], v[192:195], v[40:43]
	v_mfma_f32_16x16x32_bf16 v[28:31], v[128:131], v[200:203], v[28:31]
	v_mfma_f32_16x16x32_bf16 v[24:27], v[150:153], v[200:203], v[24:27]
	v_mfma_f32_16x16x32_bf16 v[12:15], v[128:131], v[208:211], v[12:15]
	v_mfma_f32_16x16x32_bf16 v[8:11], v[150:153], v[208:211], v[8:11]
	v_mfma_f32_16x16x32_bf16 v[60:63], v[146:149], v[188:191], v[60:63]
	v_mfma_f32_16x16x32_bf16 v[56:59], v[154:157], v[188:191], v[56:59]
	v_mfma_f32_16x16x32_bf16 v[44:47], v[146:149], v[196:199], v[44:47]
	v_mfma_f32_16x16x32_bf16 v[40:43], v[154:157], v[196:199], v[40:43]
	v_mfma_f32_16x16x32_bf16 v[28:31], v[146:149], v[204:207], v[28:31]
	v_mfma_f32_16x16x32_bf16 v[24:27], v[154:157], v[204:207], v[24:27]
	v_mfma_f32_16x16x32_bf16 v[12:15], v[146:149], v[212:215], v[12:15]
	v_mfma_f32_16x16x32_bf16 v[8:11], v[154:157], v[212:215], v[8:11]
	v_mfma_f32_16x16x32_bf16 v[52:55], v[158:161], v[184:187], v[52:55]
	v_mfma_f32_16x16x32_bf16 v[48:51], v[176:179], v[184:187], v[48:51]
	v_mfma_f32_16x16x32_bf16 v[36:39], v[158:161], v[192:195], v[36:39]
	v_mfma_f32_16x16x32_bf16 v[32:35], v[176:179], v[192:195], v[32:35]
	v_mfma_f32_16x16x32_bf16 v[20:23], v[158:161], v[200:203], v[20:23]
	v_mfma_f32_16x16x32_bf16 v[16:19], v[176:179], v[200:203], v[16:19]
	v_mfma_f32_16x16x32_bf16 v[4:7], v[158:161], v[208:211], v[4:7]
	v_mfma_f32_16x16x32_bf16 v[0:3], v[176:179], v[208:211], v[0:3]
	v_mfma_f32_16x16x32_bf16 v[52:55], v[172:175], v[188:191], v[52:55]
	v_mfma_f32_16x16x32_bf16 v[48:51], v[180:183], v[188:191], v[48:51]
	v_mfma_f32_16x16x32_bf16 v[36:39], v[172:175], v[196:199], v[36:39]
	v_mfma_f32_16x16x32_bf16 v[32:35], v[180:183], v[196:199], v[32:35]
	v_mfma_f32_16x16x32_bf16 v[20:23], v[172:175], v[204:207], v[20:23]
	v_mfma_f32_16x16x32_bf16 v[16:19], v[180:183], v[204:207], v[16:19]
	v_mfma_f32_16x16x32_bf16 v[4:7], v[172:175], v[212:215], v[4:7]
	v_mfma_f32_16x16x32_bf16 v[0:3], v[180:183], v[212:215], v[0:3]
	s_setprio 0
	s_barrier
	s_add_u32 s4, s4, 0x100
	s_addc_u32 s5, s5, 0
	s_add_u32 s0, s0, 0x100
	s_addc_u32 s1, s1, 0
	s_cmp_ge_i32 s38, s55
	s_mov_b32 s36, s38
	s_cbranch_scc0 .LBB0_20

; #define PG8_STAGE(bufoff, gbase, voff) do { _Pragma("unroll") for (int _i = 0; _i < 2; ++_i) \
;         __builtin_amdgcn_global_load_lds((const unsigned*)((const char*)(gbase) + (voff)[_i]), (PG8_LAS unsigned*)(lds + (bufoff) + ldsw + _i * 8192), 16, 0, 0); } while (0)
; #define PG8_WAIT_V(n) asm volatile("s_waitcnt vmcnt(" #n ")" ::: "memory")
; #define PG8_WAIT_L(n) asm volatile("s_waitcnt lgkmcnt(" #n ")" ::: "memory")
; #define PG8_BAR __builtin_amdgcn_s_barrier()
; template <class Epi, class Sched, bool ALIGN_EPI = false, bool SP2 = false>
; __device__ __forceinline__ void gemm_phase(PG8_LAS unsigned char* lds, const Gemm g, const Sched& S, const Epi& E, const int wid) {
;     ...
;     for (;;) {
;         const bool has_next = S.next(ui + 1, nxt);
;         const char* nA = has_next ? (const char*)g.A + (size_t)nxt.pm * tstep : cA; const char* nB = has_next ? (const char*)g.Bt + (size_t)nxt.pn * tstep : cB;
;         for (int t = 0; t < nt; t += 2) {
;             const bool last = (t == nt - 2);
;             const char* a1 = cA + (size_t)(t + 1) * kstep;
;             const char* a2 = last ? nA : cA + (size_t)(t + 2) * kstep; const char* b2 = last ? nB : cB + (size_t)(t + 2) * kstep;
;             const char* a3 = a2 + kstep; const char* b3 = b2 + kstep;
;             if (last && has_next) S.a_ready(nxt);
;             if constexpr (SP2) {
;             PG8_LDB(B0, 0, 0); PG8_LDB(B1, 0, 1); PG8_SCHED; PG8_LDA(At, 0, 0); PG8_STAGE(PG8_SA(1, 1), a1 + hstep, voffA);
;             PG8_WAIT_V(8); PG8_WAIT_L(0); PG8_BAR; PG8_MMA(0, 0, At, B0); PG8_MMA(0, 1, At, B1); PG8_BAR; PG8_SCHED;
;             PG8_LDA(At, 0, 1); PG8_STAGE(PG8_SB(0, 0), b2, voffB); PG8_STAGE(PG8_SB(0, 1), b2 + hstep, voffB); PG8_STAGE(PG8_SA(0, 0), a2, voffA);
;             PG8_WAIT_V(8); PG8_WAIT_L(0); PG8_BAR; PG8_MMA(1, 0, At, B0); PG8_MMA(1, 1, At, B1); PG8_BAR; PG8_SCHED;
;             PG8_LDB(B0, 1, 0); PG8_LDB(B1, 1, 1); PG8_SCHED; PG8_LDA(At, 1, 0); PG8_STAGE(PG8_SA(0, 1), a2 + hstep, voffA);
;             PG8_WAIT_V(8); PG8_WAIT_L(0); PG8_BAR; PG8_MMA(0, 0, At, B0); PG8_MMA(0, 1, At, B1); PG8_BAR; PG8_SCHED;
;             PG8_LDA(At, 1, 1); PG8_STAGE(PG8_SB(1, 0), b3, voffB); PG8_STAGE(PG8_SB(1, 1), b3 + hstep, voffB); PG8_STAGE(PG8_SA(1, 0), a3, voffA);
;             PG8_WAIT_V(8); PG8_WAIT_L(0); PG8_BAR; PG8_MMA(1, 0, At, B0); PG8_MMA(1, 1, At, B1); PG8_BAR; PG8_SCHED;
.LBB0_1098:
	s_andn2_b64 vcc, exec, s[28:29]
	s_cbranch_vccnz .Lz_G1B
	s_add_u32 s4, s8, 0x80
	s_addc_u32 s5, s9, 0
	s_add_u32 s0, s6, 0x100
	s_addc_u32 s1, s7, 0
	s_mov_b32 s6, 0
	ds_read_b128 v[44:47], v163
	ds_read_b128 v[52:55], v163 offset:1024
	ds_read_b128 v[60:63], v163 offset:2048
	ds_read_b128 v[68:71], v163 offset:3072
	ds_read_b128 v[166:169], v164
	ds_read_b128 v[170:173], v164 offset:1024
	ds_read_b128 v[174:177], v164 offset:2048
	ds_read_b128 v[178:181], v164 offset:3072
	s_add_i32 s8, s6, 2
	s_add_u32 s9, s4, 0x80
	s_addc_u32 s7, s5, 0
	s_cmp_eq_u32 s72, s6
	s_cselect_b32 s6, s48, s9
	s_cselect_b32 s7, s49, s7
	s_cselect_b32 s77, s51, s1
	s_cselect_b32 s76, s50, s0
	v_lshl_add_u64 v[158:159], s[4:5], 0, v[152:153]
	s_add_i32 m0, s63, 0xc000
	ds_read_b128 v[182:185], v165
	ds_read_b128 v[186:189], v165 offset:1024
	ds_read_b128 v[190:193], v165 offset:2048
	ds_read_b128 v[194:197], v165 offset:3072
	ds_read_b128 v[198:201], v165 offset:4096
	ds_read_b128 v[202:205], v165 offset:5120
	ds_read_b128 v[206:209], v165 offset:6144
	ds_read_b128 v[210:213], v165 offset:7168
	global_load_lds_dwordx4 v[158:159], off
	v_lshl_add_u64 v[158:159], s[4:5], 0, v[154:155]
	s_add_i32 m0, s63, 0xe000
	s_nop 0
	global_load_lds_dwordx4 v[158:159], off
	s_waitcnt vmcnt(8)
	s_waitcnt lgkmcnt(0)
	s_setprio 1
	s_barrier
	v_mfma_f32_16x16x32_bf16 v[140:143], v[44:47], v[182:185], 0
	v_mfma_f32_16x16x32_bf16 v[136:139], v[60:63], v[182:185], 0
	v_mfma_f32_16x16x32_bf16 v[124:127], v[44:47], v[190:193], 0
	v_mfma_f32_16x16x32_bf16 v[120:123], v[60:63], v[190:193], 0
	v_mfma_f32_16x16x32_bf16 v[108:111], v[44:47], v[198:201], 0
	v_mfma_f32_16x16x32_bf16 v[104:107], v[60:63], v[198:201], 0
	v_mfma_f32_16x16x32_bf16 v[92:95], v[44:47], v[206:209], 0
	v_mfma_f32_16x16x32_bf16 v[88:91], v[60:63], v[206:209], 0
	v_mfma_f32_16x16x32_bf16 v[140:143], v[52:55], v[186:189], v[140:143]
	v_mfma_f32_16x16x32_bf16 v[136:139], v[68:71], v[186:189], v[136:139]
	v_mfma_f32_16x16x32_bf16 v[124:127], v[52:55], v[194:197], v[124:127]
	v_mfma_f32_16x16x32_bf16 v[120:123], v[68:71], v[194:197], v[120:123]
	v_mfma_f32_16x16x32_bf16 v[108:111], v[52:55], v[202:205], v[108:111]
	v_mfma_f32_16x16x32_bf16 v[104:107], v[68:71], v[202:205], v[104:107]
	v_mfma_f32_16x16x32_bf16 v[92:95], v[52:55], v[210:213], v[92:95]
	v_mfma_f32_16x16x32_bf16 v[88:91], v[68:71], v[210:213], v[88:91]
	v_mfma_f32_16x16x32_bf16 v[132:135], v[166:169], v[182:185], 0
	v_mfma_f32_16x16x32_bf16 v[128:131], v[174:177], v[182:185], 0
	v_mfma_f32_16x16x32_bf16 v[116:119], v[166:169], v[190:193], 0
	v_mfma_f32_16x16x32_bf16 v[112:115], v[174:177], v[190:193], 0
	v_mfma_f32_16x16x32_bf16 v[100:103], v[166:169], v[198:201], 0
	v_mfma_f32_16x16x32_bf16 v[96:99], v[174:177], v[198:201], 0
	v_mfma_f32_16x16x32_bf16 v[84:87], v[166:169], v[206:209], 0
	v_mfma_f32_16x16x32_bf16 v[80:83], v[174:177], v[206:209], 0
	v_mfma_f32_16x16x32_bf16 v[132:135], v[170:173], v[186:189], v[132:135]
	v_mfma_f32_16x16x32_bf16 v[128:131], v[178:181], v[186:189], v[128:131]
	v_mfma_f32_16x16x32_bf16 v[116:119], v[170:173], v[194:197], v[116:119]
	v_mfma_f32_16x16x32_bf16 v[112:115], v[178:181], v[194:197], v[112:115]
	v_mfma_f32_16x16x32_bf16 v[100:103], v[170:173], v[202:205], v[100:103]
	v_mfma_f32_16x16x32_bf16 v[96:99], v[178:181], v[202:205], v[96:99]
	v_mfma_f32_16x16x32_bf16 v[84:87], v[170:173], v[210:213], v[84:87]
	v_mfma_f32_16x16x32_bf16 v[80:83], v[178:181], v[210:213], v[80:83]
	s_setprio 0
	s_barrier
	s_add_i32 s9, s75, s55
	v_lshl_add_u64 v[158:159], s[76:77], 0, v[148:149]
	s_mov_b32 m0, s9
	ds_read_b128 v[182:185], v165 offset:16384
	ds_read_b128 v[186:189], v165 offset:17408
	ds_read_b128 v[190:193], v165 offset:18432
	ds_read_b128 v[194:197], v165 offset:19456
	ds_read_b128 v[198:201], v165 offset:20480
	ds_read_b128 v[202:205], v165 offset:21504
	ds_read_b128 v[206:209], v165 offset:22528
	ds_read_b128 v[210:213], v165 offset:23552
	global_load_lds_dwordx4 v[158:159], off
	s_add_i32 m0, s9, 0x2000
	v_lshl_add_u64 v[214:215], s[76:77], 0, v[144:145]
	s_add_u32 s76, s76, s12
	s_addc_u32 s77, s77, s13
	s_add_i32 s9, s78, s55
	global_load_lds_dwordx4 v[214:215], off
	v_lshl_add_u64 v[216:217], s[76:77], 0, v[148:149]
	s_mov_b32 m0, s9
	v_lshl_add_u64 v[218:219], s[76:77], 0, v[144:145]
	global_load_lds_dwordx4 v[216:217], off
	s_add_i32 m0, s9, 0x2000
	v_lshl_add_u64 v[220:221], s[6:7], 0, v[150:151]
	global_load_lds_dwordx4 v[218:219], off
	s_mov_b32 m0, s63
	v_lshl_add_u64 v[222:223], s[6:7], 0, v[146:147]
	global_load_lds_dwordx4 v[220:221], off
	s_mov_b32 m0, s64
	s_nop 0
	global_load_lds_dwordx4 v[222:223], off
	s_waitcnt vmcnt(8)
	s_waitcnt lgkmcnt(0)
	s_setprio 1
	s_barrier
; #define PG8_STAGE(bufoff, gbase, voff) do { _Pragma("unroll") for (int _i = 0; _i < 2; ++_i) \
;         __builtin_amdgcn_global_load_lds((const unsigned*)((const char*)(gbase) + (voff)[_i]), (PG8_LAS unsigned*)(lds + (bufoff) + ldsw + _i * 8192), 16, 0, 0); } while (0)
; #define PG8_LDA(dst, b, h) do { _Pragma("unroll") for (int m = 0; m < 4; ++m) _Pragma("unroll") for (int k = 0; k < 2; ++k) dst[m][k] = *(const PG8_LAS bf16x8*)(lds + PG8_SA(b, h) + aoff + m * 2048 + k * 1024); } while (0)
; #define PG8_LDB(dst, b, h) do { _Pragma("unroll") for (int n = 0; n < 2; ++n) _Pragma("unroll") for (int k = 0; k < 2; ++k) dst[n][k] = *(const PG8_LAS bf16x8*)(lds + PG8_SB(b, h) + boff + n * 2048 + k * 1024); } while (0)
; #define PG8_MMA(ai, bj, At, Bt) do { __builtin_amdgcn_s_setprio(1); _Pragma("unroll") for (int m = 0; m < 4; ++m) _Pragma("unroll") for (int n = 0; n < 2; ++n) _Pragma("unroll") for (int k = 0; k < 2; ++k) \
;         acc[ai][bj][m][n] = __builtin_amdgcn_mfma_f32_16x16x32_bf16(Bt[n][k], At[m][k], acc[ai][bj][m][n], 0, 0, 0); __builtin_amdgcn_s_setprio(0); } while (0)
; template <class Epi, class Sched, bool ALIGN_EPI = false, bool SP2 = false>
; __device__ __forceinline__ void gemm_phase(PG8_LAS unsigned char* lds, const Gemm g, const Sched& S, const Epi& E, const int wid) {
;     ...
;             if constexpr (SP2) {
;             PG8_LDB(B0, 0, 0); PG8_LDB(B1, 0, 1); PG8_SCHED; PG8_LDA(At, 0, 0); PG8_STAGE(PG8_SA(1, 1), a1 + hstep, voffA);
;             PG8_WAIT_V(8); PG8_WAIT_L(0); PG8_BAR; PG8_MMA(0, 0, At, B0); PG8_MMA(0, 1, At, B1); PG8_BAR; PG8_SCHED;
;             PG8_LDA(At, 0, 1); PG8_STAGE(PG8_SB(0, 0), b2, voffB); PG8_STAGE(PG8_SB(0, 1), b2 + hstep, voffB); PG8_STAGE(PG8_SA(0, 0), a2, voffA);
;             PG8_WAIT_V(8); PG8_WAIT_L(0); PG8_BAR; PG8_MMA(1, 0, At, B0); PG8_MMA(1, 1, At, B1); PG8_BAR; PG8_SCHED;
;             PG8_LDB(B0, 1, 0); PG8_LDB(B1, 1, 1); PG8_SCHED; PG8_LDA(At, 1, 0); PG8_STAGE(PG8_SA(0, 1), a2 + hstep, voffA);
;             PG8_WAIT_V(8); PG8_WAIT_L(0); PG8_BAR; PG8_MMA(0, 0, At, B0); PG8_MMA(0, 1, At, B1); PG8_BAR; PG8_SCHED;
;             PG8_LDA(At, 1, 1); PG8_STAGE(PG8_SB(1, 0), b3, voffB); PG8_STAGE(PG8_SB(1, 1), b3 + hstep, voffB); PG8_STAGE(PG8_SA(1, 0), a3, voffA);
;             PG8_WAIT_V(8); PG8_WAIT_L(0); PG8_BAR; PG8_MMA(1, 0, At, B0); PG8_MMA(1, 1, At, B1); PG8_BAR; PG8_SCHED;
	v_mfma_f32_16x16x32_bf16 v[76:79], v[44:47], v[182:185], 0
	v_mfma_f32_16x16x32_bf16 v[72:75], v[60:63], v[182:185], 0
	v_mfma_f32_16x16x32_bf16 v[48:51], v[44:47], v[190:193], 0
	v_mfma_f32_16x16x32_bf16 v[40:43], v[60:63], v[190:193], 0
	v_mfma_f32_16x16x32_bf16 v[28:31], v[44:47], v[198:201], 0
	v_mfma_f32_16x16x32_bf16 v[24:27], v[60:63], v[198:201], 0
	v_mfma_f32_16x16x32_bf16 v[12:15], v[44:47], v[206:209], 0
	v_mfma_f32_16x16x32_bf16 v[8:11], v[60:63], v[206:209], 0
	v_mfma_f32_16x16x32_bf16 v[76:79], v[52:55], v[186:189], v[76:79]
	v_mfma_f32_16x16x32_bf16 v[72:75], v[68:71], v[186:189], v[72:75]
	v_mfma_f32_16x16x32_bf16 v[48:51], v[52:55], v[194:197], v[48:51]
	v_mfma_f32_16x16x32_bf16 v[40:43], v[68:71], v[194:197], v[40:43]
	v_mfma_f32_16x16x32_bf16 v[28:31], v[52:55], v[202:205], v[28:31]
	v_mfma_f32_16x16x32_bf16 v[24:27], v[68:71], v[202:205], v[24:27]
	v_mfma_f32_16x16x32_bf16 v[12:15], v[52:55], v[210:213], v[12:15]
	v_mfma_f32_16x16x32_bf16 v[8:11], v[68:71], v[210:213], v[8:11]
	v_mfma_f32_16x16x32_bf16 v[36:39], v[166:169], v[190:193], 0
	v_mfma_f32_16x16x32_bf16 v[32:35], v[174:177], v[190:193], 0
	v_mfma_f32_16x16x32_bf16 v[20:23], v[166:169], v[198:201], 0
	v_mfma_f32_16x16x32_bf16 v[16:19], v[174:177], v[198:201], 0
	v_mfma_f32_16x16x32_bf16 v[4:7], v[166:169], v[206:209], 0
	v_mfma_f32_16x16x32_bf16 v[0:3], v[174:177], v[206:209], 0
	v_mfma_f32_16x16x32_bf16 v[44:47], v[166:169], v[182:185], 0
	v_mfma_f32_16x16x32_bf16 v[52:55], v[174:177], v[182:185], 0
	v_mfma_f32_16x16x32_bf16 v[36:39], v[170:173], v[194:197], v[36:39]
	v_mfma_f32_16x16x32_bf16 v[32:35], v[178:181], v[194:197], v[32:35]
	v_mfma_f32_16x16x32_bf16 v[20:23], v[170:173], v[202:205], v[20:23]
	v_mfma_f32_16x16x32_bf16 v[16:19], v[178:181], v[202:205], v[16:19]
	v_mfma_f32_16x16x32_bf16 v[4:7], v[170:173], v[210:213], v[4:7]
	v_mfma_f32_16x16x32_bf16 v[0:3], v[178:181], v[210:213], v[0:3]
	v_mfma_f32_16x16x32_bf16 v[44:47], v[170:173], v[186:189], v[44:47]
	v_mfma_f32_16x16x32_bf16 v[52:55], v[178:181], v[186:189], v[52:55]
	s_setprio 0
	s_barrier
	s_add_i32 s9, 0, 0x18000
	s_add_i32 s33, 0, 0x1c000
	v_add_u32_e32 v68, s9, v162
	v_add_u32_e32 v178, s33, v162
	ds_read_b128 v[56:59], v68
	ds_read_b128 v[60:63], v68 offset:1024
	ds_read_b128 v[64:67], v68 offset:2048
	ds_read_b128 v[68:71], v68 offset:3072
	ds_read_b128 v[166:169], v178
	ds_read_b128 v[170:173], v178 offset:1024
	ds_read_b128 v[174:177], v178 offset:2048
	ds_read_b128 v[178:181], v178 offset:3072
	s_add_u32 s6, s6, s12
	s_addc_u32 s7, s7, s13
	s_mov_b32 m0, s65
	v_lshl_add_u64 v[224:225], s[6:7], 0, v[150:151]
	ds_read_b128 v[182:185], v165 offset:32768
	ds_read_b128 v[186:189], v165 offset:33792
	ds_read_b128 v[190:193], v165 offset:34816
	ds_read_b128 v[194:197], v165 offset:35840
	ds_read_b128 v[198:201], v165 offset:36864
	ds_read_b128 v[202:205], v165 offset:37888
	ds_read_b128 v[206:209], v165 offset:38912
	ds_read_b128 v[210:213], v165 offset:39936
	global_load_lds_dwordx4 v[224:225], off
	v_lshl_add_u64 v[224:225], s[6:7], 0, v[146:147]
	s_mov_b32 m0, s66
	s_nop 0
	global_load_lds_dwordx4 v[224:225], off
	s_waitcnt vmcnt(8)
	s_waitcnt lgkmcnt(0)
	s_setprio 1
	s_barrier
	v_mfma_f32_16x16x32_bf16 v[140:143], v[56:59], v[182:185], v[140:143]
	v_mfma_f32_16x16x32_bf16 v[136:139], v[64:67], v[182:185], v[136:139]
	v_mfma_f32_16x16x32_bf16 v[124:127], v[56:59], v[190:193], v[124:127]
	v_mfma_f32_16x16x32_bf16 v[120:123], v[64:67], v[190:193], v[120:123]
	v_mfma_f32_16x16x32_bf16 v[108:111], v[56:59], v[198:201], v[108:111]
	v_mfma_f32_16x16x32_bf16 v[104:107], v[64:67], v[198:201], v[104:107]
	v_mfma_f32_16x16x32_bf16 v[92:95], v[56:59], v[206:209], v[92:95]
	v_mfma_f32_16x16x32_bf16 v[88:91], v[64:67], v[206:209], v[88:91]
	v_mfma_f32_16x16x32_bf16 v[140:143], v[60:63], v[186:189], v[140:143]
	v_mfma_f32_16x16x32_bf16 v[136:139], v[68:71], v[186:189], v[136:139]
	v_mfma_f32_16x16x32_bf16 v[124:127], v[60:63], v[194:197], v[124:127]
	v_mfma_f32_16x16x32_bf16 v[120:123], v[68:71], v[194:197], v[120:123]
	v_mfma_f32_16x16x32_bf16 v[108:111], v[60:63], v[202:205], v[108:111]
	v_mfma_f32_16x16x32_bf16 v[104:107], v[68:71], v[202:205], v[104:107]
	v_mfma_f32_16x16x32_bf16 v[92:95], v[60:63], v[210:213], v[92:95]
	v_mfma_f32_16x16x32_bf16 v[88:91], v[68:71], v[210:213], v[88:91]
	v_mfma_f32_16x16x32_bf16 v[132:135], v[166:169], v[182:185], v[132:135]
	v_mfma_f32_16x16x32_bf16 v[128:131], v[174:177], v[182:185], v[128:131]
	v_mfma_f32_16x16x32_bf16 v[116:119], v[166:169], v[190:193], v[116:119]
	v_mfma_f32_16x16x32_bf16 v[112:115], v[174:177], v[190:193], v[112:115]
	v_mfma_f32_16x16x32_bf16 v[100:103], v[166:169], v[198:201], v[100:103]
	v_mfma_f32_16x16x32_bf16 v[96:99], v[174:177], v[198:201], v[96:99]
	v_mfma_f32_16x16x32_bf16 v[84:87], v[166:169], v[206:209], v[84:87]
	v_mfma_f32_16x16x32_bf16 v[80:83], v[174:177], v[206:209], v[80:83]
	v_mfma_f32_16x16x32_bf16 v[132:135], v[170:173], v[186:189], v[132:135]
	v_mfma_f32_16x16x32_bf16 v[128:131], v[178:181], v[186:189], v[128:131]
	v_mfma_f32_16x16x32_bf16 v[116:119], v[170:173], v[194:197], v[116:119]
	v_mfma_f32_16x16x32_bf16 v[112:115], v[178:181], v[194:197], v[112:115]
	v_mfma_f32_16x16x32_bf16 v[100:103], v[170:173], v[202:205], v[100:103]
	v_mfma_f32_16x16x32_bf16 v[96:99], v[178:181], v[202:205], v[96:99]
	v_mfma_f32_16x16x32_bf16 v[84:87], v[170:173], v[210:213], v[84:87]
	v_mfma_f32_16x16x32_bf16 v[80:83], v[178:181], v[210:213], v[80:83]
	s_setprio 0
	s_barrier
; #define PG8_STAGE(bufoff, gbase, voff) do { _Pragma("unroll") for (int _i = 0; _i < 2; ++_i) \
;         __builtin_amdgcn_global_load_lds((const unsigned*)((const char*)(gbase) + (voff)[_i]), (PG8_LAS unsigned*)(lds + (bufoff) + ldsw + _i * 8192), 16, 0, 0); } while (0)
; #define PG8_LDA(dst, b, h) do { _Pragma("unroll") for (int m = 0; m < 4; ++m) _Pragma("unroll") for (int k = 0; k < 2; ++k) dst[m][k] = *(const PG8_LAS bf16x8*)(lds + PG8_SA(b, h) + aoff + m * 2048 + k * 1024); } while (0)
; #define PG8_WAIT_V(n) asm volatile("s_waitcnt vmcnt(" #n ")" ::: "memory")
; #define PG8_WAIT_L(n) asm volatile("s_waitcnt lgkmcnt(" #n ")" ::: "memory")
; #define PG8_BAR __builtin_amdgcn_s_barrier()
; template <class Epi, class Sched, bool ALIGN_EPI = false, bool SP2 = false>
; __device__ __forceinline__ void gemm_phase(PG8_LAS unsigned char* lds, const Gemm g, const Sched& S, const Epi& E, const int wid) {
;     ...
;         for (int t = 0; t < nt; t += 2) {
;             const bool last = (t == nt - 2);
;             const char* a1 = cA + (size_t)(t + 1) * kstep;
;             const char* a2 = last ? nA : cA + (size_t)(t + 2) * kstep; const char* b2 = last ? nB : cB + (size_t)(t + 2) * kstep;
;             const char* a3 = a2 + kstep; const char* b3 = b2 + kstep;
;             if (last && has_next) S.a_ready(nxt);
;             if constexpr (SP2) {
;             PG8_LDB(B0, 0, 0); PG8_LDB(B1, 0, 1); PG8_SCHED; PG8_LDA(At, 0, 0); PG8_STAGE(PG8_SA(1, 1), a1 + hstep, voffA);
;             PG8_WAIT_V(8); PG8_WAIT_L(0); PG8_BAR; PG8_MMA(0, 0, At, B0); PG8_MMA(0, 1, At, B1); PG8_BAR; PG8_SCHED;
;             PG8_LDA(At, 0, 1); PG8_STAGE(PG8_SB(0, 0), b2, voffB); PG8_STAGE(PG8_SB(0, 1), b2 + hstep, voffB); PG8_STAGE(PG8_SA(0, 0), a2, voffA);
;             PG8_WAIT_V(8); PG8_WAIT_L(0); PG8_BAR; PG8_MMA(1, 0, At, B0); PG8_MMA(1, 1, At, B1); PG8_BAR; PG8_SCHED;
;             PG8_LDB(B0, 1, 0); PG8_LDB(B1, 1, 1); PG8_SCHED; PG8_LDA(At, 1, 0); PG8_STAGE(PG8_SA(0, 1), a2 + hstep, voffA);
;             PG8_WAIT_V(8); PG8_WAIT_L(0); PG8_BAR; PG8_MMA(0, 0, At, B0); PG8_MMA(0, 1, At, B1); PG8_BAR; PG8_SCHED;
;             PG8_LDA(At, 1, 1); PG8_STAGE(PG8_SB(1, 0), b3, voffB); PG8_STAGE(PG8_SB(1, 1), b3 + hstep, voffB); PG8_STAGE(PG8_SA(1, 0), a3, voffA);
;             PG8_WAIT_V(8); PG8_WAIT_L(0); PG8_BAR; PG8_MMA(1, 0, At, B0); PG8_MMA(1, 1, At, B1); PG8_BAR; PG8_SCHED;
	s_add_i32 s6, s9, s55
	v_lshl_add_u64 v[158:159], v[158:159], 0, s[26:27]
	s_mov_b32 m0, s6
	ds_read_b128 v[182:185], v165 offset:49152
	ds_read_b128 v[186:189], v165 offset:50176
	ds_read_b128 v[190:193], v165 offset:51200
	ds_read_b128 v[194:197], v165 offset:52224
	ds_read_b128 v[198:201], v165 offset:53248
	ds_read_b128 v[202:205], v165 offset:54272
	ds_read_b128 v[206:209], v165 offset:55296
	ds_read_b128 v[210:213], v165 offset:56320
	global_load_lds_dwordx4 v[158:159], off
	v_lshl_add_u64 v[158:159], v[214:215], 0, s[26:27]
	s_add_i32 m0, s6, 0x2000
	s_add_i32 s6, s33, s55
	global_load_lds_dwordx4 v[158:159], off
	v_lshl_add_u64 v[158:159], v[216:217], 0, s[26:27]
	s_mov_b32 m0, s6
	s_nop 0
	global_load_lds_dwordx4 v[158:159], off
	v_lshl_add_u64 v[158:159], v[218:219], 0, s[26:27]
	s_add_i32 m0, s6, 0x2000
	s_nop 0
	global_load_lds_dwordx4 v[158:159], off
	v_lshl_add_u64 v[158:159], v[220:221], 0, s[26:27]
	s_mov_b32 m0, s68
	s_nop 0
	global_load_lds_dwordx4 v[158:159], off
	v_lshl_add_u64 v[158:159], v[222:223], 0, s[26:27]
	s_mov_b32 m0, s69
	s_nop 0
	global_load_lds_dwordx4 v[158:159], off
	s_waitcnt vmcnt(8)
	s_waitcnt lgkmcnt(0)
	s_setprio 1
	s_barrier
	v_mfma_f32_16x16x32_bf16 v[76:79], v[56:59], v[182:185], v[76:79]
	v_mfma_f32_16x16x32_bf16 v[72:75], v[64:67], v[182:185], v[72:75]
	v_mfma_f32_16x16x32_bf16 v[48:51], v[56:59], v[190:193], v[48:51]
	v_mfma_f32_16x16x32_bf16 v[40:43], v[64:67], v[190:193], v[40:43]
	v_mfma_f32_16x16x32_bf16 v[28:31], v[56:59], v[198:201], v[28:31]
	v_mfma_f32_16x16x32_bf16 v[24:27], v[64:67], v[198:201], v[24:27]
	v_mfma_f32_16x16x32_bf16 v[12:15], v[56:59], v[206:209], v[12:15]
	v_mfma_f32_16x16x32_bf16 v[8:11], v[64:67], v[206:209], v[8:11]
	v_mfma_f32_16x16x32_bf16 v[76:79], v[60:63], v[186:189], v[76:79]
	v_mfma_f32_16x16x32_bf16 v[72:75], v[68:71], v[186:189], v[72:75]
	v_mfma_f32_16x16x32_bf16 v[48:51], v[60:63], v[194:197], v[48:51]
	v_mfma_f32_16x16x32_bf16 v[40:43], v[68:71], v[194:197], v[40:43]
	v_mfma_f32_16x16x32_bf16 v[28:31], v[60:63], v[202:205], v[28:31]
	v_mfma_f32_16x16x32_bf16 v[24:27], v[68:71], v[202:205], v[24:27]
	v_mfma_f32_16x16x32_bf16 v[12:15], v[60:63], v[210:213], v[12:15]
	v_mfma_f32_16x16x32_bf16 v[8:11], v[68:71], v[210:213], v[8:11]
	v_mfma_f32_16x16x32_bf16 v[44:47], v[166:169], v[182:185], v[44:47]
	v_mfma_f32_16x16x32_bf16 v[64:67], v[170:173], v[186:189], v[44:47]
	v_mfma_f32_16x16x32_bf16 v[44:47], v[174:177], v[182:185], v[52:55]
	v_mfma_f32_16x16x32_bf16 v[36:39], v[166:169], v[190:193], v[36:39]
	v_mfma_f32_16x16x32_bf16 v[32:35], v[174:177], v[190:193], v[32:35]
	v_mfma_f32_16x16x32_bf16 v[20:23], v[166:169], v[198:201], v[20:23]
	v_mfma_f32_16x16x32_bf16 v[16:19], v[174:177], v[198:201], v[16:19]
	v_mfma_f32_16x16x32_bf16 v[4:7], v[166:169], v[206:209], v[4:7]
	v_mfma_f32_16x16x32_bf16 v[0:3], v[174:177], v[206:209], v[0:3]
	v_mfma_f32_16x16x32_bf16 v[56:59], v[178:181], v[186:189], v[44:47]
	v_mfma_f32_16x16x32_bf16 v[36:39], v[170:173], v[194:197], v[36:39]
	v_mfma_f32_16x16x32_bf16 v[32:35], v[178:181], v[194:197], v[32:35]
	v_mfma_f32_16x16x32_bf16 v[20:23], v[170:173], v[202:205], v[20:23]
	v_mfma_f32_16x16x32_bf16 v[16:19], v[178:181], v[202:205], v[16:19]
	v_mfma_f32_16x16x32_bf16 v[4:7], v[170:173], v[210:213], v[4:7]
	v_mfma_f32_16x16x32_bf16 v[0:3], v[178:181], v[210:213], v[0:3]
	s_setprio 0
	s_barrier
	s_add_u32 s4, s4, 0x100
	s_addc_u32 s5, s5, 0
	s_add_u32 s0, s0, 0x100
	s_addc_u32 s1, s1, 0
	s_cmp_ge_i32 s8, s70
	s_mov_b32 s6, s8
	s_cbranch_scc1 .LBB0_1101
.LBB0_1100:
	ds_read_b128 v[44:47], v163
	ds_read_b128 v[52:55], v163 offset:1024
	ds_read_b128 v[60:63], v163 offset:2048
	ds_read_b128 v[68:71], v163 offset:3072
	ds_read_b128 v[166:169], v164
	ds_read_b128 v[170:173], v164 offset:1024
	ds_read_b128 v[174:177], v164 offset:2048
	ds_read_b128 v[178:181], v164 offset:3072
	s_add_i32 s8, s6, 2
	s_add_u32 s9, s4, 0x80
	s_addc_u32 s7, s5, 0
	s_cmp_eq_u32 s72, s6
	s_cselect_b32 s6, s48, s9
	s_cselect_b32 s7, s49, s7
	s_cselect_b32 s77, s51, s1
	s_cselect_b32 s76, s50, s0
	v_lshl_add_u64 v[158:159], s[4:5], 0, v[152:153]
	s_add_i32 m0, s63, 0xc000
	ds_read_b128 v[182:185], v165
	ds_read_b128 v[186:189], v165 offset:1024
	ds_read_b128 v[190:193], v165 offset:2048
	ds_read_b128 v[194:197], v165 offset:3072
	ds_read_b128 v[198:201], v165 offset:4096
	ds_read_b128 v[202:205], v165 offset:5120
	ds_read_b128 v[206:209], v165 offset:6144
	ds_read_b128 v[210:213], v165 offset:7168
	global_load_lds_dwordx4 v[158:159], off
	v_lshl_add_u64 v[158:159], s[4:5], 0, v[154:155]
	s_add_i32 m0, s63, 0xe000
	s_nop 0
	global_load_lds_dwordx4 v[158:159], off
	s_waitcnt vmcnt(8)
	s_waitcnt lgkmcnt(0)
	s_setprio 1
	s_barrier
; #define PG8_STAGE(bufoff, gbase, voff) do { _Pragma("unroll") for (int _i = 0; _i < 2; ++_i) \
;         __builtin_amdgcn_global_load_lds((const unsigned*)((const char*)(gbase) + (voff)[_i]), (PG8_LAS unsigned*)(lds + (bufoff) + ldsw + _i * 8192), 16, 0, 0); } while (0)
; #define PG8_LDA(dst, b, h) do { _Pragma("unroll") for (int m = 0; m < 4; ++m) _Pragma("unroll") for (int k = 0; k < 2; ++k) dst[m][k] = *(const PG8_LAS bf16x8*)(lds + PG8_SA(b, h) + aoff + m * 2048 + k * 1024); } while (0)
; #define PG8_LDB(dst, b, h) do { _Pragma("unroll") for (int n = 0; n < 2; ++n) _Pragma("unroll") for (int k = 0; k < 2; ++k) dst[n][k] = *(const PG8_LAS bf16x8*)(lds + PG8_SB(b, h) + boff + n * 2048 + k * 1024); } while (0)
; #define PG8_MMA(ai, bj, At, Bt) do { __builtin_amdgcn_s_setprio(1); _Pragma("unroll") for (int m = 0; m < 4; ++m) _Pragma("unroll") for (int n = 0; n < 2; ++n) _Pragma("unroll") for (int k = 0; k < 2; ++k) \
;         acc[ai][bj][m][n] = __builtin_amdgcn_mfma_f32_16x16x32_bf16(Bt[n][k], At[m][k], acc[ai][bj][m][n], 0, 0, 0); __builtin_amdgcn_s_setprio(0); } while (0)
; template <class Epi, class Sched, bool ALIGN_EPI = false, bool SP2 = false>
; __device__ __forceinline__ void gemm_phase(PG8_LAS unsigned char* lds, const Gemm g, const Sched& S, const Epi& E, const int wid) {
;     ...
;             if constexpr (SP2) {
;             PG8_LDB(B0, 0, 0); PG8_LDB(B1, 0, 1); PG8_SCHED; PG8_LDA(At, 0, 0); PG8_STAGE(PG8_SA(1, 1), a1 + hstep, voffA);
;             PG8_WAIT_V(8); PG8_WAIT_L(0); PG8_BAR; PG8_MMA(0, 0, At, B0); PG8_MMA(0, 1, At, B1); PG8_BAR; PG8_SCHED;
;             PG8_LDA(At, 0, 1); PG8_STAGE(PG8_SB(0, 0), b2, voffB); PG8_STAGE(PG8_SB(0, 1), b2 + hstep, voffB); PG8_STAGE(PG8_SA(0, 0), a2, voffA);
;             PG8_WAIT_V(8); PG8_WAIT_L(0); PG8_BAR; PG8_MMA(1, 0, At, B0); PG8_MMA(1, 1, At, B1); PG8_BAR; PG8_SCHED;
;             PG8_LDB(B0, 1, 0); PG8_LDB(B1, 1, 1); PG8_SCHED; PG8_LDA(At, 1, 0); PG8_STAGE(PG8_SA(0, 1), a2 + hstep, voffA);
;             PG8_WAIT_V(8); PG8_WAIT_L(0); PG8_BAR; PG8_MMA(0, 0, At, B0); PG8_MMA(0, 1, At, B1); PG8_BAR; PG8_SCHED;
;             PG8_LDA(At, 1, 1); PG8_STAGE(PG8_SB(1, 0), b3, voffB); PG8_STAGE(PG8_SB(1, 1), b3 + hstep, voffB); PG8_STAGE(PG8_SA(1, 0), a3, voffA);
;             PG8_WAIT_V(8); PG8_WAIT_L(0); PG8_BAR; PG8_MMA(1, 0, At, B0); PG8_MMA(1, 1, At, B1); PG8_BAR; PG8_SCHED;
	v_mfma_f32_16x16x32_bf16 v[140:143], v[44:47], v[182:185], v[140:143]
	v_mfma_f32_16x16x32_bf16 v[136:139], v[60:63], v[182:185], v[136:139]
	v_mfma_f32_16x16x32_bf16 v[124:127], v[44:47], v[190:193], v[124:127]
	v_mfma_f32_16x16x32_bf16 v[120:123], v[60:63], v[190:193], v[120:123]
	v_mfma_f32_16x16x32_bf16 v[108:111], v[44:47], v[198:201], v[108:111]
	v_mfma_f32_16x16x32_bf16 v[104:107], v[60:63], v[198:201], v[104:107]
	v_mfma_f32_16x16x32_bf16 v[92:95], v[44:47], v[206:209], v[92:95]
	v_mfma_f32_16x16x32_bf16 v[88:91], v[60:63], v[206:209], v[88:91]
	v_mfma_f32_16x16x32_bf16 v[140:143], v[52:55], v[186:189], v[140:143]
	v_mfma_f32_16x16x32_bf16 v[136:139], v[68:71], v[186:189], v[136:139]
	v_mfma_f32_16x16x32_bf16 v[124:127], v[52:55], v[194:197], v[124:127]
	v_mfma_f32_16x16x32_bf16 v[120:123], v[68:71], v[194:197], v[120:123]
	v_mfma_f32_16x16x32_bf16 v[108:111], v[52:55], v[202:205], v[108:111]
	v_mfma_f32_16x16x32_bf16 v[104:107], v[68:71], v[202:205], v[104:107]
	v_mfma_f32_16x16x32_bf16 v[92:95], v[52:55], v[210:213], v[92:95]
	v_mfma_f32_16x16x32_bf16 v[88:91], v[68:71], v[210:213], v[88:91]
	v_mfma_f32_16x16x32_bf16 v[132:135], v[166:169], v[182:185], v[132:135]
	v_mfma_f32_16x16x32_bf16 v[128:131], v[174:177], v[182:185], v[128:131]
	v_mfma_f32_16x16x32_bf16 v[116:119], v[166:169], v[190:193], v[116:119]
	v_mfma_f32_16x16x32_bf16 v[112:115], v[174:177], v[190:193], v[112:115]
	v_mfma_f32_16x16x32_bf16 v[100:103], v[166:169], v[198:201], v[100:103]
	v_mfma_f32_16x16x32_bf16 v[96:99], v[174:177], v[198:201], v[96:99]
	v_mfma_f32_16x16x32_bf16 v[84:87], v[166:169], v[206:209], v[84:87]
	v_mfma_f32_16x16x32_bf16 v[80:83], v[174:177], v[206:209], v[80:83]
	v_mfma_f32_16x16x32_bf16 v[132:135], v[170:173], v[186:189], v[132:135]
	v_mfma_f32_16x16x32_bf16 v[128:131], v[178:181], v[186:189], v[128:131]
	v_mfma_f32_16x16x32_bf16 v[116:119], v[170:173], v[194:197], v[116:119]
	v_mfma_f32_16x16x32_bf16 v[112:115], v[178:181], v[194:197], v[112:115]
	v_mfma_f32_16x16x32_bf16 v[100:103], v[170:173], v[202:205], v[100:103]
	v_mfma_f32_16x16x32_bf16 v[96:99], v[178:181], v[202:205], v[96:99]
	v_mfma_f32_16x16x32_bf16 v[84:87], v[170:173], v[210:213], v[84:87]
	v_mfma_f32_16x16x32_bf16 v[80:83], v[178:181], v[210:213], v[80:83]
	s_setprio 0
	s_barrier
	s_add_i32 s9, s75, s55
	v_lshl_add_u64 v[158:159], s[76:77], 0, v[148:149]
	s_mov_b32 m0, s9
	ds_read_b128 v[182:185], v165 offset:16384
	ds_read_b128 v[186:189], v165 offset:17408
	ds_read_b128 v[190:193], v165 offset:18432
	ds_read_b128 v[194:197], v165 offset:19456
	ds_read_b128 v[198:201], v165 offset:20480
	ds_read_b128 v[202:205], v165 offset:21504
	ds_read_b128 v[206:209], v165 offset:22528
	ds_read_b128 v[210:213], v165 offset:23552
	global_load_lds_dwordx4 v[158:159], off
	s_add_i32 m0, s9, 0x2000
	v_lshl_add_u64 v[214:215], s[76:77], 0, v[144:145]
	s_add_u32 s76, s76, s12
	s_addc_u32 s77, s77, s13
	s_add_i32 s9, s78, s55
	global_load_lds_dwordx4 v[214:215], off
	v_lshl_add_u64 v[216:217], s[76:77], 0, v[148:149]
	s_mov_b32 m0, s9
	v_lshl_add_u64 v[218:219], s[76:77], 0, v[144:145]
	global_load_lds_dwordx4 v[216:217], off
	s_add_i32 m0, s9, 0x2000
	v_lshl_add_u64 v[220:221], s[6:7], 0, v[150:151]
	global_load_lds_dwordx4 v[218:219], off
	s_mov_b32 m0, s63
	v_lshl_add_u64 v[222:223], s[6:7], 0, v[146:147]
	global_load_lds_dwordx4 v[220:221], off
	s_mov_b32 m0, s64
	s_nop 0
	global_load_lds_dwordx4 v[222:223], off
	s_waitcnt vmcnt(8)
	s_waitcnt lgkmcnt(0)
	s_setprio 1
	s_barrier
	v_mfma_f32_16x16x32_bf16 v[76:79], v[44:47], v[182:185], v[76:79]
	v_mfma_f32_16x16x32_bf16 v[72:75], v[60:63], v[182:185], v[72:75]
	v_mfma_f32_16x16x32_bf16 v[48:51], v[44:47], v[190:193], v[48:51]
	v_mfma_f32_16x16x32_bf16 v[40:43], v[60:63], v[190:193], v[40:43]
	v_mfma_f32_16x16x32_bf16 v[28:31], v[44:47], v[198:201], v[28:31]
	v_mfma_f32_16x16x32_bf16 v[24:27], v[60:63], v[198:201], v[24:27]
	v_mfma_f32_16x16x32_bf16 v[12:15], v[44:47], v[206:209], v[12:15]
	v_mfma_f32_16x16x32_bf16 v[8:11], v[60:63], v[206:209], v[8:11]
	v_mfma_f32_16x16x32_bf16 v[76:79], v[52:55], v[186:189], v[76:79]
	v_mfma_f32_16x16x32_bf16 v[72:75], v[68:71], v[186:189], v[72:75]
	v_mfma_f32_16x16x32_bf16 v[48:51], v[52:55], v[194:197], v[48:51]
	v_mfma_f32_16x16x32_bf16 v[40:43], v[68:71], v[194:197], v[40:43]
	v_mfma_f32_16x16x32_bf16 v[28:31], v[52:55], v[202:205], v[28:31]
	v_mfma_f32_16x16x32_bf16 v[24:27], v[68:71], v[202:205], v[24:27]
	v_mfma_f32_16x16x32_bf16 v[12:15], v[52:55], v[210:213], v[12:15]
	v_mfma_f32_16x16x32_bf16 v[8:11], v[68:71], v[210:213], v[8:11]
	v_mfma_f32_16x16x32_bf16 v[36:39], v[166:169], v[190:193], v[36:39]
	v_mfma_f32_16x16x32_bf16 v[32:35], v[174:177], v[190:193], v[32:35]
	v_mfma_f32_16x16x32_bf16 v[20:23], v[166:169], v[198:201], v[20:23]
	v_mfma_f32_16x16x32_bf16 v[16:19], v[174:177], v[198:201], v[16:19]
	v_mfma_f32_16x16x32_bf16 v[4:7], v[166:169], v[206:209], v[4:7]
	v_mfma_f32_16x16x32_bf16 v[0:3], v[174:177], v[206:209], v[0:3]
	v_mfma_f32_16x16x32_bf16 v[44:47], v[166:169], v[182:185], v[64:67]
	v_mfma_f32_16x16x32_bf16 v[52:55], v[174:177], v[182:185], v[56:59]
	v_mfma_f32_16x16x32_bf16 v[36:39], v[170:173], v[194:197], v[36:39]
	v_mfma_f32_16x16x32_bf16 v[32:35], v[178:181], v[194:197], v[32:35]
	v_mfma_f32_16x16x32_bf16 v[20:23], v[170:173], v[202:205], v[20:23]
	v_mfma_f32_16x16x32_bf16 v[16:19], v[178:181], v[202:205], v[16:19]
	v_mfma_f32_16x16x32_bf16 v[4:7], v[170:173], v[210:213], v[4:7]
	v_mfma_f32_16x16x32_bf16 v[0:3], v[178:181], v[210:213], v[0:3]
	v_mfma_f32_16x16x32_bf16 v[44:47], v[170:173], v[186:189], v[44:47]
	v_mfma_f32_16x16x32_bf16 v[52:55], v[178:181], v[186:189], v[52:55]
	s_setprio 0
	s_barrier
; #define PG8_STAGE(bufoff, gbase, voff) do { _Pragma("unroll") for (int _i = 0; _i < 2; ++_i) \
;         __builtin_amdgcn_global_load_lds((const unsigned*)((const char*)(gbase) + (voff)[_i]), (PG8_LAS unsigned*)(lds + (bufoff) + ldsw + _i * 8192), 16, 0, 0); } while (0)
; #define PG8_LDA(dst, b, h) do { _Pragma("unroll") for (int m = 0; m < 4; ++m) _Pragma("unroll") for (int k = 0; k < 2; ++k) dst[m][k] = *(const PG8_LAS bf16x8*)(lds + PG8_SA(b, h) + aoff + m * 2048 + k * 1024); } while (0)
; #define PG8_LDB(dst, b, h) do { _Pragma("unroll") for (int n = 0; n < 2; ++n) _Pragma("unroll") for (int k = 0; k < 2; ++k) dst[n][k] = *(const PG8_LAS bf16x8*)(lds + PG8_SB(b, h) + boff + n * 2048 + k * 1024); } while (0)
; #define PG8_MMA(ai, bj, At, Bt) do { __builtin_amdgcn_s_setprio(1); _Pragma("unroll") for (int m = 0; m < 4; ++m) _Pragma("unroll") for (int n = 0; n < 2; ++n) _Pragma("unroll") for (int k = 0; k < 2; ++k) \
;         acc[ai][bj][m][n] = __builtin_amdgcn_mfma_f32_16x16x32_bf16(Bt[n][k], At[m][k], acc[ai][bj][m][n], 0, 0, 0); __builtin_amdgcn_s_setprio(0); } while (0)
; template <class Epi, class Sched, bool ALIGN_EPI = false, bool SP2 = false>
; __device__ __forceinline__ void gemm_phase(PG8_LAS unsigned char* lds, const Gemm g, const Sched& S, const Epi& E, const int wid) {
;     ...
;             if constexpr (SP2) {
;             PG8_LDB(B0, 0, 0); PG8_LDB(B1, 0, 1); PG8_SCHED; PG8_LDA(At, 0, 0); PG8_STAGE(PG8_SA(1, 1), a1 + hstep, voffA);
;             PG8_WAIT_V(8); PG8_WAIT_L(0); PG8_BAR; PG8_MMA(0, 0, At, B0); PG8_MMA(0, 1, At, B1); PG8_BAR; PG8_SCHED;
;             PG8_LDA(At, 0, 1); PG8_STAGE(PG8_SB(0, 0), b2, voffB); PG8_STAGE(PG8_SB(0, 1), b2 + hstep, voffB); PG8_STAGE(PG8_SA(0, 0), a2, voffA);
;             PG8_WAIT_V(8); PG8_WAIT_L(0); PG8_BAR; PG8_MMA(1, 0, At, B0); PG8_MMA(1, 1, At, B1); PG8_BAR; PG8_SCHED;
;             PG8_LDB(B0, 1, 0); PG8_LDB(B1, 1, 1); PG8_SCHED; PG8_LDA(At, 1, 0); PG8_STAGE(PG8_SA(0, 1), a2 + hstep, voffA);
;             PG8_WAIT_V(8); PG8_WAIT_L(0); PG8_BAR; PG8_MMA(0, 0, At, B0); PG8_MMA(0, 1, At, B1); PG8_BAR; PG8_SCHED;
;             PG8_LDA(At, 1, 1); PG8_STAGE(PG8_SB(1, 0), b3, voffB); PG8_STAGE(PG8_SB(1, 1), b3 + hstep, voffB); PG8_STAGE(PG8_SA(1, 0), a3, voffA);
;             PG8_WAIT_V(8); PG8_WAIT_L(0); PG8_BAR; PG8_MMA(1, 0, At, B0); PG8_MMA(1, 1, At, B1); PG8_BAR; PG8_SCHED;
	s_add_i32 s9, 0, 0x18000
	s_add_i32 s33, 0, 0x1c000
	v_add_u32_e32 v68, s9, v162
	v_add_u32_e32 v178, s33, v162
	ds_read_b128 v[56:59], v68
	ds_read_b128 v[60:63], v68 offset:1024
	ds_read_b128 v[64:67], v68 offset:2048
	ds_read_b128 v[68:71], v68 offset:3072
	ds_read_b128 v[166:169], v178
	ds_read_b128 v[170:173], v178 offset:1024
	ds_read_b128 v[174:177], v178 offset:2048
	ds_read_b128 v[178:181], v178 offset:3072
	s_add_u32 s6, s6, s12
	s_addc_u32 s7, s7, s13
	s_mov_b32 m0, s65
	v_lshl_add_u64 v[224:225], s[6:7], 0, v[150:151]
	ds_read_b128 v[182:185], v165 offset:32768
	ds_read_b128 v[186:189], v165 offset:33792
	ds_read_b128 v[190:193], v165 offset:34816
	ds_read_b128 v[194:197], v165 offset:35840
	ds_read_b128 v[198:201], v165 offset:36864
	ds_read_b128 v[202:205], v165 offset:37888
	ds_read_b128 v[206:209], v165 offset:38912
	ds_read_b128 v[210:213], v165 offset:39936
	global_load_lds_dwordx4 v[224:225], off
	v_lshl_add_u64 v[224:225], s[6:7], 0, v[146:147]
	s_mov_b32 m0, s66
	s_nop 0
	global_load_lds_dwordx4 v[224:225], off
	s_waitcnt vmcnt(8)
	s_waitcnt lgkmcnt(0)
	s_setprio 1
	s_barrier
	v_mfma_f32_16x16x32_bf16 v[140:143], v[56:59], v[182:185], v[140:143]
	v_mfma_f32_16x16x32_bf16 v[136:139], v[64:67], v[182:185], v[136:139]
	v_mfma_f32_16x16x32_bf16 v[124:127], v[56:59], v[190:193], v[124:127]
	v_mfma_f32_16x16x32_bf16 v[120:123], v[64:67], v[190:193], v[120:123]
	v_mfma_f32_16x16x32_bf16 v[108:111], v[56:59], v[198:201], v[108:111]
	v_mfma_f32_16x16x32_bf16 v[104:107], v[64:67], v[198:201], v[104:107]
	v_mfma_f32_16x16x32_bf16 v[92:95], v[56:59], v[206:209], v[92:95]
	v_mfma_f32_16x16x32_bf16 v[88:91], v[64:67], v[206:209], v[88:91]
	v_mfma_f32_16x16x32_bf16 v[140:143], v[60:63], v[186:189], v[140:143]
	v_mfma_f32_16x16x32_bf16 v[136:139], v[68:71], v[186:189], v[136:139]
	v_mfma_f32_16x16x32_bf16 v[124:127], v[60:63], v[194:197], v[124:127]
	v_mfma_f32_16x16x32_bf16 v[120:123], v[68:71], v[194:197], v[120:123]
	v_mfma_f32_16x16x32_bf16 v[108:111], v[60:63], v[202:205], v[108:111]
	v_mfma_f32_16x16x32_bf16 v[104:107], v[68:71], v[202:205], v[104:107]
	v_mfma_f32_16x16x32_bf16 v[92:95], v[60:63], v[210:213], v[92:95]
	v_mfma_f32_16x16x32_bf16 v[88:91], v[68:71], v[210:213], v[88:91]
	v_mfma_f32_16x16x32_bf16 v[132:135], v[166:169], v[182:185], v[132:135]
	v_mfma_f32_16x16x32_bf16 v[128:131], v[174:177], v[182:185], v[128:131]
	v_mfma_f32_16x16x32_bf16 v[116:119], v[166:169], v[190:193], v[116:119]
	v_mfma_f32_16x16x32_bf16 v[112:115], v[174:177], v[190:193], v[112:115]
	v_mfma_f32_16x16x32_bf16 v[100:103], v[166:169], v[198:201], v[100:103]
	v_mfma_f32_16x16x32_bf16 v[96:99], v[174:177], v[198:201], v[96:99]
	v_mfma_f32_16x16x32_bf16 v[84:87], v[166:169], v[206:209], v[84:87]
	v_mfma_f32_16x16x32_bf16 v[80:83], v[174:177], v[206:209], v[80:83]
	v_mfma_f32_16x16x32_bf16 v[132:135], v[170:173], v[186:189], v[132:135]
	v_mfma_f32_16x16x32_bf16 v[128:131], v[178:181], v[186:189], v[128:131]
	v_mfma_f32_16x16x32_bf16 v[116:119], v[170:173], v[194:197], v[116:119]
	v_mfma_f32_16x16x32_bf16 v[112:115], v[178:181], v[194:197], v[112:115]
	v_mfma_f32_16x16x32_bf16 v[100:103], v[170:173], v[202:205], v[100:103]
	v_mfma_f32_16x16x32_bf16 v[96:99], v[178:181], v[202:205], v[96:99]
	v_mfma_f32_16x16x32_bf16 v[84:87], v[170:173], v[210:213], v[84:87]
	v_mfma_f32_16x16x32_bf16 v[80:83], v[178:181], v[210:213], v[80:83]
	s_setprio 0
	s_barrier
	s_add_i32 s6, s9, s55
	v_lshl_add_u64 v[158:159], v[158:159], 0, s[26:27]
	s_mov_b32 m0, s6
	ds_read_b128 v[182:185], v165 offset:49152
	ds_read_b128 v[186:189], v165 offset:50176
	ds_read_b128 v[190:193], v165 offset:51200
	ds_read_b128 v[194:197], v165 offset:52224
	ds_read_b128 v[198:201], v165 offset:53248
	ds_read_b128 v[202:205], v165 offset:54272
	ds_read_b128 v[206:209], v165 offset:55296
	ds_read_b128 v[210:213], v165 offset:56320
	global_load_lds_dwordx4 v[158:159], off
	v_lshl_add_u64 v[158:159], v[214:215], 0, s[26:27]
	s_add_i32 m0, s6, 0x2000
	s_add_i32 s6, s33, s55
	global_load_lds_dwordx4 v[158:159], off
	v_lshl_add_u64 v[158:159], v[216:217], 0, s[26:27]
	s_mov_b32 m0, s6
	s_nop 0
	global_load_lds_dwordx4 v[158:159], off
	v_lshl_add_u64 v[158:159], v[218:219], 0, s[26:27]
	s_add_i32 m0, s6, 0x2000
	s_nop 0
	global_load_lds_dwordx4 v[158:159], off
	v_lshl_add_u64 v[158:159], v[220:221], 0, s[26:27]
	s_mov_b32 m0, s68
	s_nop 0
	global_load_lds_dwordx4 v[158:159], off
	v_lshl_add_u64 v[158:159], v[222:223], 0, s[26:27]
	s_mov_b32 m0, s69
	s_nop 0
	global_load_lds_dwordx4 v[158:159], off
	s_waitcnt vmcnt(8)
	s_waitcnt lgkmcnt(0)
	s_setprio 1
	s_barrier
	v_mfma_f32_16x16x32_bf16 v[76:79], v[56:59], v[182:185], v[76:79]
	v_mfma_f32_16x16x32_bf16 v[72:75], v[64:67], v[182:185], v[72:75]
	v_mfma_f32_16x16x32_bf16 v[48:51], v[56:59], v[190:193], v[48:51]
	v_mfma_f32_16x16x32_bf16 v[40:43], v[64:67], v[190:193], v[40:43]
	v_mfma_f32_16x16x32_bf16 v[28:31], v[56:59], v[198:201], v[28:31]
	v_mfma_f32_16x16x32_bf16 v[24:27], v[64:67], v[198:201], v[24:27]
	v_mfma_f32_16x16x32_bf16 v[12:15], v[56:59], v[206:209], v[12:15]
	v_mfma_f32_16x16x32_bf16 v[8:11], v[64:67], v[206:209], v[8:11]
	v_mfma_f32_16x16x32_bf16 v[76:79], v[60:63], v[186:189], v[76:79]
	v_mfma_f32_16x16x32_bf16 v[72:75], v[68:71], v[186:189], v[72:75]
	v_mfma_f32_16x16x32_bf16 v[48:51], v[60:63], v[194:197], v[48:51]
	v_mfma_f32_16x16x32_bf16 v[40:43], v[68:71], v[194:197], v[40:43]
	v_mfma_f32_16x16x32_bf16 v[28:31], v[60:63], v[202:205], v[28:31]
	v_mfma_f32_16x16x32_bf16 v[24:27], v[68:71], v[202:205], v[24:27]
	v_mfma_f32_16x16x32_bf16 v[12:15], v[60:63], v[210:213], v[12:15]
	v_mfma_f32_16x16x32_bf16 v[8:11], v[68:71], v[210:213], v[8:11]
	v_mfma_f32_16x16x32_bf16 v[44:47], v[166:169], v[182:185], v[44:47]
	v_mfma_f32_16x16x32_bf16 v[64:67], v[170:173], v[186:189], v[44:47]
	v_mfma_f32_16x16x32_bf16 v[44:47], v[174:177], v[182:185], v[52:55]
	v_mfma_f32_16x16x32_bf16 v[36:39], v[166:169], v[190:193], v[36:39]
	v_mfma_f32_16x16x32_bf16 v[32:35], v[174:177], v[190:193], v[32:35]
	v_mfma_f32_16x16x32_bf16 v[20:23], v[166:169], v[198:201], v[20:23]
	v_mfma_f32_16x16x32_bf16 v[16:19], v[174:177], v[198:201], v[16:19]
	v_mfma_f32_16x16x32_bf16 v[4:7], v[166:169], v[206:209], v[4:7]
	v_mfma_f32_16x16x32_bf16 v[0:3], v[174:177], v[206:209], v[0:3]
	v_mfma_f32_16x16x32_bf16 v[56:59], v[178:181], v[186:189], v[44:47]
	v_mfma_f32_16x16x32_bf16 v[36:39], v[170:173], v[194:197], v[36:39]
	v_mfma_f32_16x16x32_bf16 v[32:35], v[178:181], v[194:197], v[32:35]
	v_mfma_f32_16x16x32_bf16 v[20:23], v[170:173], v[202:205], v[20:23]
	v_mfma_f32_16x16x32_bf16 v[16:19], v[178:181], v[202:205], v[16:19]
	v_mfma_f32_16x16x32_bf16 v[4:7], v[170:173], v[210:213], v[4:7]
	v_mfma_f32_16x16x32_bf16 v[0:3], v[178:181], v[210:213], v[0:3]
	s_setprio 0
	s_barrier
	s_add_u32 s4, s4, 0x100
	s_addc_u32 s5, s5, 0
	s_add_u32 s0, s0, 0x100
	s_addc_u32 s1, s1, 0
	s_cmp_ge_i32 s8, s70
	s_mov_b32 s6, s8
	s_cbranch_scc0 .LBB0_1100

; #define PG8_STAGE(bufoff, gbase, voff) do { _Pragma("unroll") for (int _i = 0; _i < 2; ++_i) \
;         __builtin_amdgcn_global_load_lds((const unsigned*)((const char*)(gbase) + (voff)[_i]), (PG8_LAS unsigned*)(lds + (bufoff) + ldsw + _i * 8192), 16, 0, 0); } while (0)
; #define PG8_WAIT_V(n) asm volatile("s_waitcnt vmcnt(" #n ")" ::: "memory")
; #define PG8_WAIT_L(n) asm volatile("s_waitcnt lgkmcnt(" #n ")" ::: "memory")
; #define PG8_BAR __builtin_amdgcn_s_barrier()
; template <class Epi, class Sched, bool ALIGN_EPI = false, bool SP2 = false>
; __device__ __forceinline__ void gemm_phase(PG8_LAS unsigned char* lds, const Gemm g, const Sched& S, const Epi& E, const int wid) {
;     ...
;     for (;;) {
;         const bool has_next = S.next(ui + 1, nxt);
;         const char* nA = has_next ? (const char*)g.A + (size_t)nxt.pm * tstep : cA; const char* nB = has_next ? (const char*)g.Bt + (size_t)nxt.pn * tstep : cB;
;         for (int t = 0; t < nt; t += 2) {
;             const bool last = (t == nt - 2);
;             const char* a1 = cA + (size_t)(t + 1) * kstep;
;             const char* a2 = last ? nA : cA + (size_t)(t + 2) * kstep; const char* b2 = last ? nB : cB + (size_t)(t + 2) * kstep;
;             const char* a3 = a2 + kstep; const char* b3 = b2 + kstep;
;             if (last && has_next) S.a_ready(nxt);
;             if constexpr (SP2) {
;             PG8_LDB(B0, 0, 0); PG8_LDB(B1, 0, 1); PG8_SCHED; PG8_LDA(At, 0, 0); PG8_STAGE(PG8_SA(1, 1), a1 + hstep, voffA);
;             PG8_WAIT_V(8); PG8_WAIT_L(0); PG8_BAR; PG8_MMA(0, 0, At, B0); PG8_MMA(0, 1, At, B1); PG8_BAR; PG8_SCHED;
;             PG8_LDA(At, 0, 1); PG8_STAGE(PG8_SB(0, 0), b2, voffB); PG8_STAGE(PG8_SB(0, 1), b2 + hstep, voffB); PG8_STAGE(PG8_SA(0, 0), a2, voffA);
;             PG8_WAIT_V(8); PG8_WAIT_L(0); PG8_BAR; PG8_MMA(1, 0, At, B0); PG8_MMA(1, 1, At, B1); PG8_BAR; PG8_SCHED;
;             PG8_LDB(B0, 1, 0); PG8_LDB(B1, 1, 1); PG8_SCHED; PG8_LDA(At, 1, 0); PG8_STAGE(PG8_SA(0, 1), a2 + hstep, voffA);
;             PG8_WAIT_V(8); PG8_WAIT_L(0); PG8_BAR; PG8_MMA(0, 0, At, B0); PG8_MMA(0, 1, At, B1); PG8_BAR; PG8_SCHED;
;             PG8_LDA(At, 1, 1); PG8_STAGE(PG8_SB(1, 0), b3, voffB); PG8_STAGE(PG8_SB(1, 1), b3 + hstep, voffB); PG8_STAGE(PG8_SA(1, 0), a3, voffA);
;             PG8_WAIT_V(8); PG8_WAIT_L(0); PG8_BAR; PG8_MMA(1, 0, At, B0); PG8_MMA(1, 1, At, B1); PG8_BAR; PG8_SCHED;
.LBB0_1177:
	s_andn2_b64 vcc, exec, s[20:21]
	s_cbranch_vccnz .Lz_GMA
	s_add_u32 s26, s26, 0x80
	s_addc_u32 s27, s27, 0
	s_add_u32 s0, s28, 0x100
	s_addc_u32 s1, s29, 0
	s_mov_b32 s28, 0
	ds_read_b128 v[142:145], v149
	ds_read_b128 v[152:155], v149 offset:1024
	ds_read_b128 v[156:159], v149 offset:2048
	ds_read_b128 v[160:163], v149 offset:3072
	ds_read_b128 v[164:167], v150
	ds_read_b128 v[168:171], v150 offset:1024
	ds_read_b128 v[172:175], v150 offset:2048
	ds_read_b128 v[176:179], v150 offset:3072
	s_add_i32 s61, s28, 2
	s_add_u32 s33, s26, 0x80
	s_addc_u32 s29, s27, 0
	s_cmp_eq_u32 s53, s28
	s_cselect_b32 s28, s4, s33
	s_cselect_b32 s29, s5, s29
	s_cselect_b32 s63, s25, s1
	s_cselect_b32 s62, s24, s0
	v_lshl_add_u64 v[212:213], s[26:27], 0, v[136:137]
	s_add_i32 m0, s42, 0xc000
	ds_read_b128 v[180:183], v151
	ds_read_b128 v[184:187], v151 offset:1024
	ds_read_b128 v[188:191], v151 offset:2048
	ds_read_b128 v[192:195], v151 offset:3072
	ds_read_b128 v[196:199], v151 offset:4096
	ds_read_b128 v[200:203], v151 offset:5120
	ds_read_b128 v[204:207], v151 offset:6144
	ds_read_b128 v[208:211], v151 offset:7168
	global_load_lds_dwordx4 v[212:213], off
	v_lshl_add_u64 v[212:213], s[26:27], 0, v[138:139]
	s_add_i32 m0, s42, 0xe000
	s_nop 0
	global_load_lds_dwordx4 v[212:213], off
	s_waitcnt vmcnt(8)
	s_waitcnt lgkmcnt(0)
	s_setprio 1
	s_barrier
	v_mfma_f32_16x16x32_bf16 v[124:127], v[142:145], v[180:183], 0
	v_mfma_f32_16x16x32_bf16 v[120:123], v[156:159], v[180:183], 0
	v_mfma_f32_16x16x32_bf16 v[108:111], v[142:145], v[188:191], 0
	v_mfma_f32_16x16x32_bf16 v[104:107], v[156:159], v[188:191], 0
	v_mfma_f32_16x16x32_bf16 v[92:95], v[142:145], v[196:199], 0
	v_mfma_f32_16x16x32_bf16 v[88:91], v[156:159], v[196:199], 0
	v_mfma_f32_16x16x32_bf16 v[76:79], v[142:145], v[204:207], 0
	v_mfma_f32_16x16x32_bf16 v[72:75], v[156:159], v[204:207], 0
	v_mfma_f32_16x16x32_bf16 v[124:127], v[152:155], v[184:187], v[124:127]
	v_mfma_f32_16x16x32_bf16 v[120:123], v[160:163], v[184:187], v[120:123]
	v_mfma_f32_16x16x32_bf16 v[108:111], v[152:155], v[192:195], v[108:111]
	v_mfma_f32_16x16x32_bf16 v[104:107], v[160:163], v[192:195], v[104:107]
	v_mfma_f32_16x16x32_bf16 v[92:95], v[152:155], v[200:203], v[92:95]
	v_mfma_f32_16x16x32_bf16 v[88:91], v[160:163], v[200:203], v[88:91]
	v_mfma_f32_16x16x32_bf16 v[76:79], v[152:155], v[208:211], v[76:79]
	v_mfma_f32_16x16x32_bf16 v[72:75], v[160:163], v[208:211], v[72:75]
	v_mfma_f32_16x16x32_bf16 v[116:119], v[164:167], v[180:183], 0
	v_mfma_f32_16x16x32_bf16 v[112:115], v[172:175], v[180:183], 0
	v_mfma_f32_16x16x32_bf16 v[100:103], v[164:167], v[188:191], 0
	v_mfma_f32_16x16x32_bf16 v[96:99], v[172:175], v[188:191], 0
	v_mfma_f32_16x16x32_bf16 v[84:87], v[164:167], v[196:199], 0
	v_mfma_f32_16x16x32_bf16 v[80:83], v[172:175], v[196:199], 0
	v_mfma_f32_16x16x32_bf16 v[68:71], v[164:167], v[204:207], 0
	v_mfma_f32_16x16x32_bf16 v[64:67], v[172:175], v[204:207], 0
	v_mfma_f32_16x16x32_bf16 v[116:119], v[168:171], v[184:187], v[116:119]
	v_mfma_f32_16x16x32_bf16 v[112:115], v[176:179], v[184:187], v[112:115]
	v_mfma_f32_16x16x32_bf16 v[100:103], v[168:171], v[192:195], v[100:103]
	v_mfma_f32_16x16x32_bf16 v[96:99], v[176:179], v[192:195], v[96:99]
	v_mfma_f32_16x16x32_bf16 v[84:87], v[168:171], v[200:203], v[84:87]
	v_mfma_f32_16x16x32_bf16 v[80:83], v[176:179], v[200:203], v[80:83]
	v_mfma_f32_16x16x32_bf16 v[68:71], v[168:171], v[208:211], v[68:71]
	v_mfma_f32_16x16x32_bf16 v[64:67], v[176:179], v[208:211], v[64:67]
	s_setprio 0
	s_barrier
	s_add_i32 s33, s55, s34
	v_lshl_add_u64 v[212:213], s[62:63], 0, v[132:133]
	s_mov_b32 m0, s33
	ds_read_b128 v[180:183], v151 offset:16384
	ds_read_b128 v[184:187], v151 offset:17408
	ds_read_b128 v[188:191], v151 offset:18432
	ds_read_b128 v[192:195], v151 offset:19456
	ds_read_b128 v[196:199], v151 offset:20480
	ds_read_b128 v[200:203], v151 offset:21504
	ds_read_b128 v[204:207], v151 offset:22528
	ds_read_b128 v[208:211], v151 offset:23552
	global_load_lds_dwordx4 v[212:213], off
	s_add_i32 m0, s33, 0x2000
	v_lshl_add_u64 v[214:215], s[62:63], 0, v[128:129]
	s_add_u32 s62, s62, s8
	s_addc_u32 s63, s63, s9
	s_add_i32 s33, s56, s34
	global_load_lds_dwordx4 v[214:215], off
	v_lshl_add_u64 v[216:217], s[62:63], 0, v[132:133]
	s_mov_b32 m0, s33
	v_lshl_add_u64 v[218:219], s[62:63], 0, v[128:129]
	global_load_lds_dwordx4 v[216:217], off
	s_add_i32 m0, s33, 0x2000
	v_lshl_add_u64 v[220:221], s[28:29], 0, v[134:135]
	global_load_lds_dwordx4 v[218:219], off
	s_mov_b32 m0, s42
	v_lshl_add_u64 v[222:223], s[28:29], 0, v[130:131]
	global_load_lds_dwordx4 v[220:221], off
	s_mov_b32 m0, s43
	s_nop 0
	global_load_lds_dwordx4 v[222:223], off
	s_waitcnt vmcnt(8)
	s_waitcnt lgkmcnt(0)
	s_setprio 1
	s_barrier
; #define PG8_STAGE(bufoff, gbase, voff) do { _Pragma("unroll") for (int _i = 0; _i < 2; ++_i) \
;         __builtin_amdgcn_global_load_lds((const unsigned*)((const char*)(gbase) + (voff)[_i]), (PG8_LAS unsigned*)(lds + (bufoff) + ldsw + _i * 8192), 16, 0, 0); } while (0)
; #define PG8_LDA(dst, b, h) do { _Pragma("unroll") for (int m = 0; m < 4; ++m) _Pragma("unroll") for (int k = 0; k < 2; ++k) dst[m][k] = *(const PG8_LAS bf16x8*)(lds + PG8_SA(b, h) + aoff + m * 2048 + k * 1024); } while (0)
; #define PG8_LDB(dst, b, h) do { _Pragma("unroll") for (int n = 0; n < 2; ++n) _Pragma("unroll") for (int k = 0; k < 2; ++k) dst[n][k] = *(const PG8_LAS bf16x8*)(lds + PG8_SB(b, h) + boff + n * 2048 + k * 1024); } while (0)
; #define PG8_MMA(ai, bj, At, Bt) do { __builtin_amdgcn_s_setprio(1); _Pragma("unroll") for (int m = 0; m < 4; ++m) _Pragma("unroll") for (int n = 0; n < 2; ++n) _Pragma("unroll") for (int k = 0; k < 2; ++k) \
;         acc[ai][bj][m][n] = __builtin_amdgcn_mfma_f32_16x16x32_bf16(Bt[n][k], At[m][k], acc[ai][bj][m][n], 0, 0, 0); __builtin_amdgcn_s_setprio(0); } while (0)
; template <class Epi, class Sched, bool ALIGN_EPI = false, bool SP2 = false>
; __device__ __forceinline__ void gemm_phase(PG8_LAS unsigned char* lds, const Gemm g, const Sched& S, const Epi& E, const int wid) {
;     ...
;             if constexpr (SP2) {
;             PG8_LDB(B0, 0, 0); PG8_LDB(B1, 0, 1); PG8_SCHED; PG8_LDA(At, 0, 0); PG8_STAGE(PG8_SA(1, 1), a1 + hstep, voffA);
;             PG8_WAIT_V(8); PG8_WAIT_L(0); PG8_BAR; PG8_MMA(0, 0, At, B0); PG8_MMA(0, 1, At, B1); PG8_BAR; PG8_SCHED;
;             PG8_LDA(At, 0, 1); PG8_STAGE(PG8_SB(0, 0), b2, voffB); PG8_STAGE(PG8_SB(0, 1), b2 + hstep, voffB); PG8_STAGE(PG8_SA(0, 0), a2, voffA);
;             PG8_WAIT_V(8); PG8_WAIT_L(0); PG8_BAR; PG8_MMA(1, 0, At, B0); PG8_MMA(1, 1, At, B1); PG8_BAR; PG8_SCHED;
;             PG8_LDB(B0, 1, 0); PG8_LDB(B1, 1, 1); PG8_SCHED; PG8_LDA(At, 1, 0); PG8_STAGE(PG8_SA(0, 1), a2 + hstep, voffA);
;             PG8_WAIT_V(8); PG8_WAIT_L(0); PG8_BAR; PG8_MMA(0, 0, At, B0); PG8_MMA(0, 1, At, B1); PG8_BAR; PG8_SCHED;
;             PG8_LDA(At, 1, 1); PG8_STAGE(PG8_SB(1, 0), b3, voffB); PG8_STAGE(PG8_SB(1, 1), b3 + hstep, voffB); PG8_STAGE(PG8_SA(1, 0), a3, voffA);
;             PG8_WAIT_V(8); PG8_WAIT_L(0); PG8_BAR; PG8_MMA(1, 0, At, B0); PG8_MMA(1, 1, At, B1); PG8_BAR; PG8_SCHED;
	v_mfma_f32_16x16x32_bf16 v[60:63], v[142:145], v[180:183], 0
	v_mfma_f32_16x16x32_bf16 v[56:59], v[156:159], v[180:183], 0
	v_mfma_f32_16x16x32_bf16 v[44:47], v[142:145], v[188:191], 0
	v_mfma_f32_16x16x32_bf16 v[40:43], v[156:159], v[188:191], 0
	v_mfma_f32_16x16x32_bf16 v[28:31], v[142:145], v[196:199], 0
	v_mfma_f32_16x16x32_bf16 v[24:27], v[156:159], v[196:199], 0
	v_mfma_f32_16x16x32_bf16 v[12:15], v[142:145], v[204:207], 0
	v_mfma_f32_16x16x32_bf16 v[8:11], v[156:159], v[204:207], 0
	v_mfma_f32_16x16x32_bf16 v[60:63], v[152:155], v[184:187], v[60:63]
	v_mfma_f32_16x16x32_bf16 v[56:59], v[160:163], v[184:187], v[56:59]
	v_mfma_f32_16x16x32_bf16 v[44:47], v[152:155], v[192:195], v[44:47]
	v_mfma_f32_16x16x32_bf16 v[40:43], v[160:163], v[192:195], v[40:43]
	v_mfma_f32_16x16x32_bf16 v[28:31], v[152:155], v[200:203], v[28:31]
	v_mfma_f32_16x16x32_bf16 v[24:27], v[160:163], v[200:203], v[24:27]
	v_mfma_f32_16x16x32_bf16 v[12:15], v[152:155], v[208:211], v[12:15]
	v_mfma_f32_16x16x32_bf16 v[8:11], v[160:163], v[208:211], v[8:11]
	v_mfma_f32_16x16x32_bf16 v[52:55], v[164:167], v[180:183], 0
	v_mfma_f32_16x16x32_bf16 v[48:51], v[172:175], v[180:183], 0
	v_mfma_f32_16x16x32_bf16 v[36:39], v[164:167], v[188:191], 0
	v_mfma_f32_16x16x32_bf16 v[32:35], v[172:175], v[188:191], 0
	v_mfma_f32_16x16x32_bf16 v[20:23], v[164:167], v[196:199], 0
	v_mfma_f32_16x16x32_bf16 v[16:19], v[172:175], v[196:199], 0
	v_mfma_f32_16x16x32_bf16 v[4:7], v[164:167], v[204:207], 0
	v_mfma_f32_16x16x32_bf16 v[0:3], v[172:175], v[204:207], 0
	v_mfma_f32_16x16x32_bf16 v[52:55], v[168:171], v[184:187], v[52:55]
	v_mfma_f32_16x16x32_bf16 v[48:51], v[176:179], v[184:187], v[48:51]
	v_mfma_f32_16x16x32_bf16 v[36:39], v[168:171], v[192:195], v[36:39]
	v_mfma_f32_16x16x32_bf16 v[32:35], v[176:179], v[192:195], v[32:35]
	v_mfma_f32_16x16x32_bf16 v[20:23], v[168:171], v[200:203], v[20:23]
	v_mfma_f32_16x16x32_bf16 v[16:19], v[176:179], v[200:203], v[16:19]
	v_mfma_f32_16x16x32_bf16 v[4:7], v[168:171], v[208:211], v[4:7]
	v_mfma_f32_16x16x32_bf16 v[0:3], v[176:179], v[208:211], v[0:3]
	s_setprio 0
	s_barrier
	s_add_i32 s33, 0, 0x18000
	s_add_i32 s62, 0, 0x1c000
	v_add_u32_e32 v160, s33, v148
	v_add_u32_e32 v176, s62, v148
	ds_read_b128 v[142:145], v160
	ds_read_b128 v[152:155], v160 offset:1024
	ds_read_b128 v[156:159], v160 offset:2048
	ds_read_b128 v[160:163], v160 offset:3072
	ds_read_b128 v[164:167], v176
	ds_read_b128 v[168:171], v176 offset:1024
	ds_read_b128 v[172:175], v176 offset:2048
	ds_read_b128 v[176:179], v176 offset:3072
	s_add_u32 s28, s28, s8
	s_addc_u32 s29, s29, s9
	s_mov_b32 m0, s44
	v_lshl_add_u64 v[224:225], s[28:29], 0, v[134:135]
	ds_read_b128 v[180:183], v151 offset:32768
	ds_read_b128 v[184:187], v151 offset:33792
	ds_read_b128 v[188:191], v151 offset:34816
	ds_read_b128 v[192:195], v151 offset:35840
	ds_read_b128 v[196:199], v151 offset:36864
	ds_read_b128 v[200:203], v151 offset:37888
	ds_read_b128 v[204:207], v151 offset:38912
	ds_read_b128 v[208:211], v151 offset:39936
	global_load_lds_dwordx4 v[224:225], off
	v_lshl_add_u64 v[224:225], s[28:29], 0, v[130:131]
	s_mov_b32 m0, s45
	s_nop 0
	global_load_lds_dwordx4 v[224:225], off
	s_waitcnt vmcnt(8)
	s_waitcnt lgkmcnt(0)
	s_setprio 1
	s_barrier
	v_mfma_f32_16x16x32_bf16 v[124:127], v[142:145], v[180:183], v[124:127]
	v_mfma_f32_16x16x32_bf16 v[120:123], v[156:159], v[180:183], v[120:123]
	v_mfma_f32_16x16x32_bf16 v[108:111], v[142:145], v[188:191], v[108:111]
	v_mfma_f32_16x16x32_bf16 v[104:107], v[156:159], v[188:191], v[104:107]
	v_mfma_f32_16x16x32_bf16 v[92:95], v[142:145], v[196:199], v[92:95]
	v_mfma_f32_16x16x32_bf16 v[88:91], v[156:159], v[196:199], v[88:91]
	v_mfma_f32_16x16x32_bf16 v[76:79], v[142:145], v[204:207], v[76:79]
	v_mfma_f32_16x16x32_bf16 v[72:75], v[156:159], v[204:207], v[72:75]
	v_mfma_f32_16x16x32_bf16 v[124:127], v[152:155], v[184:187], v[124:127]
	v_mfma_f32_16x16x32_bf16 v[120:123], v[160:163], v[184:187], v[120:123]
	v_mfma_f32_16x16x32_bf16 v[108:111], v[152:155], v[192:195], v[108:111]
	v_mfma_f32_16x16x32_bf16 v[104:107], v[160:163], v[192:195], v[104:107]
	v_mfma_f32_16x16x32_bf16 v[92:95], v[152:155], v[200:203], v[92:95]
	v_mfma_f32_16x16x32_bf16 v[88:91], v[160:163], v[200:203], v[88:91]
	v_mfma_f32_16x16x32_bf16 v[76:79], v[152:155], v[208:211], v[76:79]
	v_mfma_f32_16x16x32_bf16 v[72:75], v[160:163], v[208:211], v[72:75]
	v_mfma_f32_16x16x32_bf16 v[116:119], v[164:167], v[180:183], v[116:119]
	v_mfma_f32_16x16x32_bf16 v[112:115], v[172:175], v[180:183], v[112:115]
	v_mfma_f32_16x16x32_bf16 v[100:103], v[164:167], v[188:191], v[100:103]
	v_mfma_f32_16x16x32_bf16 v[96:99], v[172:175], v[188:191], v[96:99]
	v_mfma_f32_16x16x32_bf16 v[84:87], v[164:167], v[196:199], v[84:87]
	v_mfma_f32_16x16x32_bf16 v[80:83], v[172:175], v[196:199], v[80:83]
	v_mfma_f32_16x16x32_bf16 v[68:71], v[164:167], v[204:207], v[68:71]
	v_mfma_f32_16x16x32_bf16 v[64:67], v[172:175], v[204:207], v[64:67]
	v_mfma_f32_16x16x32_bf16 v[116:119], v[168:171], v[184:187], v[116:119]
	v_mfma_f32_16x16x32_bf16 v[112:115], v[176:179], v[184:187], v[112:115]
	v_mfma_f32_16x16x32_bf16 v[100:103], v[168:171], v[192:195], v[100:103]
	v_mfma_f32_16x16x32_bf16 v[96:99], v[176:179], v[192:195], v[96:99]
	v_mfma_f32_16x16x32_bf16 v[84:87], v[168:171], v[200:203], v[84:87]
	v_mfma_f32_16x16x32_bf16 v[80:83], v[176:179], v[200:203], v[80:83]
	v_mfma_f32_16x16x32_bf16 v[68:71], v[168:171], v[208:211], v[68:71]
	v_mfma_f32_16x16x32_bf16 v[64:67], v[176:179], v[208:211], v[64:67]
	s_setprio 0
	s_barrier
; #define PG8_STAGE(bufoff, gbase, voff) do { _Pragma("unroll") for (int _i = 0; _i < 2; ++_i) \
;         __builtin_amdgcn_global_load_lds((const unsigned*)((const char*)(gbase) + (voff)[_i]), (PG8_LAS unsigned*)(lds + (bufoff) + ldsw + _i * 8192), 16, 0, 0); } while (0)
; #define PG8_LDA(dst, b, h) do { _Pragma("unroll") for (int m = 0; m < 4; ++m) _Pragma("unroll") for (int k = 0; k < 2; ++k) dst[m][k] = *(const PG8_LAS bf16x8*)(lds + PG8_SA(b, h) + aoff + m * 2048 + k * 1024); } while (0)
; #define PG8_WAIT_V(n) asm volatile("s_waitcnt vmcnt(" #n ")" ::: "memory")
; #define PG8_WAIT_L(n) asm volatile("s_waitcnt lgkmcnt(" #n ")" ::: "memory")
; #define PG8_BAR __builtin_amdgcn_s_barrier()
; template <class Epi, class Sched, bool ALIGN_EPI = false, bool SP2 = false>
; __device__ __forceinline__ void gemm_phase(PG8_LAS unsigned char* lds, const Gemm g, const Sched& S, const Epi& E, const int wid) {
;     ...
;         for (int t = 0; t < nt; t += 2) {
;             const bool last = (t == nt - 2);
;             const char* a1 = cA + (size_t)(t + 1) * kstep;
;             const char* a2 = last ? nA : cA + (size_t)(t + 2) * kstep; const char* b2 = last ? nB : cB + (size_t)(t + 2) * kstep;
;             const char* a3 = a2 + kstep; const char* b3 = b2 + kstep;
;             if (last && has_next) S.a_ready(nxt);
;             if constexpr (SP2) {
;             PG8_LDB(B0, 0, 0); PG8_LDB(B1, 0, 1); PG8_SCHED; PG8_LDA(At, 0, 0); PG8_STAGE(PG8_SA(1, 1), a1 + hstep, voffA);
;             PG8_WAIT_V(8); PG8_WAIT_L(0); PG8_BAR; PG8_MMA(0, 0, At, B0); PG8_MMA(0, 1, At, B1); PG8_BAR; PG8_SCHED;
;             PG8_LDA(At, 0, 1); PG8_STAGE(PG8_SB(0, 0), b2, voffB); PG8_STAGE(PG8_SB(0, 1), b2 + hstep, voffB); PG8_STAGE(PG8_SA(0, 0), a2, voffA);
;             PG8_WAIT_V(8); PG8_WAIT_L(0); PG8_BAR; PG8_MMA(1, 0, At, B0); PG8_MMA(1, 1, At, B1); PG8_BAR; PG8_SCHED;
;             PG8_LDB(B0, 1, 0); PG8_LDB(B1, 1, 1); PG8_SCHED; PG8_LDA(At, 1, 0); PG8_STAGE(PG8_SA(0, 1), a2 + hstep, voffA);
;             PG8_WAIT_V(8); PG8_WAIT_L(0); PG8_BAR; PG8_MMA(0, 0, At, B0); PG8_MMA(0, 1, At, B1); PG8_BAR; PG8_SCHED;
;             PG8_LDA(At, 1, 1); PG8_STAGE(PG8_SB(1, 0), b3, voffB); PG8_STAGE(PG8_SB(1, 1), b3 + hstep, voffB); PG8_STAGE(PG8_SA(1, 0), a3, voffA);
;             PG8_WAIT_V(8); PG8_WAIT_L(0); PG8_BAR; PG8_MMA(1, 0, At, B0); PG8_MMA(1, 1, At, B1); PG8_BAR; PG8_SCHED;
	s_add_i32 s28, s33, s34
	v_lshl_add_u64 v[212:213], v[212:213], 0, s[18:19]
	s_mov_b32 m0, s28
	ds_read_b128 v[180:183], v151 offset:49152
	ds_read_b128 v[184:187], v151 offset:50176
	ds_read_b128 v[188:191], v151 offset:51200
	ds_read_b128 v[192:195], v151 offset:52224
	ds_read_b128 v[196:199], v151 offset:53248
	ds_read_b128 v[200:203], v151 offset:54272
	ds_read_b128 v[204:207], v151 offset:55296
	ds_read_b128 v[208:211], v151 offset:56320
	global_load_lds_dwordx4 v[212:213], off
	v_lshl_add_u64 v[212:213], v[214:215], 0, s[18:19]
	s_add_i32 m0, s28, 0x2000
	s_add_i32 s28, s62, s34
	global_load_lds_dwordx4 v[212:213], off
	v_lshl_add_u64 v[212:213], v[216:217], 0, s[18:19]
	s_mov_b32 m0, s28
	s_nop 0
	global_load_lds_dwordx4 v[212:213], off
	v_lshl_add_u64 v[212:213], v[218:219], 0, s[18:19]
	s_add_i32 m0, s28, 0x2000
	s_nop 0
	global_load_lds_dwordx4 v[212:213], off
	v_lshl_add_u64 v[212:213], v[220:221], 0, s[18:19]
	s_mov_b32 m0, s47
	s_nop 0
	global_load_lds_dwordx4 v[212:213], off
	v_lshl_add_u64 v[212:213], v[222:223], 0, s[18:19]
	s_mov_b32 m0, s49
	s_nop 0
	global_load_lds_dwordx4 v[212:213], off
	s_waitcnt vmcnt(8)
	s_waitcnt lgkmcnt(0)
	s_setprio 1
	s_barrier
	v_mfma_f32_16x16x32_bf16 v[60:63], v[142:145], v[180:183], v[60:63]
	v_mfma_f32_16x16x32_bf16 v[56:59], v[156:159], v[180:183], v[56:59]
	v_mfma_f32_16x16x32_bf16 v[44:47], v[142:145], v[188:191], v[44:47]
	v_mfma_f32_16x16x32_bf16 v[40:43], v[156:159], v[188:191], v[40:43]
	v_mfma_f32_16x16x32_bf16 v[28:31], v[142:145], v[196:199], v[28:31]
	v_mfma_f32_16x16x32_bf16 v[24:27], v[156:159], v[196:199], v[24:27]
	v_mfma_f32_16x16x32_bf16 v[12:15], v[142:145], v[204:207], v[12:15]
	v_mfma_f32_16x16x32_bf16 v[8:11], v[156:159], v[204:207], v[8:11]
	v_mfma_f32_16x16x32_bf16 v[60:63], v[152:155], v[184:187], v[60:63]
	v_mfma_f32_16x16x32_bf16 v[56:59], v[160:163], v[184:187], v[56:59]
	v_mfma_f32_16x16x32_bf16 v[44:47], v[152:155], v[192:195], v[44:47]
	v_mfma_f32_16x16x32_bf16 v[40:43], v[160:163], v[192:195], v[40:43]
	v_mfma_f32_16x16x32_bf16 v[28:31], v[152:155], v[200:203], v[28:31]
	v_mfma_f32_16x16x32_bf16 v[24:27], v[160:163], v[200:203], v[24:27]
	v_mfma_f32_16x16x32_bf16 v[12:15], v[152:155], v[208:211], v[12:15]
	v_mfma_f32_16x16x32_bf16 v[8:11], v[160:163], v[208:211], v[8:11]
	v_mfma_f32_16x16x32_bf16 v[52:55], v[164:167], v[180:183], v[52:55]
	v_mfma_f32_16x16x32_bf16 v[48:51], v[172:175], v[180:183], v[48:51]
	v_mfma_f32_16x16x32_bf16 v[36:39], v[164:167], v[188:191], v[36:39]
	v_mfma_f32_16x16x32_bf16 v[32:35], v[172:175], v[188:191], v[32:35]
	v_mfma_f32_16x16x32_bf16 v[20:23], v[164:167], v[196:199], v[20:23]
	v_mfma_f32_16x16x32_bf16 v[16:19], v[172:175], v[196:199], v[16:19]
	v_mfma_f32_16x16x32_bf16 v[4:7], v[164:167], v[204:207], v[4:7]
	v_mfma_f32_16x16x32_bf16 v[0:3], v[172:175], v[204:207], v[0:3]
	v_mfma_f32_16x16x32_bf16 v[52:55], v[168:171], v[184:187], v[52:55]
	v_mfma_f32_16x16x32_bf16 v[48:51], v[176:179], v[184:187], v[48:51]
	v_mfma_f32_16x16x32_bf16 v[36:39], v[168:171], v[192:195], v[36:39]
	v_mfma_f32_16x16x32_bf16 v[32:35], v[176:179], v[192:195], v[32:35]
	v_mfma_f32_16x16x32_bf16 v[20:23], v[168:171], v[200:203], v[20:23]
	v_mfma_f32_16x16x32_bf16 v[16:19], v[176:179], v[200:203], v[16:19]
	v_mfma_f32_16x16x32_bf16 v[4:7], v[168:171], v[208:211], v[4:7]
	v_mfma_f32_16x16x32_bf16 v[0:3], v[176:179], v[208:211], v[0:3]
	s_setprio 0
	s_barrier
	s_add_u32 s26, s26, 0x100
	s_addc_u32 s27, s27, 0
	s_add_u32 s0, s0, 0x100
	s_addc_u32 s1, s1, 0
	s_cmp_ge_i32 s61, s50
	s_mov_b32 s28, s61
	s_cbranch_scc1 .LBB0_1180
.LBB0_1179:
	ds_read_b128 v[142:145], v149
	ds_read_b128 v[152:155], v149 offset:1024
	ds_read_b128 v[156:159], v149 offset:2048
	ds_read_b128 v[160:163], v149 offset:3072
	ds_read_b128 v[164:167], v150
	ds_read_b128 v[168:171], v150 offset:1024
	ds_read_b128 v[172:175], v150 offset:2048
	ds_read_b128 v[176:179], v150 offset:3072
	s_add_i32 s61, s28, 2
	s_add_u32 s33, s26, 0x80
	s_addc_u32 s29, s27, 0
	s_cmp_eq_u32 s53, s28
	s_cselect_b32 s28, s4, s33
	s_cselect_b32 s29, s5, s29
	s_cselect_b32 s63, s25, s1
	s_cselect_b32 s62, s24, s0
	v_lshl_add_u64 v[212:213], s[26:27], 0, v[136:137]
	s_add_i32 m0, s42, 0xc000
	ds_read_b128 v[180:183], v151
	ds_read_b128 v[184:187], v151 offset:1024
	ds_read_b128 v[188:191], v151 offset:2048
	ds_read_b128 v[192:195], v151 offset:3072
	ds_read_b128 v[196:199], v151 offset:4096
	ds_read_b128 v[200:203], v151 offset:5120
	ds_read_b128 v[204:207], v151 offset:6144
	ds_read_b128 v[208:211], v151 offset:7168
	global_load_lds_dwordx4 v[212:213], off
	v_lshl_add_u64 v[212:213], s[26:27], 0, v[138:139]
	s_add_i32 m0, s42, 0xe000
	s_nop 0
	global_load_lds_dwordx4 v[212:213], off
	s_waitcnt vmcnt(8)
	s_waitcnt lgkmcnt(0)
	s_setprio 1
	s_barrier
; #define PG8_STAGE(bufoff, gbase, voff) do { _Pragma("unroll") for (int _i = 0; _i < 2; ++_i) \
;         __builtin_amdgcn_global_load_lds((const unsigned*)((const char*)(gbase) + (voff)[_i]), (PG8_LAS unsigned*)(lds + (bufoff) + ldsw + _i * 8192), 16, 0, 0); } while (0)
; #define PG8_LDA(dst, b, h) do { _Pragma("unroll") for (int m = 0; m < 4; ++m) _Pragma("unroll") for (int k = 0; k < 2; ++k) dst[m][k] = *(const PG8_LAS bf16x8*)(lds + PG8_SA(b, h) + aoff + m * 2048 + k * 1024); } while (0)
; #define PG8_LDB(dst, b, h) do { _Pragma("unroll") for (int n = 0; n < 2; ++n) _Pragma("unroll") for (int k = 0; k < 2; ++k) dst[n][k] = *(const PG8_LAS bf16x8*)(lds + PG8_SB(b, h) + boff + n * 2048 + k * 1024); } while (0)
; #define PG8_MMA(ai, bj, At, Bt) do { __builtin_amdgcn_s_setprio(1); _Pragma("unroll") for (int m = 0; m < 4; ++m) _Pragma("unroll") for (int n = 0; n < 2; ++n) _Pragma("unroll") for (int k = 0; k < 2; ++k) \
;         acc[ai][bj][m][n] = __builtin_amdgcn_mfma_f32_16x16x32_bf16(Bt[n][k], At[m][k], acc[ai][bj][m][n], 0, 0, 0); __builtin_amdgcn_s_setprio(0); } while (0)
; template <class Epi, class Sched, bool ALIGN_EPI = false, bool SP2 = false>
; __device__ __forceinline__ void gemm_phase(PG8_LAS unsigned char* lds, const Gemm g, const Sched& S, const Epi& E, const int wid) {
;     ...
;             if constexpr (SP2) {
;             PG8_LDB(B0, 0, 0); PG8_LDB(B1, 0, 1); PG8_SCHED; PG8_LDA(At, 0, 0); PG8_STAGE(PG8_SA(1, 1), a1 + hstep, voffA);
;             PG8_WAIT_V(8); PG8_WAIT_L(0); PG8_BAR; PG8_MMA(0, 0, At, B0); PG8_MMA(0, 1, At, B1); PG8_BAR; PG8_SCHED;
;             PG8_LDA(At, 0, 1); PG8_STAGE(PG8_SB(0, 0), b2, voffB); PG8_STAGE(PG8_SB(0, 1), b2 + hstep, voffB); PG8_STAGE(PG8_SA(0, 0), a2, voffA);
;             PG8_WAIT_V(8); PG8_WAIT_L(0); PG8_BAR; PG8_MMA(1, 0, At, B0); PG8_MMA(1, 1, At, B1); PG8_BAR; PG8_SCHED;
;             PG8_LDB(B0, 1, 0); PG8_LDB(B1, 1, 1); PG8_SCHED; PG8_LDA(At, 1, 0); PG8_STAGE(PG8_SA(0, 1), a2 + hstep, voffA);
;             PG8_WAIT_V(8); PG8_WAIT_L(0); PG8_BAR; PG8_MMA(0, 0, At, B0); PG8_MMA(0, 1, At, B1); PG8_BAR; PG8_SCHED;
;             PG8_LDA(At, 1, 1); PG8_STAGE(PG8_SB(1, 0), b3, voffB); PG8_STAGE(PG8_SB(1, 1), b3 + hstep, voffB); PG8_STAGE(PG8_SA(1, 0), a3, voffA);
;             PG8_WAIT_V(8); PG8_WAIT_L(0); PG8_BAR; PG8_MMA(1, 0, At, B0); PG8_MMA(1, 1, At, B1); PG8_BAR; PG8_SCHED;
	v_mfma_f32_16x16x32_bf16 v[124:127], v[142:145], v[180:183], v[124:127]
	v_mfma_f32_16x16x32_bf16 v[120:123], v[156:159], v[180:183], v[120:123]
	v_mfma_f32_16x16x32_bf16 v[108:111], v[142:145], v[188:191], v[108:111]
	v_mfma_f32_16x16x32_bf16 v[104:107], v[156:159], v[188:191], v[104:107]
	v_mfma_f32_16x16x32_bf16 v[92:95], v[142:145], v[196:199], v[92:95]
	v_mfma_f32_16x16x32_bf16 v[88:91], v[156:159], v[196:199], v[88:91]
	v_mfma_f32_16x16x32_bf16 v[76:79], v[142:145], v[204:207], v[76:79]
	v_mfma_f32_16x16x32_bf16 v[72:75], v[156:159], v[204:207], v[72:75]
	v_mfma_f32_16x16x32_bf16 v[124:127], v[152:155], v[184:187], v[124:127]
	v_mfma_f32_16x16x32_bf16 v[120:123], v[160:163], v[184:187], v[120:123]
	v_mfma_f32_16x16x32_bf16 v[108:111], v[152:155], v[192:195], v[108:111]
	v_mfma_f32_16x16x32_bf16 v[104:107], v[160:163], v[192:195], v[104:107]
	v_mfma_f32_16x16x32_bf16 v[92:95], v[152:155], v[200:203], v[92:95]
	v_mfma_f32_16x16x32_bf16 v[88:91], v[160:163], v[200:203], v[88:91]
	v_mfma_f32_16x16x32_bf16 v[76:79], v[152:155], v[208:211], v[76:79]
	v_mfma_f32_16x16x32_bf16 v[72:75], v[160:163], v[208:211], v[72:75]
	v_mfma_f32_16x16x32_bf16 v[116:119], v[164:167], v[180:183], v[116:119]
	v_mfma_f32_16x16x32_bf16 v[112:115], v[172:175], v[180:183], v[112:115]
	v_mfma_f32_16x16x32_bf16 v[100:103], v[164:167], v[188:191], v[100:103]
	v_mfma_f32_16x16x32_bf16 v[96:99], v[172:175], v[188:191], v[96:99]
	v_mfma_f32_16x16x32_bf16 v[84:87], v[164:167], v[196:199], v[84:87]
	v_mfma_f32_16x16x32_bf16 v[80:83], v[172:175], v[196:199], v[80:83]
	v_mfma_f32_16x16x32_bf16 v[68:71], v[164:167], v[204:207], v[68:71]
	v_mfma_f32_16x16x32_bf16 v[64:67], v[172:175], v[204:207], v[64:67]
	v_mfma_f32_16x16x32_bf16 v[116:119], v[168:171], v[184:187], v[116:119]
	v_mfma_f32_16x16x32_bf16 v[112:115], v[176:179], v[184:187], v[112:115]
	v_mfma_f32_16x16x32_bf16 v[100:103], v[168:171], v[192:195], v[100:103]
	v_mfma_f32_16x16x32_bf16 v[96:99], v[176:179], v[192:195], v[96:99]
	v_mfma_f32_16x16x32_bf16 v[84:87], v[168:171], v[200:203], v[84:87]
	v_mfma_f32_16x16x32_bf16 v[80:83], v[176:179], v[200:203], v[80:83]
	v_mfma_f32_16x16x32_bf16 v[68:71], v[168:171], v[208:211], v[68:71]
	v_mfma_f32_16x16x32_bf16 v[64:67], v[176:179], v[208:211], v[64:67]
	s_setprio 0
	s_barrier
	s_add_i32 s33, s55, s34
	v_lshl_add_u64 v[212:213], s[62:63], 0, v[132:133]
	s_mov_b32 m0, s33
	ds_read_b128 v[180:183], v151 offset:16384
	ds_read_b128 v[184:187], v151 offset:17408
	ds_read_b128 v[188:191], v151 offset:18432
	ds_read_b128 v[192:195], v151 offset:19456
	ds_read_b128 v[196:199], v151 offset:20480
	ds_read_b128 v[200:203], v151 offset:21504
	ds_read_b128 v[204:207], v151 offset:22528
	ds_read_b128 v[208:211], v151 offset:23552
	global_load_lds_dwordx4 v[212:213], off
	s_add_i32 m0, s33, 0x2000
	v_lshl_add_u64 v[214:215], s[62:63], 0, v[128:129]
	s_add_u32 s62, s62, s8
	s_addc_u32 s63, s63, s9
	s_add_i32 s33, s56, s34
	global_load_lds_dwordx4 v[214:215], off
	v_lshl_add_u64 v[216:217], s[62:63], 0, v[132:133]
	s_mov_b32 m0, s33
	v_lshl_add_u64 v[218:219], s[62:63], 0, v[128:129]
	global_load_lds_dwordx4 v[216:217], off
	s_add_i32 m0, s33, 0x2000
	v_lshl_add_u64 v[220:221], s[28:29], 0, v[134:135]
	global_load_lds_dwordx4 v[218:219], off
	s_mov_b32 m0, s42
	v_lshl_add_u64 v[222:223], s[28:29], 0, v[130:131]
	global_load_lds_dwordx4 v[220:221], off
	s_mov_b32 m0, s43
	s_nop 0
	global_load_lds_dwordx4 v[222:223], off
	s_waitcnt vmcnt(8)
	s_waitcnt lgkmcnt(0)
	s_setprio 1
	s_barrier
	v_mfma_f32_16x16x32_bf16 v[60:63], v[142:145], v[180:183], v[60:63]
	v_mfma_f32_16x16x32_bf16 v[56:59], v[156:159], v[180:183], v[56:59]
	v_mfma_f32_16x16x32_bf16 v[44:47], v[142:145], v[188:191], v[44:47]
	v_mfma_f32_16x16x32_bf16 v[40:43], v[156:159], v[188:191], v[40:43]
	v_mfma_f32_16x16x32_bf16 v[28:31], v[142:145], v[196:199], v[28:31]
	v_mfma_f32_16x16x32_bf16 v[24:27], v[156:159], v[196:199], v[24:27]
	v_mfma_f32_16x16x32_bf16 v[12:15], v[142:145], v[204:207], v[12:15]
	v_mfma_f32_16x16x32_bf16 v[8:11], v[156:159], v[204:207], v[8:11]
	v_mfma_f32_16x16x32_bf16 v[60:63], v[152:155], v[184:187], v[60:63]
	v_mfma_f32_16x16x32_bf16 v[56:59], v[160:163], v[184:187], v[56:59]
	v_mfma_f32_16x16x32_bf16 v[44:47], v[152:155], v[192:195], v[44:47]
	v_mfma_f32_16x16x32_bf16 v[40:43], v[160:163], v[192:195], v[40:43]
	v_mfma_f32_16x16x32_bf16 v[28:31], v[152:155], v[200:203], v[28:31]
	v_mfma_f32_16x16x32_bf16 v[24:27], v[160:163], v[200:203], v[24:27]
	v_mfma_f32_16x16x32_bf16 v[12:15], v[152:155], v[208:211], v[12:15]
	v_mfma_f32_16x16x32_bf16 v[8:11], v[160:163], v[208:211], v[8:11]
	v_mfma_f32_16x16x32_bf16 v[52:55], v[164:167], v[180:183], v[52:55]
	v_mfma_f32_16x16x32_bf16 v[48:51], v[172:175], v[180:183], v[48:51]
	v_mfma_f32_16x16x32_bf16 v[36:39], v[164:167], v[188:191], v[36:39]
	v_mfma_f32_16x16x32_bf16 v[32:35], v[172:175], v[188:191], v[32:35]
	v_mfma_f32_16x16x32_bf16 v[20:23], v[164:167], v[196:199], v[20:23]
	v_mfma_f32_16x16x32_bf16 v[16:19], v[172:175], v[196:199], v[16:19]
	v_mfma_f32_16x16x32_bf16 v[4:7], v[164:167], v[204:207], v[4:7]
	v_mfma_f32_16x16x32_bf16 v[0:3], v[172:175], v[204:207], v[0:3]
	v_mfma_f32_16x16x32_bf16 v[52:55], v[168:171], v[184:187], v[52:55]
	v_mfma_f32_16x16x32_bf16 v[48:51], v[176:179], v[184:187], v[48:51]
	v_mfma_f32_16x16x32_bf16 v[36:39], v[168:171], v[192:195], v[36:39]
	v_mfma_f32_16x16x32_bf16 v[32:35], v[176:179], v[192:195], v[32:35]
	v_mfma_f32_16x16x32_bf16 v[20:23], v[168:171], v[200:203], v[20:23]
	v_mfma_f32_16x16x32_bf16 v[16:19], v[176:179], v[200:203], v[16:19]
	v_mfma_f32_16x16x32_bf16 v[4:7], v[168:171], v[208:211], v[4:7]
	v_mfma_f32_16x16x32_bf16 v[0:3], v[176:179], v[208:211], v[0:3]
	s_setprio 0
	s_barrier
; #define PG8_STAGE(bufoff, gbase, voff) do { _Pragma("unroll") for (int _i = 0; _i < 2; ++_i) \
;         __builtin_amdgcn_global_load_lds((const unsigned*)((const char*)(gbase) + (voff)[_i]), (PG8_LAS unsigned*)(lds + (bufoff) + ldsw + _i * 8192), 16, 0, 0); } while (0)
; #define PG8_LDA(dst, b, h) do { _Pragma("unroll") for (int m = 0; m < 4; ++m) _Pragma("unroll") for (int k = 0; k < 2; ++k) dst[m][k] = *(const PG8_LAS bf16x8*)(lds + PG8_SA(b, h) + aoff + m * 2048 + k * 1024); } while (0)
; #define PG8_WAIT_V(n) asm volatile("s_waitcnt vmcnt(" #n ")" ::: "memory")
; #define PG8_WAIT_L(n) asm volatile("s_waitcnt lgkmcnt(" #n ")" ::: "memory")
; #define PG8_BAR __builtin_amdgcn_s_barrier()
; template <class Epi, class Sched, bool ALIGN_EPI = false, bool SP2 = false>
; __device__ __forceinline__ void gemm_phase(PG8_LAS unsigned char* lds, const Gemm g, const Sched& S, const Epi& E, const int wid) {
;     ...
;         for (int t = 0; t < nt; t += 2) {
;             const bool last = (t == nt - 2);
;             const char* a1 = cA + (size_t)(t + 1) * kstep;
;             const char* a2 = last ? nA : cA + (size_t)(t + 2) * kstep; const char* b2 = last ? nB : cB + (size_t)(t + 2) * kstep;
;             const char* a3 = a2 + kstep; const char* b3 = b2 + kstep;
;             if (last && has_next) S.a_ready(nxt);
;             if constexpr (SP2) {
;             PG8_LDB(B0, 0, 0); PG8_LDB(B1, 0, 1); PG8_SCHED; PG8_LDA(At, 0, 0); PG8_STAGE(PG8_SA(1, 1), a1 + hstep, voffA);
;             PG8_WAIT_V(8); PG8_WAIT_L(0); PG8_BAR; PG8_MMA(0, 0, At, B0); PG8_MMA(0, 1, At, B1); PG8_BAR; PG8_SCHED;
;             PG8_LDA(At, 0, 1); PG8_STAGE(PG8_SB(0, 0), b2, voffB); PG8_STAGE(PG8_SB(0, 1), b2 + hstep, voffB); PG8_STAGE(PG8_SA(0, 0), a2, voffA);
;             PG8_WAIT_V(8); PG8_WAIT_L(0); PG8_BAR; PG8_MMA(1, 0, At, B0); PG8_MMA(1, 1, At, B1); PG8_BAR; PG8_SCHED;
;             PG8_LDB(B0, 1, 0); PG8_LDB(B1, 1, 1); PG8_SCHED; PG8_LDA(At, 1, 0); PG8_STAGE(PG8_SA(0, 1), a2 + hstep, voffA);
;             PG8_WAIT_V(8); PG8_WAIT_L(0); PG8_BAR; PG8_MMA(0, 0, At, B0); PG8_MMA(0, 1, At, B1); PG8_BAR; PG8_SCHED;
;             PG8_LDA(At, 1, 1); PG8_STAGE(PG8_SB(1, 0), b3, voffB); PG8_STAGE(PG8_SB(1, 1), b3 + hstep, voffB); PG8_STAGE(PG8_SA(1, 0), a3, voffA);
;             PG8_WAIT_V(8); PG8_WAIT_L(0); PG8_BAR; PG8_MMA(1, 0, At, B0); PG8_MMA(1, 1, At, B1); PG8_BAR; PG8_SCHED;
	s_add_i32 s33, 0, 0x18000
	s_add_i32 s62, 0, 0x1c000
	v_add_u32_e32 v160, s33, v148
	v_add_u32_e32 v176, s62, v148
	ds_read_b128 v[142:145], v160
	ds_read_b128 v[152:155], v160 offset:1024
	ds_read_b128 v[156:159], v160 offset:2048
	ds_read_b128 v[160:163], v160 offset:3072
	ds_read_b128 v[164:167], v176
	ds_read_b128 v[168:171], v176 offset:1024
	ds_read_b128 v[172:175], v176 offset:2048
	ds_read_b128 v[176:179], v176 offset:3072
	s_add_u32 s28, s28, s8
	s_addc_u32 s29, s29, s9
	s_mov_b32 m0, s44
	v_lshl_add_u64 v[224:225], s[28:29], 0, v[134:135]
	ds_read_b128 v[180:183], v151 offset:32768
	ds_read_b128 v[184:187], v151 offset:33792
	ds_read_b128 v[188:191], v151 offset:34816
	ds_read_b128 v[192:195], v151 offset:35840
	ds_read_b128 v[196:199], v151 offset:36864
	ds_read_b128 v[200:203], v151 offset:37888
	ds_read_b128 v[204:207], v151 offset:38912
	ds_read_b128 v[208:211], v151 offset:39936
	global_load_lds_dwordx4 v[224:225], off
	v_lshl_add_u64 v[224:225], s[28:29], 0, v[130:131]
	s_mov_b32 m0, s45
	s_nop 0
	global_load_lds_dwordx4 v[224:225], off
	s_waitcnt vmcnt(8)
	s_waitcnt lgkmcnt(0)
	s_setprio 1
	s_barrier
	v_mfma_f32_16x16x32_bf16 v[124:127], v[142:145], v[180:183], v[124:127]
	v_mfma_f32_16x16x32_bf16 v[120:123], v[156:159], v[180:183], v[120:123]
	v_mfma_f32_16x16x32_bf16 v[108:111], v[142:145], v[188:191], v[108:111]
	v_mfma_f32_16x16x32_bf16 v[104:107], v[156:159], v[188:191], v[104:107]
	v_mfma_f32_16x16x32_bf16 v[92:95], v[142:145], v[196:199], v[92:95]
	v_mfma_f32_16x16x32_bf16 v[88:91], v[156:159], v[196:199], v[88:91]
	v_mfma_f32_16x16x32_bf16 v[76:79], v[142:145], v[204:207], v[76:79]
	v_mfma_f32_16x16x32_bf16 v[72:75], v[156:159], v[204:207], v[72:75]
	v_mfma_f32_16x16x32_bf16 v[124:127], v[152:155], v[184:187], v[124:127]
	v_mfma_f32_16x16x32_bf16 v[120:123], v[160:163], v[184:187], v[120:123]
	v_mfma_f32_16x16x32_bf16 v[108:111], v[152:155], v[192:195], v[108:111]
	v_mfma_f32_16x16x32_bf16 v[104:107], v[160:163], v[192:195], v[104:107]
	v_mfma_f32_16x16x32_bf16 v[92:95], v[152:155], v[200:203], v[92:95]
	v_mfma_f32_16x16x32_bf16 v[88:91], v[160:163], v[200:203], v[88:91]
	v_mfma_f32_16x16x32_bf16 v[76:79], v[152:155], v[208:211], v[76:79]
	v_mfma_f32_16x16x32_bf16 v[72:75], v[160:163], v[208:211], v[72:75]
	v_mfma_f32_16x16x32_bf16 v[116:119], v[164:167], v[180:183], v[116:119]
	v_mfma_f32_16x16x32_bf16 v[112:115], v[172:175], v[180:183], v[112:115]
	v_mfma_f32_16x16x32_bf16 v[100:103], v[164:167], v[188:191], v[100:103]
	v_mfma_f32_16x16x32_bf16 v[96:99], v[172:175], v[188:191], v[96:99]
	v_mfma_f32_16x16x32_bf16 v[84:87], v[164:167], v[196:199], v[84:87]
	v_mfma_f32_16x16x32_bf16 v[80:83], v[172:175], v[196:199], v[80:83]
	v_mfma_f32_16x16x32_bf16 v[68:71], v[164:167], v[204:207], v[68:71]
	v_mfma_f32_16x16x32_bf16 v[64:67], v[172:175], v[204:207], v[64:67]
	v_mfma_f32_16x16x32_bf16 v[116:119], v[168:171], v[184:187], v[116:119]
	v_mfma_f32_16x16x32_bf16 v[112:115], v[176:179], v[184:187], v[112:115]
	v_mfma_f32_16x16x32_bf16 v[100:103], v[168:171], v[192:195], v[100:103]
	v_mfma_f32_16x16x32_bf16 v[96:99], v[176:179], v[192:195], v[96:99]
	v_mfma_f32_16x16x32_bf16 v[84:87], v[168:171], v[200:203], v[84:87]
	v_mfma_f32_16x16x32_bf16 v[80:83], v[176:179], v[200:203], v[80:83]
	v_mfma_f32_16x16x32_bf16 v[68:71], v[168:171], v[208:211], v[68:71]
	v_mfma_f32_16x16x32_bf16 v[64:67], v[176:179], v[208:211], v[64:67]
	s_setprio 0
	s_barrier
	s_add_i32 s28, s33, s34
	v_lshl_add_u64 v[212:213], v[212:213], 0, s[18:19]
	s_mov_b32 m0, s28
	ds_read_b128 v[180:183], v151 offset:49152
	ds_read_b128 v[184:187], v151 offset:50176
	ds_read_b128 v[188:191], v151 offset:51200
	ds_read_b128 v[192:195], v151 offset:52224
	ds_read_b128 v[196:199], v151 offset:53248
	ds_read_b128 v[200:203], v151 offset:54272
	ds_read_b128 v[204:207], v151 offset:55296
	ds_read_b128 v[208:211], v151 offset:56320
	global_load_lds_dwordx4 v[212:213], off
	v_lshl_add_u64 v[212:213], v[214:215], 0, s[18:19]
	s_add_i32 m0, s28, 0x2000
	s_add_i32 s28, s62, s34
	global_load_lds_dwordx4 v[212:213], off
	v_lshl_add_u64 v[212:213], v[216:217], 0, s[18:19]
	s_mov_b32 m0, s28
	s_nop 0
	global_load_lds_dwordx4 v[212:213], off
	v_lshl_add_u64 v[212:213], v[218:219], 0, s[18:19]
	s_add_i32 m0, s28, 0x2000
	s_nop 0
	global_load_lds_dwordx4 v[212:213], off
	v_lshl_add_u64 v[212:213], v[220:221], 0, s[18:19]
	s_mov_b32 m0, s47
	s_nop 0
	global_load_lds_dwordx4 v[212:213], off
	v_lshl_add_u64 v[212:213], v[222:223], 0, s[18:19]
	s_mov_b32 m0, s49
	s_nop 0
	global_load_lds_dwordx4 v[212:213], off
	s_waitcnt vmcnt(8)
	s_waitcnt lgkmcnt(0)
	s_setprio 1
	s_barrier
	v_mfma_f32_16x16x32_bf16 v[60:63], v[142:145], v[180:183], v[60:63]
	v_mfma_f32_16x16x32_bf16 v[56:59], v[156:159], v[180:183], v[56:59]
	v_mfma_f32_16x16x32_bf16 v[44:47], v[142:145], v[188:191], v[44:47]
	v_mfma_f32_16x16x32_bf16 v[40:43], v[156:159], v[188:191], v[40:43]
	v_mfma_f32_16x16x32_bf16 v[28:31], v[142:145], v[196:199], v[28:31]
	v_mfma_f32_16x16x32_bf16 v[24:27], v[156:159], v[196:199], v[24:27]
	v_mfma_f32_16x16x32_bf16 v[12:15], v[142:145], v[204:207], v[12:15]
	v_mfma_f32_16x16x32_bf16 v[8:11], v[156:159], v[204:207], v[8:11]
	v_mfma_f32_16x16x32_bf16 v[60:63], v[152:155], v[184:187], v[60:63]
	v_mfma_f32_16x16x32_bf16 v[56:59], v[160:163], v[184:187], v[56:59]
	v_mfma_f32_16x16x32_bf16 v[44:47], v[152:155], v[192:195], v[44:47]
	v_mfma_f32_16x16x32_bf16 v[40:43], v[160:163], v[192:195], v[40:43]
	v_mfma_f32_16x16x32_bf16 v[28:31], v[152:155], v[200:203], v[28:31]
	v_mfma_f32_16x16x32_bf16 v[24:27], v[160:163], v[200:203], v[24:27]
	v_mfma_f32_16x16x32_bf16 v[12:15], v[152:155], v[208:211], v[12:15]
	v_mfma_f32_16x16x32_bf16 v[8:11], v[160:163], v[208:211], v[8:11]
	v_mfma_f32_16x16x32_bf16 v[52:55], v[164:167], v[180:183], v[52:55]
	v_mfma_f32_16x16x32_bf16 v[48:51], v[172:175], v[180:183], v[48:51]
	v_mfma_f32_16x16x32_bf16 v[36:39], v[164:167], v[188:191], v[36:39]
	v_mfma_f32_16x16x32_bf16 v[32:35], v[172:175], v[188:191], v[32:35]
	v_mfma_f32_16x16x32_bf16 v[20:23], v[164:167], v[196:199], v[20:23]
	v_mfma_f32_16x16x32_bf16 v[16:19], v[172:175], v[196:199], v[16:19]
	v_mfma_f32_16x16x32_bf16 v[4:7], v[164:167], v[204:207], v[4:7]
	v_mfma_f32_16x16x32_bf16 v[0:3], v[172:175], v[204:207], v[0:3]
	v_mfma_f32_16x16x32_bf16 v[52:55], v[168:171], v[184:187], v[52:55]
	v_mfma_f32_16x16x32_bf16 v[48:51], v[176:179], v[184:187], v[48:51]
	v_mfma_f32_16x16x32_bf16 v[36:39], v[168:171], v[192:195], v[36:39]
	v_mfma_f32_16x16x32_bf16 v[32:35], v[176:179], v[192:195], v[32:35]
	v_mfma_f32_16x16x32_bf16 v[20:23], v[168:171], v[200:203], v[20:23]
	v_mfma_f32_16x16x32_bf16 v[16:19], v[176:179], v[200:203], v[16:19]
	v_mfma_f32_16x16x32_bf16 v[4:7], v[168:171], v[208:211], v[4:7]
	v_mfma_f32_16x16x32_bf16 v[0:3], v[176:179], v[208:211], v[0:3]
	s_setprio 0
	s_barrier
	s_add_u32 s26, s26, 0x100
	s_addc_u32 s27, s27, 0
	s_add_u32 s0, s0, 0x100
	s_addc_u32 s1, s1, 0
	s_cmp_ge_i32 s61, s50
	s_mov_b32 s28, s61
	s_cbranch_scc0 .LBB0_1179

; #define PG8_STAGE(bufoff, gbase, voff) do { _Pragma("unroll") for (int _i = 0; _i < 2; ++_i) \
;         __builtin_amdgcn_global_load_lds((const unsigned*)((const char*)(gbase) + (voff)[_i]), (PG8_LAS unsigned*)(lds + (bufoff) + ldsw + _i * 8192), 16, 0, 0); } while (0)
; #define PG8_LDA(dst, b, h) do { _Pragma("unroll") for (int m = 0; m < 4; ++m) _Pragma("unroll") for (int k = 0; k < 2; ++k) dst[m][k] = *(const PG8_LAS bf16x8*)(lds + PG8_SA(b, h) + aoff + m * 2048 + k * 1024); } while (0)
; #define PG8_LDB(dst, b, h) do { _Pragma("unroll") for (int n = 0; n < 2; ++n) _Pragma("unroll") for (int k = 0; k < 2; ++k) dst[n][k] = *(const PG8_LAS bf16x8*)(lds + PG8_SB(b, h) + boff + n * 2048 + k * 1024); } while (0)
; #define PG8_WAIT_V(n) asm volatile("s_waitcnt vmcnt(" #n ")" ::: "memory")
; #define PG8_WAIT_L(n) asm volatile("s_waitcnt lgkmcnt(" #n ")" ::: "memory")
; #define PG8_BAR __builtin_amdgcn_s_barrier()
; #define PG8_SCHED __builtin_amdgcn_sched_barrier(0)
; template <class Epi, class Sched, bool ALIGN_EPI = false, bool SP2 = false>
; __device__ __forceinline__ void gemm_phase(PG8_LAS unsigned char* lds, const Gemm g, const Sched& S, const Epi& E, const int wid) {
;     ...
;         const bool has_next = S.next(ui + 1, nxt);
;         const char* nA = has_next ? (const char*)g.A + (size_t)nxt.pm * tstep : cA; const char* nB = has_next ? (const char*)g.Bt + (size_t)nxt.pn * tstep : cB;
;         for (int t = 0; t < nt; t += 2) {
;             const bool last = (t == nt - 2);
;             const char* a1 = cA + (size_t)(t + 1) * kstep;
;             const char* a2 = last ? nA : cA + (size_t)(t + 2) * kstep; const char* b2 = last ? nB : cB + (size_t)(t + 2) * kstep;
;             const char* a3 = a2 + kstep; const char* b3 = b2 + kstep;
;             if (last && has_next) S.a_ready(nxt);
;             if constexpr (SP2) {
;             PG8_LDB(B0, 0, 0); PG8_LDB(B1, 0, 1); PG8_SCHED; PG8_LDA(At, 0, 0); PG8_STAGE(PG8_SA(1, 1), a1 + hstep, voffA);
;             PG8_WAIT_V(8); PG8_WAIT_L(0); PG8_BAR; PG8_MMA(0, 0, At, B0); PG8_MMA(0, 1, At, B1); PG8_BAR; PG8_SCHED;
;             PG8_LDA(At, 0, 1); PG8_STAGE(PG8_SB(0, 0), b2, voffB); PG8_STAGE(PG8_SB(0, 1), b2 + hstep, voffB); PG8_STAGE(PG8_SA(0, 0), a2, voffA);
;             PG8_WAIT_V(8); PG8_WAIT_L(0); PG8_BAR; PG8_MMA(1, 0, At, B0); PG8_MMA(1, 1, At, B1); PG8_BAR; PG8_SCHED;
.LBB0_1256:
	s_andn2_b64 vcc, exec, s[20:21]
	s_cbranch_vccnz .Lz_GMB
	s_add_u32 s28, s28, 0x80
	s_addc_u32 s29, s29, 0
	s_add_u32 s0, s30, 0x100
	s_addc_u32 s1, s31, 0
	s_mov_b32 s30, 0
	ds_read_b128 v[142:145], v149
	ds_read_b128 v[152:155], v149 offset:1024
	ds_read_b128 v[156:159], v149 offset:2048
	ds_read_b128 v[160:163], v149 offset:3072
	ds_read_b128 v[164:167], v150
	ds_read_b128 v[168:171], v150 offset:1024
	ds_read_b128 v[172:175], v150 offset:2048
	ds_read_b128 v[176:179], v150 offset:3072
	s_add_i32 s66, s30, 2
	s_add_u32 s33, s28, 0x80
	s_addc_u32 s31, s29, 0
	s_cmp_eq_u32 s57, s30
	s_cselect_b32 s30, s4, s33
	s_cselect_b32 s31, s5, s31
	s_cselect_b32 s69, s27, s1
	s_cselect_b32 s68, s26, s0
	v_lshl_add_u64 v[212:213], s[28:29], 0, v[136:137]
	s_add_i32 m0, s46, 0xc000
	ds_read_b128 v[180:183], v151
	ds_read_b128 v[184:187], v151 offset:1024
	ds_read_b128 v[188:191], v151 offset:2048
	ds_read_b128 v[192:195], v151 offset:3072
	ds_read_b128 v[196:199], v151 offset:4096
	ds_read_b128 v[200:203], v151 offset:5120
	ds_read_b128 v[204:207], v151 offset:6144
	ds_read_b128 v[208:211], v151 offset:7168
	global_load_lds_dwordx4 v[212:213], off
	v_lshl_add_u64 v[212:213], s[28:29], 0, v[138:139]
	s_add_i32 m0, s46, 0xe000
	s_nop 0
	global_load_lds_dwordx4 v[212:213], off
	s_waitcnt vmcnt(8)
	s_waitcnt lgkmcnt(0)
	s_setprio 1
	s_barrier
	v_mfma_f32_16x16x32_bf16 v[124:127], v[142:145], v[180:183], 0
	v_mfma_f32_16x16x32_bf16 v[120:123], v[156:159], v[180:183], 0
	v_mfma_f32_16x16x32_bf16 v[108:111], v[142:145], v[188:191], 0
	v_mfma_f32_16x16x32_bf16 v[104:107], v[156:159], v[188:191], 0
	v_mfma_f32_16x16x32_bf16 v[92:95], v[142:145], v[196:199], 0
	v_mfma_f32_16x16x32_bf16 v[88:91], v[156:159], v[196:199], 0
	v_mfma_f32_16x16x32_bf16 v[76:79], v[142:145], v[204:207], 0
	v_mfma_f32_16x16x32_bf16 v[72:75], v[156:159], v[204:207], 0
	v_mfma_f32_16x16x32_bf16 v[124:127], v[152:155], v[184:187], v[124:127]
	v_mfma_f32_16x16x32_bf16 v[120:123], v[160:163], v[184:187], v[120:123]
	v_mfma_f32_16x16x32_bf16 v[108:111], v[152:155], v[192:195], v[108:111]
	v_mfma_f32_16x16x32_bf16 v[104:107], v[160:163], v[192:195], v[104:107]
	v_mfma_f32_16x16x32_bf16 v[92:95], v[152:155], v[200:203], v[92:95]
	v_mfma_f32_16x16x32_bf16 v[88:91], v[160:163], v[200:203], v[88:91]
	v_mfma_f32_16x16x32_bf16 v[76:79], v[152:155], v[208:211], v[76:79]
	v_mfma_f32_16x16x32_bf16 v[72:75], v[160:163], v[208:211], v[72:75]
	v_mfma_f32_16x16x32_bf16 v[116:119], v[164:167], v[180:183], 0
	v_mfma_f32_16x16x32_bf16 v[112:115], v[172:175], v[180:183], 0
	v_mfma_f32_16x16x32_bf16 v[100:103], v[164:167], v[188:191], 0
	v_mfma_f32_16x16x32_bf16 v[96:99], v[172:175], v[188:191], 0
	v_mfma_f32_16x16x32_bf16 v[84:87], v[164:167], v[196:199], 0
	v_mfma_f32_16x16x32_bf16 v[80:83], v[172:175], v[196:199], 0
	v_mfma_f32_16x16x32_bf16 v[68:71], v[164:167], v[204:207], 0
	v_mfma_f32_16x16x32_bf16 v[64:67], v[172:175], v[204:207], 0
	v_mfma_f32_16x16x32_bf16 v[116:119], v[168:171], v[184:187], v[116:119]
	v_mfma_f32_16x16x32_bf16 v[112:115], v[176:179], v[184:187], v[112:115]
	v_mfma_f32_16x16x32_bf16 v[100:103], v[168:171], v[192:195], v[100:103]
	v_mfma_f32_16x16x32_bf16 v[96:99], v[176:179], v[192:195], v[96:99]
	v_mfma_f32_16x16x32_bf16 v[84:87], v[168:171], v[200:203], v[84:87]
	v_mfma_f32_16x16x32_bf16 v[80:83], v[176:179], v[200:203], v[80:83]
	v_mfma_f32_16x16x32_bf16 v[68:71], v[168:171], v[208:211], v[68:71]
	v_mfma_f32_16x16x32_bf16 v[64:67], v[176:179], v[208:211], v[64:67]
	s_setprio 0
	s_barrier
	s_add_i32 s33, s59, s38
	v_lshl_add_u64 v[212:213], s[68:69], 0, v[132:133]
	s_mov_b32 m0, s33
	ds_read_b128 v[180:183], v151 offset:16384
	ds_read_b128 v[184:187], v151 offset:17408
	ds_read_b128 v[188:191], v151 offset:18432
	ds_read_b128 v[192:195], v151 offset:19456
	ds_read_b128 v[196:199], v151 offset:20480
	ds_read_b128 v[200:203], v151 offset:21504
	ds_read_b128 v[204:207], v151 offset:22528
	ds_read_b128 v[208:211], v151 offset:23552
	global_load_lds_dwordx4 v[212:213], off
	s_add_i32 m0, s33, 0x2000
	v_lshl_add_u64 v[214:215], s[68:69], 0, v[128:129]
	s_add_u32 s68, s68, s8
	s_addc_u32 s69, s69, s9
	s_add_i32 s33, s60, s38
	global_load_lds_dwordx4 v[214:215], off
	v_lshl_add_u64 v[216:217], s[68:69], 0, v[132:133]
	s_mov_b32 m0, s33
	v_lshl_add_u64 v[218:219], s[68:69], 0, v[128:129]
	global_load_lds_dwordx4 v[216:217], off
	s_add_i32 m0, s33, 0x2000
	v_lshl_add_u64 v[220:221], s[30:31], 0, v[134:135]
	global_load_lds_dwordx4 v[218:219], off
	s_mov_b32 m0, s46
	v_lshl_add_u64 v[222:223], s[30:31], 0, v[130:131]
	global_load_lds_dwordx4 v[220:221], off
	s_mov_b32 m0, s47
	s_nop 0
	global_load_lds_dwordx4 v[222:223], off
	s_waitcnt vmcnt(8)
	s_waitcnt lgkmcnt(0)
	s_setprio 1
	s_barrier
; #define PG8_STAGE(bufoff, gbase, voff) do { _Pragma("unroll") for (int _i = 0; _i < 2; ++_i) \
;         __builtin_amdgcn_global_load_lds((const unsigned*)((const char*)(gbase) + (voff)[_i]), (PG8_LAS unsigned*)(lds + (bufoff) + ldsw + _i * 8192), 16, 0, 0); } while (0)
; #define PG8_LDA(dst, b, h) do { _Pragma("unroll") for (int m = 0; m < 4; ++m) _Pragma("unroll") for (int k = 0; k < 2; ++k) dst[m][k] = *(const PG8_LAS bf16x8*)(lds + PG8_SA(b, h) + aoff + m * 2048 + k * 1024); } while (0)
; #define PG8_LDB(dst, b, h) do { _Pragma("unroll") for (int n = 0; n < 2; ++n) _Pragma("unroll") for (int k = 0; k < 2; ++k) dst[n][k] = *(const PG8_LAS bf16x8*)(lds + PG8_SB(b, h) + boff + n * 2048 + k * 1024); } while (0)
; #define PG8_MMA(ai, bj, At, Bt) do { __builtin_amdgcn_s_setprio(1); _Pragma("unroll") for (int m = 0; m < 4; ++m) _Pragma("unroll") for (int n = 0; n < 2; ++n) _Pragma("unroll") for (int k = 0; k < 2; ++k) \
;         acc[ai][bj][m][n] = __builtin_amdgcn_mfma_f32_16x16x32_bf16(Bt[n][k], At[m][k], acc[ai][bj][m][n], 0, 0, 0); __builtin_amdgcn_s_setprio(0); } while (0)
; #define PG8_WAIT_V(n) asm volatile("s_waitcnt vmcnt(" #n ")" ::: "memory")
; #define PG8_WAIT_L(n) asm volatile("s_waitcnt lgkmcnt(" #n ")" ::: "memory")
; #define PG8_BAR __builtin_amdgcn_s_barrier()
; #define PG8_SCHED __builtin_amdgcn_sched_barrier(0)
; template <class Epi, class Sched, bool ALIGN_EPI = false, bool SP2 = false>
; __device__ __forceinline__ void gemm_phase(PG8_LAS unsigned char* lds, const Gemm g, const Sched& S, const Epi& E, const int wid) {
;     ...
;             PG8_WAIT_V(8); PG8_WAIT_L(0); PG8_BAR; PG8_MMA(0, 0, At, B0); PG8_MMA(0, 1, At, B1); PG8_BAR; PG8_SCHED;
;             PG8_LDA(At, 0, 1); PG8_STAGE(PG8_SB(0, 0), b2, voffB); PG8_STAGE(PG8_SB(0, 1), b2 + hstep, voffB); PG8_STAGE(PG8_SA(0, 0), a2, voffA);
;             PG8_WAIT_V(8); PG8_WAIT_L(0); PG8_BAR; PG8_MMA(1, 0, At, B0); PG8_MMA(1, 1, At, B1); PG8_BAR; PG8_SCHED;
;             PG8_LDB(B0, 1, 0); PG8_LDB(B1, 1, 1); PG8_SCHED; PG8_LDA(At, 1, 0); PG8_STAGE(PG8_SA(0, 1), a2 + hstep, voffA);
	v_mfma_f32_16x16x32_bf16 v[60:63], v[142:145], v[180:183], 0
	v_mfma_f32_16x16x32_bf16 v[56:59], v[156:159], v[180:183], 0
	v_mfma_f32_16x16x32_bf16 v[44:47], v[142:145], v[188:191], 0
	v_mfma_f32_16x16x32_bf16 v[40:43], v[156:159], v[188:191], 0
	v_mfma_f32_16x16x32_bf16 v[28:31], v[142:145], v[196:199], 0
	v_mfma_f32_16x16x32_bf16 v[24:27], v[156:159], v[196:199], 0
	v_mfma_f32_16x16x32_bf16 v[12:15], v[142:145], v[204:207], 0
	v_mfma_f32_16x16x32_bf16 v[8:11], v[156:159], v[204:207], 0
	v_mfma_f32_16x16x32_bf16 v[60:63], v[152:155], v[184:187], v[60:63]
	v_mfma_f32_16x16x32_bf16 v[56:59], v[160:163], v[184:187], v[56:59]
	v_mfma_f32_16x16x32_bf16 v[44:47], v[152:155], v[192:195], v[44:47]
	v_mfma_f32_16x16x32_bf16 v[40:43], v[160:163], v[192:195], v[40:43]
	v_mfma_f32_16x16x32_bf16 v[28:31], v[152:155], v[200:203], v[28:31]
	v_mfma_f32_16x16x32_bf16 v[24:27], v[160:163], v[200:203], v[24:27]
	v_mfma_f32_16x16x32_bf16 v[12:15], v[152:155], v[208:211], v[12:15]
	v_mfma_f32_16x16x32_bf16 v[8:11], v[160:163], v[208:211], v[8:11]
	v_mfma_f32_16x16x32_bf16 v[52:55], v[164:167], v[180:183], 0
	v_mfma_f32_16x16x32_bf16 v[48:51], v[172:175], v[180:183], 0
	v_mfma_f32_16x16x32_bf16 v[36:39], v[164:167], v[188:191], 0
	v_mfma_f32_16x16x32_bf16 v[32:35], v[172:175], v[188:191], 0
	v_mfma_f32_16x16x32_bf16 v[20:23], v[164:167], v[196:199], 0
	v_mfma_f32_16x16x32_bf16 v[16:19], v[172:175], v[196:199], 0
	v_mfma_f32_16x16x32_bf16 v[4:7], v[164:167], v[204:207], 0
	v_mfma_f32_16x16x32_bf16 v[0:3], v[172:175], v[204:207], 0
	v_mfma_f32_16x16x32_bf16 v[52:55], v[168:171], v[184:187], v[52:55]
	v_mfma_f32_16x16x32_bf16 v[48:51], v[176:179], v[184:187], v[48:51]
	v_mfma_f32_16x16x32_bf16 v[36:39], v[168:171], v[192:195], v[36:39]
	v_mfma_f32_16x16x32_bf16 v[32:35], v[176:179], v[192:195], v[32:35]
	v_mfma_f32_16x16x32_bf16 v[20:23], v[168:171], v[200:203], v[20:23]
	v_mfma_f32_16x16x32_bf16 v[16:19], v[176:179], v[200:203], v[16:19]
	v_mfma_f32_16x16x32_bf16 v[4:7], v[168:171], v[208:211], v[4:7]
	v_mfma_f32_16x16x32_bf16 v[0:3], v[176:179], v[208:211], v[0:3]
	s_setprio 0
	s_barrier
	s_add_i32 s33, 0, 0x18000
	s_add_i32 s67, 0, 0x1c000
	v_add_u32_e32 v160, s33, v148
	v_add_u32_e32 v176, s67, v148
	ds_read_b128 v[142:145], v160
	ds_read_b128 v[152:155], v160 offset:1024
	ds_read_b128 v[156:159], v160 offset:2048
	ds_read_b128 v[160:163], v160 offset:3072
	ds_read_b128 v[164:167], v176
	ds_read_b128 v[168:171], v176 offset:1024
	ds_read_b128 v[172:175], v176 offset:2048
	ds_read_b128 v[176:179], v176 offset:3072
	s_add_u32 s30, s30, s8
	s_addc_u32 s31, s31, s9
	s_mov_b32 m0, s49
	v_lshl_add_u64 v[224:225], s[30:31], 0, v[134:135]
	ds_read_b128 v[180:183], v151 offset:32768
	ds_read_b128 v[184:187], v151 offset:33792
	ds_read_b128 v[188:191], v151 offset:34816
	ds_read_b128 v[192:195], v151 offset:35840
	ds_read_b128 v[196:199], v151 offset:36864
	ds_read_b128 v[200:203], v151 offset:37888
	ds_read_b128 v[204:207], v151 offset:38912
	ds_read_b128 v[208:211], v151 offset:39936
	global_load_lds_dwordx4 v[224:225], off
	v_lshl_add_u64 v[224:225], s[30:31], 0, v[130:131]
	s_mov_b32 m0, s50
	s_nop 0
	global_load_lds_dwordx4 v[224:225], off
	s_waitcnt vmcnt(8)
	s_waitcnt lgkmcnt(0)
	s_setprio 1
	s_barrier
	v_mfma_f32_16x16x32_bf16 v[124:127], v[142:145], v[180:183], v[124:127]
	v_mfma_f32_16x16x32_bf16 v[120:123], v[156:159], v[180:183], v[120:123]
	v_mfma_f32_16x16x32_bf16 v[108:111], v[142:145], v[188:191], v[108:111]
	v_mfma_f32_16x16x32_bf16 v[104:107], v[156:159], v[188:191], v[104:107]
	v_mfma_f32_16x16x32_bf16 v[92:95], v[142:145], v[196:199], v[92:95]
	v_mfma_f32_16x16x32_bf16 v[88:91], v[156:159], v[196:199], v[88:91]
	v_mfma_f32_16x16x32_bf16 v[76:79], v[142:145], v[204:207], v[76:79]
	v_mfma_f32_16x16x32_bf16 v[72:75], v[156:159], v[204:207], v[72:75]
	v_mfma_f32_16x16x32_bf16 v[124:127], v[152:155], v[184:187], v[124:127]
	v_mfma_f32_16x16x32_bf16 v[120:123], v[160:163], v[184:187], v[120:123]
	v_mfma_f32_16x16x32_bf16 v[108:111], v[152:155], v[192:195], v[108:111]
	v_mfma_f32_16x16x32_bf16 v[104:107], v[160:163], v[192:195], v[104:107]
	v_mfma_f32_16x16x32_bf16 v[92:95], v[152:155], v[200:203], v[92:95]
	v_mfma_f32_16x16x32_bf16 v[88:91], v[160:163], v[200:203], v[88:91]
	v_mfma_f32_16x16x32_bf16 v[76:79], v[152:155], v[208:211], v[76:79]
	v_mfma_f32_16x16x32_bf16 v[72:75], v[160:163], v[208:211], v[72:75]
	v_mfma_f32_16x16x32_bf16 v[116:119], v[164:167], v[180:183], v[116:119]
	v_mfma_f32_16x16x32_bf16 v[112:115], v[172:175], v[180:183], v[112:115]
	v_mfma_f32_16x16x32_bf16 v[100:103], v[164:167], v[188:191], v[100:103]
	v_mfma_f32_16x16x32_bf16 v[96:99], v[172:175], v[188:191], v[96:99]
	v_mfma_f32_16x16x32_bf16 v[84:87], v[164:167], v[196:199], v[84:87]
	v_mfma_f32_16x16x32_bf16 v[80:83], v[172:175], v[196:199], v[80:83]
	v_mfma_f32_16x16x32_bf16 v[68:71], v[164:167], v[204:207], v[68:71]
	v_mfma_f32_16x16x32_bf16 v[64:67], v[172:175], v[204:207], v[64:67]
	v_mfma_f32_16x16x32_bf16 v[116:119], v[168:171], v[184:187], v[116:119]
	v_mfma_f32_16x16x32_bf16 v[112:115], v[176:179], v[184:187], v[112:115]
	v_mfma_f32_16x16x32_bf16 v[100:103], v[168:171], v[192:195], v[100:103]
	v_mfma_f32_16x16x32_bf16 v[96:99], v[176:179], v[192:195], v[96:99]
	v_mfma_f32_16x16x32_bf16 v[84:87], v[168:171], v[200:203], v[84:87]
	v_mfma_f32_16x16x32_bf16 v[80:83], v[176:179], v[200:203], v[80:83]
	v_mfma_f32_16x16x32_bf16 v[68:71], v[168:171], v[208:211], v[68:71]
	v_mfma_f32_16x16x32_bf16 v[64:67], v[176:179], v[208:211], v[64:67]
	s_setprio 0
	s_barrier
; #define PG8_STAGE(bufoff, gbase, voff) do { _Pragma("unroll") for (int _i = 0; _i < 2; ++_i) \
;         __builtin_amdgcn_global_load_lds((const unsigned*)((const char*)(gbase) + (voff)[_i]), (PG8_LAS unsigned*)(lds + (bufoff) + ldsw + _i * 8192), 16, 0, 0); } while (0)
; #define PG8_LDA(dst, b, h) do { _Pragma("unroll") for (int m = 0; m < 4; ++m) _Pragma("unroll") for (int k = 0; k < 2; ++k) dst[m][k] = *(const PG8_LAS bf16x8*)(lds + PG8_SA(b, h) + aoff + m * 2048 + k * 1024); } while (0)
; #define PG8_WAIT_V(n) asm volatile("s_waitcnt vmcnt(" #n ")" ::: "memory")
; #define PG8_WAIT_L(n) asm volatile("s_waitcnt lgkmcnt(" #n ")" ::: "memory")
; #define PG8_BAR __builtin_amdgcn_s_barrier()
; template <class Epi, class Sched, bool ALIGN_EPI = false, bool SP2 = false>
; __device__ __forceinline__ void gemm_phase(PG8_LAS unsigned char* lds, const Gemm g, const Sched& S, const Epi& E, const int wid) {
;     ...
;         for (int t = 0; t < nt; t += 2) {
;             const bool last = (t == nt - 2);
;             const char* a1 = cA + (size_t)(t + 1) * kstep;
;             const char* a2 = last ? nA : cA + (size_t)(t + 2) * kstep; const char* b2 = last ? nB : cB + (size_t)(t + 2) * kstep;
;             const char* a3 = a2 + kstep; const char* b3 = b2 + kstep;
;             if (last && has_next) S.a_ready(nxt);
;             if constexpr (SP2) {
;             PG8_LDB(B0, 0, 0); PG8_LDB(B1, 0, 1); PG8_SCHED; PG8_LDA(At, 0, 0); PG8_STAGE(PG8_SA(1, 1), a1 + hstep, voffA);
;             PG8_WAIT_V(8); PG8_WAIT_L(0); PG8_BAR; PG8_MMA(0, 0, At, B0); PG8_MMA(0, 1, At, B1); PG8_BAR; PG8_SCHED;
;             PG8_LDA(At, 0, 1); PG8_STAGE(PG8_SB(0, 0), b2, voffB); PG8_STAGE(PG8_SB(0, 1), b2 + hstep, voffB); PG8_STAGE(PG8_SA(0, 0), a2, voffA);
;             PG8_WAIT_V(8); PG8_WAIT_L(0); PG8_BAR; PG8_MMA(1, 0, At, B0); PG8_MMA(1, 1, At, B1); PG8_BAR; PG8_SCHED;
;             PG8_LDB(B0, 1, 0); PG8_LDB(B1, 1, 1); PG8_SCHED; PG8_LDA(At, 1, 0); PG8_STAGE(PG8_SA(0, 1), a2 + hstep, voffA);
;             PG8_WAIT_V(8); PG8_WAIT_L(0); PG8_BAR; PG8_MMA(0, 0, At, B0); PG8_MMA(0, 1, At, B1); PG8_BAR; PG8_SCHED;
;             PG8_LDA(At, 1, 1); PG8_STAGE(PG8_SB(1, 0), b3, voffB); PG8_STAGE(PG8_SB(1, 1), b3 + hstep, voffB); PG8_STAGE(PG8_SA(1, 0), a3, voffA);
;             PG8_WAIT_V(8); PG8_WAIT_L(0); PG8_BAR; PG8_MMA(1, 0, At, B0); PG8_MMA(1, 1, At, B1); PG8_BAR; PG8_SCHED;
	s_add_i32 s30, s33, s38
	v_lshl_add_u64 v[212:213], v[212:213], 0, s[18:19]
	s_mov_b32 m0, s30
	ds_read_b128 v[180:183], v151 offset:49152
	ds_read_b128 v[184:187], v151 offset:50176
	ds_read_b128 v[188:191], v151 offset:51200
	ds_read_b128 v[192:195], v151 offset:52224
	ds_read_b128 v[196:199], v151 offset:53248
	ds_read_b128 v[200:203], v151 offset:54272
	ds_read_b128 v[204:207], v151 offset:55296
	ds_read_b128 v[208:211], v151 offset:56320
	global_load_lds_dwordx4 v[212:213], off
	v_lshl_add_u64 v[212:213], v[214:215], 0, s[18:19]
	s_add_i32 m0, s30, 0x2000
	s_add_i32 s30, s67, s38
	global_load_lds_dwordx4 v[212:213], off
	v_lshl_add_u64 v[212:213], v[216:217], 0, s[18:19]
	s_mov_b32 m0, s30
	s_nop 0
	global_load_lds_dwordx4 v[212:213], off
	v_lshl_add_u64 v[212:213], v[218:219], 0, s[18:19]
	s_add_i32 m0, s30, 0x2000
	s_nop 0
	global_load_lds_dwordx4 v[212:213], off
	v_lshl_add_u64 v[212:213], v[220:221], 0, s[18:19]
	s_mov_b32 m0, s52
	s_nop 0
	global_load_lds_dwordx4 v[212:213], off
	v_lshl_add_u64 v[212:213], v[222:223], 0, s[18:19]
	s_mov_b32 m0, s53
	s_nop 0
	global_load_lds_dwordx4 v[212:213], off
	s_waitcnt vmcnt(8)
	s_waitcnt lgkmcnt(0)
	s_setprio 1
	s_barrier
	v_mfma_f32_16x16x32_bf16 v[60:63], v[142:145], v[180:183], v[60:63]
	v_mfma_f32_16x16x32_bf16 v[56:59], v[156:159], v[180:183], v[56:59]
	v_mfma_f32_16x16x32_bf16 v[44:47], v[142:145], v[188:191], v[44:47]
	v_mfma_f32_16x16x32_bf16 v[40:43], v[156:159], v[188:191], v[40:43]
	v_mfma_f32_16x16x32_bf16 v[28:31], v[142:145], v[196:199], v[28:31]
	v_mfma_f32_16x16x32_bf16 v[24:27], v[156:159], v[196:199], v[24:27]
	v_mfma_f32_16x16x32_bf16 v[12:15], v[142:145], v[204:207], v[12:15]
	v_mfma_f32_16x16x32_bf16 v[8:11], v[156:159], v[204:207], v[8:11]
	v_mfma_f32_16x16x32_bf16 v[60:63], v[152:155], v[184:187], v[60:63]
	v_mfma_f32_16x16x32_bf16 v[56:59], v[160:163], v[184:187], v[56:59]
	v_mfma_f32_16x16x32_bf16 v[44:47], v[152:155], v[192:195], v[44:47]
	v_mfma_f32_16x16x32_bf16 v[40:43], v[160:163], v[192:195], v[40:43]
	v_mfma_f32_16x16x32_bf16 v[28:31], v[152:155], v[200:203], v[28:31]
	v_mfma_f32_16x16x32_bf16 v[24:27], v[160:163], v[200:203], v[24:27]
	v_mfma_f32_16x16x32_bf16 v[12:15], v[152:155], v[208:211], v[12:15]
	v_mfma_f32_16x16x32_bf16 v[8:11], v[160:163], v[208:211], v[8:11]
	v_mfma_f32_16x16x32_bf16 v[52:55], v[164:167], v[180:183], v[52:55]
	v_mfma_f32_16x16x32_bf16 v[48:51], v[172:175], v[180:183], v[48:51]
	v_mfma_f32_16x16x32_bf16 v[36:39], v[164:167], v[188:191], v[36:39]
	v_mfma_f32_16x16x32_bf16 v[32:35], v[172:175], v[188:191], v[32:35]
	v_mfma_f32_16x16x32_bf16 v[20:23], v[164:167], v[196:199], v[20:23]
	v_mfma_f32_16x16x32_bf16 v[16:19], v[172:175], v[196:199], v[16:19]
	v_mfma_f32_16x16x32_bf16 v[4:7], v[164:167], v[204:207], v[4:7]
	v_mfma_f32_16x16x32_bf16 v[0:3], v[172:175], v[204:207], v[0:3]
	v_mfma_f32_16x16x32_bf16 v[52:55], v[168:171], v[184:187], v[52:55]
	v_mfma_f32_16x16x32_bf16 v[48:51], v[176:179], v[184:187], v[48:51]
	v_mfma_f32_16x16x32_bf16 v[36:39], v[168:171], v[192:195], v[36:39]
	v_mfma_f32_16x16x32_bf16 v[32:35], v[176:179], v[192:195], v[32:35]
	v_mfma_f32_16x16x32_bf16 v[20:23], v[168:171], v[200:203], v[20:23]
	v_mfma_f32_16x16x32_bf16 v[16:19], v[176:179], v[200:203], v[16:19]
	v_mfma_f32_16x16x32_bf16 v[4:7], v[168:171], v[208:211], v[4:7]
	v_mfma_f32_16x16x32_bf16 v[0:3], v[176:179], v[208:211], v[0:3]
	s_setprio 0
	s_barrier
	s_add_u32 s28, s28, 0x100
	s_addc_u32 s29, s29, 0
	s_add_u32 s0, s0, 0x100
	s_addc_u32 s1, s1, 0
	s_cmp_ge_i32 s66, s54
	s_mov_b32 s30, s66
	s_cbranch_scc1 .LBB0_1259
.LBB0_1258:
	ds_read_b128 v[142:145], v149
	ds_read_b128 v[152:155], v149 offset:1024
	ds_read_b128 v[156:159], v149 offset:2048
	ds_read_b128 v[160:163], v149 offset:3072
	ds_read_b128 v[164:167], v150
	ds_read_b128 v[168:171], v150 offset:1024
	ds_read_b128 v[172:175], v150 offset:2048
	ds_read_b128 v[176:179], v150 offset:3072
	s_add_i32 s66, s30, 2
	s_add_u32 s33, s28, 0x80
	s_addc_u32 s31, s29, 0
	s_cmp_eq_u32 s57, s30
	s_cselect_b32 s30, s4, s33
	s_cselect_b32 s31, s5, s31
	s_cselect_b32 s69, s27, s1
	s_cselect_b32 s68, s26, s0
	v_lshl_add_u64 v[212:213], s[28:29], 0, v[136:137]
	s_add_i32 m0, s46, 0xc000
	ds_read_b128 v[180:183], v151
	ds_read_b128 v[184:187], v151 offset:1024
	ds_read_b128 v[188:191], v151 offset:2048
	ds_read_b128 v[192:195], v151 offset:3072
	ds_read_b128 v[196:199], v151 offset:4096
	ds_read_b128 v[200:203], v151 offset:5120
	ds_read_b128 v[204:207], v151 offset:6144
	ds_read_b128 v[208:211], v151 offset:7168
	global_load_lds_dwordx4 v[212:213], off
	v_lshl_add_u64 v[212:213], s[28:29], 0, v[138:139]
	s_add_i32 m0, s46, 0xe000
	s_nop 0
	global_load_lds_dwordx4 v[212:213], off
	s_waitcnt vmcnt(8)
	s_waitcnt lgkmcnt(0)
	s_setprio 1
	s_barrier
; #define PG8_STAGE(bufoff, gbase, voff) do { _Pragma("unroll") for (int _i = 0; _i < 2; ++_i) \
;         __builtin_amdgcn_global_load_lds((const unsigned*)((const char*)(gbase) + (voff)[_i]), (PG8_LAS unsigned*)(lds + (bufoff) + ldsw + _i * 8192), 16, 0, 0); } while (0)
; #define PG8_LDA(dst, b, h) do { _Pragma("unroll") for (int m = 0; m < 4; ++m) _Pragma("unroll") for (int k = 0; k < 2; ++k) dst[m][k] = *(const PG8_LAS bf16x8*)(lds + PG8_SA(b, h) + aoff + m * 2048 + k * 1024); } while (0)
; #define PG8_LDB(dst, b, h) do { _Pragma("unroll") for (int n = 0; n < 2; ++n) _Pragma("unroll") for (int k = 0; k < 2; ++k) dst[n][k] = *(const PG8_LAS bf16x8*)(lds + PG8_SB(b, h) + boff + n * 2048 + k * 1024); } while (0)
; #define PG8_MMA(ai, bj, At, Bt) do { __builtin_amdgcn_s_setprio(1); _Pragma("unroll") for (int m = 0; m < 4; ++m) _Pragma("unroll") for (int n = 0; n < 2; ++n) _Pragma("unroll") for (int k = 0; k < 2; ++k) \
;         acc[ai][bj][m][n] = __builtin_amdgcn_mfma_f32_16x16x32_bf16(Bt[n][k], At[m][k], acc[ai][bj][m][n], 0, 0, 0); __builtin_amdgcn_s_setprio(0); } while (0)
; #define PG8_WAIT_V(n) asm volatile("s_waitcnt vmcnt(" #n ")" ::: "memory")
; #define PG8_WAIT_L(n) asm volatile("s_waitcnt lgkmcnt(" #n ")" ::: "memory")
; #define PG8_BAR __builtin_amdgcn_s_barrier()
; #define PG8_SCHED __builtin_amdgcn_sched_barrier(0)
; template <class Epi, class Sched, bool ALIGN_EPI = false, bool SP2 = false>
; __device__ __forceinline__ void gemm_phase(PG8_LAS unsigned char* lds, const Gemm g, const Sched& S, const Epi& E, const int wid) {
;     ...
;             PG8_LDB(B0, 0, 0); PG8_LDB(B1, 0, 1); PG8_SCHED; PG8_LDA(At, 0, 0); PG8_STAGE(PG8_SA(1, 1), a1 + hstep, voffA);
;             PG8_WAIT_V(8); PG8_WAIT_L(0); PG8_BAR; PG8_MMA(0, 0, At, B0); PG8_MMA(0, 1, At, B1); PG8_BAR; PG8_SCHED;
;             PG8_LDA(At, 0, 1); PG8_STAGE(PG8_SB(0, 0), b2, voffB); PG8_STAGE(PG8_SB(0, 1), b2 + hstep, voffB); PG8_STAGE(PG8_SA(0, 0), a2, voffA);
;             PG8_WAIT_V(8); PG8_WAIT_L(0); PG8_BAR; PG8_MMA(1, 0, At, B0); PG8_MMA(1, 1, At, B1); PG8_BAR; PG8_SCHED;
;             PG8_LDB(B0, 1, 0); PG8_LDB(B1, 1, 1); PG8_SCHED; PG8_LDA(At, 1, 0); PG8_STAGE(PG8_SA(0, 1), a2 + hstep, voffA);
;             PG8_WAIT_V(8); PG8_WAIT_L(0); PG8_BAR; PG8_MMA(0, 0, At, B0); PG8_MMA(0, 1, At, B1); PG8_BAR; PG8_SCHED;
	v_mfma_f32_16x16x32_bf16 v[124:127], v[142:145], v[180:183], v[124:127]
	v_mfma_f32_16x16x32_bf16 v[120:123], v[156:159], v[180:183], v[120:123]
	v_mfma_f32_16x16x32_bf16 v[108:111], v[142:145], v[188:191], v[108:111]
	v_mfma_f32_16x16x32_bf16 v[104:107], v[156:159], v[188:191], v[104:107]
	v_mfma_f32_16x16x32_bf16 v[92:95], v[142:145], v[196:199], v[92:95]
	v_mfma_f32_16x16x32_bf16 v[88:91], v[156:159], v[196:199], v[88:91]
	v_mfma_f32_16x16x32_bf16 v[76:79], v[142:145], v[204:207], v[76:79]
	v_mfma_f32_16x16x32_bf16 v[72:75], v[156:159], v[204:207], v[72:75]
	v_mfma_f32_16x16x32_bf16 v[124:127], v[152:155], v[184:187], v[124:127]
	v_mfma_f32_16x16x32_bf16 v[120:123], v[160:163], v[184:187], v[120:123]
	v_mfma_f32_16x16x32_bf16 v[108:111], v[152:155], v[192:195], v[108:111]
	v_mfma_f32_16x16x32_bf16 v[104:107], v[160:163], v[192:195], v[104:107]
	v_mfma_f32_16x16x32_bf16 v[92:95], v[152:155], v[200:203], v[92:95]
	v_mfma_f32_16x16x32_bf16 v[88:91], v[160:163], v[200:203], v[88:91]
	v_mfma_f32_16x16x32_bf16 v[76:79], v[152:155], v[208:211], v[76:79]
	v_mfma_f32_16x16x32_bf16 v[72:75], v[160:163], v[208:211], v[72:75]
	v_mfma_f32_16x16x32_bf16 v[116:119], v[164:167], v[180:183], v[116:119]
	v_mfma_f32_16x16x32_bf16 v[112:115], v[172:175], v[180:183], v[112:115]
	v_mfma_f32_16x16x32_bf16 v[100:103], v[164:167], v[188:191], v[100:103]
	v_mfma_f32_16x16x32_bf16 v[96:99], v[172:175], v[188:191], v[96:99]
	v_mfma_f32_16x16x32_bf16 v[84:87], v[164:167], v[196:199], v[84:87]
	v_mfma_f32_16x16x32_bf16 v[80:83], v[172:175], v[196:199], v[80:83]
	v_mfma_f32_16x16x32_bf16 v[68:71], v[164:167], v[204:207], v[68:71]
	v_mfma_f32_16x16x32_bf16 v[64:67], v[172:175], v[204:207], v[64:67]
	v_mfma_f32_16x16x32_bf16 v[116:119], v[168:171], v[184:187], v[116:119]
	v_mfma_f32_16x16x32_bf16 v[112:115], v[176:179], v[184:187], v[112:115]
	v_mfma_f32_16x16x32_bf16 v[100:103], v[168:171], v[192:195], v[100:103]
	v_mfma_f32_16x16x32_bf16 v[96:99], v[176:179], v[192:195], v[96:99]
	v_mfma_f32_16x16x32_bf16 v[84:87], v[168:171], v[200:203], v[84:87]
	v_mfma_f32_16x16x32_bf16 v[80:83], v[176:179], v[200:203], v[80:83]
	v_mfma_f32_16x16x32_bf16 v[68:71], v[168:171], v[208:211], v[68:71]
	v_mfma_f32_16x16x32_bf16 v[64:67], v[176:179], v[208:211], v[64:67]
	s_setprio 0
	s_barrier
	s_add_i32 s33, s59, s38
	v_lshl_add_u64 v[212:213], s[68:69], 0, v[132:133]
	s_mov_b32 m0, s33
	ds_read_b128 v[180:183], v151 offset:16384
	ds_read_b128 v[184:187], v151 offset:17408
	ds_read_b128 v[188:191], v151 offset:18432
	ds_read_b128 v[192:195], v151 offset:19456
	ds_read_b128 v[196:199], v151 offset:20480
	ds_read_b128 v[200:203], v151 offset:21504
	ds_read_b128 v[204:207], v151 offset:22528
	ds_read_b128 v[208:211], v151 offset:23552
	global_load_lds_dwordx4 v[212:213], off
	s_add_i32 m0, s33, 0x2000
	v_lshl_add_u64 v[214:215], s[68:69], 0, v[128:129]
	s_add_u32 s68, s68, s8
	s_addc_u32 s69, s69, s9
	s_add_i32 s33, s60, s38
	global_load_lds_dwordx4 v[214:215], off
	v_lshl_add_u64 v[216:217], s[68:69], 0, v[132:133]
	s_mov_b32 m0, s33
	v_lshl_add_u64 v[218:219], s[68:69], 0, v[128:129]
	global_load_lds_dwordx4 v[216:217], off
	s_add_i32 m0, s33, 0x2000
	v_lshl_add_u64 v[220:221], s[30:31], 0, v[134:135]
	global_load_lds_dwordx4 v[218:219], off
	s_mov_b32 m0, s46
	v_lshl_add_u64 v[222:223], s[30:31], 0, v[130:131]
	global_load_lds_dwordx4 v[220:221], off
	s_mov_b32 m0, s47
	s_nop 0
	global_load_lds_dwordx4 v[222:223], off
	s_waitcnt vmcnt(8)
	s_waitcnt lgkmcnt(0)
	s_setprio 1
	s_barrier
	v_mfma_f32_16x16x32_bf16 v[60:63], v[142:145], v[180:183], v[60:63]
	v_mfma_f32_16x16x32_bf16 v[56:59], v[156:159], v[180:183], v[56:59]
	v_mfma_f32_16x16x32_bf16 v[44:47], v[142:145], v[188:191], v[44:47]
	v_mfma_f32_16x16x32_bf16 v[40:43], v[156:159], v[188:191], v[40:43]
	v_mfma_f32_16x16x32_bf16 v[28:31], v[142:145], v[196:199], v[28:31]
	v_mfma_f32_16x16x32_bf16 v[24:27], v[156:159], v[196:199], v[24:27]
	v_mfma_f32_16x16x32_bf16 v[12:15], v[142:145], v[204:207], v[12:15]
	v_mfma_f32_16x16x32_bf16 v[8:11], v[156:159], v[204:207], v[8:11]
	v_mfma_f32_16x16x32_bf16 v[60:63], v[152:155], v[184:187], v[60:63]
	v_mfma_f32_16x16x32_bf16 v[56:59], v[160:163], v[184:187], v[56:59]
	v_mfma_f32_16x16x32_bf16 v[44:47], v[152:155], v[192:195], v[44:47]
	v_mfma_f32_16x16x32_bf16 v[40:43], v[160:163], v[192:195], v[40:43]
	v_mfma_f32_16x16x32_bf16 v[28:31], v[152:155], v[200:203], v[28:31]
	v_mfma_f32_16x16x32_bf16 v[24:27], v[160:163], v[200:203], v[24:27]
	v_mfma_f32_16x16x32_bf16 v[12:15], v[152:155], v[208:211], v[12:15]
	v_mfma_f32_16x16x32_bf16 v[8:11], v[160:163], v[208:211], v[8:11]
	v_mfma_f32_16x16x32_bf16 v[52:55], v[164:167], v[180:183], v[52:55]
	v_mfma_f32_16x16x32_bf16 v[48:51], v[172:175], v[180:183], v[48:51]
	v_mfma_f32_16x16x32_bf16 v[36:39], v[164:167], v[188:191], v[36:39]
	v_mfma_f32_16x16x32_bf16 v[32:35], v[172:175], v[188:191], v[32:35]
	v_mfma_f32_16x16x32_bf16 v[20:23], v[164:167], v[196:199], v[20:23]
	v_mfma_f32_16x16x32_bf16 v[16:19], v[172:175], v[196:199], v[16:19]
	v_mfma_f32_16x16x32_bf16 v[4:7], v[164:167], v[204:207], v[4:7]
	v_mfma_f32_16x16x32_bf16 v[0:3], v[172:175], v[204:207], v[0:3]
	v_mfma_f32_16x16x32_bf16 v[52:55], v[168:171], v[184:187], v[52:55]
	v_mfma_f32_16x16x32_bf16 v[48:51], v[176:179], v[184:187], v[48:51]
	v_mfma_f32_16x16x32_bf16 v[36:39], v[168:171], v[192:195], v[36:39]
	v_mfma_f32_16x16x32_bf16 v[32:35], v[176:179], v[192:195], v[32:35]
	v_mfma_f32_16x16x32_bf16 v[20:23], v[168:171], v[200:203], v[20:23]
	v_mfma_f32_16x16x32_bf16 v[16:19], v[176:179], v[200:203], v[16:19]
	v_mfma_f32_16x16x32_bf16 v[4:7], v[168:171], v[208:211], v[4:7]
	v_mfma_f32_16x16x32_bf16 v[0:3], v[176:179], v[208:211], v[0:3]
	s_setprio 0
	s_barrier
; #define PG8_STAGE(bufoff, gbase, voff) do { _Pragma("unroll") for (int _i = 0; _i < 2; ++_i) \
;         __builtin_amdgcn_global_load_lds((const unsigned*)((const char*)(gbase) + (voff)[_i]), (PG8_LAS unsigned*)(lds + (bufoff) + ldsw + _i * 8192), 16, 0, 0); } while (0)
; #define PG8_LDA(dst, b, h) do { _Pragma("unroll") for (int m = 0; m < 4; ++m) _Pragma("unroll") for (int k = 0; k < 2; ++k) dst[m][k] = *(const PG8_LAS bf16x8*)(lds + PG8_SA(b, h) + aoff + m * 2048 + k * 1024); } while (0)
; #define PG8_LDB(dst, b, h) do { _Pragma("unroll") for (int n = 0; n < 2; ++n) _Pragma("unroll") for (int k = 0; k < 2; ++k) dst[n][k] = *(const PG8_LAS bf16x8*)(lds + PG8_SB(b, h) + boff + n * 2048 + k * 1024); } while (0)
; #define PG8_MMA(ai, bj, At, Bt) do { __builtin_amdgcn_s_setprio(1); _Pragma("unroll") for (int m = 0; m < 4; ++m) _Pragma("unroll") for (int n = 0; n < 2; ++n) _Pragma("unroll") for (int k = 0; k < 2; ++k) \
;         acc[ai][bj][m][n] = __builtin_amdgcn_mfma_f32_16x16x32_bf16(Bt[n][k], At[m][k], acc[ai][bj][m][n], 0, 0, 0); __builtin_amdgcn_s_setprio(0); } while (0)
; #define PG8_WAIT_V(n) asm volatile("s_waitcnt vmcnt(" #n ")" ::: "memory")
; #define PG8_WAIT_L(n) asm volatile("s_waitcnt lgkmcnt(" #n ")" ::: "memory")
; #define PG8_BAR __builtin_amdgcn_s_barrier()
; #define PG8_SCHED __builtin_amdgcn_sched_barrier(0)
; template <class Epi, class Sched, bool ALIGN_EPI = false, bool SP2 = false>
; __device__ __forceinline__ void gemm_phase(PG8_LAS unsigned char* lds, const Gemm g, const Sched& S, const Epi& E, const int wid) {
;     ...
;         for (int t = 0; t < nt; t += 2) {
;     ...
;             PG8_LDB(B0, 1, 0); PG8_LDB(B1, 1, 1); PG8_SCHED; PG8_LDA(At, 1, 0); PG8_STAGE(PG8_SA(0, 1), a2 + hstep, voffA);
;             PG8_WAIT_V(8); PG8_WAIT_L(0); PG8_BAR; PG8_MMA(0, 0, At, B0); PG8_MMA(0, 1, At, B1); PG8_BAR; PG8_SCHED;
;             PG8_LDA(At, 1, 1); PG8_STAGE(PG8_SB(1, 0), b3, voffB); PG8_STAGE(PG8_SB(1, 1), b3 + hstep, voffB); PG8_STAGE(PG8_SA(1, 0), a3, voffA);
;             PG8_WAIT_V(8); PG8_WAIT_L(0); PG8_BAR; PG8_MMA(1, 0, At, B0); PG8_MMA(1, 1, At, B1); PG8_BAR; PG8_SCHED;
	s_add_i32 s33, 0, 0x18000
	s_add_i32 s67, 0, 0x1c000
	v_add_u32_e32 v160, s33, v148
	v_add_u32_e32 v176, s67, v148
	ds_read_b128 v[142:145], v160
	ds_read_b128 v[152:155], v160 offset:1024
	ds_read_b128 v[156:159], v160 offset:2048
	ds_read_b128 v[160:163], v160 offset:3072
	ds_read_b128 v[164:167], v176
	ds_read_b128 v[168:171], v176 offset:1024
	ds_read_b128 v[172:175], v176 offset:2048
	ds_read_b128 v[176:179], v176 offset:3072
	s_add_u32 s30, s30, s8
	s_addc_u32 s31, s31, s9
	s_mov_b32 m0, s49
	v_lshl_add_u64 v[224:225], s[30:31], 0, v[134:135]
	ds_read_b128 v[180:183], v151 offset:32768
	ds_read_b128 v[184:187], v151 offset:33792
	ds_read_b128 v[188:191], v151 offset:34816
	ds_read_b128 v[192:195], v151 offset:35840
	ds_read_b128 v[196:199], v151 offset:36864
	ds_read_b128 v[200:203], v151 offset:37888
	ds_read_b128 v[204:207], v151 offset:38912
	ds_read_b128 v[208:211], v151 offset:39936
	global_load_lds_dwordx4 v[224:225], off
	v_lshl_add_u64 v[224:225], s[30:31], 0, v[130:131]
	s_mov_b32 m0, s50
	s_nop 0
	global_load_lds_dwordx4 v[224:225], off
	s_waitcnt vmcnt(8)
	s_waitcnt lgkmcnt(0)
	s_setprio 1
	s_barrier
	v_mfma_f32_16x16x32_bf16 v[124:127], v[142:145], v[180:183], v[124:127]
	v_mfma_f32_16x16x32_bf16 v[120:123], v[156:159], v[180:183], v[120:123]
	v_mfma_f32_16x16x32_bf16 v[108:111], v[142:145], v[188:191], v[108:111]
	v_mfma_f32_16x16x32_bf16 v[104:107], v[156:159], v[188:191], v[104:107]
	v_mfma_f32_16x16x32_bf16 v[92:95], v[142:145], v[196:199], v[92:95]
	v_mfma_f32_16x16x32_bf16 v[88:91], v[156:159], v[196:199], v[88:91]
	v_mfma_f32_16x16x32_bf16 v[76:79], v[142:145], v[204:207], v[76:79]
	v_mfma_f32_16x16x32_bf16 v[72:75], v[156:159], v[204:207], v[72:75]
	v_mfma_f32_16x16x32_bf16 v[124:127], v[152:155], v[184:187], v[124:127]
	v_mfma_f32_16x16x32_bf16 v[120:123], v[160:163], v[184:187], v[120:123]
	v_mfma_f32_16x16x32_bf16 v[108:111], v[152:155], v[192:195], v[108:111]
	v_mfma_f32_16x16x32_bf16 v[104:107], v[160:163], v[192:195], v[104:107]
	v_mfma_f32_16x16x32_bf16 v[92:95], v[152:155], v[200:203], v[92:95]
	v_mfma_f32_16x16x32_bf16 v[88:91], v[160:163], v[200:203], v[88:91]
	v_mfma_f32_16x16x32_bf16 v[76:79], v[152:155], v[208:211], v[76:79]
	v_mfma_f32_16x16x32_bf16 v[72:75], v[160:163], v[208:211], v[72:75]
	v_mfma_f32_16x16x32_bf16 v[116:119], v[164:167], v[180:183], v[116:119]
	v_mfma_f32_16x16x32_bf16 v[112:115], v[172:175], v[180:183], v[112:115]
	v_mfma_f32_16x16x32_bf16 v[100:103], v[164:167], v[188:191], v[100:103]
	v_mfma_f32_16x16x32_bf16 v[96:99], v[172:175], v[188:191], v[96:99]
	v_mfma_f32_16x16x32_bf16 v[84:87], v[164:167], v[196:199], v[84:87]
	v_mfma_f32_16x16x32_bf16 v[80:83], v[172:175], v[196:199], v[80:83]
	v_mfma_f32_16x16x32_bf16 v[68:71], v[164:167], v[204:207], v[68:71]
	v_mfma_f32_16x16x32_bf16 v[64:67], v[172:175], v[204:207], v[64:67]
	v_mfma_f32_16x16x32_bf16 v[116:119], v[168:171], v[184:187], v[116:119]
	v_mfma_f32_16x16x32_bf16 v[112:115], v[176:179], v[184:187], v[112:115]
	v_mfma_f32_16x16x32_bf16 v[100:103], v[168:171], v[192:195], v[100:103]
	v_mfma_f32_16x16x32_bf16 v[96:99], v[176:179], v[192:195], v[96:99]
	v_mfma_f32_16x16x32_bf16 v[84:87], v[168:171], v[200:203], v[84:87]
	v_mfma_f32_16x16x32_bf16 v[80:83], v[176:179], v[200:203], v[80:83]
	v_mfma_f32_16x16x32_bf16 v[68:71], v[168:171], v[208:211], v[68:71]
	v_mfma_f32_16x16x32_bf16 v[64:67], v[176:179], v[208:211], v[64:67]
	s_setprio 0
	s_barrier
	s_add_i32 s30, s33, s38
	v_lshl_add_u64 v[212:213], v[212:213], 0, s[18:19]
	s_mov_b32 m0, s30
	ds_read_b128 v[180:183], v151 offset:49152
	ds_read_b128 v[184:187], v151 offset:50176
	ds_read_b128 v[188:191], v151 offset:51200
	ds_read_b128 v[192:195], v151 offset:52224
	ds_read_b128 v[196:199], v151 offset:53248
	ds_read_b128 v[200:203], v151 offset:54272
	ds_read_b128 v[204:207], v151 offset:55296
	ds_read_b128 v[208:211], v151 offset:56320
	global_load_lds_dwordx4 v[212:213], off
	v_lshl_add_u64 v[212:213], v[214:215], 0, s[18:19]
	s_add_i32 m0, s30, 0x2000
	s_add_i32 s30, s67, s38
	global_load_lds_dwordx4 v[212:213], off
	v_lshl_add_u64 v[212:213], v[216:217], 0, s[18:19]
	s_mov_b32 m0, s30
	s_nop 0
	global_load_lds_dwordx4 v[212:213], off
	v_lshl_add_u64 v[212:213], v[218:219], 0, s[18:19]
	s_add_i32 m0, s30, 0x2000
	s_nop 0
	global_load_lds_dwordx4 v[212:213], off
	v_lshl_add_u64 v[212:213], v[220:221], 0, s[18:19]
	s_mov_b32 m0, s52
	s_nop 0
	global_load_lds_dwordx4 v[212:213], off
	v_lshl_add_u64 v[212:213], v[222:223], 0, s[18:19]
	s_mov_b32 m0, s53
	s_nop 0
	global_load_lds_dwordx4 v[212:213], off
	s_waitcnt vmcnt(8)
	s_waitcnt lgkmcnt(0)
	s_setprio 1
	s_barrier
	v_mfma_f32_16x16x32_bf16 v[60:63], v[142:145], v[180:183], v[60:63]
	v_mfma_f32_16x16x32_bf16 v[56:59], v[156:159], v[180:183], v[56:59]
	v_mfma_f32_16x16x32_bf16 v[44:47], v[142:145], v[188:191], v[44:47]
	v_mfma_f32_16x16x32_bf16 v[40:43], v[156:159], v[188:191], v[40:43]
	v_mfma_f32_16x16x32_bf16 v[28:31], v[142:145], v[196:199], v[28:31]
	v_mfma_f32_16x16x32_bf16 v[24:27], v[156:159], v[196:199], v[24:27]
	v_mfma_f32_16x16x32_bf16 v[12:15], v[142:145], v[204:207], v[12:15]
	v_mfma_f32_16x16x32_bf16 v[8:11], v[156:159], v[204:207], v[8:11]
	v_mfma_f32_16x16x32_bf16 v[60:63], v[152:155], v[184:187], v[60:63]
	v_mfma_f32_16x16x32_bf16 v[56:59], v[160:163], v[184:187], v[56:59]
	v_mfma_f32_16x16x32_bf16 v[44:47], v[152:155], v[192:195], v[44:47]
	v_mfma_f32_16x16x32_bf16 v[40:43], v[160:163], v[192:195], v[40:43]
	v_mfma_f32_16x16x32_bf16 v[28:31], v[152:155], v[200:203], v[28:31]
	v_mfma_f32_16x16x32_bf16 v[24:27], v[160:163], v[200:203], v[24:27]
	v_mfma_f32_16x16x32_bf16 v[12:15], v[152:155], v[208:211], v[12:15]
	v_mfma_f32_16x16x32_bf16 v[8:11], v[160:163], v[208:211], v[8:11]
	v_mfma_f32_16x16x32_bf16 v[52:55], v[164:167], v[180:183], v[52:55]
	v_mfma_f32_16x16x32_bf16 v[48:51], v[172:175], v[180:183], v[48:51]
	v_mfma_f32_16x16x32_bf16 v[36:39], v[164:167], v[188:191], v[36:39]
	v_mfma_f32_16x16x32_bf16 v[32:35], v[172:175], v[188:191], v[32:35]
	v_mfma_f32_16x16x32_bf16 v[20:23], v[164:167], v[196:199], v[20:23]
	v_mfma_f32_16x16x32_bf16 v[16:19], v[172:175], v[196:199], v[16:19]
	v_mfma_f32_16x16x32_bf16 v[4:7], v[164:167], v[204:207], v[4:7]
	v_mfma_f32_16x16x32_bf16 v[0:3], v[172:175], v[204:207], v[0:3]
	v_mfma_f32_16x16x32_bf16 v[52:55], v[168:171], v[184:187], v[52:55]
	v_mfma_f32_16x16x32_bf16 v[48:51], v[176:179], v[184:187], v[48:51]
	v_mfma_f32_16x16x32_bf16 v[36:39], v[168:171], v[192:195], v[36:39]
	v_mfma_f32_16x16x32_bf16 v[32:35], v[176:179], v[192:195], v[32:35]
	v_mfma_f32_16x16x32_bf16 v[20:23], v[168:171], v[200:203], v[20:23]
	v_mfma_f32_16x16x32_bf16 v[16:19], v[176:179], v[200:203], v[16:19]
	v_mfma_f32_16x16x32_bf16 v[4:7], v[168:171], v[208:211], v[4:7]
	v_mfma_f32_16x16x32_bf16 v[0:3], v[176:179], v[208:211], v[0:3]
	s_setprio 0
	s_barrier
	s_add_u32 s28, s28, 0x100
	s_addc_u32 s29, s29, 0
	s_add_u32 s0, s0, 0x100
	s_addc_u32 s1, s1, 0
	s_cmp_ge_i32 s66, s54
	s_mov_b32 s30, s66
	s_cbranch_scc0 .LBB0_1258

; #define PG8_STAGE(bufoff, gbase, voff) do { _Pragma("unroll") for (int _i = 0; _i < 2; ++_i) \
;         __builtin_amdgcn_global_load_lds((const unsigned*)((const char*)(gbase) + (voff)[_i]), (PG8_LAS unsigned*)(lds + (bufoff) + ldsw + _i * 8192), 16, 0, 0); } while (0)
; #define PG8_LDA(dst, b, h) do { _Pragma("unroll") for (int m = 0; m < 4; ++m) _Pragma("unroll") for (int k = 0; k < 2; ++k) dst[m][k] = *(const PG8_LAS bf16x8*)(lds + PG8_SA(b, h) + aoff + m * 2048 + k * 1024); } while (0)
; #define PG8_LDB(dst, b, h) do { _Pragma("unroll") for (int n = 0; n < 2; ++n) _Pragma("unroll") for (int k = 0; k < 2; ++k) dst[n][k] = *(const PG8_LAS bf16x8*)(lds + PG8_SB(b, h) + boff + n * 2048 + k * 1024); } while (0)
; #define PG8_WAIT_V(n) asm volatile("s_waitcnt vmcnt(" #n ")" ::: "memory")
; #define PG8_WAIT_L(n) asm volatile("s_waitcnt lgkmcnt(" #n ")" ::: "memory")
; #define PG8_BAR __builtin_amdgcn_s_barrier()
; #define PG8_SCHED __builtin_amdgcn_sched_barrier(0)
; template <class Epi, class Sched, bool ALIGN_EPI = false, bool SP2 = false>
; __device__ __forceinline__ void gemm_phase(PG8_LAS unsigned char* lds, const Gemm g, const Sched& S, const Epi& E, const int wid) {
;     ...
;         const bool has_next = S.next(ui + 1, nxt);
;         const char* nA = has_next ? (const char*)g.A + (size_t)nxt.pm * tstep : cA; const char* nB = has_next ? (const char*)g.Bt + (size_t)nxt.pn * tstep : cB;
;         for (int t = 0; t < nt; t += 2) {
;             const bool last = (t == nt - 2);
;             const char* a1 = cA + (size_t)(t + 1) * kstep;
;             const char* a2 = last ? nA : cA + (size_t)(t + 2) * kstep; const char* b2 = last ? nB : cB + (size_t)(t + 2) * kstep;
;             const char* a3 = a2 + kstep; const char* b3 = b2 + kstep;
;             if (last && has_next) S.a_ready(nxt);
;             if constexpr (SP2) {
;             PG8_LDB(B0, 0, 0); PG8_LDB(B1, 0, 1); PG8_SCHED; PG8_LDA(At, 0, 0); PG8_STAGE(PG8_SA(1, 1), a1 + hstep, voffA);
;             PG8_WAIT_V(8); PG8_WAIT_L(0); PG8_BAR; PG8_MMA(0, 0, At, B0); PG8_MMA(0, 1, At, B1); PG8_BAR; PG8_SCHED;
;             PG8_LDA(At, 0, 1); PG8_STAGE(PG8_SB(0, 0), b2, voffB); PG8_STAGE(PG8_SB(0, 1), b2 + hstep, voffB); PG8_STAGE(PG8_SA(0, 0), a2, voffA);
;             PG8_WAIT_V(8); PG8_WAIT_L(0); PG8_BAR; PG8_MMA(1, 0, At, B0); PG8_MMA(1, 1, At, B1); PG8_BAR; PG8_SCHED;
.LBB0_1337:
	s_andn2_b64 vcc, exec, s[24:25]
	s_waitcnt lgkmcnt(0)
	s_cbranch_vccnz .Lz_GOUT
	s_add_u32 s4, s36, 0x80
	s_addc_u32 s5, s37, 0
	s_add_u32 s0, s34, 0x100
	s_addc_u32 s1, s35, 0
	s_mov_b32 s34, 0
	ds_read_b128 v[142:145], v149
	ds_read_b128 v[154:157], v149 offset:1024
	ds_read_b128 v[158:161], v149 offset:2048
	ds_read_b128 v[162:165], v149 offset:3072
	ds_read_b128 v[166:169], v150
	ds_read_b128 v[170:173], v150 offset:1024
	ds_read_b128 v[174:177], v150 offset:2048
	ds_read_b128 v[178:181], v150 offset:3072
	s_add_i32 s36, s34, 2
	s_add_u32 s33, s4, 0x80
	s_addc_u32 s35, s5, 0
	s_cmp_eq_u32 s54, s34
	s_cselect_b32 s34, s28, s33
	s_cselect_b32 s35, s29, s35
	s_cselect_b32 s69, s31, s1
	s_cselect_b32 s68, s30, s0
	v_lshl_add_u64 v[214:215], s[4:5], 0, v[136:137]
	s_add_i32 m0, s43, 0xc000
	ds_read_b128 v[182:185], v151
	ds_read_b128 v[186:189], v151 offset:1024
	ds_read_b128 v[190:193], v151 offset:2048
	ds_read_b128 v[194:197], v151 offset:3072
	ds_read_b128 v[198:201], v151 offset:4096
	ds_read_b128 v[202:205], v151 offset:5120
	ds_read_b128 v[206:209], v151 offset:6144
	ds_read_b128 v[210:213], v151 offset:7168
	global_load_lds_dwordx4 v[214:215], off
	v_lshl_add_u64 v[214:215], s[4:5], 0, v[138:139]
	s_add_i32 m0, s43, 0xe000
	s_nop 0
	global_load_lds_dwordx4 v[214:215], off
	s_waitcnt vmcnt(8)
	s_waitcnt lgkmcnt(0)
	s_setprio 1
	s_barrier
	v_mfma_f32_16x16x32_bf16 v[120:123], v[142:145], v[182:185], 0
	v_mfma_f32_16x16x32_bf16 v[124:127], v[158:161], v[182:185], 0
	v_mfma_f32_16x16x32_bf16 v[108:111], v[142:145], v[190:193], 0
	v_mfma_f32_16x16x32_bf16 v[104:107], v[158:161], v[190:193], 0
	v_mfma_f32_16x16x32_bf16 v[92:95], v[142:145], v[198:201], 0
	v_mfma_f32_16x16x32_bf16 v[88:91], v[158:161], v[198:201], 0
	v_mfma_f32_16x16x32_bf16 v[76:79], v[142:145], v[206:209], 0
	v_mfma_f32_16x16x32_bf16 v[72:75], v[158:161], v[206:209], 0
	v_mfma_f32_16x16x32_bf16 v[120:123], v[154:157], v[186:189], v[120:123]
	v_mfma_f32_16x16x32_bf16 v[124:127], v[162:165], v[186:189], v[124:127]
	v_mfma_f32_16x16x32_bf16 v[108:111], v[154:157], v[194:197], v[108:111]
	v_mfma_f32_16x16x32_bf16 v[104:107], v[162:165], v[194:197], v[104:107]
	v_mfma_f32_16x16x32_bf16 v[92:95], v[154:157], v[202:205], v[92:95]
	v_mfma_f32_16x16x32_bf16 v[88:91], v[162:165], v[202:205], v[88:91]
	v_mfma_f32_16x16x32_bf16 v[76:79], v[154:157], v[210:213], v[76:79]
	v_mfma_f32_16x16x32_bf16 v[72:75], v[162:165], v[210:213], v[72:75]
	v_mfma_f32_16x16x32_bf16 v[116:119], v[166:169], v[182:185], 0
	v_mfma_f32_16x16x32_bf16 v[112:115], v[174:177], v[182:185], 0
	v_mfma_f32_16x16x32_bf16 v[100:103], v[166:169], v[190:193], 0
	v_mfma_f32_16x16x32_bf16 v[96:99], v[174:177], v[190:193], 0
	v_mfma_f32_16x16x32_bf16 v[84:87], v[166:169], v[198:201], 0
	v_mfma_f32_16x16x32_bf16 v[80:83], v[174:177], v[198:201], 0
	v_mfma_f32_16x16x32_bf16 v[68:71], v[166:169], v[206:209], 0
	v_mfma_f32_16x16x32_bf16 v[64:67], v[174:177], v[206:209], 0
	v_mfma_f32_16x16x32_bf16 v[116:119], v[170:173], v[186:189], v[116:119]
	v_mfma_f32_16x16x32_bf16 v[112:115], v[178:181], v[186:189], v[112:115]
	v_mfma_f32_16x16x32_bf16 v[100:103], v[170:173], v[194:197], v[100:103]
	v_mfma_f32_16x16x32_bf16 v[96:99], v[178:181], v[194:197], v[96:99]
	v_mfma_f32_16x16x32_bf16 v[84:87], v[170:173], v[202:205], v[84:87]
	v_mfma_f32_16x16x32_bf16 v[80:83], v[178:181], v[202:205], v[80:83]
	v_mfma_f32_16x16x32_bf16 v[68:71], v[170:173], v[210:213], v[68:71]
	v_mfma_f32_16x16x32_bf16 v[64:67], v[178:181], v[210:213], v[64:67]
	s_setprio 0
	s_barrier
	s_add_i32 s33, s62, s42
	v_lshl_add_u64 v[214:215], s[68:69], 0, v[130:131]
	s_mov_b32 m0, s33
	ds_read_b128 v[182:185], v151 offset:16384
	ds_read_b128 v[186:189], v151 offset:17408
	ds_read_b128 v[190:193], v151 offset:18432
	ds_read_b128 v[194:197], v151 offset:19456
	ds_read_b128 v[198:201], v151 offset:20480
	ds_read_b128 v[202:205], v151 offset:21504
	ds_read_b128 v[206:209], v151 offset:22528
	ds_read_b128 v[210:213], v151 offset:23552
	global_load_lds_dwordx4 v[214:215], off
	s_add_i32 m0, s33, 0x2000
	v_lshl_add_u64 v[216:217], s[68:69], 0, v[134:135]
	s_add_u32 s68, s68, s8
	s_addc_u32 s69, s69, s9
	s_add_i32 s33, s63, s42
	global_load_lds_dwordx4 v[216:217], off
	v_lshl_add_u64 v[218:219], s[68:69], 0, v[130:131]
	s_mov_b32 m0, s33
	v_lshl_add_u64 v[220:221], s[68:69], 0, v[134:135]
	global_load_lds_dwordx4 v[218:219], off
	s_add_i32 m0, s33, 0x2000
	v_lshl_add_u64 v[222:223], s[34:35], 0, v[128:129]
	global_load_lds_dwordx4 v[220:221], off
	s_mov_b32 m0, s43
	v_lshl_add_u64 v[224:225], s[34:35], 0, v[132:133]
	global_load_lds_dwordx4 v[222:223], off
	s_mov_b32 m0, s44
	s_nop 0
	global_load_lds_dwordx4 v[224:225], off
	s_waitcnt vmcnt(8)
	s_waitcnt lgkmcnt(0)
	s_setprio 1
	s_barrier
; #define PG8_STAGE(bufoff, gbase, voff) do { _Pragma("unroll") for (int _i = 0; _i < 2; ++_i) \
;         __builtin_amdgcn_global_load_lds((const unsigned*)((const char*)(gbase) + (voff)[_i]), (PG8_LAS unsigned*)(lds + (bufoff) + ldsw + _i * 8192), 16, 0, 0); } while (0)
; #define PG8_LDA(dst, b, h) do { _Pragma("unroll") for (int m = 0; m < 4; ++m) _Pragma("unroll") for (int k = 0; k < 2; ++k) dst[m][k] = *(const PG8_LAS bf16x8*)(lds + PG8_SA(b, h) + aoff + m * 2048 + k * 1024); } while (0)
; #define PG8_LDB(dst, b, h) do { _Pragma("unroll") for (int n = 0; n < 2; ++n) _Pragma("unroll") for (int k = 0; k < 2; ++k) dst[n][k] = *(const PG8_LAS bf16x8*)(lds + PG8_SB(b, h) + boff + n * 2048 + k * 1024); } while (0)
; #define PG8_MMA(ai, bj, At, Bt) do { __builtin_amdgcn_s_setprio(1); _Pragma("unroll") for (int m = 0; m < 4; ++m) _Pragma("unroll") for (int n = 0; n < 2; ++n) _Pragma("unroll") for (int k = 0; k < 2; ++k) \
;         acc[ai][bj][m][n] = __builtin_amdgcn_mfma_f32_16x16x32_bf16(Bt[n][k], At[m][k], acc[ai][bj][m][n], 0, 0, 0); __builtin_amdgcn_s_setprio(0); } while (0)
; #define PG8_WAIT_V(n) asm volatile("s_waitcnt vmcnt(" #n ")" ::: "memory")
; #define PG8_WAIT_L(n) asm volatile("s_waitcnt lgkmcnt(" #n ")" ::: "memory")
; #define PG8_BAR __builtin_amdgcn_s_barrier()
; #define PG8_SCHED __builtin_amdgcn_sched_barrier(0)
; template <class Epi, class Sched, bool ALIGN_EPI = false, bool SP2 = false>
; __device__ __forceinline__ void gemm_phase(PG8_LAS unsigned char* lds, const Gemm g, const Sched& S, const Epi& E, const int wid) {
;     ...
;             PG8_WAIT_V(8); PG8_WAIT_L(0); PG8_BAR; PG8_MMA(0, 0, At, B0); PG8_MMA(0, 1, At, B1); PG8_BAR; PG8_SCHED;
;             PG8_LDA(At, 0, 1); PG8_STAGE(PG8_SB(0, 0), b2, voffB); PG8_STAGE(PG8_SB(0, 1), b2 + hstep, voffB); PG8_STAGE(PG8_SA(0, 0), a2, voffA);
;             PG8_WAIT_V(8); PG8_WAIT_L(0); PG8_BAR; PG8_MMA(1, 0, At, B0); PG8_MMA(1, 1, At, B1); PG8_BAR; PG8_SCHED;
;             PG8_LDB(B0, 1, 0); PG8_LDB(B1, 1, 1); PG8_SCHED; PG8_LDA(At, 1, 0); PG8_STAGE(PG8_SA(0, 1), a2 + hstep, voffA);
	v_mfma_f32_16x16x32_bf16 v[60:63], v[142:145], v[182:185], 0
	v_mfma_f32_16x16x32_bf16 v[56:59], v[158:161], v[182:185], 0
	v_mfma_f32_16x16x32_bf16 v[44:47], v[142:145], v[190:193], 0
	v_mfma_f32_16x16x32_bf16 v[40:43], v[158:161], v[190:193], 0
	v_mfma_f32_16x16x32_bf16 v[28:31], v[142:145], v[198:201], 0
	v_mfma_f32_16x16x32_bf16 v[24:27], v[158:161], v[198:201], 0
	v_mfma_f32_16x16x32_bf16 v[12:15], v[142:145], v[206:209], 0
	v_mfma_f32_16x16x32_bf16 v[8:11], v[158:161], v[206:209], 0
	v_mfma_f32_16x16x32_bf16 v[60:63], v[154:157], v[186:189], v[60:63]
	v_mfma_f32_16x16x32_bf16 v[56:59], v[162:165], v[186:189], v[56:59]
	v_mfma_f32_16x16x32_bf16 v[44:47], v[154:157], v[194:197], v[44:47]
	v_mfma_f32_16x16x32_bf16 v[40:43], v[162:165], v[194:197], v[40:43]
	v_mfma_f32_16x16x32_bf16 v[28:31], v[154:157], v[202:205], v[28:31]
	v_mfma_f32_16x16x32_bf16 v[24:27], v[162:165], v[202:205], v[24:27]
	v_mfma_f32_16x16x32_bf16 v[12:15], v[154:157], v[210:213], v[12:15]
	v_mfma_f32_16x16x32_bf16 v[8:11], v[162:165], v[210:213], v[8:11]
	v_mfma_f32_16x16x32_bf16 v[52:55], v[166:169], v[182:185], 0
	v_mfma_f32_16x16x32_bf16 v[48:51], v[174:177], v[182:185], 0
	v_mfma_f32_16x16x32_bf16 v[36:39], v[166:169], v[190:193], 0
	v_mfma_f32_16x16x32_bf16 v[32:35], v[174:177], v[190:193], 0
	v_mfma_f32_16x16x32_bf16 v[20:23], v[166:169], v[198:201], 0
	v_mfma_f32_16x16x32_bf16 v[16:19], v[174:177], v[198:201], 0
	v_mfma_f32_16x16x32_bf16 v[4:7], v[166:169], v[206:209], 0
	v_mfma_f32_16x16x32_bf16 v[0:3], v[174:177], v[206:209], 0
	v_mfma_f32_16x16x32_bf16 v[52:55], v[170:173], v[186:189], v[52:55]
	v_mfma_f32_16x16x32_bf16 v[48:51], v[178:181], v[186:189], v[48:51]
	v_mfma_f32_16x16x32_bf16 v[36:39], v[170:173], v[194:197], v[36:39]
	v_mfma_f32_16x16x32_bf16 v[32:35], v[178:181], v[194:197], v[32:35]
	v_mfma_f32_16x16x32_bf16 v[20:23], v[170:173], v[202:205], v[20:23]
	v_mfma_f32_16x16x32_bf16 v[16:19], v[178:181], v[202:205], v[16:19]
	v_mfma_f32_16x16x32_bf16 v[4:7], v[170:173], v[210:213], v[4:7]
	v_mfma_f32_16x16x32_bf16 v[0:3], v[178:181], v[210:213], v[0:3]
	s_setprio 0
	s_barrier
	s_add_i32 s33, 0, 0x18000
	v_add_u32_e32 v153, s33, v148
	s_add_i32 s37, 0, 0x1c000
	ds_read_b128 v[142:145], v153
	ds_read_b128 v[154:157], v153 offset:1024
	ds_read_b128 v[158:161], v153 offset:2048
	ds_read_b128 v[162:165], v153 offset:3072
	v_add_u32_e32 v153, s37, v148
	ds_read_b128 v[166:169], v153
	ds_read_b128 v[170:173], v153 offset:1024
	ds_read_b128 v[174:177], v153 offset:2048
	ds_read_b128 v[178:181], v153 offset:3072
	s_add_u32 s34, s34, s8
	s_addc_u32 s35, s35, s9
	s_mov_b32 m0, s45
	v_lshl_add_u64 v[226:227], s[34:35], 0, v[128:129]
	ds_read_b128 v[182:185], v151 offset:32768
	ds_read_b128 v[186:189], v151 offset:33792
	ds_read_b128 v[190:193], v151 offset:34816
	ds_read_b128 v[194:197], v151 offset:35840
	ds_read_b128 v[198:201], v151 offset:36864
	ds_read_b128 v[202:205], v151 offset:37888
	ds_read_b128 v[206:209], v151 offset:38912
	ds_read_b128 v[210:213], v151 offset:39936
	global_load_lds_dwordx4 v[226:227], off
	v_lshl_add_u64 v[226:227], s[34:35], 0, v[132:133]
	s_mov_b32 m0, s46
	s_nop 0
	global_load_lds_dwordx4 v[226:227], off
	s_waitcnt vmcnt(8)
	s_waitcnt lgkmcnt(0)
	s_setprio 1
	s_barrier
	v_mfma_f32_16x16x32_bf16 v[120:123], v[142:145], v[182:185], v[120:123]
	v_mfma_f32_16x16x32_bf16 v[124:127], v[158:161], v[182:185], v[124:127]
	v_mfma_f32_16x16x32_bf16 v[108:111], v[142:145], v[190:193], v[108:111]
	v_mfma_f32_16x16x32_bf16 v[104:107], v[158:161], v[190:193], v[104:107]
	v_mfma_f32_16x16x32_bf16 v[92:95], v[142:145], v[198:201], v[92:95]
	v_mfma_f32_16x16x32_bf16 v[88:91], v[158:161], v[198:201], v[88:91]
	v_mfma_f32_16x16x32_bf16 v[76:79], v[142:145], v[206:209], v[76:79]
	v_mfma_f32_16x16x32_bf16 v[72:75], v[158:161], v[206:209], v[72:75]
	v_mfma_f32_16x16x32_bf16 v[120:123], v[154:157], v[186:189], v[120:123]
	v_mfma_f32_16x16x32_bf16 v[124:127], v[162:165], v[186:189], v[124:127]
	v_mfma_f32_16x16x32_bf16 v[108:111], v[154:157], v[194:197], v[108:111]
	v_mfma_f32_16x16x32_bf16 v[104:107], v[162:165], v[194:197], v[104:107]
	v_mfma_f32_16x16x32_bf16 v[92:95], v[154:157], v[202:205], v[92:95]
	v_mfma_f32_16x16x32_bf16 v[88:91], v[162:165], v[202:205], v[88:91]
	v_mfma_f32_16x16x32_bf16 v[76:79], v[154:157], v[210:213], v[76:79]
	v_mfma_f32_16x16x32_bf16 v[72:75], v[162:165], v[210:213], v[72:75]
	v_mfma_f32_16x16x32_bf16 v[116:119], v[166:169], v[182:185], v[116:119]
	v_mfma_f32_16x16x32_bf16 v[112:115], v[174:177], v[182:185], v[112:115]
	v_mfma_f32_16x16x32_bf16 v[100:103], v[166:169], v[190:193], v[100:103]
	v_mfma_f32_16x16x32_bf16 v[96:99], v[174:177], v[190:193], v[96:99]
	v_mfma_f32_16x16x32_bf16 v[84:87], v[166:169], v[198:201], v[84:87]
	v_mfma_f32_16x16x32_bf16 v[80:83], v[174:177], v[198:201], v[80:83]
	v_mfma_f32_16x16x32_bf16 v[68:71], v[166:169], v[206:209], v[68:71]
	v_mfma_f32_16x16x32_bf16 v[64:67], v[174:177], v[206:209], v[64:67]
	v_mfma_f32_16x16x32_bf16 v[116:119], v[170:173], v[186:189], v[116:119]
	v_mfma_f32_16x16x32_bf16 v[112:115], v[178:181], v[186:189], v[112:115]
	v_mfma_f32_16x16x32_bf16 v[100:103], v[170:173], v[194:197], v[100:103]
	v_mfma_f32_16x16x32_bf16 v[96:99], v[178:181], v[194:197], v[96:99]
	v_mfma_f32_16x16x32_bf16 v[84:87], v[170:173], v[202:205], v[84:87]
	v_mfma_f32_16x16x32_bf16 v[80:83], v[178:181], v[202:205], v[80:83]
	v_mfma_f32_16x16x32_bf16 v[68:71], v[170:173], v[210:213], v[68:71]
	v_mfma_f32_16x16x32_bf16 v[64:67], v[178:181], v[210:213], v[64:67]
	s_setprio 0
	s_barrier
; #define PG8_STAGE(bufoff, gbase, voff) do { _Pragma("unroll") for (int _i = 0; _i < 2; ++_i) \
;         __builtin_amdgcn_global_load_lds((const unsigned*)((const char*)(gbase) + (voff)[_i]), (PG8_LAS unsigned*)(lds + (bufoff) + ldsw + _i * 8192), 16, 0, 0); } while (0)
; #define PG8_LDA(dst, b, h) do { _Pragma("unroll") for (int m = 0; m < 4; ++m) _Pragma("unroll") for (int k = 0; k < 2; ++k) dst[m][k] = *(const PG8_LAS bf16x8*)(lds + PG8_SA(b, h) + aoff + m * 2048 + k * 1024); } while (0)
; #define PG8_WAIT_V(n) asm volatile("s_waitcnt vmcnt(" #n ")" ::: "memory")
; #define PG8_WAIT_L(n) asm volatile("s_waitcnt lgkmcnt(" #n ")" ::: "memory")
; #define PG8_BAR __builtin_amdgcn_s_barrier()
; template <class Epi, class Sched, bool ALIGN_EPI = false, bool SP2 = false>
; __device__ __forceinline__ void gemm_phase(PG8_LAS unsigned char* lds, const Gemm g, const Sched& S, const Epi& E, const int wid) {
;     ...
;         for (int t = 0; t < nt; t += 2) {
;             const bool last = (t == nt - 2);
;             const char* a1 = cA + (size_t)(t + 1) * kstep;
;             const char* a2 = last ? nA : cA + (size_t)(t + 2) * kstep; const char* b2 = last ? nB : cB + (size_t)(t + 2) * kstep;
;             const char* a3 = a2 + kstep; const char* b3 = b2 + kstep;
;             if (last && has_next) S.a_ready(nxt);
;             if constexpr (SP2) {
;             PG8_LDB(B0, 0, 0); PG8_LDB(B1, 0, 1); PG8_SCHED; PG8_LDA(At, 0, 0); PG8_STAGE(PG8_SA(1, 1), a1 + hstep, voffA);
;             PG8_WAIT_V(8); PG8_WAIT_L(0); PG8_BAR; PG8_MMA(0, 0, At, B0); PG8_MMA(0, 1, At, B1); PG8_BAR; PG8_SCHED;
;             PG8_LDA(At, 0, 1); PG8_STAGE(PG8_SB(0, 0), b2, voffB); PG8_STAGE(PG8_SB(0, 1), b2 + hstep, voffB); PG8_STAGE(PG8_SA(0, 0), a2, voffA);
;             PG8_WAIT_V(8); PG8_WAIT_L(0); PG8_BAR; PG8_MMA(1, 0, At, B0); PG8_MMA(1, 1, At, B1); PG8_BAR; PG8_SCHED;
;             PG8_LDB(B0, 1, 0); PG8_LDB(B1, 1, 1); PG8_SCHED; PG8_LDA(At, 1, 0); PG8_STAGE(PG8_SA(0, 1), a2 + hstep, voffA);
;             PG8_WAIT_V(8); PG8_WAIT_L(0); PG8_BAR; PG8_MMA(0, 0, At, B0); PG8_MMA(0, 1, At, B1); PG8_BAR; PG8_SCHED;
;             PG8_LDA(At, 1, 1); PG8_STAGE(PG8_SB(1, 0), b3, voffB); PG8_STAGE(PG8_SB(1, 1), b3 + hstep, voffB); PG8_STAGE(PG8_SA(1, 0), a3, voffA);
;             PG8_WAIT_V(8); PG8_WAIT_L(0); PG8_BAR; PG8_MMA(1, 0, At, B0); PG8_MMA(1, 1, At, B1); PG8_BAR; PG8_SCHED;
	s_add_i32 s33, s33, s42
	v_lshl_add_u64 v[214:215], v[214:215], 0, s[22:23]
	s_mov_b32 m0, s33
	ds_read_b128 v[182:185], v151 offset:49152
	ds_read_b128 v[186:189], v151 offset:50176
	ds_read_b128 v[190:193], v151 offset:51200
	ds_read_b128 v[194:197], v151 offset:52224
	ds_read_b128 v[198:201], v151 offset:53248
	ds_read_b128 v[202:205], v151 offset:54272
	ds_read_b128 v[206:209], v151 offset:55296
	ds_read_b128 v[210:213], v151 offset:56320
	global_load_lds_dwordx4 v[214:215], off
	v_lshl_add_u64 v[214:215], v[216:217], 0, s[22:23]
	s_add_i32 m0, s33, 0x2000
	s_add_i32 s33, s37, s42
	global_load_lds_dwordx4 v[214:215], off
	v_lshl_add_u64 v[214:215], v[218:219], 0, s[22:23]
	s_mov_b32 m0, s33
	s_nop 0
	global_load_lds_dwordx4 v[214:215], off
	v_lshl_add_u64 v[214:215], v[220:221], 0, s[22:23]
	s_add_i32 m0, s33, 0x2000
	s_nop 0
	global_load_lds_dwordx4 v[214:215], off
	v_lshl_add_u64 v[214:215], v[222:223], 0, s[22:23]
	s_mov_b32 m0, s47
	s_nop 0
	global_load_lds_dwordx4 v[214:215], off
	v_lshl_add_u64 v[214:215], v[224:225], 0, s[22:23]
	s_mov_b32 m0, s49
	s_nop 0
	global_load_lds_dwordx4 v[214:215], off
	s_waitcnt vmcnt(8)
	s_waitcnt lgkmcnt(0)
	s_setprio 1
	s_barrier
	v_mfma_f32_16x16x32_bf16 v[60:63], v[142:145], v[182:185], v[60:63]
	v_mfma_f32_16x16x32_bf16 v[56:59], v[158:161], v[182:185], v[56:59]
	v_mfma_f32_16x16x32_bf16 v[44:47], v[142:145], v[190:193], v[44:47]
	v_mfma_f32_16x16x32_bf16 v[40:43], v[158:161], v[190:193], v[40:43]
	v_mfma_f32_16x16x32_bf16 v[28:31], v[142:145], v[198:201], v[28:31]
	v_mfma_f32_16x16x32_bf16 v[24:27], v[158:161], v[198:201], v[24:27]
	v_mfma_f32_16x16x32_bf16 v[12:15], v[142:145], v[206:209], v[12:15]
	v_mfma_f32_16x16x32_bf16 v[8:11], v[158:161], v[206:209], v[8:11]
	v_mfma_f32_16x16x32_bf16 v[60:63], v[154:157], v[186:189], v[60:63]
	v_mfma_f32_16x16x32_bf16 v[56:59], v[162:165], v[186:189], v[56:59]
	v_mfma_f32_16x16x32_bf16 v[44:47], v[154:157], v[194:197], v[44:47]
	v_mfma_f32_16x16x32_bf16 v[40:43], v[162:165], v[194:197], v[40:43]
	v_mfma_f32_16x16x32_bf16 v[28:31], v[154:157], v[202:205], v[28:31]
	v_mfma_f32_16x16x32_bf16 v[24:27], v[162:165], v[202:205], v[24:27]
	v_mfma_f32_16x16x32_bf16 v[12:15], v[154:157], v[210:213], v[12:15]
	v_mfma_f32_16x16x32_bf16 v[8:11], v[162:165], v[210:213], v[8:11]
	v_mfma_f32_16x16x32_bf16 v[52:55], v[166:169], v[182:185], v[52:55]
	v_mfma_f32_16x16x32_bf16 v[48:51], v[174:177], v[182:185], v[48:51]
	v_mfma_f32_16x16x32_bf16 v[36:39], v[166:169], v[190:193], v[36:39]
	v_mfma_f32_16x16x32_bf16 v[32:35], v[174:177], v[190:193], v[32:35]
	v_mfma_f32_16x16x32_bf16 v[20:23], v[166:169], v[198:201], v[20:23]
	v_mfma_f32_16x16x32_bf16 v[16:19], v[174:177], v[198:201], v[16:19]
	v_mfma_f32_16x16x32_bf16 v[4:7], v[166:169], v[206:209], v[4:7]
	v_mfma_f32_16x16x32_bf16 v[0:3], v[174:177], v[206:209], v[0:3]
	v_mfma_f32_16x16x32_bf16 v[52:55], v[170:173], v[186:189], v[52:55]
	v_mfma_f32_16x16x32_bf16 v[48:51], v[178:181], v[186:189], v[48:51]
	v_mfma_f32_16x16x32_bf16 v[36:39], v[170:173], v[194:197], v[36:39]
	v_mfma_f32_16x16x32_bf16 v[32:35], v[178:181], v[194:197], v[32:35]
	v_mfma_f32_16x16x32_bf16 v[20:23], v[170:173], v[202:205], v[20:23]
	v_mfma_f32_16x16x32_bf16 v[16:19], v[178:181], v[202:205], v[16:19]
	v_mfma_f32_16x16x32_bf16 v[4:7], v[170:173], v[210:213], v[4:7]
	v_mfma_f32_16x16x32_bf16 v[0:3], v[178:181], v[210:213], v[0:3]
	s_setprio 0
	s_barrier
	s_add_u32 s4, s4, 0x100
	s_addc_u32 s5, s5, 0
	s_add_u32 s0, s0, 0x100
	s_addc_u32 s1, s1, 0
	s_cmp_ge_i32 s36, s51
	s_mov_b32 s34, s36
	s_cbranch_scc1 .LBB0_1340
.LBB0_1339:
	ds_read_b128 v[142:145], v149
	ds_read_b128 v[154:157], v149 offset:1024
	ds_read_b128 v[158:161], v149 offset:2048
	ds_read_b128 v[162:165], v149 offset:3072
	ds_read_b128 v[166:169], v150
	ds_read_b128 v[170:173], v150 offset:1024
	ds_read_b128 v[174:177], v150 offset:2048
	ds_read_b128 v[178:181], v150 offset:3072
	s_add_i32 s36, s34, 2
	s_add_u32 s33, s4, 0x80
	s_addc_u32 s35, s5, 0
	s_cmp_eq_u32 s54, s34
	s_cselect_b32 s34, s28, s33
	s_cselect_b32 s35, s29, s35
	s_cselect_b32 s69, s31, s1
	s_cselect_b32 s68, s30, s0
	v_lshl_add_u64 v[214:215], s[4:5], 0, v[136:137]
	s_add_i32 m0, s43, 0xc000
	ds_read_b128 v[182:185], v151
	ds_read_b128 v[186:189], v151 offset:1024
	ds_read_b128 v[190:193], v151 offset:2048
	ds_read_b128 v[194:197], v151 offset:3072
	ds_read_b128 v[198:201], v151 offset:4096
	ds_read_b128 v[202:205], v151 offset:5120
	ds_read_b128 v[206:209], v151 offset:6144
	ds_read_b128 v[210:213], v151 offset:7168
	global_load_lds_dwordx4 v[214:215], off
	v_lshl_add_u64 v[214:215], s[4:5], 0, v[138:139]
	s_add_i32 m0, s43, 0xe000
	s_nop 0
	global_load_lds_dwordx4 v[214:215], off
	s_waitcnt vmcnt(8)
	s_waitcnt lgkmcnt(0)
	s_setprio 1
	s_barrier
; #define PG8_STAGE(bufoff, gbase, voff) do { _Pragma("unroll") for (int _i = 0; _i < 2; ++_i) \
;         __builtin_amdgcn_global_load_lds((const unsigned*)((const char*)(gbase) + (voff)[_i]), (PG8_LAS unsigned*)(lds + (bufoff) + ldsw + _i * 8192), 16, 0, 0); } while (0)
; #define PG8_LDA(dst, b, h) do { _Pragma("unroll") for (int m = 0; m < 4; ++m) _Pragma("unroll") for (int k = 0; k < 2; ++k) dst[m][k] = *(const PG8_LAS bf16x8*)(lds + PG8_SA(b, h) + aoff + m * 2048 + k * 1024); } while (0)
; #define PG8_LDB(dst, b, h) do { _Pragma("unroll") for (int n = 0; n < 2; ++n) _Pragma("unroll") for (int k = 0; k < 2; ++k) dst[n][k] = *(const PG8_LAS bf16x8*)(lds + PG8_SB(b, h) + boff + n * 2048 + k * 1024); } while (0)
; #define PG8_MMA(ai, bj, At, Bt) do { __builtin_amdgcn_s_setprio(1); _Pragma("unroll") for (int m = 0; m < 4; ++m) _Pragma("unroll") for (int n = 0; n < 2; ++n) _Pragma("unroll") for (int k = 0; k < 2; ++k) \
;         acc[ai][bj][m][n] = __builtin_amdgcn_mfma_f32_16x16x32_bf16(Bt[n][k], At[m][k], acc[ai][bj][m][n], 0, 0, 0); __builtin_amdgcn_s_setprio(0); } while (0)
; #define PG8_WAIT_V(n) asm volatile("s_waitcnt vmcnt(" #n ")" ::: "memory")
; #define PG8_WAIT_L(n) asm volatile("s_waitcnt lgkmcnt(" #n ")" ::: "memory")
; #define PG8_BAR __builtin_amdgcn_s_barrier()
; #define PG8_SCHED __builtin_amdgcn_sched_barrier(0)
; template <class Epi, class Sched, bool ALIGN_EPI = false, bool SP2 = false>
; __device__ __forceinline__ void gemm_phase(PG8_LAS unsigned char* lds, const Gemm g, const Sched& S, const Epi& E, const int wid) {
;     ...
;             PG8_LDB(B0, 0, 0); PG8_LDB(B1, 0, 1); PG8_SCHED; PG8_LDA(At, 0, 0); PG8_STAGE(PG8_SA(1, 1), a1 + hstep, voffA);
;             PG8_WAIT_V(8); PG8_WAIT_L(0); PG8_BAR; PG8_MMA(0, 0, At, B0); PG8_MMA(0, 1, At, B1); PG8_BAR; PG8_SCHED;
;             PG8_LDA(At, 0, 1); PG8_STAGE(PG8_SB(0, 0), b2, voffB); PG8_STAGE(PG8_SB(0, 1), b2 + hstep, voffB); PG8_STAGE(PG8_SA(0, 0), a2, voffA);
;             PG8_WAIT_V(8); PG8_WAIT_L(0); PG8_BAR; PG8_MMA(1, 0, At, B0); PG8_MMA(1, 1, At, B1); PG8_BAR; PG8_SCHED;
;             PG8_LDB(B0, 1, 0); PG8_LDB(B1, 1, 1); PG8_SCHED; PG8_LDA(At, 1, 0); PG8_STAGE(PG8_SA(0, 1), a2 + hstep, voffA);
;             PG8_WAIT_V(8); PG8_WAIT_L(0); PG8_BAR; PG8_MMA(0, 0, At, B0); PG8_MMA(0, 1, At, B1); PG8_BAR; PG8_SCHED;
	v_mfma_f32_16x16x32_bf16 v[120:123], v[142:145], v[182:185], v[120:123]
	v_mfma_f32_16x16x32_bf16 v[124:127], v[158:161], v[182:185], v[124:127]
	v_mfma_f32_16x16x32_bf16 v[108:111], v[142:145], v[190:193], v[108:111]
	v_mfma_f32_16x16x32_bf16 v[104:107], v[158:161], v[190:193], v[104:107]
	v_mfma_f32_16x16x32_bf16 v[92:95], v[142:145], v[198:201], v[92:95]
	v_mfma_f32_16x16x32_bf16 v[88:91], v[158:161], v[198:201], v[88:91]
	v_mfma_f32_16x16x32_bf16 v[76:79], v[142:145], v[206:209], v[76:79]
	v_mfma_f32_16x16x32_bf16 v[72:75], v[158:161], v[206:209], v[72:75]
	v_mfma_f32_16x16x32_bf16 v[120:123], v[154:157], v[186:189], v[120:123]
	v_mfma_f32_16x16x32_bf16 v[124:127], v[162:165], v[186:189], v[124:127]
	v_mfma_f32_16x16x32_bf16 v[108:111], v[154:157], v[194:197], v[108:111]
	v_mfma_f32_16x16x32_bf16 v[104:107], v[162:165], v[194:197], v[104:107]
	v_mfma_f32_16x16x32_bf16 v[92:95], v[154:157], v[202:205], v[92:95]
	v_mfma_f32_16x16x32_bf16 v[88:91], v[162:165], v[202:205], v[88:91]
	v_mfma_f32_16x16x32_bf16 v[76:79], v[154:157], v[210:213], v[76:79]
	v_mfma_f32_16x16x32_bf16 v[72:75], v[162:165], v[210:213], v[72:75]
	v_mfma_f32_16x16x32_bf16 v[116:119], v[166:169], v[182:185], v[116:119]
	v_mfma_f32_16x16x32_bf16 v[112:115], v[174:177], v[182:185], v[112:115]
	v_mfma_f32_16x16x32_bf16 v[100:103], v[166:169], v[190:193], v[100:103]
	v_mfma_f32_16x16x32_bf16 v[96:99], v[174:177], v[190:193], v[96:99]
	v_mfma_f32_16x16x32_bf16 v[84:87], v[166:169], v[198:201], v[84:87]
	v_mfma_f32_16x16x32_bf16 v[80:83], v[174:177], v[198:201], v[80:83]
	v_mfma_f32_16x16x32_bf16 v[68:71], v[166:169], v[206:209], v[68:71]
	v_mfma_f32_16x16x32_bf16 v[64:67], v[174:177], v[206:209], v[64:67]
	v_mfma_f32_16x16x32_bf16 v[116:119], v[170:173], v[186:189], v[116:119]
	v_mfma_f32_16x16x32_bf16 v[112:115], v[178:181], v[186:189], v[112:115]
	v_mfma_f32_16x16x32_bf16 v[100:103], v[170:173], v[194:197], v[100:103]
	v_mfma_f32_16x16x32_bf16 v[96:99], v[178:181], v[194:197], v[96:99]
	v_mfma_f32_16x16x32_bf16 v[84:87], v[170:173], v[202:205], v[84:87]
	v_mfma_f32_16x16x32_bf16 v[80:83], v[178:181], v[202:205], v[80:83]
	v_mfma_f32_16x16x32_bf16 v[68:71], v[170:173], v[210:213], v[68:71]
	v_mfma_f32_16x16x32_bf16 v[64:67], v[178:181], v[210:213], v[64:67]
	s_setprio 0
	s_barrier
	s_add_i32 s33, s62, s42
	v_lshl_add_u64 v[214:215], s[68:69], 0, v[130:131]
	s_mov_b32 m0, s33
	ds_read_b128 v[182:185], v151 offset:16384
	ds_read_b128 v[186:189], v151 offset:17408
	ds_read_b128 v[190:193], v151 offset:18432
	ds_read_b128 v[194:197], v151 offset:19456
	ds_read_b128 v[198:201], v151 offset:20480
	ds_read_b128 v[202:205], v151 offset:21504
	ds_read_b128 v[206:209], v151 offset:22528
	ds_read_b128 v[210:213], v151 offset:23552
	global_load_lds_dwordx4 v[214:215], off
	s_add_i32 m0, s33, 0x2000
	v_lshl_add_u64 v[216:217], s[68:69], 0, v[134:135]
	s_add_u32 s68, s68, s8
	s_addc_u32 s69, s69, s9
	s_add_i32 s33, s63, s42
	global_load_lds_dwordx4 v[216:217], off
	v_lshl_add_u64 v[218:219], s[68:69], 0, v[130:131]
	s_mov_b32 m0, s33
	v_lshl_add_u64 v[220:221], s[68:69], 0, v[134:135]
	global_load_lds_dwordx4 v[218:219], off
	s_add_i32 m0, s33, 0x2000
	v_lshl_add_u64 v[222:223], s[34:35], 0, v[128:129]
	global_load_lds_dwordx4 v[220:221], off
	s_mov_b32 m0, s43
	v_lshl_add_u64 v[224:225], s[34:35], 0, v[132:133]
	global_load_lds_dwordx4 v[222:223], off
	s_mov_b32 m0, s44
	s_nop 0
	global_load_lds_dwordx4 v[224:225], off
	s_waitcnt vmcnt(8)
	s_waitcnt lgkmcnt(0)
	s_setprio 1
	s_barrier
	v_mfma_f32_16x16x32_bf16 v[60:63], v[142:145], v[182:185], v[60:63]
	v_mfma_f32_16x16x32_bf16 v[56:59], v[158:161], v[182:185], v[56:59]
	v_mfma_f32_16x16x32_bf16 v[44:47], v[142:145], v[190:193], v[44:47]
	v_mfma_f32_16x16x32_bf16 v[40:43], v[158:161], v[190:193], v[40:43]
	v_mfma_f32_16x16x32_bf16 v[28:31], v[142:145], v[198:201], v[28:31]
	v_mfma_f32_16x16x32_bf16 v[24:27], v[158:161], v[198:201], v[24:27]
	v_mfma_f32_16x16x32_bf16 v[12:15], v[142:145], v[206:209], v[12:15]
	v_mfma_f32_16x16x32_bf16 v[8:11], v[158:161], v[206:209], v[8:11]
	v_mfma_f32_16x16x32_bf16 v[60:63], v[154:157], v[186:189], v[60:63]
	v_mfma_f32_16x16x32_bf16 v[56:59], v[162:165], v[186:189], v[56:59]
	v_mfma_f32_16x16x32_bf16 v[44:47], v[154:157], v[194:197], v[44:47]
	v_mfma_f32_16x16x32_bf16 v[40:43], v[162:165], v[194:197], v[40:43]
	v_mfma_f32_16x16x32_bf16 v[28:31], v[154:157], v[202:205], v[28:31]
	v_mfma_f32_16x16x32_bf16 v[24:27], v[162:165], v[202:205], v[24:27]
	v_mfma_f32_16x16x32_bf16 v[12:15], v[154:157], v[210:213], v[12:15]
	v_mfma_f32_16x16x32_bf16 v[8:11], v[162:165], v[210:213], v[8:11]
	v_mfma_f32_16x16x32_bf16 v[52:55], v[166:169], v[182:185], v[52:55]
	v_mfma_f32_16x16x32_bf16 v[48:51], v[174:177], v[182:185], v[48:51]
	v_mfma_f32_16x16x32_bf16 v[36:39], v[166:169], v[190:193], v[36:39]
	v_mfma_f32_16x16x32_bf16 v[32:35], v[174:177], v[190:193], v[32:35]
	v_mfma_f32_16x16x32_bf16 v[20:23], v[166:169], v[198:201], v[20:23]
	v_mfma_f32_16x16x32_bf16 v[16:19], v[174:177], v[198:201], v[16:19]
	v_mfma_f32_16x16x32_bf16 v[4:7], v[166:169], v[206:209], v[4:7]
	v_mfma_f32_16x16x32_bf16 v[0:3], v[174:177], v[206:209], v[0:3]
	v_mfma_f32_16x16x32_bf16 v[52:55], v[170:173], v[186:189], v[52:55]
	v_mfma_f32_16x16x32_bf16 v[48:51], v[178:181], v[186:189], v[48:51]
	v_mfma_f32_16x16x32_bf16 v[36:39], v[170:173], v[194:197], v[36:39]
	v_mfma_f32_16x16x32_bf16 v[32:35], v[178:181], v[194:197], v[32:35]
	v_mfma_f32_16x16x32_bf16 v[20:23], v[170:173], v[202:205], v[20:23]
	v_mfma_f32_16x16x32_bf16 v[16:19], v[178:181], v[202:205], v[16:19]
	v_mfma_f32_16x16x32_bf16 v[4:7], v[170:173], v[210:213], v[4:7]
	v_mfma_f32_16x16x32_bf16 v[0:3], v[178:181], v[210:213], v[0:3]
	s_setprio 0
	s_barrier
; #define PG8_STAGE(bufoff, gbase, voff) do { _Pragma("unroll") for (int _i = 0; _i < 2; ++_i) \
;         __builtin_amdgcn_global_load_lds((const unsigned*)((const char*)(gbase) + (voff)[_i]), (PG8_LAS unsigned*)(lds + (bufoff) + ldsw + _i * 8192), 16, 0, 0); } while (0)
; #define PG8_LDA(dst, b, h) do { _Pragma("unroll") for (int m = 0; m < 4; ++m) _Pragma("unroll") for (int k = 0; k < 2; ++k) dst[m][k] = *(const PG8_LAS bf16x8*)(lds + PG8_SA(b, h) + aoff + m * 2048 + k * 1024); } while (0)
; #define PG8_LDB(dst, b, h) do { _Pragma("unroll") for (int n = 0; n < 2; ++n) _Pragma("unroll") for (int k = 0; k < 2; ++k) dst[n][k] = *(const PG8_LAS bf16x8*)(lds + PG8_SB(b, h) + boff + n * 2048 + k * 1024); } while (0)
; #define PG8_MMA(ai, bj, At, Bt) do { __builtin_amdgcn_s_setprio(1); _Pragma("unroll") for (int m = 0; m < 4; ++m) _Pragma("unroll") for (int n = 0; n < 2; ++n) _Pragma("unroll") for (int k = 0; k < 2; ++k) \
;         acc[ai][bj][m][n] = __builtin_amdgcn_mfma_f32_16x16x32_bf16(Bt[n][k], At[m][k], acc[ai][bj][m][n], 0, 0, 0); __builtin_amdgcn_s_setprio(0); } while (0)
; #define PG8_WAIT_V(n) asm volatile("s_waitcnt vmcnt(" #n ")" ::: "memory")
; #define PG8_WAIT_L(n) asm volatile("s_waitcnt lgkmcnt(" #n ")" ::: "memory")
; #define PG8_BAR __builtin_amdgcn_s_barrier()
; #define PG8_SCHED __builtin_amdgcn_sched_barrier(0)
; template <class Epi, class Sched, bool ALIGN_EPI = false, bool SP2 = false>
; __device__ __forceinline__ void gemm_phase(PG8_LAS unsigned char* lds, const Gemm g, const Sched& S, const Epi& E, const int wid) {
;     ...
;         for (int t = 0; t < nt; t += 2) {
;     ...
;             PG8_LDB(B0, 1, 0); PG8_LDB(B1, 1, 1); PG8_SCHED; PG8_LDA(At, 1, 0); PG8_STAGE(PG8_SA(0, 1), a2 + hstep, voffA);
;             PG8_WAIT_V(8); PG8_WAIT_L(0); PG8_BAR; PG8_MMA(0, 0, At, B0); PG8_MMA(0, 1, At, B1); PG8_BAR; PG8_SCHED;
;             PG8_LDA(At, 1, 1); PG8_STAGE(PG8_SB(1, 0), b3, voffB); PG8_STAGE(PG8_SB(1, 1), b3 + hstep, voffB); PG8_STAGE(PG8_SA(1, 0), a3, voffA);
;             PG8_WAIT_V(8); PG8_WAIT_L(0); PG8_BAR; PG8_MMA(1, 0, At, B0); PG8_MMA(1, 1, At, B1); PG8_BAR; PG8_SCHED;
	s_add_i32 s33, 0, 0x18000
	v_add_u32_e32 v153, s33, v148
	s_add_i32 s37, 0, 0x1c000
	ds_read_b128 v[142:145], v153
	ds_read_b128 v[154:157], v153 offset:1024
	ds_read_b128 v[158:161], v153 offset:2048
	ds_read_b128 v[162:165], v153 offset:3072
	v_add_u32_e32 v153, s37, v148
	ds_read_b128 v[166:169], v153
	ds_read_b128 v[170:173], v153 offset:1024
	ds_read_b128 v[174:177], v153 offset:2048
	ds_read_b128 v[178:181], v153 offset:3072
	s_add_u32 s34, s34, s8
	s_addc_u32 s35, s35, s9
	s_mov_b32 m0, s45
	v_lshl_add_u64 v[226:227], s[34:35], 0, v[128:129]
	ds_read_b128 v[182:185], v151 offset:32768
	ds_read_b128 v[186:189], v151 offset:33792
	ds_read_b128 v[190:193], v151 offset:34816
	ds_read_b128 v[194:197], v151 offset:35840
	ds_read_b128 v[198:201], v151 offset:36864
	ds_read_b128 v[202:205], v151 offset:37888
	ds_read_b128 v[206:209], v151 offset:38912
	ds_read_b128 v[210:213], v151 offset:39936
	global_load_lds_dwordx4 v[226:227], off
	v_lshl_add_u64 v[226:227], s[34:35], 0, v[132:133]
	s_mov_b32 m0, s46
	s_nop 0
	global_load_lds_dwordx4 v[226:227], off
	s_waitcnt vmcnt(8)
	s_waitcnt lgkmcnt(0)
	s_setprio 1
	s_barrier
	v_mfma_f32_16x16x32_bf16 v[120:123], v[142:145], v[182:185], v[120:123]
	v_mfma_f32_16x16x32_bf16 v[124:127], v[158:161], v[182:185], v[124:127]
	v_mfma_f32_16x16x32_bf16 v[108:111], v[142:145], v[190:193], v[108:111]
	v_mfma_f32_16x16x32_bf16 v[104:107], v[158:161], v[190:193], v[104:107]
	v_mfma_f32_16x16x32_bf16 v[92:95], v[142:145], v[198:201], v[92:95]
	v_mfma_f32_16x16x32_bf16 v[88:91], v[158:161], v[198:201], v[88:91]
	v_mfma_f32_16x16x32_bf16 v[76:79], v[142:145], v[206:209], v[76:79]
	v_mfma_f32_16x16x32_bf16 v[72:75], v[158:161], v[206:209], v[72:75]
	v_mfma_f32_16x16x32_bf16 v[120:123], v[154:157], v[186:189], v[120:123]
	v_mfma_f32_16x16x32_bf16 v[124:127], v[162:165], v[186:189], v[124:127]
	v_mfma_f32_16x16x32_bf16 v[108:111], v[154:157], v[194:197], v[108:111]
	v_mfma_f32_16x16x32_bf16 v[104:107], v[162:165], v[194:197], v[104:107]
	v_mfma_f32_16x16x32_bf16 v[92:95], v[154:157], v[202:205], v[92:95]
	v_mfma_f32_16x16x32_bf16 v[88:91], v[162:165], v[202:205], v[88:91]
	v_mfma_f32_16x16x32_bf16 v[76:79], v[154:157], v[210:213], v[76:79]
	v_mfma_f32_16x16x32_bf16 v[72:75], v[162:165], v[210:213], v[72:75]
	v_mfma_f32_16x16x32_bf16 v[116:119], v[166:169], v[182:185], v[116:119]
	v_mfma_f32_16x16x32_bf16 v[112:115], v[174:177], v[182:185], v[112:115]
	v_mfma_f32_16x16x32_bf16 v[100:103], v[166:169], v[190:193], v[100:103]
	v_mfma_f32_16x16x32_bf16 v[96:99], v[174:177], v[190:193], v[96:99]
	v_mfma_f32_16x16x32_bf16 v[84:87], v[166:169], v[198:201], v[84:87]
	v_mfma_f32_16x16x32_bf16 v[80:83], v[174:177], v[198:201], v[80:83]
	v_mfma_f32_16x16x32_bf16 v[68:71], v[166:169], v[206:209], v[68:71]
	v_mfma_f32_16x16x32_bf16 v[64:67], v[174:177], v[206:209], v[64:67]
	v_mfma_f32_16x16x32_bf16 v[116:119], v[170:173], v[186:189], v[116:119]
	v_mfma_f32_16x16x32_bf16 v[112:115], v[178:181], v[186:189], v[112:115]
	v_mfma_f32_16x16x32_bf16 v[100:103], v[170:173], v[194:197], v[100:103]
	v_mfma_f32_16x16x32_bf16 v[96:99], v[178:181], v[194:197], v[96:99]
	v_mfma_f32_16x16x32_bf16 v[84:87], v[170:173], v[202:205], v[84:87]
	v_mfma_f32_16x16x32_bf16 v[80:83], v[178:181], v[202:205], v[80:83]
	v_mfma_f32_16x16x32_bf16 v[68:71], v[170:173], v[210:213], v[68:71]
	v_mfma_f32_16x16x32_bf16 v[64:67], v[178:181], v[210:213], v[64:67]
	s_setprio 0
	s_barrier
	s_add_i32 s33, s33, s42
	v_lshl_add_u64 v[214:215], v[214:215], 0, s[22:23]
	s_mov_b32 m0, s33
	ds_read_b128 v[182:185], v151 offset:49152
	ds_read_b128 v[186:189], v151 offset:50176
	ds_read_b128 v[190:193], v151 offset:51200
	ds_read_b128 v[194:197], v151 offset:52224
	ds_read_b128 v[198:201], v151 offset:53248
	ds_read_b128 v[202:205], v151 offset:54272
	ds_read_b128 v[206:209], v151 offset:55296
	ds_read_b128 v[210:213], v151 offset:56320
	global_load_lds_dwordx4 v[214:215], off
	v_lshl_add_u64 v[214:215], v[216:217], 0, s[22:23]
	s_add_i32 m0, s33, 0x2000
	s_add_i32 s33, s37, s42
	global_load_lds_dwordx4 v[214:215], off
	v_lshl_add_u64 v[214:215], v[218:219], 0, s[22:23]
	s_mov_b32 m0, s33
	s_nop 0
	global_load_lds_dwordx4 v[214:215], off
	v_lshl_add_u64 v[214:215], v[220:221], 0, s[22:23]
	s_add_i32 m0, s33, 0x2000
	s_nop 0
	global_load_lds_dwordx4 v[214:215], off
	v_lshl_add_u64 v[214:215], v[222:223], 0, s[22:23]
	s_mov_b32 m0, s47
	s_nop 0
	global_load_lds_dwordx4 v[214:215], off
	v_lshl_add_u64 v[214:215], v[224:225], 0, s[22:23]
	s_mov_b32 m0, s49
	s_nop 0
	global_load_lds_dwordx4 v[214:215], off
	s_waitcnt vmcnt(8)
	s_waitcnt lgkmcnt(0)
	s_setprio 1
	s_barrier
	v_mfma_f32_16x16x32_bf16 v[60:63], v[142:145], v[182:185], v[60:63]
	v_mfma_f32_16x16x32_bf16 v[56:59], v[158:161], v[182:185], v[56:59]
	v_mfma_f32_16x16x32_bf16 v[44:47], v[142:145], v[190:193], v[44:47]
	v_mfma_f32_16x16x32_bf16 v[40:43], v[158:161], v[190:193], v[40:43]
	v_mfma_f32_16x16x32_bf16 v[28:31], v[142:145], v[198:201], v[28:31]
	v_mfma_f32_16x16x32_bf16 v[24:27], v[158:161], v[198:201], v[24:27]
	v_mfma_f32_16x16x32_bf16 v[12:15], v[142:145], v[206:209], v[12:15]
	v_mfma_f32_16x16x32_bf16 v[8:11], v[158:161], v[206:209], v[8:11]
	v_mfma_f32_16x16x32_bf16 v[60:63], v[154:157], v[186:189], v[60:63]
	v_mfma_f32_16x16x32_bf16 v[56:59], v[162:165], v[186:189], v[56:59]
	v_mfma_f32_16x16x32_bf16 v[44:47], v[154:157], v[194:197], v[44:47]
	v_mfma_f32_16x16x32_bf16 v[40:43], v[162:165], v[194:197], v[40:43]
	v_mfma_f32_16x16x32_bf16 v[28:31], v[154:157], v[202:205], v[28:31]
	v_mfma_f32_16x16x32_bf16 v[24:27], v[162:165], v[202:205], v[24:27]
	v_mfma_f32_16x16x32_bf16 v[12:15], v[154:157], v[210:213], v[12:15]
	v_mfma_f32_16x16x32_bf16 v[8:11], v[162:165], v[210:213], v[8:11]
	v_mfma_f32_16x16x32_bf16 v[52:55], v[166:169], v[182:185], v[52:55]
	v_mfma_f32_16x16x32_bf16 v[48:51], v[174:177], v[182:185], v[48:51]
	v_mfma_f32_16x16x32_bf16 v[36:39], v[166:169], v[190:193], v[36:39]
	v_mfma_f32_16x16x32_bf16 v[32:35], v[174:177], v[190:193], v[32:35]
	v_mfma_f32_16x16x32_bf16 v[20:23], v[166:169], v[198:201], v[20:23]
	v_mfma_f32_16x16x32_bf16 v[16:19], v[174:177], v[198:201], v[16:19]
	v_mfma_f32_16x16x32_bf16 v[4:7], v[166:169], v[206:209], v[4:7]
	v_mfma_f32_16x16x32_bf16 v[0:3], v[174:177], v[206:209], v[0:3]
	v_mfma_f32_16x16x32_bf16 v[52:55], v[170:173], v[186:189], v[52:55]
	v_mfma_f32_16x16x32_bf16 v[48:51], v[178:181], v[186:189], v[48:51]
	v_mfma_f32_16x16x32_bf16 v[36:39], v[170:173], v[194:197], v[36:39]
	v_mfma_f32_16x16x32_bf16 v[32:35], v[178:181], v[194:197], v[32:35]
	v_mfma_f32_16x16x32_bf16 v[20:23], v[170:173], v[202:205], v[20:23]
	v_mfma_f32_16x16x32_bf16 v[16:19], v[178:181], v[202:205], v[16:19]
	v_mfma_f32_16x16x32_bf16 v[4:7], v[170:173], v[210:213], v[4:7]
	v_mfma_f32_16x16x32_bf16 v[0:3], v[178:181], v[210:213], v[0:3]
	s_setprio 0
	s_barrier
	s_add_u32 s4, s4, 0x100
	s_addc_u32 s5, s5, 0
	s_add_u32 s0, s0, 0x100
	s_addc_u32 s1, s1, 0
	s_cmp_ge_i32 s36, s51
	s_mov_b32 s34, s36
	s_cbranch_scc0 .LBB0_1339

; #define PG8_STAGE(bufoff, gbase, voff) do { _Pragma("unroll") for (int _i = 0; _i < 2; ++_i) \
;         __builtin_amdgcn_global_load_lds((const unsigned*)((const char*)(gbase) + (voff)[_i]), (PG8_LAS unsigned*)(lds + (bufoff) + ldsw + _i * 8192), 16, 0, 0); } while (0)
; #define PG8_LDA(dst, b, h) do { _Pragma("unroll") for (int m = 0; m < 4; ++m) _Pragma("unroll") for (int k = 0; k < 2; ++k) dst[m][k] = *(const PG8_LAS bf16x8*)(lds + PG8_SA(b, h) + aoff + m * 2048 + k * 1024); } while (0)
; #define PG8_LDB(dst, b, h) do { _Pragma("unroll") for (int n = 0; n < 2; ++n) _Pragma("unroll") for (int k = 0; k < 2; ++k) dst[n][k] = *(const PG8_LAS bf16x8*)(lds + PG8_SB(b, h) + boff + n * 2048 + k * 1024); } while (0)
; #define PG8_WAIT_V(n) asm volatile("s_waitcnt vmcnt(" #n ")" ::: "memory")
; #define PG8_WAIT_L(n) asm volatile("s_waitcnt lgkmcnt(" #n ")" ::: "memory")
; #define PG8_BAR __builtin_amdgcn_s_barrier()
; #define PG8_SCHED __builtin_amdgcn_sched_barrier(0)
; template <class Epi, class Sched, bool ALIGN_EPI = false, bool SP2 = false>
; __device__ __forceinline__ void gemm_phase(PG8_LAS unsigned char* lds, const Gemm g, const Sched& S, const Epi& E, const int wid) {
;     ...
;         const bool has_next = S.next(ui + 1, nxt);
;         const char* nA = has_next ? (const char*)g.A + (size_t)nxt.pm * tstep : cA; const char* nB = has_next ? (const char*)g.Bt + (size_t)nxt.pn * tstep : cB;
;         for (int t = 0; t < nt; t += 2) {
;             const bool last = (t == nt - 2);
;             const char* a1 = cA + (size_t)(t + 1) * kstep;
;             const char* a2 = last ? nA : cA + (size_t)(t + 2) * kstep; const char* b2 = last ? nB : cB + (size_t)(t + 2) * kstep;
;             const char* a3 = a2 + kstep; const char* b3 = b2 + kstep;
;             if (last && has_next) S.a_ready(nxt);
;             if constexpr (SP2) {
;             PG8_LDB(B0, 0, 0); PG8_LDB(B1, 0, 1); PG8_SCHED; PG8_LDA(At, 0, 0); PG8_STAGE(PG8_SA(1, 1), a1 + hstep, voffA);
;             PG8_WAIT_V(8); PG8_WAIT_L(0); PG8_BAR; PG8_MMA(0, 0, At, B0); PG8_MMA(0, 1, At, B1); PG8_BAR; PG8_SCHED;
;             PG8_LDA(At, 0, 1); PG8_STAGE(PG8_SB(0, 0), b2, voffB); PG8_STAGE(PG8_SB(0, 1), b2 + hstep, voffB); PG8_STAGE(PG8_SA(0, 0), a2, voffA);
;             PG8_WAIT_V(8); PG8_WAIT_L(0); PG8_BAR; PG8_MMA(1, 0, At, B0); PG8_MMA(1, 1, At, B1); PG8_BAR; PG8_SCHED;
.LBB0_1493:
	s_andn2_b64 vcc, exec, s[22:23]
	s_cbranch_vccnz .Lz_FFN1
	s_add_u32 s4, s8, 0x80
	s_addc_u32 s5, s9, 0
	s_add_u32 s0, s6, 0x100
	s_addc_u32 s1, s7, 0
	s_mov_b32 s6, 0
	ds_read_b128 v[142:145], v149
	ds_read_b128 v[152:155], v149 offset:1024
	ds_read_b128 v[156:159], v149 offset:2048
	ds_read_b128 v[160:163], v149 offset:3072
	ds_read_b128 v[164:167], v150
	ds_read_b128 v[168:171], v150 offset:1024
	ds_read_b128 v[172:175], v150 offset:2048
	ds_read_b128 v[176:179], v150 offset:3072
	s_add_i32 s8, s6, 2
	s_add_u32 s9, s4, 0x80
	s_addc_u32 s7, s5, 0
	s_cmp_eq_u32 s55, s6
	s_cselect_b32 s6, s26, s9
	s_cselect_b32 s7, s27, s7
	s_cselect_b32 s65, s29, s1
	s_cselect_b32 s64, s28, s0
	v_lshl_add_u64 v[212:213], s[4:5], 0, v[136:137]
	s_add_i32 m0, s44, 0xc000
	ds_read_b128 v[180:183], v151
	ds_read_b128 v[184:187], v151 offset:1024
	ds_read_b128 v[188:191], v151 offset:2048
	ds_read_b128 v[192:195], v151 offset:3072
	ds_read_b128 v[196:199], v151 offset:4096
	ds_read_b128 v[200:203], v151 offset:5120
	ds_read_b128 v[204:207], v151 offset:6144
	ds_read_b128 v[208:211], v151 offset:7168
	global_load_lds_dwordx4 v[212:213], off
	v_lshl_add_u64 v[212:213], s[4:5], 0, v[138:139]
	s_add_i32 m0, s44, 0xe000
	s_nop 0
	global_load_lds_dwordx4 v[212:213], off
	s_waitcnt vmcnt(8)
	s_waitcnt lgkmcnt(0)
	s_setprio 1
	s_barrier
	v_mfma_f32_16x16x32_bf16 v[120:123], v[142:145], v[180:183], 0
	v_mfma_f32_16x16x32_bf16 v[112:115], v[156:159], v[180:183], 0
	v_mfma_f32_16x16x32_bf16 v[104:107], v[142:145], v[188:191], 0
	v_mfma_f32_16x16x32_bf16 v[96:99], v[156:159], v[188:191], 0
	v_mfma_f32_16x16x32_bf16 v[88:91], v[142:145], v[196:199], 0
	v_mfma_f32_16x16x32_bf16 v[80:83], v[156:159], v[196:199], 0
	v_mfma_f32_16x16x32_bf16 v[72:75], v[142:145], v[204:207], 0
	v_mfma_f32_16x16x32_bf16 v[64:67], v[156:159], v[204:207], 0
	v_mfma_f32_16x16x32_bf16 v[120:123], v[152:155], v[184:187], v[120:123]
	v_mfma_f32_16x16x32_bf16 v[112:115], v[160:163], v[184:187], v[112:115]
	v_mfma_f32_16x16x32_bf16 v[104:107], v[152:155], v[192:195], v[104:107]
	v_mfma_f32_16x16x32_bf16 v[96:99], v[160:163], v[192:195], v[96:99]
	v_mfma_f32_16x16x32_bf16 v[88:91], v[152:155], v[200:203], v[88:91]
	v_mfma_f32_16x16x32_bf16 v[80:83], v[160:163], v[200:203], v[80:83]
	v_mfma_f32_16x16x32_bf16 v[72:75], v[152:155], v[208:211], v[72:75]
	v_mfma_f32_16x16x32_bf16 v[64:67], v[160:163], v[208:211], v[64:67]
	v_mfma_f32_16x16x32_bf16 v[124:127], v[164:167], v[180:183], 0
	v_mfma_f32_16x16x32_bf16 v[116:119], v[172:175], v[180:183], 0
	v_mfma_f32_16x16x32_bf16 v[108:111], v[164:167], v[188:191], 0
	v_mfma_f32_16x16x32_bf16 v[100:103], v[172:175], v[188:191], 0
	v_mfma_f32_16x16x32_bf16 v[92:95], v[164:167], v[196:199], 0
	v_mfma_f32_16x16x32_bf16 v[84:87], v[172:175], v[196:199], 0
	v_mfma_f32_16x16x32_bf16 v[76:79], v[164:167], v[204:207], 0
	v_mfma_f32_16x16x32_bf16 v[68:71], v[172:175], v[204:207], 0
	v_mfma_f32_16x16x32_bf16 v[124:127], v[168:171], v[184:187], v[124:127]
	v_mfma_f32_16x16x32_bf16 v[116:119], v[176:179], v[184:187], v[116:119]
	v_mfma_f32_16x16x32_bf16 v[108:111], v[168:171], v[192:195], v[108:111]
	v_mfma_f32_16x16x32_bf16 v[100:103], v[176:179], v[192:195], v[100:103]
	v_mfma_f32_16x16x32_bf16 v[92:95], v[168:171], v[200:203], v[92:95]
	v_mfma_f32_16x16x32_bf16 v[84:87], v[176:179], v[200:203], v[84:87]
	v_mfma_f32_16x16x32_bf16 v[76:79], v[168:171], v[208:211], v[76:79]
	v_mfma_f32_16x16x32_bf16 v[68:71], v[176:179], v[208:211], v[68:71]
	s_setprio 0
	s_barrier
	s_add_i32 s9, s57, s36
	v_lshl_add_u64 v[212:213], s[64:65], 0, v[132:133]
	s_mov_b32 m0, s9
	ds_read_b128 v[180:183], v151 offset:16384
	ds_read_b128 v[184:187], v151 offset:17408
	ds_read_b128 v[188:191], v151 offset:18432
	ds_read_b128 v[192:195], v151 offset:19456
	ds_read_b128 v[196:199], v151 offset:20480
	ds_read_b128 v[200:203], v151 offset:21504
	ds_read_b128 v[204:207], v151 offset:22528
	ds_read_b128 v[208:211], v151 offset:23552
	global_load_lds_dwordx4 v[212:213], off
	s_add_i32 m0, s9, 0x2000
	v_lshl_add_u64 v[214:215], s[64:65], 0, v[128:129]
	s_add_u32 s64, s64, s12
	s_addc_u32 s65, s65, s13
	s_add_i32 s9, s58, s36
	global_load_lds_dwordx4 v[214:215], off
	v_lshl_add_u64 v[216:217], s[64:65], 0, v[132:133]
	s_mov_b32 m0, s9
	v_lshl_add_u64 v[218:219], s[64:65], 0, v[128:129]
	global_load_lds_dwordx4 v[216:217], off
	s_add_i32 m0, s9, 0x2000
	v_lshl_add_u64 v[220:221], s[6:7], 0, v[134:135]
	global_load_lds_dwordx4 v[218:219], off
	s_mov_b32 m0, s44
	v_lshl_add_u64 v[222:223], s[6:7], 0, v[130:131]
	global_load_lds_dwordx4 v[220:221], off
	s_mov_b32 m0, s45
	s_nop 0
	global_load_lds_dwordx4 v[222:223], off
	s_waitcnt vmcnt(8)
	s_waitcnt lgkmcnt(0)
	s_setprio 1
	s_barrier
; #define PG8_STAGE(bufoff, gbase, voff) do { _Pragma("unroll") for (int _i = 0; _i < 2; ++_i) \
;         __builtin_amdgcn_global_load_lds((const unsigned*)((const char*)(gbase) + (voff)[_i]), (PG8_LAS unsigned*)(lds + (bufoff) + ldsw + _i * 8192), 16, 0, 0); } while (0)
; #define PG8_LDA(dst, b, h) do { _Pragma("unroll") for (int m = 0; m < 4; ++m) _Pragma("unroll") for (int k = 0; k < 2; ++k) dst[m][k] = *(const PG8_LAS bf16x8*)(lds + PG8_SA(b, h) + aoff + m * 2048 + k * 1024); } while (0)
; #define PG8_LDB(dst, b, h) do { _Pragma("unroll") for (int n = 0; n < 2; ++n) _Pragma("unroll") for (int k = 0; k < 2; ++k) dst[n][k] = *(const PG8_LAS bf16x8*)(lds + PG8_SB(b, h) + boff + n * 2048 + k * 1024); } while (0)
; #define PG8_MMA(ai, bj, At, Bt) do { __builtin_amdgcn_s_setprio(1); _Pragma("unroll") for (int m = 0; m < 4; ++m) _Pragma("unroll") for (int n = 0; n < 2; ++n) _Pragma("unroll") for (int k = 0; k < 2; ++k) \
;         acc[ai][bj][m][n] = __builtin_amdgcn_mfma_f32_16x16x32_bf16(Bt[n][k], At[m][k], acc[ai][bj][m][n], 0, 0, 0); __builtin_amdgcn_s_setprio(0); } while (0)
; #define PG8_WAIT_V(n) asm volatile("s_waitcnt vmcnt(" #n ")" ::: "memory")
; #define PG8_WAIT_L(n) asm volatile("s_waitcnt lgkmcnt(" #n ")" ::: "memory")
; #define PG8_BAR __builtin_amdgcn_s_barrier()
; #define PG8_SCHED __builtin_amdgcn_sched_barrier(0)
; template <class Epi, class Sched, bool ALIGN_EPI = false, bool SP2 = false>
; __device__ __forceinline__ void gemm_phase(PG8_LAS unsigned char* lds, const Gemm g, const Sched& S, const Epi& E, const int wid) {
;     ...
;             PG8_WAIT_V(8); PG8_WAIT_L(0); PG8_BAR; PG8_MMA(0, 0, At, B0); PG8_MMA(0, 1, At, B1); PG8_BAR; PG8_SCHED;
;             PG8_LDA(At, 0, 1); PG8_STAGE(PG8_SB(0, 0), b2, voffB); PG8_STAGE(PG8_SB(0, 1), b2 + hstep, voffB); PG8_STAGE(PG8_SA(0, 0), a2, voffA);
;             PG8_WAIT_V(8); PG8_WAIT_L(0); PG8_BAR; PG8_MMA(1, 0, At, B0); PG8_MMA(1, 1, At, B1); PG8_BAR; PG8_SCHED;
;             PG8_LDB(B0, 1, 0); PG8_LDB(B1, 1, 1); PG8_SCHED; PG8_LDA(At, 1, 0); PG8_STAGE(PG8_SA(0, 1), a2 + hstep, voffA);
	v_mfma_f32_16x16x32_bf16 v[56:59], v[142:145], v[180:183], 0
	v_mfma_f32_16x16x32_bf16 v[48:51], v[156:159], v[180:183], 0
	v_mfma_f32_16x16x32_bf16 v[40:43], v[142:145], v[188:191], 0
	v_mfma_f32_16x16x32_bf16 v[32:35], v[156:159], v[188:191], 0
	v_mfma_f32_16x16x32_bf16 v[24:27], v[142:145], v[196:199], 0
	v_mfma_f32_16x16x32_bf16 v[16:19], v[156:159], v[196:199], 0
	v_mfma_f32_16x16x32_bf16 v[8:11], v[142:145], v[204:207], 0
	v_mfma_f32_16x16x32_bf16 v[4:7], v[156:159], v[204:207], 0
	v_mfma_f32_16x16x32_bf16 v[56:59], v[152:155], v[184:187], v[56:59]
	v_mfma_f32_16x16x32_bf16 v[48:51], v[160:163], v[184:187], v[48:51]
	v_mfma_f32_16x16x32_bf16 v[40:43], v[152:155], v[192:195], v[40:43]
	v_mfma_f32_16x16x32_bf16 v[32:35], v[160:163], v[192:195], v[32:35]
	v_mfma_f32_16x16x32_bf16 v[24:27], v[152:155], v[200:203], v[24:27]
	v_mfma_f32_16x16x32_bf16 v[16:19], v[160:163], v[200:203], v[16:19]
	v_mfma_f32_16x16x32_bf16 v[8:11], v[152:155], v[208:211], v[8:11]
	v_mfma_f32_16x16x32_bf16 v[4:7], v[160:163], v[208:211], v[4:7]
	v_mfma_f32_16x16x32_bf16 v[60:63], v[164:167], v[180:183], 0
	v_mfma_f32_16x16x32_bf16 v[52:55], v[172:175], v[180:183], 0
	v_mfma_f32_16x16x32_bf16 v[44:47], v[164:167], v[188:191], 0
	v_mfma_f32_16x16x32_bf16 v[36:39], v[172:175], v[188:191], 0
	v_mfma_f32_16x16x32_bf16 v[28:31], v[164:167], v[196:199], 0
	v_mfma_f32_16x16x32_bf16 v[20:23], v[172:175], v[196:199], 0
	v_mfma_f32_16x16x32_bf16 v[12:15], v[164:167], v[204:207], 0
	v_mfma_f32_16x16x32_bf16 v[0:3], v[172:175], v[204:207], 0
	v_mfma_f32_16x16x32_bf16 v[60:63], v[168:171], v[184:187], v[60:63]
	v_mfma_f32_16x16x32_bf16 v[52:55], v[176:179], v[184:187], v[52:55]
	v_mfma_f32_16x16x32_bf16 v[44:47], v[168:171], v[192:195], v[44:47]
	v_mfma_f32_16x16x32_bf16 v[36:39], v[176:179], v[192:195], v[36:39]
	v_mfma_f32_16x16x32_bf16 v[28:31], v[168:171], v[200:203], v[28:31]
	v_mfma_f32_16x16x32_bf16 v[20:23], v[176:179], v[200:203], v[20:23]
	v_mfma_f32_16x16x32_bf16 v[12:15], v[168:171], v[208:211], v[12:15]
	v_mfma_f32_16x16x32_bf16 v[0:3], v[176:179], v[208:211], v[0:3]
	s_setprio 0
	s_barrier
	s_add_i32 s9, 0, 0x18000
	s_add_i32 s33, 0, 0x1c000
	v_add_u32_e32 v160, s9, v148
	v_add_u32_e32 v176, s33, v148
	ds_read_b128 v[142:145], v160
	ds_read_b128 v[152:155], v160 offset:1024
	ds_read_b128 v[156:159], v160 offset:2048
	ds_read_b128 v[160:163], v160 offset:3072
	ds_read_b128 v[164:167], v176
	ds_read_b128 v[168:171], v176 offset:1024
	ds_read_b128 v[172:175], v176 offset:2048
	ds_read_b128 v[176:179], v176 offset:3072
	s_add_u32 s6, s6, s12
	s_addc_u32 s7, s7, s13
	s_mov_b32 m0, s46
	v_lshl_add_u64 v[224:225], s[6:7], 0, v[134:135]
	ds_read_b128 v[180:183], v151 offset:32768
	ds_read_b128 v[184:187], v151 offset:33792
	ds_read_b128 v[188:191], v151 offset:34816
	ds_read_b128 v[192:195], v151 offset:35840
	ds_read_b128 v[196:199], v151 offset:36864
	ds_read_b128 v[200:203], v151 offset:37888
	ds_read_b128 v[204:207], v151 offset:38912
	ds_read_b128 v[208:211], v151 offset:39936
	global_load_lds_dwordx4 v[224:225], off
	v_lshl_add_u64 v[224:225], s[6:7], 0, v[130:131]
	s_mov_b32 m0, s47
	s_nop 0
	global_load_lds_dwordx4 v[224:225], off
	s_waitcnt vmcnt(8)
	s_waitcnt lgkmcnt(0)
	s_setprio 1
	s_barrier
	v_mfma_f32_16x16x32_bf16 v[120:123], v[142:145], v[180:183], v[120:123]
	v_mfma_f32_16x16x32_bf16 v[112:115], v[156:159], v[180:183], v[112:115]
	v_mfma_f32_16x16x32_bf16 v[104:107], v[142:145], v[188:191], v[104:107]
	v_mfma_f32_16x16x32_bf16 v[96:99], v[156:159], v[188:191], v[96:99]
	v_mfma_f32_16x16x32_bf16 v[88:91], v[142:145], v[196:199], v[88:91]
	v_mfma_f32_16x16x32_bf16 v[80:83], v[156:159], v[196:199], v[80:83]
	v_mfma_f32_16x16x32_bf16 v[72:75], v[142:145], v[204:207], v[72:75]
	v_mfma_f32_16x16x32_bf16 v[64:67], v[156:159], v[204:207], v[64:67]
	v_mfma_f32_16x16x32_bf16 v[120:123], v[152:155], v[184:187], v[120:123]
	v_mfma_f32_16x16x32_bf16 v[112:115], v[160:163], v[184:187], v[112:115]
	v_mfma_f32_16x16x32_bf16 v[104:107], v[152:155], v[192:195], v[104:107]
	v_mfma_f32_16x16x32_bf16 v[96:99], v[160:163], v[192:195], v[96:99]
	v_mfma_f32_16x16x32_bf16 v[88:91], v[152:155], v[200:203], v[88:91]
	v_mfma_f32_16x16x32_bf16 v[80:83], v[160:163], v[200:203], v[80:83]
	v_mfma_f32_16x16x32_bf16 v[72:75], v[152:155], v[208:211], v[72:75]
	v_mfma_f32_16x16x32_bf16 v[64:67], v[160:163], v[208:211], v[64:67]
	v_mfma_f32_16x16x32_bf16 v[124:127], v[164:167], v[180:183], v[124:127]
	v_mfma_f32_16x16x32_bf16 v[116:119], v[172:175], v[180:183], v[116:119]
	v_mfma_f32_16x16x32_bf16 v[108:111], v[164:167], v[188:191], v[108:111]
	v_mfma_f32_16x16x32_bf16 v[100:103], v[172:175], v[188:191], v[100:103]
	v_mfma_f32_16x16x32_bf16 v[92:95], v[164:167], v[196:199], v[92:95]
	v_mfma_f32_16x16x32_bf16 v[84:87], v[172:175], v[196:199], v[84:87]
	v_mfma_f32_16x16x32_bf16 v[76:79], v[164:167], v[204:207], v[76:79]
	v_mfma_f32_16x16x32_bf16 v[68:71], v[172:175], v[204:207], v[68:71]
	v_mfma_f32_16x16x32_bf16 v[124:127], v[168:171], v[184:187], v[124:127]
	v_mfma_f32_16x16x32_bf16 v[116:119], v[176:179], v[184:187], v[116:119]
	v_mfma_f32_16x16x32_bf16 v[108:111], v[168:171], v[192:195], v[108:111]
	v_mfma_f32_16x16x32_bf16 v[100:103], v[176:179], v[192:195], v[100:103]
	v_mfma_f32_16x16x32_bf16 v[92:95], v[168:171], v[200:203], v[92:95]
	v_mfma_f32_16x16x32_bf16 v[84:87], v[176:179], v[200:203], v[84:87]
	v_mfma_f32_16x16x32_bf16 v[76:79], v[168:171], v[208:211], v[76:79]
	v_mfma_f32_16x16x32_bf16 v[68:71], v[176:179], v[208:211], v[68:71]
	s_setprio 0
	s_barrier
; #define PG8_STAGE(bufoff, gbase, voff) do { _Pragma("unroll") for (int _i = 0; _i < 2; ++_i) \
;         __builtin_amdgcn_global_load_lds((const unsigned*)((const char*)(gbase) + (voff)[_i]), (PG8_LAS unsigned*)(lds + (bufoff) + ldsw + _i * 8192), 16, 0, 0); } while (0)
; #define PG8_LDA(dst, b, h) do { _Pragma("unroll") for (int m = 0; m < 4; ++m) _Pragma("unroll") for (int k = 0; k < 2; ++k) dst[m][k] = *(const PG8_LAS bf16x8*)(lds + PG8_SA(b, h) + aoff + m * 2048 + k * 1024); } while (0)
; #define PG8_WAIT_V(n) asm volatile("s_waitcnt vmcnt(" #n ")" ::: "memory")
; #define PG8_WAIT_L(n) asm volatile("s_waitcnt lgkmcnt(" #n ")" ::: "memory")
; #define PG8_BAR __builtin_amdgcn_s_barrier()
; template <class Epi, class Sched, bool ALIGN_EPI = false, bool SP2 = false>
; __device__ __forceinline__ void gemm_phase(PG8_LAS unsigned char* lds, const Gemm g, const Sched& S, const Epi& E, const int wid) {
;     ...
;         for (int t = 0; t < nt; t += 2) {
;             const bool last = (t == nt - 2);
;             const char* a1 = cA + (size_t)(t + 1) * kstep;
;             const char* a2 = last ? nA : cA + (size_t)(t + 2) * kstep; const char* b2 = last ? nB : cB + (size_t)(t + 2) * kstep;
;             const char* a3 = a2 + kstep; const char* b3 = b2 + kstep;
;             if (last && has_next) S.a_ready(nxt);
;             if constexpr (SP2) {
;             PG8_LDB(B0, 0, 0); PG8_LDB(B1, 0, 1); PG8_SCHED; PG8_LDA(At, 0, 0); PG8_STAGE(PG8_SA(1, 1), a1 + hstep, voffA);
;             PG8_WAIT_V(8); PG8_WAIT_L(0); PG8_BAR; PG8_MMA(0, 0, At, B0); PG8_MMA(0, 1, At, B1); PG8_BAR; PG8_SCHED;
;             PG8_LDA(At, 0, 1); PG8_STAGE(PG8_SB(0, 0), b2, voffB); PG8_STAGE(PG8_SB(0, 1), b2 + hstep, voffB); PG8_STAGE(PG8_SA(0, 0), a2, voffA);
;             PG8_WAIT_V(8); PG8_WAIT_L(0); PG8_BAR; PG8_MMA(1, 0, At, B0); PG8_MMA(1, 1, At, B1); PG8_BAR; PG8_SCHED;
;             PG8_LDB(B0, 1, 0); PG8_LDB(B1, 1, 1); PG8_SCHED; PG8_LDA(At, 1, 0); PG8_STAGE(PG8_SA(0, 1), a2 + hstep, voffA);
;             PG8_WAIT_V(8); PG8_WAIT_L(0); PG8_BAR; PG8_MMA(0, 0, At, B0); PG8_MMA(0, 1, At, B1); PG8_BAR; PG8_SCHED;
;             PG8_LDA(At, 1, 1); PG8_STAGE(PG8_SB(1, 0), b3, voffB); PG8_STAGE(PG8_SB(1, 1), b3 + hstep, voffB); PG8_STAGE(PG8_SA(1, 0), a3, voffA);
;             PG8_WAIT_V(8); PG8_WAIT_L(0); PG8_BAR; PG8_MMA(1, 0, At, B0); PG8_MMA(1, 1, At, B1); PG8_BAR; PG8_SCHED;
	s_add_i32 s6, s9, s36
	v_lshl_add_u64 v[212:213], v[212:213], 0, s[20:21]
	s_mov_b32 m0, s6
	ds_read_b128 v[180:183], v151 offset:49152
	ds_read_b128 v[184:187], v151 offset:50176
	ds_read_b128 v[188:191], v151 offset:51200
	ds_read_b128 v[192:195], v151 offset:52224
	ds_read_b128 v[196:199], v151 offset:53248
	ds_read_b128 v[200:203], v151 offset:54272
	ds_read_b128 v[204:207], v151 offset:55296
	ds_read_b128 v[208:211], v151 offset:56320
	global_load_lds_dwordx4 v[212:213], off
	v_lshl_add_u64 v[212:213], v[214:215], 0, s[20:21]
	s_add_i32 m0, s6, 0x2000
	s_add_i32 s6, s33, s36
	global_load_lds_dwordx4 v[212:213], off
	v_lshl_add_u64 v[212:213], v[216:217], 0, s[20:21]
	s_mov_b32 m0, s6
	s_nop 0
	global_load_lds_dwordx4 v[212:213], off
	v_lshl_add_u64 v[212:213], v[218:219], 0, s[20:21]
	s_add_i32 m0, s6, 0x2000
	s_nop 0
	global_load_lds_dwordx4 v[212:213], off
	v_lshl_add_u64 v[212:213], v[220:221], 0, s[20:21]
	s_mov_b32 m0, s50
	s_nop 0
	global_load_lds_dwordx4 v[212:213], off
	v_lshl_add_u64 v[212:213], v[222:223], 0, s[20:21]
	s_mov_b32 m0, s51
	s_nop 0
	global_load_lds_dwordx4 v[212:213], off
	s_waitcnt vmcnt(8)
	s_waitcnt lgkmcnt(0)
	s_setprio 1
	s_barrier
	v_mfma_f32_16x16x32_bf16 v[56:59], v[142:145], v[180:183], v[56:59]
	v_mfma_f32_16x16x32_bf16 v[48:51], v[156:159], v[180:183], v[48:51]
	v_mfma_f32_16x16x32_bf16 v[40:43], v[142:145], v[188:191], v[40:43]
	v_mfma_f32_16x16x32_bf16 v[32:35], v[156:159], v[188:191], v[32:35]
	v_mfma_f32_16x16x32_bf16 v[24:27], v[142:145], v[196:199], v[24:27]
	v_mfma_f32_16x16x32_bf16 v[16:19], v[156:159], v[196:199], v[16:19]
	v_mfma_f32_16x16x32_bf16 v[8:11], v[142:145], v[204:207], v[8:11]
	v_mfma_f32_16x16x32_bf16 v[4:7], v[156:159], v[204:207], v[4:7]
	v_mfma_f32_16x16x32_bf16 v[56:59], v[152:155], v[184:187], v[56:59]
	v_mfma_f32_16x16x32_bf16 v[48:51], v[160:163], v[184:187], v[48:51]
	v_mfma_f32_16x16x32_bf16 v[40:43], v[152:155], v[192:195], v[40:43]
	v_mfma_f32_16x16x32_bf16 v[32:35], v[160:163], v[192:195], v[32:35]
	v_mfma_f32_16x16x32_bf16 v[24:27], v[152:155], v[200:203], v[24:27]
	v_mfma_f32_16x16x32_bf16 v[16:19], v[160:163], v[200:203], v[16:19]
	v_mfma_f32_16x16x32_bf16 v[8:11], v[152:155], v[208:211], v[8:11]
	v_mfma_f32_16x16x32_bf16 v[4:7], v[160:163], v[208:211], v[4:7]
	v_mfma_f32_16x16x32_bf16 v[60:63], v[164:167], v[180:183], v[60:63]
	v_mfma_f32_16x16x32_bf16 v[52:55], v[172:175], v[180:183], v[52:55]
	v_mfma_f32_16x16x32_bf16 v[44:47], v[164:167], v[188:191], v[44:47]
	v_mfma_f32_16x16x32_bf16 v[36:39], v[172:175], v[188:191], v[36:39]
	v_mfma_f32_16x16x32_bf16 v[28:31], v[164:167], v[196:199], v[28:31]
	v_mfma_f32_16x16x32_bf16 v[20:23], v[172:175], v[196:199], v[20:23]
	v_mfma_f32_16x16x32_bf16 v[12:15], v[164:167], v[204:207], v[12:15]
	v_mfma_f32_16x16x32_bf16 v[0:3], v[172:175], v[204:207], v[0:3]
	v_mfma_f32_16x16x32_bf16 v[60:63], v[168:171], v[184:187], v[60:63]
	v_mfma_f32_16x16x32_bf16 v[52:55], v[176:179], v[184:187], v[52:55]
	v_mfma_f32_16x16x32_bf16 v[44:47], v[168:171], v[192:195], v[44:47]
	v_mfma_f32_16x16x32_bf16 v[36:39], v[176:179], v[192:195], v[36:39]
	v_mfma_f32_16x16x32_bf16 v[28:31], v[168:171], v[200:203], v[28:31]
	v_mfma_f32_16x16x32_bf16 v[20:23], v[176:179], v[200:203], v[20:23]
	v_mfma_f32_16x16x32_bf16 v[12:15], v[168:171], v[208:211], v[12:15]
	v_mfma_f32_16x16x32_bf16 v[0:3], v[176:179], v[208:211], v[0:3]
	s_setprio 0
	s_barrier
	s_add_u32 s4, s4, 0x100
	s_addc_u32 s5, s5, 0
	s_add_u32 s0, s0, 0x100
	s_addc_u32 s1, s1, 0
	s_cmp_ge_i32 s8, s52
	s_mov_b32 s6, s8
	s_cbranch_scc1 .LBB0_1496
.LBB0_1495:
	ds_read_b128 v[142:145], v149
	ds_read_b128 v[152:155], v149 offset:1024
	ds_read_b128 v[156:159], v149 offset:2048
	ds_read_b128 v[160:163], v149 offset:3072
	ds_read_b128 v[164:167], v150
	ds_read_b128 v[168:171], v150 offset:1024
	ds_read_b128 v[172:175], v150 offset:2048
	ds_read_b128 v[176:179], v150 offset:3072
	s_add_i32 s8, s6, 2
	s_add_u32 s9, s4, 0x80
	s_addc_u32 s7, s5, 0
	s_cmp_eq_u32 s55, s6
	s_cselect_b32 s6, s26, s9
	s_cselect_b32 s7, s27, s7
	s_cselect_b32 s65, s29, s1
	s_cselect_b32 s64, s28, s0
	v_lshl_add_u64 v[212:213], s[4:5], 0, v[136:137]
	s_add_i32 m0, s44, 0xc000
	ds_read_b128 v[180:183], v151
	ds_read_b128 v[184:187], v151 offset:1024
	ds_read_b128 v[188:191], v151 offset:2048
	ds_read_b128 v[192:195], v151 offset:3072
	ds_read_b128 v[196:199], v151 offset:4096
	ds_read_b128 v[200:203], v151 offset:5120
	ds_read_b128 v[204:207], v151 offset:6144
	ds_read_b128 v[208:211], v151 offset:7168
	global_load_lds_dwordx4 v[212:213], off
	v_lshl_add_u64 v[212:213], s[4:5], 0, v[138:139]
	s_add_i32 m0, s44, 0xe000
	s_nop 0
	global_load_lds_dwordx4 v[212:213], off
	s_waitcnt vmcnt(8)
	s_waitcnt lgkmcnt(0)
	s_setprio 1
	s_barrier
; #define PG8_STAGE(bufoff, gbase, voff) do { _Pragma("unroll") for (int _i = 0; _i < 2; ++_i) \
;         __builtin_amdgcn_global_load_lds((const unsigned*)((const char*)(gbase) + (voff)[_i]), (PG8_LAS unsigned*)(lds + (bufoff) + ldsw + _i * 8192), 16, 0, 0); } while (0)
; #define PG8_LDA(dst, b, h) do { _Pragma("unroll") for (int m = 0; m < 4; ++m) _Pragma("unroll") for (int k = 0; k < 2; ++k) dst[m][k] = *(const PG8_LAS bf16x8*)(lds + PG8_SA(b, h) + aoff + m * 2048 + k * 1024); } while (0)
; #define PG8_LDB(dst, b, h) do { _Pragma("unroll") for (int n = 0; n < 2; ++n) _Pragma("unroll") for (int k = 0; k < 2; ++k) dst[n][k] = *(const PG8_LAS bf16x8*)(lds + PG8_SB(b, h) + boff + n * 2048 + k * 1024); } while (0)
; #define PG8_MMA(ai, bj, At, Bt) do { __builtin_amdgcn_s_setprio(1); _Pragma("unroll") for (int m = 0; m < 4; ++m) _Pragma("unroll") for (int n = 0; n < 2; ++n) _Pragma("unroll") for (int k = 0; k < 2; ++k) \
;         acc[ai][bj][m][n] = __builtin_amdgcn_mfma_f32_16x16x32_bf16(Bt[n][k], At[m][k], acc[ai][bj][m][n], 0, 0, 0); __builtin_amdgcn_s_setprio(0); } while (0)
; #define PG8_WAIT_V(n) asm volatile("s_waitcnt vmcnt(" #n ")" ::: "memory")
; #define PG8_WAIT_L(n) asm volatile("s_waitcnt lgkmcnt(" #n ")" ::: "memory")
; #define PG8_BAR __builtin_amdgcn_s_barrier()
; #define PG8_SCHED __builtin_amdgcn_sched_barrier(0)
; template <class Epi, class Sched, bool ALIGN_EPI = false, bool SP2 = false>
; __device__ __forceinline__ void gemm_phase(PG8_LAS unsigned char* lds, const Gemm g, const Sched& S, const Epi& E, const int wid) {
;     ...
;             PG8_LDB(B0, 0, 0); PG8_LDB(B1, 0, 1); PG8_SCHED; PG8_LDA(At, 0, 0); PG8_STAGE(PG8_SA(1, 1), a1 + hstep, voffA);
;             PG8_WAIT_V(8); PG8_WAIT_L(0); PG8_BAR; PG8_MMA(0, 0, At, B0); PG8_MMA(0, 1, At, B1); PG8_BAR; PG8_SCHED;
;             PG8_LDA(At, 0, 1); PG8_STAGE(PG8_SB(0, 0), b2, voffB); PG8_STAGE(PG8_SB(0, 1), b2 + hstep, voffB); PG8_STAGE(PG8_SA(0, 0), a2, voffA);
;             PG8_WAIT_V(8); PG8_WAIT_L(0); PG8_BAR; PG8_MMA(1, 0, At, B0); PG8_MMA(1, 1, At, B1); PG8_BAR; PG8_SCHED;
;             PG8_LDB(B0, 1, 0); PG8_LDB(B1, 1, 1); PG8_SCHED; PG8_LDA(At, 1, 0); PG8_STAGE(PG8_SA(0, 1), a2 + hstep, voffA);
;             PG8_WAIT_V(8); PG8_WAIT_L(0); PG8_BAR; PG8_MMA(0, 0, At, B0); PG8_MMA(0, 1, At, B1); PG8_BAR; PG8_SCHED;
	v_mfma_f32_16x16x32_bf16 v[120:123], v[142:145], v[180:183], v[120:123]
	v_mfma_f32_16x16x32_bf16 v[112:115], v[156:159], v[180:183], v[112:115]
	v_mfma_f32_16x16x32_bf16 v[104:107], v[142:145], v[188:191], v[104:107]
	v_mfma_f32_16x16x32_bf16 v[96:99], v[156:159], v[188:191], v[96:99]
	v_mfma_f32_16x16x32_bf16 v[88:91], v[142:145], v[196:199], v[88:91]
	v_mfma_f32_16x16x32_bf16 v[80:83], v[156:159], v[196:199], v[80:83]
	v_mfma_f32_16x16x32_bf16 v[72:75], v[142:145], v[204:207], v[72:75]
	v_mfma_f32_16x16x32_bf16 v[64:67], v[156:159], v[204:207], v[64:67]
	v_mfma_f32_16x16x32_bf16 v[120:123], v[152:155], v[184:187], v[120:123]
	v_mfma_f32_16x16x32_bf16 v[112:115], v[160:163], v[184:187], v[112:115]
	v_mfma_f32_16x16x32_bf16 v[104:107], v[152:155], v[192:195], v[104:107]
	v_mfma_f32_16x16x32_bf16 v[96:99], v[160:163], v[192:195], v[96:99]
	v_mfma_f32_16x16x32_bf16 v[88:91], v[152:155], v[200:203], v[88:91]
	v_mfma_f32_16x16x32_bf16 v[80:83], v[160:163], v[200:203], v[80:83]
	v_mfma_f32_16x16x32_bf16 v[72:75], v[152:155], v[208:211], v[72:75]
	v_mfma_f32_16x16x32_bf16 v[64:67], v[160:163], v[208:211], v[64:67]
	v_mfma_f32_16x16x32_bf16 v[124:127], v[164:167], v[180:183], v[124:127]
	v_mfma_f32_16x16x32_bf16 v[116:119], v[172:175], v[180:183], v[116:119]
	v_mfma_f32_16x16x32_bf16 v[108:111], v[164:167], v[188:191], v[108:111]
	v_mfma_f32_16x16x32_bf16 v[100:103], v[172:175], v[188:191], v[100:103]
	v_mfma_f32_16x16x32_bf16 v[92:95], v[164:167], v[196:199], v[92:95]
	v_mfma_f32_16x16x32_bf16 v[84:87], v[172:175], v[196:199], v[84:87]
	v_mfma_f32_16x16x32_bf16 v[76:79], v[164:167], v[204:207], v[76:79]
	v_mfma_f32_16x16x32_bf16 v[68:71], v[172:175], v[204:207], v[68:71]
	v_mfma_f32_16x16x32_bf16 v[124:127], v[168:171], v[184:187], v[124:127]
	v_mfma_f32_16x16x32_bf16 v[116:119], v[176:179], v[184:187], v[116:119]
	v_mfma_f32_16x16x32_bf16 v[108:111], v[168:171], v[192:195], v[108:111]
	v_mfma_f32_16x16x32_bf16 v[100:103], v[176:179], v[192:195], v[100:103]
	v_mfma_f32_16x16x32_bf16 v[92:95], v[168:171], v[200:203], v[92:95]
	v_mfma_f32_16x16x32_bf16 v[84:87], v[176:179], v[200:203], v[84:87]
	v_mfma_f32_16x16x32_bf16 v[76:79], v[168:171], v[208:211], v[76:79]
	v_mfma_f32_16x16x32_bf16 v[68:71], v[176:179], v[208:211], v[68:71]
	s_setprio 0
	s_barrier
	s_add_i32 s9, s57, s36
	v_lshl_add_u64 v[212:213], s[64:65], 0, v[132:133]
	s_mov_b32 m0, s9
	ds_read_b128 v[180:183], v151 offset:16384
	ds_read_b128 v[184:187], v151 offset:17408
	ds_read_b128 v[188:191], v151 offset:18432
	ds_read_b128 v[192:195], v151 offset:19456
	ds_read_b128 v[196:199], v151 offset:20480
	ds_read_b128 v[200:203], v151 offset:21504
	ds_read_b128 v[204:207], v151 offset:22528
	ds_read_b128 v[208:211], v151 offset:23552
	global_load_lds_dwordx4 v[212:213], off
	s_add_i32 m0, s9, 0x2000
	v_lshl_add_u64 v[214:215], s[64:65], 0, v[128:129]
	s_add_u32 s64, s64, s12
	s_addc_u32 s65, s65, s13
	s_add_i32 s9, s58, s36
	global_load_lds_dwordx4 v[214:215], off
	v_lshl_add_u64 v[216:217], s[64:65], 0, v[132:133]
	s_mov_b32 m0, s9
	v_lshl_add_u64 v[218:219], s[64:65], 0, v[128:129]
	global_load_lds_dwordx4 v[216:217], off
	s_add_i32 m0, s9, 0x2000
	v_lshl_add_u64 v[220:221], s[6:7], 0, v[134:135]
	global_load_lds_dwordx4 v[218:219], off
	s_mov_b32 m0, s44
	v_lshl_add_u64 v[222:223], s[6:7], 0, v[130:131]
	global_load_lds_dwordx4 v[220:221], off
	s_mov_b32 m0, s45
	s_nop 0
	global_load_lds_dwordx4 v[222:223], off
	s_waitcnt vmcnt(8)
	s_waitcnt lgkmcnt(0)
	s_setprio 1
	s_barrier
	v_mfma_f32_16x16x32_bf16 v[56:59], v[142:145], v[180:183], v[56:59]
	v_mfma_f32_16x16x32_bf16 v[48:51], v[156:159], v[180:183], v[48:51]
	v_mfma_f32_16x16x32_bf16 v[40:43], v[142:145], v[188:191], v[40:43]
	v_mfma_f32_16x16x32_bf16 v[32:35], v[156:159], v[188:191], v[32:35]
	v_mfma_f32_16x16x32_bf16 v[24:27], v[142:145], v[196:199], v[24:27]
	v_mfma_f32_16x16x32_bf16 v[16:19], v[156:159], v[196:199], v[16:19]
	v_mfma_f32_16x16x32_bf16 v[8:11], v[142:145], v[204:207], v[8:11]
	v_mfma_f32_16x16x32_bf16 v[4:7], v[156:159], v[204:207], v[4:7]
	v_mfma_f32_16x16x32_bf16 v[56:59], v[152:155], v[184:187], v[56:59]
	v_mfma_f32_16x16x32_bf16 v[48:51], v[160:163], v[184:187], v[48:51]
	v_mfma_f32_16x16x32_bf16 v[40:43], v[152:155], v[192:195], v[40:43]
	v_mfma_f32_16x16x32_bf16 v[32:35], v[160:163], v[192:195], v[32:35]
	v_mfma_f32_16x16x32_bf16 v[24:27], v[152:155], v[200:203], v[24:27]
	v_mfma_f32_16x16x32_bf16 v[16:19], v[160:163], v[200:203], v[16:19]
	v_mfma_f32_16x16x32_bf16 v[8:11], v[152:155], v[208:211], v[8:11]
	v_mfma_f32_16x16x32_bf16 v[4:7], v[160:163], v[208:211], v[4:7]
	v_mfma_f32_16x16x32_bf16 v[60:63], v[164:167], v[180:183], v[60:63]
	v_mfma_f32_16x16x32_bf16 v[52:55], v[172:175], v[180:183], v[52:55]
	v_mfma_f32_16x16x32_bf16 v[44:47], v[164:167], v[188:191], v[44:47]
	v_mfma_f32_16x16x32_bf16 v[36:39], v[172:175], v[188:191], v[36:39]
	v_mfma_f32_16x16x32_bf16 v[28:31], v[164:167], v[196:199], v[28:31]
	v_mfma_f32_16x16x32_bf16 v[20:23], v[172:175], v[196:199], v[20:23]
	v_mfma_f32_16x16x32_bf16 v[12:15], v[164:167], v[204:207], v[12:15]
	v_mfma_f32_16x16x32_bf16 v[0:3], v[172:175], v[204:207], v[0:3]
	v_mfma_f32_16x16x32_bf16 v[60:63], v[168:171], v[184:187], v[60:63]
	v_mfma_f32_16x16x32_bf16 v[52:55], v[176:179], v[184:187], v[52:55]
	v_mfma_f32_16x16x32_bf16 v[44:47], v[168:171], v[192:195], v[44:47]
	v_mfma_f32_16x16x32_bf16 v[36:39], v[176:179], v[192:195], v[36:39]
	v_mfma_f32_16x16x32_bf16 v[28:31], v[168:171], v[200:203], v[28:31]
	v_mfma_f32_16x16x32_bf16 v[20:23], v[176:179], v[200:203], v[20:23]
	v_mfma_f32_16x16x32_bf16 v[12:15], v[168:171], v[208:211], v[12:15]
	v_mfma_f32_16x16x32_bf16 v[0:3], v[176:179], v[208:211], v[0:3]
	s_setprio 0
	s_barrier
; #define PG8_STAGE(bufoff, gbase, voff) do { _Pragma("unroll") for (int _i = 0; _i < 2; ++_i) \
;         __builtin_amdgcn_global_load_lds((const unsigned*)((const char*)(gbase) + (voff)[_i]), (PG8_LAS unsigned*)(lds + (bufoff) + ldsw + _i * 8192), 16, 0, 0); } while (0)
; #define PG8_LDA(dst, b, h) do { _Pragma("unroll") for (int m = 0; m < 4; ++m) _Pragma("unroll") for (int k = 0; k < 2; ++k) dst[m][k] = *(const PG8_LAS bf16x8*)(lds + PG8_SA(b, h) + aoff + m * 2048 + k * 1024); } while (0)
; #define PG8_LDB(dst, b, h) do { _Pragma("unroll") for (int n = 0; n < 2; ++n) _Pragma("unroll") for (int k = 0; k < 2; ++k) dst[n][k] = *(const PG8_LAS bf16x8*)(lds + PG8_SB(b, h) + boff + n * 2048 + k * 1024); } while (0)
; #define PG8_MMA(ai, bj, At, Bt) do { __builtin_amdgcn_s_setprio(1); _Pragma("unroll") for (int m = 0; m < 4; ++m) _Pragma("unroll") for (int n = 0; n < 2; ++n) _Pragma("unroll") for (int k = 0; k < 2; ++k) \
;         acc[ai][bj][m][n] = __builtin_amdgcn_mfma_f32_16x16x32_bf16(Bt[n][k], At[m][k], acc[ai][bj][m][n], 0, 0, 0); __builtin_amdgcn_s_setprio(0); } while (0)
; #define PG8_WAIT_V(n) asm volatile("s_waitcnt vmcnt(" #n ")" ::: "memory")
; #define PG8_WAIT_L(n) asm volatile("s_waitcnt lgkmcnt(" #n ")" ::: "memory")
; #define PG8_BAR __builtin_amdgcn_s_barrier()
; #define PG8_SCHED __builtin_amdgcn_sched_barrier(0)
; template <class Epi, class Sched, bool ALIGN_EPI = false, bool SP2 = false>
; __device__ __forceinline__ void gemm_phase(PG8_LAS unsigned char* lds, const Gemm g, const Sched& S, const Epi& E, const int wid) {
;     ...
;         for (int t = 0; t < nt; t += 2) {
;     ...
;             PG8_LDB(B0, 1, 0); PG8_LDB(B1, 1, 1); PG8_SCHED; PG8_LDA(At, 1, 0); PG8_STAGE(PG8_SA(0, 1), a2 + hstep, voffA);
;             PG8_WAIT_V(8); PG8_WAIT_L(0); PG8_BAR; PG8_MMA(0, 0, At, B0); PG8_MMA(0, 1, At, B1); PG8_BAR; PG8_SCHED;
;             PG8_LDA(At, 1, 1); PG8_STAGE(PG8_SB(1, 0), b3, voffB); PG8_STAGE(PG8_SB(1, 1), b3 + hstep, voffB); PG8_STAGE(PG8_SA(1, 0), a3, voffA);
;             PG8_WAIT_V(8); PG8_WAIT_L(0); PG8_BAR; PG8_MMA(1, 0, At, B0); PG8_MMA(1, 1, At, B1); PG8_BAR; PG8_SCHED;
	s_add_i32 s9, 0, 0x18000
	s_add_i32 s33, 0, 0x1c000
	v_add_u32_e32 v160, s9, v148
	v_add_u32_e32 v176, s33, v148
	ds_read_b128 v[142:145], v160
	ds_read_b128 v[152:155], v160 offset:1024
	ds_read_b128 v[156:159], v160 offset:2048
	ds_read_b128 v[160:163], v160 offset:3072
	ds_read_b128 v[164:167], v176
	ds_read_b128 v[168:171], v176 offset:1024
	ds_read_b128 v[172:175], v176 offset:2048
	ds_read_b128 v[176:179], v176 offset:3072
	s_add_u32 s6, s6, s12
	s_addc_u32 s7, s7, s13
	s_mov_b32 m0, s46
	v_lshl_add_u64 v[224:225], s[6:7], 0, v[134:135]
	ds_read_b128 v[180:183], v151 offset:32768
	ds_read_b128 v[184:187], v151 offset:33792
	ds_read_b128 v[188:191], v151 offset:34816
	ds_read_b128 v[192:195], v151 offset:35840
	ds_read_b128 v[196:199], v151 offset:36864
	ds_read_b128 v[200:203], v151 offset:37888
	ds_read_b128 v[204:207], v151 offset:38912
	ds_read_b128 v[208:211], v151 offset:39936
	global_load_lds_dwordx4 v[224:225], off
	v_lshl_add_u64 v[224:225], s[6:7], 0, v[130:131]
	s_mov_b32 m0, s47
	s_nop 0
	global_load_lds_dwordx4 v[224:225], off
	s_waitcnt vmcnt(8)
	s_waitcnt lgkmcnt(0)
	s_setprio 1
	s_barrier
	v_mfma_f32_16x16x32_bf16 v[120:123], v[142:145], v[180:183], v[120:123]
	v_mfma_f32_16x16x32_bf16 v[112:115], v[156:159], v[180:183], v[112:115]
	v_mfma_f32_16x16x32_bf16 v[104:107], v[142:145], v[188:191], v[104:107]
	v_mfma_f32_16x16x32_bf16 v[96:99], v[156:159], v[188:191], v[96:99]
	v_mfma_f32_16x16x32_bf16 v[88:91], v[142:145], v[196:199], v[88:91]
	v_mfma_f32_16x16x32_bf16 v[80:83], v[156:159], v[196:199], v[80:83]
	v_mfma_f32_16x16x32_bf16 v[72:75], v[142:145], v[204:207], v[72:75]
	v_mfma_f32_16x16x32_bf16 v[64:67], v[156:159], v[204:207], v[64:67]
	v_mfma_f32_16x16x32_bf16 v[120:123], v[152:155], v[184:187], v[120:123]
	v_mfma_f32_16x16x32_bf16 v[112:115], v[160:163], v[184:187], v[112:115]
	v_mfma_f32_16x16x32_bf16 v[104:107], v[152:155], v[192:195], v[104:107]
	v_mfma_f32_16x16x32_bf16 v[96:99], v[160:163], v[192:195], v[96:99]
	v_mfma_f32_16x16x32_bf16 v[88:91], v[152:155], v[200:203], v[88:91]
	v_mfma_f32_16x16x32_bf16 v[80:83], v[160:163], v[200:203], v[80:83]
	v_mfma_f32_16x16x32_bf16 v[72:75], v[152:155], v[208:211], v[72:75]
	v_mfma_f32_16x16x32_bf16 v[64:67], v[160:163], v[208:211], v[64:67]
	v_mfma_f32_16x16x32_bf16 v[124:127], v[164:167], v[180:183], v[124:127]
	v_mfma_f32_16x16x32_bf16 v[116:119], v[172:175], v[180:183], v[116:119]
	v_mfma_f32_16x16x32_bf16 v[108:111], v[164:167], v[188:191], v[108:111]
	v_mfma_f32_16x16x32_bf16 v[100:103], v[172:175], v[188:191], v[100:103]
	v_mfma_f32_16x16x32_bf16 v[92:95], v[164:167], v[196:199], v[92:95]
	v_mfma_f32_16x16x32_bf16 v[84:87], v[172:175], v[196:199], v[84:87]
	v_mfma_f32_16x16x32_bf16 v[76:79], v[164:167], v[204:207], v[76:79]
	v_mfma_f32_16x16x32_bf16 v[68:71], v[172:175], v[204:207], v[68:71]
	v_mfma_f32_16x16x32_bf16 v[124:127], v[168:171], v[184:187], v[124:127]
	v_mfma_f32_16x16x32_bf16 v[116:119], v[176:179], v[184:187], v[116:119]
	v_mfma_f32_16x16x32_bf16 v[108:111], v[168:171], v[192:195], v[108:111]
	v_mfma_f32_16x16x32_bf16 v[100:103], v[176:179], v[192:195], v[100:103]
	v_mfma_f32_16x16x32_bf16 v[92:95], v[168:171], v[200:203], v[92:95]
	v_mfma_f32_16x16x32_bf16 v[84:87], v[176:179], v[200:203], v[84:87]
	v_mfma_f32_16x16x32_bf16 v[76:79], v[168:171], v[208:211], v[76:79]
	v_mfma_f32_16x16x32_bf16 v[68:71], v[176:179], v[208:211], v[68:71]
	s_setprio 0
	s_barrier
	s_add_i32 s6, s9, s36
	v_lshl_add_u64 v[212:213], v[212:213], 0, s[20:21]
	s_mov_b32 m0, s6
	ds_read_b128 v[180:183], v151 offset:49152
	ds_read_b128 v[184:187], v151 offset:50176
	ds_read_b128 v[188:191], v151 offset:51200
	ds_read_b128 v[192:195], v151 offset:52224
	ds_read_b128 v[196:199], v151 offset:53248
	ds_read_b128 v[200:203], v151 offset:54272
	ds_read_b128 v[204:207], v151 offset:55296
	ds_read_b128 v[208:211], v151 offset:56320
	global_load_lds_dwordx4 v[212:213], off
	v_lshl_add_u64 v[212:213], v[214:215], 0, s[20:21]
	s_add_i32 m0, s6, 0x2000
	s_add_i32 s6, s33, s36
	global_load_lds_dwordx4 v[212:213], off
	v_lshl_add_u64 v[212:213], v[216:217], 0, s[20:21]
	s_mov_b32 m0, s6
	s_nop 0
	global_load_lds_dwordx4 v[212:213], off
	v_lshl_add_u64 v[212:213], v[218:219], 0, s[20:21]
	s_add_i32 m0, s6, 0x2000
	s_nop 0
	global_load_lds_dwordx4 v[212:213], off
	v_lshl_add_u64 v[212:213], v[220:221], 0, s[20:21]
	s_mov_b32 m0, s50
	s_nop 0
	global_load_lds_dwordx4 v[212:213], off
	v_lshl_add_u64 v[212:213], v[222:223], 0, s[20:21]
	s_mov_b32 m0, s51
	s_nop 0
	global_load_lds_dwordx4 v[212:213], off
	s_waitcnt vmcnt(8)
	s_waitcnt lgkmcnt(0)
	s_setprio 1
	s_barrier
	v_mfma_f32_16x16x32_bf16 v[56:59], v[142:145], v[180:183], v[56:59]
	v_mfma_f32_16x16x32_bf16 v[48:51], v[156:159], v[180:183], v[48:51]
	v_mfma_f32_16x16x32_bf16 v[40:43], v[142:145], v[188:191], v[40:43]
	v_mfma_f32_16x16x32_bf16 v[32:35], v[156:159], v[188:191], v[32:35]
	v_mfma_f32_16x16x32_bf16 v[24:27], v[142:145], v[196:199], v[24:27]
	v_mfma_f32_16x16x32_bf16 v[16:19], v[156:159], v[196:199], v[16:19]
	v_mfma_f32_16x16x32_bf16 v[8:11], v[142:145], v[204:207], v[8:11]
	v_mfma_f32_16x16x32_bf16 v[4:7], v[156:159], v[204:207], v[4:7]
	v_mfma_f32_16x16x32_bf16 v[56:59], v[152:155], v[184:187], v[56:59]
	v_mfma_f32_16x16x32_bf16 v[48:51], v[160:163], v[184:187], v[48:51]
	v_mfma_f32_16x16x32_bf16 v[40:43], v[152:155], v[192:195], v[40:43]
	v_mfma_f32_16x16x32_bf16 v[32:35], v[160:163], v[192:195], v[32:35]
	v_mfma_f32_16x16x32_bf16 v[24:27], v[152:155], v[200:203], v[24:27]
	v_mfma_f32_16x16x32_bf16 v[16:19], v[160:163], v[200:203], v[16:19]
	v_mfma_f32_16x16x32_bf16 v[8:11], v[152:155], v[208:211], v[8:11]
	v_mfma_f32_16x16x32_bf16 v[4:7], v[160:163], v[208:211], v[4:7]
	v_mfma_f32_16x16x32_bf16 v[60:63], v[164:167], v[180:183], v[60:63]
	v_mfma_f32_16x16x32_bf16 v[52:55], v[172:175], v[180:183], v[52:55]
	v_mfma_f32_16x16x32_bf16 v[44:47], v[164:167], v[188:191], v[44:47]
	v_mfma_f32_16x16x32_bf16 v[36:39], v[172:175], v[188:191], v[36:39]
	v_mfma_f32_16x16x32_bf16 v[28:31], v[164:167], v[196:199], v[28:31]
	v_mfma_f32_16x16x32_bf16 v[20:23], v[172:175], v[196:199], v[20:23]
	v_mfma_f32_16x16x32_bf16 v[12:15], v[164:167], v[204:207], v[12:15]
	v_mfma_f32_16x16x32_bf16 v[0:3], v[172:175], v[204:207], v[0:3]
	v_mfma_f32_16x16x32_bf16 v[60:63], v[168:171], v[184:187], v[60:63]
	v_mfma_f32_16x16x32_bf16 v[52:55], v[176:179], v[184:187], v[52:55]
	v_mfma_f32_16x16x32_bf16 v[44:47], v[168:171], v[192:195], v[44:47]
	v_mfma_f32_16x16x32_bf16 v[36:39], v[176:179], v[192:195], v[36:39]
	v_mfma_f32_16x16x32_bf16 v[28:31], v[168:171], v[200:203], v[28:31]
	v_mfma_f32_16x16x32_bf16 v[20:23], v[176:179], v[200:203], v[20:23]
	v_mfma_f32_16x16x32_bf16 v[12:15], v[168:171], v[208:211], v[12:15]
	v_mfma_f32_16x16x32_bf16 v[0:3], v[176:179], v[208:211], v[0:3]
	s_setprio 0
	s_barrier
	s_add_u32 s4, s4, 0x100
	s_addc_u32 s5, s5, 0
	s_add_u32 s0, s0, 0x100
	s_addc_u32 s1, s1, 0
	s_cmp_ge_i32 s8, s52
	s_mov_b32 s6, s8
	s_cbranch_scc0 .LBB0_1495

; #define PG8_STAGE(bufoff, gbase, voff) do { _Pragma("unroll") for (int _i = 0; _i < 2; ++_i) \
;         __builtin_amdgcn_global_load_lds((const unsigned*)((const char*)(gbase) + (voff)[_i]), (PG8_LAS unsigned*)(lds + (bufoff) + ldsw + _i * 8192), 16, 0, 0); } while (0)
; #define PG8_LDA(dst, b, h) do { _Pragma("unroll") for (int m = 0; m < 4; ++m) _Pragma("unroll") for (int k = 0; k < 2; ++k) dst[m][k] = *(const PG8_LAS bf16x8*)(lds + PG8_SA(b, h) + aoff + m * 2048 + k * 1024); } while (0)
; #define PG8_LDB(dst, b, h) do { _Pragma("unroll") for (int n = 0; n < 2; ++n) _Pragma("unroll") for (int k = 0; k < 2; ++k) dst[n][k] = *(const PG8_LAS bf16x8*)(lds + PG8_SB(b, h) + boff + n * 2048 + k * 1024); } while (0)
; #define PG8_WAIT_V(n) asm volatile("s_waitcnt vmcnt(" #n ")" ::: "memory")
; #define PG8_WAIT_L(n) asm volatile("s_waitcnt lgkmcnt(" #n ")" ::: "memory")
; #define PG8_BAR __builtin_amdgcn_s_barrier()
; #define PG8_SCHED __builtin_amdgcn_sched_barrier(0)
; template <class Epi, class Sched, bool ALIGN_EPI = false, bool SP2 = false>
; __device__ __forceinline__ void gemm_phase(PG8_LAS unsigned char* lds, const Gemm g, const Sched& S, const Epi& E, const int wid) {
;     ...
;         const bool has_next = S.next(ui + 1, nxt);
;         const char* nA = has_next ? (const char*)g.A + (size_t)nxt.pm * tstep : cA; const char* nB = has_next ? (const char*)g.Bt + (size_t)nxt.pn * tstep : cB;
;         for (int t = 0; t < nt; t += 2) {
;             const bool last = (t == nt - 2);
;             const char* a1 = cA + (size_t)(t + 1) * kstep;
;             const char* a2 = last ? nA : cA + (size_t)(t + 2) * kstep; const char* b2 = last ? nB : cB + (size_t)(t + 2) * kstep;
;             const char* a3 = a2 + kstep; const char* b3 = b2 + kstep;
;             if (last && has_next) S.a_ready(nxt);
;             if constexpr (SP2) {
;             PG8_LDB(B0, 0, 0); PG8_LDB(B1, 0, 1); PG8_SCHED; PG8_LDA(At, 0, 0); PG8_STAGE(PG8_SA(1, 1), a1 + hstep, voffA);
;             PG8_WAIT_V(8); PG8_WAIT_L(0); PG8_BAR; PG8_MMA(0, 0, At, B0); PG8_MMA(0, 1, At, B1); PG8_BAR; PG8_SCHED;
;             PG8_LDA(At, 0, 1); PG8_STAGE(PG8_SB(0, 0), b2, voffB); PG8_STAGE(PG8_SB(0, 1), b2 + hstep, voffB); PG8_STAGE(PG8_SA(0, 0), a2, voffA);
;             PG8_WAIT_V(8); PG8_WAIT_L(0); PG8_BAR; PG8_MMA(1, 0, At, B0); PG8_MMA(1, 1, At, B1); PG8_BAR; PG8_SCHED;
.LBB0_1572:
	s_andn2_b64 vcc, exec, s[18:19]
	s_cbranch_vccnz .Lz_FFN2
	s_add_u32 s40, s40, 0x80
	s_addc_u32 s41, s41, 0
	s_add_u32 s73, s42, 0x100
	s_addc_u32 s74, s43, 0
	s_mov_b32 s42, 0
	ds_read_b128 v[146:149], v143
	ds_read_b128 v[150:153], v143 offset:1024
	ds_read_b128 v[154:157], v143 offset:2048
	ds_read_b128 v[158:161], v143 offset:3072
	ds_read_b128 v[162:165], v144
	ds_read_b128 v[166:169], v144 offset:1024
	ds_read_b128 v[170:173], v144 offset:2048
	ds_read_b128 v[174:177], v144 offset:3072
	s_add_i32 s75, s42, 2
	s_add_u32 s33, s40, 0x80
	s_addc_u32 s43, s41, 0
	s_cmp_eq_u32 s65, s42
	s_cselect_b32 s42, s2, s33
	s_cselect_b32 s43, s3, s43
	s_cselect_b32 s77, s39, s74
	s_cselect_b32 s76, s38, s73
	v_lshl_add_u64 v[138:139], s[40:41], 0, v[132:133]
	s_add_i32 m0, s55, 0xc000
	ds_read_b128 v[178:181], v145
	ds_read_b128 v[182:185], v145 offset:1024
	ds_read_b128 v[186:189], v145 offset:2048
	ds_read_b128 v[190:193], v145 offset:3072
	ds_read_b128 v[194:197], v145 offset:4096
	ds_read_b128 v[198:201], v145 offset:5120
	ds_read_b128 v[202:205], v145 offset:6144
	ds_read_b128 v[206:209], v145 offset:7168
	global_load_lds_dwordx4 v[138:139], off
	v_lshl_add_u64 v[138:139], s[40:41], 0, v[134:135]
	s_add_i32 m0, s55, 0xe000
	s_nop 0
	global_load_lds_dwordx4 v[138:139], off
	s_waitcnt vmcnt(8)
	s_waitcnt lgkmcnt(0)
	s_setprio 1
	s_barrier
	v_mfma_f32_16x16x32_bf16 v[124:127], v[146:149], v[178:181], 0
	v_mfma_f32_16x16x32_bf16 v[120:123], v[154:157], v[178:181], 0
	v_mfma_f32_16x16x32_bf16 v[108:111], v[146:149], v[186:189], 0
	v_mfma_f32_16x16x32_bf16 v[104:107], v[154:157], v[186:189], 0
	v_mfma_f32_16x16x32_bf16 v[92:95], v[146:149], v[194:197], 0
	v_mfma_f32_16x16x32_bf16 v[88:91], v[154:157], v[194:197], 0
	v_mfma_f32_16x16x32_bf16 v[76:79], v[146:149], v[202:205], 0
	v_mfma_f32_16x16x32_bf16 v[72:75], v[154:157], v[202:205], 0
	v_mfma_f32_16x16x32_bf16 v[124:127], v[150:153], v[182:185], v[124:127]
	v_mfma_f32_16x16x32_bf16 v[120:123], v[158:161], v[182:185], v[120:123]
	v_mfma_f32_16x16x32_bf16 v[108:111], v[150:153], v[190:193], v[108:111]
	v_mfma_f32_16x16x32_bf16 v[104:107], v[158:161], v[190:193], v[104:107]
	v_mfma_f32_16x16x32_bf16 v[92:95], v[150:153], v[198:201], v[92:95]
	v_mfma_f32_16x16x32_bf16 v[88:91], v[158:161], v[198:201], v[88:91]
	v_mfma_f32_16x16x32_bf16 v[76:79], v[150:153], v[206:209], v[76:79]
	v_mfma_f32_16x16x32_bf16 v[72:75], v[158:161], v[206:209], v[72:75]
	v_mfma_f32_16x16x32_bf16 v[116:119], v[162:165], v[178:181], 0
	v_mfma_f32_16x16x32_bf16 v[112:115], v[170:173], v[178:181], 0
	v_mfma_f32_16x16x32_bf16 v[100:103], v[162:165], v[186:189], 0
	v_mfma_f32_16x16x32_bf16 v[96:99], v[170:173], v[186:189], 0
	v_mfma_f32_16x16x32_bf16 v[84:87], v[162:165], v[194:197], 0
	v_mfma_f32_16x16x32_bf16 v[80:83], v[170:173], v[194:197], 0
	v_mfma_f32_16x16x32_bf16 v[68:71], v[162:165], v[202:205], 0
	v_mfma_f32_16x16x32_bf16 v[64:67], v[170:173], v[202:205], 0
	v_mfma_f32_16x16x32_bf16 v[116:119], v[166:169], v[182:185], v[116:119]
	v_mfma_f32_16x16x32_bf16 v[112:115], v[174:177], v[182:185], v[112:115]
	v_mfma_f32_16x16x32_bf16 v[100:103], v[166:169], v[190:193], v[100:103]
	v_mfma_f32_16x16x32_bf16 v[96:99], v[174:177], v[190:193], v[96:99]
	v_mfma_f32_16x16x32_bf16 v[84:87], v[166:169], v[198:201], v[84:87]
	v_mfma_f32_16x16x32_bf16 v[80:83], v[174:177], v[198:201], v[80:83]
	v_mfma_f32_16x16x32_bf16 v[68:71], v[166:169], v[206:209], v[68:71]
	v_mfma_f32_16x16x32_bf16 v[64:67], v[174:177], v[206:209], v[64:67]
	s_setprio 0
	s_barrier
	s_add_i32 s33, s67, s47
	v_lshl_add_u64 v[138:139], s[76:77], 0, v[130:131]
	s_mov_b32 m0, s33
	ds_read_b128 v[178:181], v145 offset:16384
	ds_read_b128 v[182:185], v145 offset:17408
	ds_read_b128 v[186:189], v145 offset:18432
	ds_read_b128 v[190:193], v145 offset:19456
	ds_read_b128 v[194:197], v145 offset:20480
	ds_read_b128 v[198:201], v145 offset:21504
	ds_read_b128 v[202:205], v145 offset:22528
	ds_read_b128 v[206:209], v145 offset:23552
	global_load_lds_dwordx4 v[138:139], off
	s_add_i32 m0, s33, 0x2000
	v_lshl_add_u64 v[210:211], s[76:77], 0, v[128:129]
	s_add_u32 s76, s76, s8
	s_addc_u32 s77, s77, s9
	s_add_i32 s33, s68, s47
	global_load_lds_dwordx4 v[210:211], off
	v_lshl_add_u64 v[212:213], s[76:77], 0, v[130:131]
	s_mov_b32 m0, s33
	v_lshl_add_u64 v[214:215], s[76:77], 0, v[128:129]
	global_load_lds_dwordx4 v[212:213], off
	s_add_i32 m0, s33, 0x2000
	v_lshl_add_u64 v[216:217], s[42:43], 0, v[130:131]
	global_load_lds_dwordx4 v[214:215], off
	s_mov_b32 m0, s55
	v_lshl_add_u64 v[218:219], s[42:43], 0, v[128:129]
	global_load_lds_dwordx4 v[216:217], off
	s_mov_b32 m0, s56
	s_nop 0
	global_load_lds_dwordx4 v[218:219], off
	s_waitcnt vmcnt(8)
	s_waitcnt lgkmcnt(0)
	s_setprio 1
	s_barrier
; #define PG8_STAGE(bufoff, gbase, voff) do { _Pragma("unroll") for (int _i = 0; _i < 2; ++_i) \
;         __builtin_amdgcn_global_load_lds((const unsigned*)((const char*)(gbase) + (voff)[_i]), (PG8_LAS unsigned*)(lds + (bufoff) + ldsw + _i * 8192), 16, 0, 0); } while (0)
; #define PG8_LDA(dst, b, h) do { _Pragma("unroll") for (int m = 0; m < 4; ++m) _Pragma("unroll") for (int k = 0; k < 2; ++k) dst[m][k] = *(const PG8_LAS bf16x8*)(lds + PG8_SA(b, h) + aoff + m * 2048 + k * 1024); } while (0)
; #define PG8_LDB(dst, b, h) do { _Pragma("unroll") for (int n = 0; n < 2; ++n) _Pragma("unroll") for (int k = 0; k < 2; ++k) dst[n][k] = *(const PG8_LAS bf16x8*)(lds + PG8_SB(b, h) + boff + n * 2048 + k * 1024); } while (0)
; #define PG8_MMA(ai, bj, At, Bt) do { __builtin_amdgcn_s_setprio(1); _Pragma("unroll") for (int m = 0; m < 4; ++m) _Pragma("unroll") for (int n = 0; n < 2; ++n) _Pragma("unroll") for (int k = 0; k < 2; ++k) \
;         acc[ai][bj][m][n] = __builtin_amdgcn_mfma_f32_16x16x32_bf16(Bt[n][k], At[m][k], acc[ai][bj][m][n], 0, 0, 0); __builtin_amdgcn_s_setprio(0); } while (0)
; #define PG8_WAIT_V(n) asm volatile("s_waitcnt vmcnt(" #n ")" ::: "memory")
; #define PG8_WAIT_L(n) asm volatile("s_waitcnt lgkmcnt(" #n ")" ::: "memory")
; #define PG8_BAR __builtin_amdgcn_s_barrier()
; #define PG8_SCHED __builtin_amdgcn_sched_barrier(0)
; template <class Epi, class Sched, bool ALIGN_EPI = false, bool SP2 = false>
; __device__ __forceinline__ void gemm_phase(PG8_LAS unsigned char* lds, const Gemm g, const Sched& S, const Epi& E, const int wid) {
;     ...
;             PG8_WAIT_V(8); PG8_WAIT_L(0); PG8_BAR; PG8_MMA(0, 0, At, B0); PG8_MMA(0, 1, At, B1); PG8_BAR; PG8_SCHED;
;             PG8_LDA(At, 0, 1); PG8_STAGE(PG8_SB(0, 0), b2, voffB); PG8_STAGE(PG8_SB(0, 1), b2 + hstep, voffB); PG8_STAGE(PG8_SA(0, 0), a2, voffA);
;             PG8_WAIT_V(8); PG8_WAIT_L(0); PG8_BAR; PG8_MMA(1, 0, At, B0); PG8_MMA(1, 1, At, B1); PG8_BAR; PG8_SCHED;
;             PG8_LDB(B0, 1, 0); PG8_LDB(B1, 1, 1); PG8_SCHED; PG8_LDA(At, 1, 0); PG8_STAGE(PG8_SA(0, 1), a2 + hstep, voffA);
	v_mfma_f32_16x16x32_bf16 v[60:63], v[146:149], v[178:181], 0
	v_mfma_f32_16x16x32_bf16 v[56:59], v[154:157], v[178:181], 0
	v_mfma_f32_16x16x32_bf16 v[44:47], v[146:149], v[186:189], 0
	v_mfma_f32_16x16x32_bf16 v[40:43], v[154:157], v[186:189], 0
	v_mfma_f32_16x16x32_bf16 v[28:31], v[146:149], v[194:197], 0
	v_mfma_f32_16x16x32_bf16 v[24:27], v[154:157], v[194:197], 0
	v_mfma_f32_16x16x32_bf16 v[12:15], v[146:149], v[202:205], 0
	v_mfma_f32_16x16x32_bf16 v[8:11], v[154:157], v[202:205], 0
	v_mfma_f32_16x16x32_bf16 v[60:63], v[150:153], v[182:185], v[60:63]
	v_mfma_f32_16x16x32_bf16 v[56:59], v[158:161], v[182:185], v[56:59]
	v_mfma_f32_16x16x32_bf16 v[44:47], v[150:153], v[190:193], v[44:47]
	v_mfma_f32_16x16x32_bf16 v[40:43], v[158:161], v[190:193], v[40:43]
	v_mfma_f32_16x16x32_bf16 v[28:31], v[150:153], v[198:201], v[28:31]
	v_mfma_f32_16x16x32_bf16 v[24:27], v[158:161], v[198:201], v[24:27]
	v_mfma_f32_16x16x32_bf16 v[12:15], v[150:153], v[206:209], v[12:15]
	v_mfma_f32_16x16x32_bf16 v[8:11], v[158:161], v[206:209], v[8:11]
	v_mfma_f32_16x16x32_bf16 v[52:55], v[162:165], v[178:181], 0
	v_mfma_f32_16x16x32_bf16 v[48:51], v[170:173], v[178:181], 0
	v_mfma_f32_16x16x32_bf16 v[36:39], v[162:165], v[186:189], 0
	v_mfma_f32_16x16x32_bf16 v[32:35], v[170:173], v[186:189], 0
	v_mfma_f32_16x16x32_bf16 v[20:23], v[162:165], v[194:197], 0
	v_mfma_f32_16x16x32_bf16 v[16:19], v[170:173], v[194:197], 0
	v_mfma_f32_16x16x32_bf16 v[4:7], v[162:165], v[202:205], 0
	v_mfma_f32_16x16x32_bf16 v[0:3], v[170:173], v[202:205], 0
	v_mfma_f32_16x16x32_bf16 v[52:55], v[166:169], v[182:185], v[52:55]
	v_mfma_f32_16x16x32_bf16 v[48:51], v[174:177], v[182:185], v[48:51]
	v_mfma_f32_16x16x32_bf16 v[36:39], v[166:169], v[190:193], v[36:39]
	v_mfma_f32_16x16x32_bf16 v[32:35], v[174:177], v[190:193], v[32:35]
	v_mfma_f32_16x16x32_bf16 v[20:23], v[166:169], v[198:201], v[20:23]
	v_mfma_f32_16x16x32_bf16 v[16:19], v[174:177], v[198:201], v[16:19]
	v_mfma_f32_16x16x32_bf16 v[4:7], v[166:169], v[206:209], v[4:7]
	v_mfma_f32_16x16x32_bf16 v[0:3], v[174:177], v[206:209], v[0:3]
	s_setprio 0
	s_barrier
	s_add_i32 s33, 0, 0x18000
	s_add_i32 s76, 0, 0x1c000
	v_add_u32_e32 v158, s33, v142
	v_add_u32_e32 v174, s76, v142
	ds_read_b128 v[146:149], v158
	ds_read_b128 v[150:153], v158 offset:1024
	ds_read_b128 v[154:157], v158 offset:2048
	ds_read_b128 v[158:161], v158 offset:3072
	ds_read_b128 v[162:165], v174
	ds_read_b128 v[166:169], v174 offset:1024
	ds_read_b128 v[170:173], v174 offset:2048
	ds_read_b128 v[174:177], v174 offset:3072
	s_add_u32 s42, s42, s8
	s_addc_u32 s43, s43, s9
	s_mov_b32 m0, s57
	v_lshl_add_u64 v[220:221], s[42:43], 0, v[130:131]
	ds_read_b128 v[178:181], v145 offset:32768
	ds_read_b128 v[182:185], v145 offset:33792
	ds_read_b128 v[186:189], v145 offset:34816
	ds_read_b128 v[190:193], v145 offset:35840
	ds_read_b128 v[194:197], v145 offset:36864
	ds_read_b128 v[198:201], v145 offset:37888
	ds_read_b128 v[202:205], v145 offset:38912
	ds_read_b128 v[206:209], v145 offset:39936
	global_load_lds_dwordx4 v[220:221], off
	v_lshl_add_u64 v[220:221], s[42:43], 0, v[128:129]
	s_mov_b32 m0, s58
	s_nop 0
	global_load_lds_dwordx4 v[220:221], off
	s_waitcnt vmcnt(8)
	s_waitcnt lgkmcnt(0)
	s_setprio 1
	s_barrier
	v_mfma_f32_16x16x32_bf16 v[124:127], v[146:149], v[178:181], v[124:127]
	v_mfma_f32_16x16x32_bf16 v[120:123], v[154:157], v[178:181], v[120:123]
	v_mfma_f32_16x16x32_bf16 v[108:111], v[146:149], v[186:189], v[108:111]
	v_mfma_f32_16x16x32_bf16 v[104:107], v[154:157], v[186:189], v[104:107]
	v_mfma_f32_16x16x32_bf16 v[92:95], v[146:149], v[194:197], v[92:95]
	v_mfma_f32_16x16x32_bf16 v[88:91], v[154:157], v[194:197], v[88:91]
	v_mfma_f32_16x16x32_bf16 v[76:79], v[146:149], v[202:205], v[76:79]
	v_mfma_f32_16x16x32_bf16 v[72:75], v[154:157], v[202:205], v[72:75]
	v_mfma_f32_16x16x32_bf16 v[124:127], v[150:153], v[182:185], v[124:127]
	v_mfma_f32_16x16x32_bf16 v[120:123], v[158:161], v[182:185], v[120:123]
	v_mfma_f32_16x16x32_bf16 v[108:111], v[150:153], v[190:193], v[108:111]
	v_mfma_f32_16x16x32_bf16 v[104:107], v[158:161], v[190:193], v[104:107]
	v_mfma_f32_16x16x32_bf16 v[92:95], v[150:153], v[198:201], v[92:95]
	v_mfma_f32_16x16x32_bf16 v[88:91], v[158:161], v[198:201], v[88:91]
	v_mfma_f32_16x16x32_bf16 v[76:79], v[150:153], v[206:209], v[76:79]
	v_mfma_f32_16x16x32_bf16 v[72:75], v[158:161], v[206:209], v[72:75]
	v_mfma_f32_16x16x32_bf16 v[116:119], v[162:165], v[178:181], v[116:119]
	v_mfma_f32_16x16x32_bf16 v[112:115], v[170:173], v[178:181], v[112:115]
	v_mfma_f32_16x16x32_bf16 v[100:103], v[162:165], v[186:189], v[100:103]
	v_mfma_f32_16x16x32_bf16 v[96:99], v[170:173], v[186:189], v[96:99]
	v_mfma_f32_16x16x32_bf16 v[84:87], v[162:165], v[194:197], v[84:87]
	v_mfma_f32_16x16x32_bf16 v[80:83], v[170:173], v[194:197], v[80:83]
	v_mfma_f32_16x16x32_bf16 v[68:71], v[162:165], v[202:205], v[68:71]
	v_mfma_f32_16x16x32_bf16 v[64:67], v[170:173], v[202:205], v[64:67]
	v_mfma_f32_16x16x32_bf16 v[116:119], v[166:169], v[182:185], v[116:119]
	v_mfma_f32_16x16x32_bf16 v[112:115], v[174:177], v[182:185], v[112:115]
	v_mfma_f32_16x16x32_bf16 v[100:103], v[166:169], v[190:193], v[100:103]
	v_mfma_f32_16x16x32_bf16 v[96:99], v[174:177], v[190:193], v[96:99]
	v_mfma_f32_16x16x32_bf16 v[84:87], v[166:169], v[198:201], v[84:87]
	v_mfma_f32_16x16x32_bf16 v[80:83], v[174:177], v[198:201], v[80:83]
	v_mfma_f32_16x16x32_bf16 v[68:71], v[166:169], v[206:209], v[68:71]
	v_mfma_f32_16x16x32_bf16 v[64:67], v[174:177], v[206:209], v[64:67]
	s_setprio 0
	s_barrier
; #define PG8_STAGE(bufoff, gbase, voff) do { _Pragma("unroll") for (int _i = 0; _i < 2; ++_i) \
;         __builtin_amdgcn_global_load_lds((const unsigned*)((const char*)(gbase) + (voff)[_i]), (PG8_LAS unsigned*)(lds + (bufoff) + ldsw + _i * 8192), 16, 0, 0); } while (0)
; #define PG8_LDA(dst, b, h) do { _Pragma("unroll") for (int m = 0; m < 4; ++m) _Pragma("unroll") for (int k = 0; k < 2; ++k) dst[m][k] = *(const PG8_LAS bf16x8*)(lds + PG8_SA(b, h) + aoff + m * 2048 + k * 1024); } while (0)
; #define PG8_WAIT_V(n) asm volatile("s_waitcnt vmcnt(" #n ")" ::: "memory")
; #define PG8_WAIT_L(n) asm volatile("s_waitcnt lgkmcnt(" #n ")" ::: "memory")
; #define PG8_BAR __builtin_amdgcn_s_barrier()
; template <class Epi, class Sched, bool ALIGN_EPI = false, bool SP2 = false>
; __device__ __forceinline__ void gemm_phase(PG8_LAS unsigned char* lds, const Gemm g, const Sched& S, const Epi& E, const int wid) {
;     ...
;         for (int t = 0; t < nt; t += 2) {
;             const bool last = (t == nt - 2);
;             const char* a1 = cA + (size_t)(t + 1) * kstep;
;             const char* a2 = last ? nA : cA + (size_t)(t + 2) * kstep; const char* b2 = last ? nB : cB + (size_t)(t + 2) * kstep;
;             const char* a3 = a2 + kstep; const char* b3 = b2 + kstep;
;             if (last && has_next) S.a_ready(nxt);
;             if constexpr (SP2) {
;             PG8_LDB(B0, 0, 0); PG8_LDB(B1, 0, 1); PG8_SCHED; PG8_LDA(At, 0, 0); PG8_STAGE(PG8_SA(1, 1), a1 + hstep, voffA);
;             PG8_WAIT_V(8); PG8_WAIT_L(0); PG8_BAR; PG8_MMA(0, 0, At, B0); PG8_MMA(0, 1, At, B1); PG8_BAR; PG8_SCHED;
;             PG8_LDA(At, 0, 1); PG8_STAGE(PG8_SB(0, 0), b2, voffB); PG8_STAGE(PG8_SB(0, 1), b2 + hstep, voffB); PG8_STAGE(PG8_SA(0, 0), a2, voffA);
;             PG8_WAIT_V(8); PG8_WAIT_L(0); PG8_BAR; PG8_MMA(1, 0, At, B0); PG8_MMA(1, 1, At, B1); PG8_BAR; PG8_SCHED;
;             PG8_LDB(B0, 1, 0); PG8_LDB(B1, 1, 1); PG8_SCHED; PG8_LDA(At, 1, 0); PG8_STAGE(PG8_SA(0, 1), a2 + hstep, voffA);
;             PG8_WAIT_V(8); PG8_WAIT_L(0); PG8_BAR; PG8_MMA(0, 0, At, B0); PG8_MMA(0, 1, At, B1); PG8_BAR; PG8_SCHED;
;             PG8_LDA(At, 1, 1); PG8_STAGE(PG8_SB(1, 0), b3, voffB); PG8_STAGE(PG8_SB(1, 1), b3 + hstep, voffB); PG8_STAGE(PG8_SA(1, 0), a3, voffA);
;             PG8_WAIT_V(8); PG8_WAIT_L(0); PG8_BAR; PG8_MMA(1, 0, At, B0); PG8_MMA(1, 1, At, B1); PG8_BAR; PG8_SCHED;
	s_add_i32 s33, s33, s47
	v_lshl_add_u64 v[138:139], v[138:139], 0, s[16:17]
	s_mov_b32 m0, s33
	ds_read_b128 v[178:181], v145 offset:49152
	ds_read_b128 v[182:185], v145 offset:50176
	ds_read_b128 v[186:189], v145 offset:51200
	ds_read_b128 v[190:193], v145 offset:52224
	ds_read_b128 v[194:197], v145 offset:53248
	ds_read_b128 v[198:201], v145 offset:54272
	ds_read_b128 v[202:205], v145 offset:55296
	ds_read_b128 v[206:209], v145 offset:56320
	global_load_lds_dwordx4 v[138:139], off
	v_lshl_add_u64 v[138:139], v[210:211], 0, s[16:17]
	s_add_i32 m0, s33, 0x2000
	s_add_i32 s33, s76, s47
	global_load_lds_dwordx4 v[138:139], off
	v_lshl_add_u64 v[138:139], v[212:213], 0, s[16:17]
	s_mov_b32 m0, s33
	s_nop 0
	global_load_lds_dwordx4 v[138:139], off
	v_lshl_add_u64 v[138:139], v[214:215], 0, s[16:17]
	s_add_i32 m0, s33, 0x2000
	s_nop 0
	global_load_lds_dwordx4 v[138:139], off
	v_lshl_add_u64 v[138:139], v[216:217], 0, s[16:17]
	s_mov_b32 m0, s60
	s_nop 0
	global_load_lds_dwordx4 v[138:139], off
	v_lshl_add_u64 v[138:139], v[218:219], 0, s[16:17]
	s_mov_b32 m0, s61
	s_nop 0
	global_load_lds_dwordx4 v[138:139], off
	s_waitcnt vmcnt(8)
	s_waitcnt lgkmcnt(0)
	s_setprio 1
	s_barrier
	v_mfma_f32_16x16x32_bf16 v[60:63], v[146:149], v[178:181], v[60:63]
	v_mfma_f32_16x16x32_bf16 v[56:59], v[154:157], v[178:181], v[56:59]
	v_mfma_f32_16x16x32_bf16 v[44:47], v[146:149], v[186:189], v[44:47]
	v_mfma_f32_16x16x32_bf16 v[40:43], v[154:157], v[186:189], v[40:43]
	v_mfma_f32_16x16x32_bf16 v[28:31], v[146:149], v[194:197], v[28:31]
	v_mfma_f32_16x16x32_bf16 v[24:27], v[154:157], v[194:197], v[24:27]
	v_mfma_f32_16x16x32_bf16 v[12:15], v[146:149], v[202:205], v[12:15]
	v_mfma_f32_16x16x32_bf16 v[8:11], v[154:157], v[202:205], v[8:11]
	v_mfma_f32_16x16x32_bf16 v[60:63], v[150:153], v[182:185], v[60:63]
	v_mfma_f32_16x16x32_bf16 v[56:59], v[158:161], v[182:185], v[56:59]
	v_mfma_f32_16x16x32_bf16 v[44:47], v[150:153], v[190:193], v[44:47]
	v_mfma_f32_16x16x32_bf16 v[40:43], v[158:161], v[190:193], v[40:43]
	v_mfma_f32_16x16x32_bf16 v[28:31], v[150:153], v[198:201], v[28:31]
	v_mfma_f32_16x16x32_bf16 v[24:27], v[158:161], v[198:201], v[24:27]
	v_mfma_f32_16x16x32_bf16 v[12:15], v[150:153], v[206:209], v[12:15]
	v_mfma_f32_16x16x32_bf16 v[8:11], v[158:161], v[206:209], v[8:11]
	v_mfma_f32_16x16x32_bf16 v[52:55], v[162:165], v[178:181], v[52:55]
	v_mfma_f32_16x16x32_bf16 v[48:51], v[170:173], v[178:181], v[48:51]
	v_mfma_f32_16x16x32_bf16 v[36:39], v[162:165], v[186:189], v[36:39]
	v_mfma_f32_16x16x32_bf16 v[32:35], v[170:173], v[186:189], v[32:35]
	v_mfma_f32_16x16x32_bf16 v[20:23], v[162:165], v[194:197], v[20:23]
	v_mfma_f32_16x16x32_bf16 v[16:19], v[170:173], v[194:197], v[16:19]
	v_mfma_f32_16x16x32_bf16 v[4:7], v[162:165], v[202:205], v[4:7]
	v_mfma_f32_16x16x32_bf16 v[0:3], v[170:173], v[202:205], v[0:3]
	v_mfma_f32_16x16x32_bf16 v[52:55], v[166:169], v[182:185], v[52:55]
	v_mfma_f32_16x16x32_bf16 v[48:51], v[174:177], v[182:185], v[48:51]
	v_mfma_f32_16x16x32_bf16 v[36:39], v[166:169], v[190:193], v[36:39]
	v_mfma_f32_16x16x32_bf16 v[32:35], v[174:177], v[190:193], v[32:35]
	v_mfma_f32_16x16x32_bf16 v[20:23], v[166:169], v[198:201], v[20:23]
	v_mfma_f32_16x16x32_bf16 v[16:19], v[174:177], v[198:201], v[16:19]
	v_mfma_f32_16x16x32_bf16 v[4:7], v[166:169], v[206:209], v[4:7]
	v_mfma_f32_16x16x32_bf16 v[0:3], v[174:177], v[206:209], v[0:3]
	s_setprio 0
	s_barrier
	s_add_u32 s40, s40, 0x100
	s_addc_u32 s41, s41, 0
	s_add_u32 s73, s73, 0x100
	s_addc_u32 s74, s74, 0
	s_cmp_ge_i32 s75, s62
	s_mov_b32 s42, s75
	s_cbranch_scc1 .LBB0_1575
.LBB0_1574:
	ds_read_b128 v[146:149], v143
	ds_read_b128 v[150:153], v143 offset:1024
	ds_read_b128 v[154:157], v143 offset:2048
	ds_read_b128 v[158:161], v143 offset:3072
	ds_read_b128 v[162:165], v144
	ds_read_b128 v[166:169], v144 offset:1024
	ds_read_b128 v[170:173], v144 offset:2048
	ds_read_b128 v[174:177], v144 offset:3072
	s_add_i32 s75, s42, 2
	s_add_u32 s33, s40, 0x80
	s_addc_u32 s43, s41, 0
	s_cmp_eq_u32 s65, s42
	s_cselect_b32 s42, s2, s33
	s_cselect_b32 s43, s3, s43
	s_cselect_b32 s77, s39, s74
	s_cselect_b32 s76, s38, s73
	v_lshl_add_u64 v[138:139], s[40:41], 0, v[132:133]
	s_add_i32 m0, s55, 0xc000
	ds_read_b128 v[178:181], v145
	ds_read_b128 v[182:185], v145 offset:1024
	ds_read_b128 v[186:189], v145 offset:2048
	ds_read_b128 v[190:193], v145 offset:3072
	ds_read_b128 v[194:197], v145 offset:4096
	ds_read_b128 v[198:201], v145 offset:5120
	ds_read_b128 v[202:205], v145 offset:6144
	ds_read_b128 v[206:209], v145 offset:7168
	global_load_lds_dwordx4 v[138:139], off
	v_lshl_add_u64 v[138:139], s[40:41], 0, v[134:135]
	s_add_i32 m0, s55, 0xe000
	s_nop 0
	global_load_lds_dwordx4 v[138:139], off
	s_waitcnt vmcnt(8)
	s_waitcnt lgkmcnt(0)
	s_setprio 1
	s_barrier
; #define PG8_STAGE(bufoff, gbase, voff) do { _Pragma("unroll") for (int _i = 0; _i < 2; ++_i) \
;         __builtin_amdgcn_global_load_lds((const unsigned*)((const char*)(gbase) + (voff)[_i]), (PG8_LAS unsigned*)(lds + (bufoff) + ldsw + _i * 8192), 16, 0, 0); } while (0)
; #define PG8_LDA(dst, b, h) do { _Pragma("unroll") for (int m = 0; m < 4; ++m) _Pragma("unroll") for (int k = 0; k < 2; ++k) dst[m][k] = *(const PG8_LAS bf16x8*)(lds + PG8_SA(b, h) + aoff + m * 2048 + k * 1024); } while (0)
; #define PG8_LDB(dst, b, h) do { _Pragma("unroll") for (int n = 0; n < 2; ++n) _Pragma("unroll") for (int k = 0; k < 2; ++k) dst[n][k] = *(const PG8_LAS bf16x8*)(lds + PG8_SB(b, h) + boff + n * 2048 + k * 1024); } while (0)
; #define PG8_MMA(ai, bj, At, Bt) do { __builtin_amdgcn_s_setprio(1); _Pragma("unroll") for (int m = 0; m < 4; ++m) _Pragma("unroll") for (int n = 0; n < 2; ++n) _Pragma("unroll") for (int k = 0; k < 2; ++k) \
;         acc[ai][bj][m][n] = __builtin_amdgcn_mfma_f32_16x16x32_bf16(Bt[n][k], At[m][k], acc[ai][bj][m][n], 0, 0, 0); __builtin_amdgcn_s_setprio(0); } while (0)
; #define PG8_WAIT_V(n) asm volatile("s_waitcnt vmcnt(" #n ")" ::: "memory")
; #define PG8_WAIT_L(n) asm volatile("s_waitcnt lgkmcnt(" #n ")" ::: "memory")
; #define PG8_BAR __builtin_amdgcn_s_barrier()
; #define PG8_SCHED __builtin_amdgcn_sched_barrier(0)
; template <class Epi, class Sched, bool ALIGN_EPI = false, bool SP2 = false>
; __device__ __forceinline__ void gemm_phase(PG8_LAS unsigned char* lds, const Gemm g, const Sched& S, const Epi& E, const int wid) {
;     ...
;             PG8_LDB(B0, 0, 0); PG8_LDB(B1, 0, 1); PG8_SCHED; PG8_LDA(At, 0, 0); PG8_STAGE(PG8_SA(1, 1), a1 + hstep, voffA);
;             PG8_WAIT_V(8); PG8_WAIT_L(0); PG8_BAR; PG8_MMA(0, 0, At, B0); PG8_MMA(0, 1, At, B1); PG8_BAR; PG8_SCHED;
;             PG8_LDA(At, 0, 1); PG8_STAGE(PG8_SB(0, 0), b2, voffB); PG8_STAGE(PG8_SB(0, 1), b2 + hstep, voffB); PG8_STAGE(PG8_SA(0, 0), a2, voffA);
;             PG8_WAIT_V(8); PG8_WAIT_L(0); PG8_BAR; PG8_MMA(1, 0, At, B0); PG8_MMA(1, 1, At, B1); PG8_BAR; PG8_SCHED;
;             PG8_LDB(B0, 1, 0); PG8_LDB(B1, 1, 1); PG8_SCHED; PG8_LDA(At, 1, 0); PG8_STAGE(PG8_SA(0, 1), a2 + hstep, voffA);
;             PG8_WAIT_V(8); PG8_WAIT_L(0); PG8_BAR; PG8_MMA(0, 0, At, B0); PG8_MMA(0, 1, At, B1); PG8_BAR; PG8_SCHED;
	v_mfma_f32_16x16x32_bf16 v[124:127], v[146:149], v[178:181], v[124:127]
	v_mfma_f32_16x16x32_bf16 v[120:123], v[154:157], v[178:181], v[120:123]
	v_mfma_f32_16x16x32_bf16 v[108:111], v[146:149], v[186:189], v[108:111]
	v_mfma_f32_16x16x32_bf16 v[104:107], v[154:157], v[186:189], v[104:107]
	v_mfma_f32_16x16x32_bf16 v[92:95], v[146:149], v[194:197], v[92:95]
	v_mfma_f32_16x16x32_bf16 v[88:91], v[154:157], v[194:197], v[88:91]
	v_mfma_f32_16x16x32_bf16 v[76:79], v[146:149], v[202:205], v[76:79]
	v_mfma_f32_16x16x32_bf16 v[72:75], v[154:157], v[202:205], v[72:75]
	v_mfma_f32_16x16x32_bf16 v[124:127], v[150:153], v[182:185], v[124:127]
	v_mfma_f32_16x16x32_bf16 v[120:123], v[158:161], v[182:185], v[120:123]
	v_mfma_f32_16x16x32_bf16 v[108:111], v[150:153], v[190:193], v[108:111]
	v_mfma_f32_16x16x32_bf16 v[104:107], v[158:161], v[190:193], v[104:107]
	v_mfma_f32_16x16x32_bf16 v[92:95], v[150:153], v[198:201], v[92:95]
	v_mfma_f32_16x16x32_bf16 v[88:91], v[158:161], v[198:201], v[88:91]
	v_mfma_f32_16x16x32_bf16 v[76:79], v[150:153], v[206:209], v[76:79]
	v_mfma_f32_16x16x32_bf16 v[72:75], v[158:161], v[206:209], v[72:75]
	v_mfma_f32_16x16x32_bf16 v[116:119], v[162:165], v[178:181], v[116:119]
	v_mfma_f32_16x16x32_bf16 v[112:115], v[170:173], v[178:181], v[112:115]
	v_mfma_f32_16x16x32_bf16 v[100:103], v[162:165], v[186:189], v[100:103]
	v_mfma_f32_16x16x32_bf16 v[96:99], v[170:173], v[186:189], v[96:99]
	v_mfma_f32_16x16x32_bf16 v[84:87], v[162:165], v[194:197], v[84:87]
	v_mfma_f32_16x16x32_bf16 v[80:83], v[170:173], v[194:197], v[80:83]
	v_mfma_f32_16x16x32_bf16 v[68:71], v[162:165], v[202:205], v[68:71]
	v_mfma_f32_16x16x32_bf16 v[64:67], v[170:173], v[202:205], v[64:67]
	v_mfma_f32_16x16x32_bf16 v[116:119], v[166:169], v[182:185], v[116:119]
	v_mfma_f32_16x16x32_bf16 v[112:115], v[174:177], v[182:185], v[112:115]
	v_mfma_f32_16x16x32_bf16 v[100:103], v[166:169], v[190:193], v[100:103]
	v_mfma_f32_16x16x32_bf16 v[96:99], v[174:177], v[190:193], v[96:99]
	v_mfma_f32_16x16x32_bf16 v[84:87], v[166:169], v[198:201], v[84:87]
	v_mfma_f32_16x16x32_bf16 v[80:83], v[174:177], v[198:201], v[80:83]
	v_mfma_f32_16x16x32_bf16 v[68:71], v[166:169], v[206:209], v[68:71]
	v_mfma_f32_16x16x32_bf16 v[64:67], v[174:177], v[206:209], v[64:67]
	s_setprio 0
	s_barrier
	s_add_i32 s33, s67, s47
	v_lshl_add_u64 v[138:139], s[76:77], 0, v[130:131]
	s_mov_b32 m0, s33
	ds_read_b128 v[178:181], v145 offset:16384
	ds_read_b128 v[182:185], v145 offset:17408
	ds_read_b128 v[186:189], v145 offset:18432
	ds_read_b128 v[190:193], v145 offset:19456
	ds_read_b128 v[194:197], v145 offset:20480
	ds_read_b128 v[198:201], v145 offset:21504
	ds_read_b128 v[202:205], v145 offset:22528
	ds_read_b128 v[206:209], v145 offset:23552
	global_load_lds_dwordx4 v[138:139], off
	s_add_i32 m0, s33, 0x2000
	v_lshl_add_u64 v[210:211], s[76:77], 0, v[128:129]
	s_add_u32 s76, s76, s8
	s_addc_u32 s77, s77, s9
	s_add_i32 s33, s68, s47
	global_load_lds_dwordx4 v[210:211], off
	v_lshl_add_u64 v[212:213], s[76:77], 0, v[130:131]
	s_mov_b32 m0, s33
	v_lshl_add_u64 v[214:215], s[76:77], 0, v[128:129]
	global_load_lds_dwordx4 v[212:213], off
	s_add_i32 m0, s33, 0x2000
	v_lshl_add_u64 v[216:217], s[42:43], 0, v[130:131]
	global_load_lds_dwordx4 v[214:215], off
	s_mov_b32 m0, s55
	v_lshl_add_u64 v[218:219], s[42:43], 0, v[128:129]
	global_load_lds_dwordx4 v[216:217], off
	s_mov_b32 m0, s56
	s_nop 0
	global_load_lds_dwordx4 v[218:219], off
	s_waitcnt vmcnt(8)
	s_waitcnt lgkmcnt(0)
	s_setprio 1
	s_barrier
	v_mfma_f32_16x16x32_bf16 v[60:63], v[146:149], v[178:181], v[60:63]
	v_mfma_f32_16x16x32_bf16 v[56:59], v[154:157], v[178:181], v[56:59]
	v_mfma_f32_16x16x32_bf16 v[44:47], v[146:149], v[186:189], v[44:47]
	v_mfma_f32_16x16x32_bf16 v[40:43], v[154:157], v[186:189], v[40:43]
	v_mfma_f32_16x16x32_bf16 v[28:31], v[146:149], v[194:197], v[28:31]
	v_mfma_f32_16x16x32_bf16 v[24:27], v[154:157], v[194:197], v[24:27]
	v_mfma_f32_16x16x32_bf16 v[12:15], v[146:149], v[202:205], v[12:15]
	v_mfma_f32_16x16x32_bf16 v[8:11], v[154:157], v[202:205], v[8:11]
	v_mfma_f32_16x16x32_bf16 v[60:63], v[150:153], v[182:185], v[60:63]
	v_mfma_f32_16x16x32_bf16 v[56:59], v[158:161], v[182:185], v[56:59]
	v_mfma_f32_16x16x32_bf16 v[44:47], v[150:153], v[190:193], v[44:47]
	v_mfma_f32_16x16x32_bf16 v[40:43], v[158:161], v[190:193], v[40:43]
	v_mfma_f32_16x16x32_bf16 v[28:31], v[150:153], v[198:201], v[28:31]
	v_mfma_f32_16x16x32_bf16 v[24:27], v[158:161], v[198:201], v[24:27]
	v_mfma_f32_16x16x32_bf16 v[12:15], v[150:153], v[206:209], v[12:15]
	v_mfma_f32_16x16x32_bf16 v[8:11], v[158:161], v[206:209], v[8:11]
	v_mfma_f32_16x16x32_bf16 v[52:55], v[162:165], v[178:181], v[52:55]
	v_mfma_f32_16x16x32_bf16 v[48:51], v[170:173], v[178:181], v[48:51]
	v_mfma_f32_16x16x32_bf16 v[36:39], v[162:165], v[186:189], v[36:39]
	v_mfma_f32_16x16x32_bf16 v[32:35], v[170:173], v[186:189], v[32:35]
	v_mfma_f32_16x16x32_bf16 v[20:23], v[162:165], v[194:197], v[20:23]
	v_mfma_f32_16x16x32_bf16 v[16:19], v[170:173], v[194:197], v[16:19]
	v_mfma_f32_16x16x32_bf16 v[4:7], v[162:165], v[202:205], v[4:7]
	v_mfma_f32_16x16x32_bf16 v[0:3], v[170:173], v[202:205], v[0:3]
	v_mfma_f32_16x16x32_bf16 v[52:55], v[166:169], v[182:185], v[52:55]
	v_mfma_f32_16x16x32_bf16 v[48:51], v[174:177], v[182:185], v[48:51]
	v_mfma_f32_16x16x32_bf16 v[36:39], v[166:169], v[190:193], v[36:39]
	v_mfma_f32_16x16x32_bf16 v[32:35], v[174:177], v[190:193], v[32:35]
	v_mfma_f32_16x16x32_bf16 v[20:23], v[166:169], v[198:201], v[20:23]
	v_mfma_f32_16x16x32_bf16 v[16:19], v[174:177], v[198:201], v[16:19]
	v_mfma_f32_16x16x32_bf16 v[4:7], v[166:169], v[206:209], v[4:7]
	v_mfma_f32_16x16x32_bf16 v[0:3], v[174:177], v[206:209], v[0:3]
	s_setprio 0
	s_barrier
; #define PG8_STAGE(bufoff, gbase, voff) do { _Pragma("unroll") for (int _i = 0; _i < 2; ++_i) \
;         __builtin_amdgcn_global_load_lds((const unsigned*)((const char*)(gbase) + (voff)[_i]), (PG8_LAS unsigned*)(lds + (bufoff) + ldsw + _i * 8192), 16, 0, 0); } while (0)
; #define PG8_LDA(dst, b, h) do { _Pragma("unroll") for (int m = 0; m < 4; ++m) _Pragma("unroll") for (int k = 0; k < 2; ++k) dst[m][k] = *(const PG8_LAS bf16x8*)(lds + PG8_SA(b, h) + aoff + m * 2048 + k * 1024); } while (0)
; #define PG8_LDB(dst, b, h) do { _Pragma("unroll") for (int n = 0; n < 2; ++n) _Pragma("unroll") for (int k = 0; k < 2; ++k) dst[n][k] = *(const PG8_LAS bf16x8*)(lds + PG8_SB(b, h) + boff + n * 2048 + k * 1024); } while (0)
; #define PG8_MMA(ai, bj, At, Bt) do { __builtin_amdgcn_s_setprio(1); _Pragma("unroll") for (int m = 0; m < 4; ++m) _Pragma("unroll") for (int n = 0; n < 2; ++n) _Pragma("unroll") for (int k = 0; k < 2; ++k) \
;         acc[ai][bj][m][n] = __builtin_amdgcn_mfma_f32_16x16x32_bf16(Bt[n][k], At[m][k], acc[ai][bj][m][n], 0, 0, 0); __builtin_amdgcn_s_setprio(0); } while (0)
; #define PG8_WAIT_V(n) asm volatile("s_waitcnt vmcnt(" #n ")" ::: "memory")
; #define PG8_WAIT_L(n) asm volatile("s_waitcnt lgkmcnt(" #n ")" ::: "memory")
; #define PG8_BAR __builtin_amdgcn_s_barrier()
; #define PG8_SCHED __builtin_amdgcn_sched_barrier(0)
; template <class Epi, class Sched, bool ALIGN_EPI = false, bool SP2 = false>
; __device__ __forceinline__ void gemm_phase(PG8_LAS unsigned char* lds, const Gemm g, const Sched& S, const Epi& E, const int wid) {
;     ...
;         for (int t = 0; t < nt; t += 2) {
;     ...
;             PG8_LDB(B0, 1, 0); PG8_LDB(B1, 1, 1); PG8_SCHED; PG8_LDA(At, 1, 0); PG8_STAGE(PG8_SA(0, 1), a2 + hstep, voffA);
;             PG8_WAIT_V(8); PG8_WAIT_L(0); PG8_BAR; PG8_MMA(0, 0, At, B0); PG8_MMA(0, 1, At, B1); PG8_BAR; PG8_SCHED;
;             PG8_LDA(At, 1, 1); PG8_STAGE(PG8_SB(1, 0), b3, voffB); PG8_STAGE(PG8_SB(1, 1), b3 + hstep, voffB); PG8_STAGE(PG8_SA(1, 0), a3, voffA);
;             PG8_WAIT_V(8); PG8_WAIT_L(0); PG8_BAR; PG8_MMA(1, 0, At, B0); PG8_MMA(1, 1, At, B1); PG8_BAR; PG8_SCHED;
	s_add_i32 s33, 0, 0x18000
	s_add_i32 s76, 0, 0x1c000
	v_add_u32_e32 v158, s33, v142
	v_add_u32_e32 v174, s76, v142
	ds_read_b128 v[146:149], v158
	ds_read_b128 v[150:153], v158 offset:1024
	ds_read_b128 v[154:157], v158 offset:2048
	ds_read_b128 v[158:161], v158 offset:3072
	ds_read_b128 v[162:165], v174
	ds_read_b128 v[166:169], v174 offset:1024
	ds_read_b128 v[170:173], v174 offset:2048
	ds_read_b128 v[174:177], v174 offset:3072
	s_add_u32 s42, s42, s8
	s_addc_u32 s43, s43, s9
	s_mov_b32 m0, s57
	v_lshl_add_u64 v[220:221], s[42:43], 0, v[130:131]
	ds_read_b128 v[178:181], v145 offset:32768
	ds_read_b128 v[182:185], v145 offset:33792
	ds_read_b128 v[186:189], v145 offset:34816
	ds_read_b128 v[190:193], v145 offset:35840
	ds_read_b128 v[194:197], v145 offset:36864
	ds_read_b128 v[198:201], v145 offset:37888
	ds_read_b128 v[202:205], v145 offset:38912
	ds_read_b128 v[206:209], v145 offset:39936
	global_load_lds_dwordx4 v[220:221], off
	v_lshl_add_u64 v[220:221], s[42:43], 0, v[128:129]
	s_mov_b32 m0, s58
	s_nop 0
	global_load_lds_dwordx4 v[220:221], off
	s_waitcnt vmcnt(8)
	s_waitcnt lgkmcnt(0)
	s_setprio 1
	s_barrier
	v_mfma_f32_16x16x32_bf16 v[124:127], v[146:149], v[178:181], v[124:127]
	v_mfma_f32_16x16x32_bf16 v[120:123], v[154:157], v[178:181], v[120:123]
	v_mfma_f32_16x16x32_bf16 v[108:111], v[146:149], v[186:189], v[108:111]
	v_mfma_f32_16x16x32_bf16 v[104:107], v[154:157], v[186:189], v[104:107]
	v_mfma_f32_16x16x32_bf16 v[92:95], v[146:149], v[194:197], v[92:95]
	v_mfma_f32_16x16x32_bf16 v[88:91], v[154:157], v[194:197], v[88:91]
	v_mfma_f32_16x16x32_bf16 v[76:79], v[146:149], v[202:205], v[76:79]
	v_mfma_f32_16x16x32_bf16 v[72:75], v[154:157], v[202:205], v[72:75]
	v_mfma_f32_16x16x32_bf16 v[124:127], v[150:153], v[182:185], v[124:127]
	v_mfma_f32_16x16x32_bf16 v[120:123], v[158:161], v[182:185], v[120:123]
	v_mfma_f32_16x16x32_bf16 v[108:111], v[150:153], v[190:193], v[108:111]
	v_mfma_f32_16x16x32_bf16 v[104:107], v[158:161], v[190:193], v[104:107]
	v_mfma_f32_16x16x32_bf16 v[92:95], v[150:153], v[198:201], v[92:95]
	v_mfma_f32_16x16x32_bf16 v[88:91], v[158:161], v[198:201], v[88:91]
	v_mfma_f32_16x16x32_bf16 v[76:79], v[150:153], v[206:209], v[76:79]
	v_mfma_f32_16x16x32_bf16 v[72:75], v[158:161], v[206:209], v[72:75]
	v_mfma_f32_16x16x32_bf16 v[116:119], v[162:165], v[178:181], v[116:119]
	v_mfma_f32_16x16x32_bf16 v[112:115], v[170:173], v[178:181], v[112:115]
	v_mfma_f32_16x16x32_bf16 v[100:103], v[162:165], v[186:189], v[100:103]
	v_mfma_f32_16x16x32_bf16 v[96:99], v[170:173], v[186:189], v[96:99]
	v_mfma_f32_16x16x32_bf16 v[84:87], v[162:165], v[194:197], v[84:87]
	v_mfma_f32_16x16x32_bf16 v[80:83], v[170:173], v[194:197], v[80:83]
	v_mfma_f32_16x16x32_bf16 v[68:71], v[162:165], v[202:205], v[68:71]
	v_mfma_f32_16x16x32_bf16 v[64:67], v[170:173], v[202:205], v[64:67]
	v_mfma_f32_16x16x32_bf16 v[116:119], v[166:169], v[182:185], v[116:119]
	v_mfma_f32_16x16x32_bf16 v[112:115], v[174:177], v[182:185], v[112:115]
	v_mfma_f32_16x16x32_bf16 v[100:103], v[166:169], v[190:193], v[100:103]
	v_mfma_f32_16x16x32_bf16 v[96:99], v[174:177], v[190:193], v[96:99]
	v_mfma_f32_16x16x32_bf16 v[84:87], v[166:169], v[198:201], v[84:87]
	v_mfma_f32_16x16x32_bf16 v[80:83], v[174:177], v[198:201], v[80:83]
	v_mfma_f32_16x16x32_bf16 v[68:71], v[166:169], v[206:209], v[68:71]
	v_mfma_f32_16x16x32_bf16 v[64:67], v[174:177], v[206:209], v[64:67]
	s_setprio 0
	s_barrier
	s_add_i32 s33, s33, s47
	v_lshl_add_u64 v[138:139], v[138:139], 0, s[16:17]
	s_mov_b32 m0, s33
	ds_read_b128 v[178:181], v145 offset:49152
	ds_read_b128 v[182:185], v145 offset:50176
	ds_read_b128 v[186:189], v145 offset:51200
	ds_read_b128 v[190:193], v145 offset:52224
	ds_read_b128 v[194:197], v145 offset:53248
	ds_read_b128 v[198:201], v145 offset:54272
	ds_read_b128 v[202:205], v145 offset:55296
	ds_read_b128 v[206:209], v145 offset:56320
	global_load_lds_dwordx4 v[138:139], off
	v_lshl_add_u64 v[138:139], v[210:211], 0, s[16:17]
	s_add_i32 m0, s33, 0x2000
	s_add_i32 s33, s76, s47
	global_load_lds_dwordx4 v[138:139], off
	v_lshl_add_u64 v[138:139], v[212:213], 0, s[16:17]
	s_mov_b32 m0, s33
	s_nop 0
	global_load_lds_dwordx4 v[138:139], off
	v_lshl_add_u64 v[138:139], v[214:215], 0, s[16:17]
	s_add_i32 m0, s33, 0x2000
	s_nop 0
	global_load_lds_dwordx4 v[138:139], off
	v_lshl_add_u64 v[138:139], v[216:217], 0, s[16:17]
	s_mov_b32 m0, s60
	s_nop 0
	global_load_lds_dwordx4 v[138:139], off
	v_lshl_add_u64 v[138:139], v[218:219], 0, s[16:17]
	s_mov_b32 m0, s61
	s_nop 0
	global_load_lds_dwordx4 v[138:139], off
	s_waitcnt vmcnt(8)
	s_waitcnt lgkmcnt(0)
	s_setprio 1
	s_barrier
	v_mfma_f32_16x16x32_bf16 v[60:63], v[146:149], v[178:181], v[60:63]
	v_mfma_f32_16x16x32_bf16 v[56:59], v[154:157], v[178:181], v[56:59]
	v_mfma_f32_16x16x32_bf16 v[44:47], v[146:149], v[186:189], v[44:47]
	v_mfma_f32_16x16x32_bf16 v[40:43], v[154:157], v[186:189], v[40:43]
	v_mfma_f32_16x16x32_bf16 v[28:31], v[146:149], v[194:197], v[28:31]
	v_mfma_f32_16x16x32_bf16 v[24:27], v[154:157], v[194:197], v[24:27]
	v_mfma_f32_16x16x32_bf16 v[12:15], v[146:149], v[202:205], v[12:15]
	v_mfma_f32_16x16x32_bf16 v[8:11], v[154:157], v[202:205], v[8:11]
	v_mfma_f32_16x16x32_bf16 v[60:63], v[150:153], v[182:185], v[60:63]
	v_mfma_f32_16x16x32_bf16 v[56:59], v[158:161], v[182:185], v[56:59]
	v_mfma_f32_16x16x32_bf16 v[44:47], v[150:153], v[190:193], v[44:47]
	v_mfma_f32_16x16x32_bf16 v[40:43], v[158:161], v[190:193], v[40:43]
	v_mfma_f32_16x16x32_bf16 v[28:31], v[150:153], v[198:201], v[28:31]
	v_mfma_f32_16x16x32_bf16 v[24:27], v[158:161], v[198:201], v[24:27]
	v_mfma_f32_16x16x32_bf16 v[12:15], v[150:153], v[206:209], v[12:15]
	v_mfma_f32_16x16x32_bf16 v[8:11], v[158:161], v[206:209], v[8:11]
	v_mfma_f32_16x16x32_bf16 v[52:55], v[162:165], v[178:181], v[52:55]
	v_mfma_f32_16x16x32_bf16 v[48:51], v[170:173], v[178:181], v[48:51]
	v_mfma_f32_16x16x32_bf16 v[36:39], v[162:165], v[186:189], v[36:39]
	v_mfma_f32_16x16x32_bf16 v[32:35], v[170:173], v[186:189], v[32:35]
	v_mfma_f32_16x16x32_bf16 v[20:23], v[162:165], v[194:197], v[20:23]
	v_mfma_f32_16x16x32_bf16 v[16:19], v[170:173], v[194:197], v[16:19]
	v_mfma_f32_16x16x32_bf16 v[4:7], v[162:165], v[202:205], v[4:7]
	v_mfma_f32_16x16x32_bf16 v[0:3], v[170:173], v[202:205], v[0:3]
	v_mfma_f32_16x16x32_bf16 v[52:55], v[166:169], v[182:185], v[52:55]
	v_mfma_f32_16x16x32_bf16 v[48:51], v[174:177], v[182:185], v[48:51]
	v_mfma_f32_16x16x32_bf16 v[36:39], v[166:169], v[190:193], v[36:39]
	v_mfma_f32_16x16x32_bf16 v[32:35], v[174:177], v[190:193], v[32:35]
	v_mfma_f32_16x16x32_bf16 v[20:23], v[166:169], v[198:201], v[20:23]
	v_mfma_f32_16x16x32_bf16 v[16:19], v[174:177], v[198:201], v[16:19]
	v_mfma_f32_16x16x32_bf16 v[4:7], v[166:169], v[206:209], v[4:7]
	v_mfma_f32_16x16x32_bf16 v[0:3], v[174:177], v[206:209], v[0:3]
	s_setprio 0
	s_barrier
	s_add_u32 s40, s40, 0x100
	s_addc_u32 s41, s41, 0
	s_add_u32 s73, s73, 0x100
	s_addc_u32 s74, s74, 0
	s_cmp_ge_i32 s75, s62
	s_mov_b32 s42, s75
	s_cbranch_scc0 .LBB0_1574
